# GEMM: accumulator zero-init removed; first K iteration of each unit runs MFMA segments 0/1 with C=0 (flagged out-of-line copies)
# baseline (speedup 1.0000x reference)
.Lzc0_0:
	s_setprio 1
	s_waitcnt lgkmcnt(0)
	v_mfma_f32_16x16x32_bf16 v[124:127], v[128:131], v[186:189], 0
	v_mfma_f32_16x16x32_bf16 v[120:123], v[136:139], v[186:189], 0
	v_mfma_f32_16x16x32_bf16 v[108:111], v[128:131], v[194:197], 0
	v_mfma_f32_16x16x32_bf16 v[104:107], v[136:139], v[194:197], 0
	v_mfma_f32_16x16x32_bf16 v[92:95], v[128:131], v[202:205], 0
	v_mfma_f32_16x16x32_bf16 v[88:91], v[136:139], v[202:205], 0
	v_mfma_f32_16x16x32_bf16 v[76:79], v[128:131], v[210:213], 0
	v_mfma_f32_16x16x32_bf16 v[72:75], v[136:139], v[210:213], 0
	v_mfma_f32_16x16x32_bf16 v[124:127], v[132:135], v[190:193], v[124:127]
	v_mfma_f32_16x16x32_bf16 v[120:123], v[146:149], v[190:193], v[120:123]
	v_mfma_f32_16x16x32_bf16 v[108:111], v[132:135], v[198:201], v[108:111]
	v_mfma_f32_16x16x32_bf16 v[104:107], v[146:149], v[198:201], v[104:107]
	v_mfma_f32_16x16x32_bf16 v[92:95], v[132:135], v[206:209], v[92:95]
	v_mfma_f32_16x16x32_bf16 v[88:91], v[146:149], v[206:209], v[88:91]
	v_mfma_f32_16x16x32_bf16 v[76:79], v[132:135], v[218:221], v[76:79]
	v_mfma_f32_16x16x32_bf16 v[72:75], v[146:149], v[218:221], v[72:75]
	s_setprio 0
	s_setprio 1
	v_mfma_f32_16x16x32_bf16 v[116:119], v[150:153], v[186:189], 0
	v_mfma_f32_16x16x32_bf16 v[112:115], v[158:161], v[186:189], 0
	v_mfma_f32_16x16x32_bf16 v[100:103], v[150:153], v[194:197], 0
	v_mfma_f32_16x16x32_bf16 v[96:99], v[158:161], v[194:197], 0
	v_mfma_f32_16x16x32_bf16 v[84:87], v[150:153], v[202:205], 0
	v_mfma_f32_16x16x32_bf16 v[80:83], v[158:161], v[202:205], 0
	v_mfma_f32_16x16x32_bf16 v[68:71], v[150:153], v[210:213], 0
	v_mfma_f32_16x16x32_bf16 v[64:67], v[158:161], v[210:213], 0
	v_mfma_f32_16x16x32_bf16 v[116:119], v[154:157], v[190:193], v[116:119]
	v_mfma_f32_16x16x32_bf16 v[112:115], v[162:165], v[190:193], v[112:115]
	v_mfma_f32_16x16x32_bf16 v[100:103], v[154:157], v[198:201], v[100:103]
	v_mfma_f32_16x16x32_bf16 v[96:99], v[162:165], v[198:201], v[96:99]
	v_mfma_f32_16x16x32_bf16 v[84:87], v[154:157], v[206:209], v[84:87]
	v_mfma_f32_16x16x32_bf16 v[80:83], v[162:165], v[206:209], v[80:83]
	v_mfma_f32_16x16x32_bf16 v[68:71], v[154:157], v[218:221], v[68:71]
	v_mfma_f32_16x16x32_bf16 v[64:67], v[162:165], v[218:221], v[64:67]
	s_setprio 0
	s_branch .Lzc0_0j
.Lzc0_1:
	s_setprio 1
	s_waitcnt lgkmcnt(0)
	v_mfma_f32_16x16x32_bf16 v[60:63], v[128:131], v[186:189], 0
	v_mfma_f32_16x16x32_bf16 v[56:59], v[136:139], v[186:189], 0
	v_mfma_f32_16x16x32_bf16 v[44:47], v[128:131], v[194:197], 0
	v_mfma_f32_16x16x32_bf16 v[40:43], v[136:139], v[194:197], 0
	v_mfma_f32_16x16x32_bf16 v[28:31], v[128:131], v[202:205], 0
	v_mfma_f32_16x16x32_bf16 v[24:27], v[136:139], v[202:205], 0
	v_mfma_f32_16x16x32_bf16 v[12:15], v[128:131], v[210:213], 0
	v_mfma_f32_16x16x32_bf16 v[8:11], v[136:139], v[210:213], 0
	v_mfma_f32_16x16x32_bf16 v[60:63], v[132:135], v[190:193], v[60:63]
	v_mfma_f32_16x16x32_bf16 v[56:59], v[146:149], v[190:193], v[56:59]
	v_mfma_f32_16x16x32_bf16 v[44:47], v[132:135], v[198:201], v[44:47]
	v_mfma_f32_16x16x32_bf16 v[40:43], v[146:149], v[198:201], v[40:43]
	v_mfma_f32_16x16x32_bf16 v[28:31], v[132:135], v[206:209], v[28:31]
	v_mfma_f32_16x16x32_bf16 v[24:27], v[146:149], v[206:209], v[24:27]
	v_mfma_f32_16x16x32_bf16 v[12:15], v[132:135], v[218:221], v[12:15]
	v_mfma_f32_16x16x32_bf16 v[8:11], v[146:149], v[218:221], v[8:11]
	s_setprio 0
	s_setprio 1
	v_mfma_f32_16x16x32_bf16 v[52:55], v[150:153], v[186:189], 0
	v_mfma_f32_16x16x32_bf16 v[48:51], v[158:161], v[186:189], 0
	v_mfma_f32_16x16x32_bf16 v[36:39], v[150:153], v[194:197], 0
	v_mfma_f32_16x16x32_bf16 v[32:35], v[158:161], v[194:197], 0
	v_mfma_f32_16x16x32_bf16 v[20:23], v[150:153], v[202:205], 0
	v_mfma_f32_16x16x32_bf16 v[16:19], v[158:161], v[202:205], 0
	v_mfma_f32_16x16x32_bf16 v[4:7], v[150:153], v[210:213], 0
	v_mfma_f32_16x16x32_bf16 v[0:3], v[158:161], v[210:213], 0
	v_mfma_f32_16x16x32_bf16 v[52:55], v[154:157], v[190:193], v[52:55]
	v_mfma_f32_16x16x32_bf16 v[48:51], v[162:165], v[190:193], v[48:51]
	v_mfma_f32_16x16x32_bf16 v[36:39], v[154:157], v[198:201], v[36:39]
	v_mfma_f32_16x16x32_bf16 v[32:35], v[162:165], v[198:201], v[32:35]
	v_mfma_f32_16x16x32_bf16 v[20:23], v[154:157], v[206:209], v[20:23]
	v_mfma_f32_16x16x32_bf16 v[16:19], v[162:165], v[206:209], v[16:19]
	v_mfma_f32_16x16x32_bf16 v[4:7], v[154:157], v[218:221], v[4:7]
	v_mfma_f32_16x16x32_bf16 v[0:3], v[162:165], v[218:221], v[0:3]
	s_setprio 0
	s_branch .Lzc0_1j
.Lzc0_skip:
	v_mov_b32_e32 v0, 0
	v_mov_b32_e32 v1, 0
	v_mov_b32_e32 v2, 0
	v_mov_b32_e32 v3, 0
	v_mov_b32_e32 v4, 0
	v_mov_b32_e32 v5, 0
	v_mov_b32_e32 v6, 0
	v_mov_b32_e32 v7, 0
	v_mov_b32_e32 v8, 0
	v_mov_b32_e32 v9, 0
	v_mov_b32_e32 v10, 0
	v_mov_b32_e32 v11, 0
	v_mov_b32_e32 v12, 0
	v_mov_b32_e32 v13, 0
	v_mov_b32_e32 v14, 0
	v_mov_b32_e32 v15, 0
	v_mov_b32_e32 v16, 0
	v_mov_b32_e32 v17, 0
	v_mov_b32_e32 v18, 0
	v_mov_b32_e32 v19, 0
	v_mov_b32_e32 v20, 0
	v_mov_b32_e32 v21, 0
	v_mov_b32_e32 v22, 0
	v_mov_b32_e32 v23, 0
	v_mov_b32_e32 v24, 0
	v_mov_b32_e32 v25, 0
	v_mov_b32_e32 v26, 0
	v_mov_b32_e32 v27, 0
	v_mov_b32_e32 v28, 0
	v_mov_b32_e32 v29, 0
	v_mov_b32_e32 v30, 0
	v_mov_b32_e32 v31, 0
	v_mov_b32_e32 v32, 0
	v_mov_b32_e32 v33, 0
	v_mov_b32_e32 v34, 0
	v_mov_b32_e32 v35, 0
	v_mov_b32_e32 v36, 0
	v_mov_b32_e32 v37, 0
	v_mov_b32_e32 v38, 0
	v_mov_b32_e32 v39, 0
	v_mov_b32_e32 v40, 0
	v_mov_b32_e32 v41, 0
	v_mov_b32_e32 v42, 0
	v_mov_b32_e32 v43, 0
	v_mov_b32_e32 v44, 0
	v_mov_b32_e32 v45, 0
	v_mov_b32_e32 v46, 0
	v_mov_b32_e32 v47, 0
	v_mov_b32_e32 v48, 0
	v_mov_b32_e32 v49, 0
	v_mov_b32_e32 v50, 0
	v_mov_b32_e32 v51, 0
	v_mov_b32_e32 v52, 0
	v_mov_b32_e32 v53, 0
	v_mov_b32_e32 v54, 0
	v_mov_b32_e32 v55, 0
	v_mov_b32_e32 v56, 0
	v_mov_b32_e32 v57, 0
	v_mov_b32_e32 v58, 0
	v_mov_b32_e32 v59, 0
	v_mov_b32_e32 v60, 0
	v_mov_b32_e32 v61, 0
	v_mov_b32_e32 v62, 0
	v_mov_b32_e32 v63, 0
	v_mov_b32_e32 v64, 0
	v_mov_b32_e32 v65, 0
	v_mov_b32_e32 v66, 0
	v_mov_b32_e32 v67, 0
	v_mov_b32_e32 v68, 0
	v_mov_b32_e32 v69, 0
	v_mov_b32_e32 v70, 0
	v_mov_b32_e32 v71, 0
	v_mov_b32_e32 v72, 0
	v_mov_b32_e32 v73, 0
	v_mov_b32_e32 v74, 0
	v_mov_b32_e32 v75, 0
	v_mov_b32_e32 v76, 0
	v_mov_b32_e32 v77, 0
	v_mov_b32_e32 v78, 0
	v_mov_b32_e32 v79, 0
	v_mov_b32_e32 v80, 0
	v_mov_b32_e32 v81, 0
	v_mov_b32_e32 v82, 0
	v_mov_b32_e32 v83, 0
	v_mov_b32_e32 v84, 0
	v_mov_b32_e32 v85, 0
	v_mov_b32_e32 v86, 0
	v_mov_b32_e32 v87, 0
	v_mov_b32_e32 v88, 0
	v_mov_b32_e32 v89, 0
	v_mov_b32_e32 v90, 0
	v_mov_b32_e32 v91, 0
	v_mov_b32_e32 v92, 0
	v_mov_b32_e32 v93, 0
	v_mov_b32_e32 v94, 0
	v_mov_b32_e32 v95, 0
	v_mov_b32_e32 v96, 0
	v_mov_b32_e32 v97, 0
	v_mov_b32_e32 v98, 0
	v_mov_b32_e32 v99, 0
	v_mov_b32_e32 v100, 0
	v_mov_b32_e32 v101, 0
	v_mov_b32_e32 v102, 0
	v_mov_b32_e32 v103, 0
	v_mov_b32_e32 v104, 0
	v_mov_b32_e32 v105, 0
	v_mov_b32_e32 v106, 0
	v_mov_b32_e32 v107, 0
	v_mov_b32_e32 v108, 0
	v_mov_b32_e32 v109, 0
	v_mov_b32_e32 v110, 0
	v_mov_b32_e32 v111, 0
	v_mov_b32_e32 v112, 0
	v_mov_b32_e32 v113, 0
	v_mov_b32_e32 v114, 0
	v_mov_b32_e32 v115, 0
	v_mov_b32_e32 v116, 0
	v_mov_b32_e32 v117, 0
	v_mov_b32_e32 v118, 0
	v_mov_b32_e32 v119, 0
	v_mov_b32_e32 v120, 0
	v_mov_b32_e32 v121, 0
	v_mov_b32_e32 v122, 0
	v_mov_b32_e32 v123, 0
	v_mov_b32_e32 v124, 0
	v_mov_b32_e32 v125, 0
	v_mov_b32_e32 v126, 0
	v_mov_b32_e32 v127, 0
	s_branch .LBB0_43

.LBB0_40:
	s_ashr_i32 s61, s60, 31
	s_lshl_b64 s[20:21], s[60:61], 21
	s_add_u32 s64, s24, s20
	s_addc_u32 s65, s25, s21
	s_ashr_i32 s63, s62, 31
	s_lshl_b64 s[20:21], s[62:63], 21
	v_readlane_b32 s42, v254, 54
	s_add_u32 s66, s42, s20
	v_readlane_b32 s20, v254, 62
	s_addc_u32 s67, s20, s21
	s_andn2_b64 vcc, exec, s[56:57]
	s_waitcnt lgkmcnt(0)
	s_cbranch_vccnz .Lzc0_skip
	s_and_b64 s[20:21], s[38:39], exec
	s_cselect_b32 s42, s65, s1
	s_cselect_b32 s43, s64, s0
	s_cselect_b32 s44, s67, s3
	s_cselect_b32 s45, s66, s2
	s_add_u32 s0, s0, 0x100080
	s_addc_u32 s1, s1, 0
	s_add_u32 s46, s2, 0x100
	s_addc_u32 s47, s3, 0
	s_mov_b32 s2, 0
	s_mov_b32 s32, 1
.LBB0_42:
	s_add_i32 s53, s2, 2
	s_add_u32 s3, s0, 0xfff00080
	s_addc_u32 s20, s1, -1
	s_add_i32 s50, 0, 0x10000
	s_cmp_eq_u32 s48, s2
	s_cselect_b32 s21, s42, s20
	s_cselect_b32 s20, s43, s3
	s_cselect_b32 s3, s44, s47
	s_cselect_b32 s2, s45, s46
	s_add_i32 s51, 0, 0x14000
	v_add_u32_e32 v146, s50, v215
	v_add_u32_e32 v162, s51, v215
	ds_read_b128 v[128:131], v146
	ds_read_b128 v[132:135], v146 offset:1024
	ds_read_b128 v[136:139], v146 offset:2048
	ds_read_b128 v[146:149], v146 offset:3072
	ds_read_b128 v[150:153], v162
	ds_read_b128 v[154:157], v162 offset:1024
	ds_read_b128 v[158:161], v162 offset:2048
	ds_read_b128 v[162:165], v162 offset:3072
	v_lshl_add_u64 v[166:167], s[0:1], 0, v[142:143]
	s_add_i32 m0, s27, 0xc000
	ds_read_b128 v[186:189], v216
	ds_read_b128 v[190:193], v216 offset:1024
	ds_read_b128 v[194:197], v216 offset:2048
	ds_read_b128 v[198:201], v216 offset:3072
	ds_read_b128 v[202:205], v216 offset:4096
	ds_read_b128 v[206:209], v216 offset:5120
	ds_read_b128 v[210:213], v216 offset:6144
	ds_read_b128 v[218:221], v216 offset:7168
	global_load_lds_dwordx4 v[166:167], off
	v_lshl_add_u64 v[166:167], s[0:1], 0, v[144:145]
	s_add_i32 m0, s27, 0xe000
	s_nop 0
	global_load_lds_dwordx4 v[166:167], off
	s_waitcnt vmcnt(8)
	s_waitcnt lgkmcnt(0)
	s_barrier
	s_cmp_lg_u32 s32, 0
	s_cbranch_scc1 .Lzc0_0
	s_setprio 1
	s_waitcnt lgkmcnt(0)
	v_mfma_f32_16x16x32_bf16 v[124:127], v[128:131], v[186:189], v[124:127]
	v_mfma_f32_16x16x32_bf16 v[120:123], v[136:139], v[186:189], v[120:123]
	v_mfma_f32_16x16x32_bf16 v[108:111], v[128:131], v[194:197], v[108:111]
	v_mfma_f32_16x16x32_bf16 v[104:107], v[136:139], v[194:197], v[104:107]
	v_mfma_f32_16x16x32_bf16 v[92:95], v[128:131], v[202:205], v[92:95]
	v_mfma_f32_16x16x32_bf16 v[88:91], v[136:139], v[202:205], v[88:91]
	v_mfma_f32_16x16x32_bf16 v[76:79], v[128:131], v[210:213], v[76:79]
	v_mfma_f32_16x16x32_bf16 v[72:75], v[136:139], v[210:213], v[72:75]
	v_mfma_f32_16x16x32_bf16 v[124:127], v[132:135], v[190:193], v[124:127]
	v_mfma_f32_16x16x32_bf16 v[120:123], v[146:149], v[190:193], v[120:123]
	v_mfma_f32_16x16x32_bf16 v[108:111], v[132:135], v[198:201], v[108:111]
	v_mfma_f32_16x16x32_bf16 v[104:107], v[146:149], v[198:201], v[104:107]
	v_mfma_f32_16x16x32_bf16 v[92:95], v[132:135], v[206:209], v[92:95]
	v_mfma_f32_16x16x32_bf16 v[88:91], v[146:149], v[206:209], v[88:91]
	v_mfma_f32_16x16x32_bf16 v[76:79], v[132:135], v[218:221], v[76:79]
	v_mfma_f32_16x16x32_bf16 v[72:75], v[146:149], v[218:221], v[72:75]
	s_setprio 0
	s_setprio 1
	v_mfma_f32_16x16x32_bf16 v[116:119], v[150:153], v[186:189], v[116:119]
	v_mfma_f32_16x16x32_bf16 v[112:115], v[158:161], v[186:189], v[112:115]
	v_mfma_f32_16x16x32_bf16 v[100:103], v[150:153], v[194:197], v[100:103]
	v_mfma_f32_16x16x32_bf16 v[96:99], v[158:161], v[194:197], v[96:99]
	v_mfma_f32_16x16x32_bf16 v[84:87], v[150:153], v[202:205], v[84:87]
	v_mfma_f32_16x16x32_bf16 v[80:83], v[158:161], v[202:205], v[80:83]
	v_mfma_f32_16x16x32_bf16 v[68:71], v[150:153], v[210:213], v[68:71]
	v_mfma_f32_16x16x32_bf16 v[64:67], v[158:161], v[210:213], v[64:67]
	v_mfma_f32_16x16x32_bf16 v[116:119], v[154:157], v[190:193], v[116:119]
	v_mfma_f32_16x16x32_bf16 v[112:115], v[162:165], v[190:193], v[112:115]
	v_mfma_f32_16x16x32_bf16 v[100:103], v[154:157], v[198:201], v[100:103]
	v_mfma_f32_16x16x32_bf16 v[96:99], v[162:165], v[198:201], v[96:99]
	v_mfma_f32_16x16x32_bf16 v[84:87], v[154:157], v[206:209], v[84:87]
	v_mfma_f32_16x16x32_bf16 v[80:83], v[162:165], v[206:209], v[80:83]
	v_mfma_f32_16x16x32_bf16 v[68:71], v[154:157], v[218:221], v[68:71]
	v_mfma_f32_16x16x32_bf16 v[64:67], v[162:165], v[218:221], v[64:67]
	s_setprio 0
.Lzc0_0j:
	s_barrier
	s_add_i32 s50, s50, s26
	v_lshl_add_u64 v[166:167], s[2:3], 0, v[168:169]
	s_mov_b32 m0, s50
	ds_read_b128 v[186:189], v216 offset:16384
	ds_read_b128 v[190:193], v216 offset:17408
	ds_read_b128 v[194:197], v216 offset:18432
	ds_read_b128 v[198:201], v216 offset:19456
	ds_read_b128 v[202:205], v216 offset:20480
	ds_read_b128 v[206:209], v216 offset:21504
	ds_read_b128 v[210:213], v216 offset:22528
	ds_read_b128 v[218:221], v216 offset:23552
	global_load_lds_dwordx4 v[166:167], off
	s_add_i32 m0, s50, 0x2000
	s_add_u32 s68, s2, 0x100000
	v_lshl_add_u64 v[222:223], s[2:3], 0, v[140:141]
	s_addc_u32 s69, s3, 0
	s_add_i32 s50, s51, s26
	global_load_lds_dwordx4 v[222:223], off
	v_lshl_add_u64 v[234:235], s[68:69], 0, v[168:169]
	s_mov_b32 m0, s50
	v_lshl_add_u64 v[236:237], s[20:21], 0, v[140:141]
	global_load_lds_dwordx4 v[234:235], off
	v_lshl_add_u64 v[234:235], s[68:69], 0, v[140:141]
	s_add_i32 m0, s50, 0x2000
	s_nop 0
	global_load_lds_dwordx4 v[234:235], off
	v_lshl_add_u64 v[234:235], s[20:21], 0, v[168:169]
	s_mov_b32 m0, s27
	s_nop 0
	global_load_lds_dwordx4 v[234:235], off
	s_mov_b32 m0, s34
	s_nop 0
	global_load_lds_dwordx4 v[236:237], off
	s_waitcnt vmcnt(8)
	s_waitcnt lgkmcnt(0)
	s_barrier
	s_cmp_lg_u32 s32, 0
	s_cbranch_scc1 .Lzc0_1
	s_setprio 1
	s_waitcnt lgkmcnt(0)
	v_mfma_f32_16x16x32_bf16 v[60:63], v[128:131], v[186:189], v[60:63]
	v_mfma_f32_16x16x32_bf16 v[56:59], v[136:139], v[186:189], v[56:59]
	v_mfma_f32_16x16x32_bf16 v[44:47], v[128:131], v[194:197], v[44:47]
	v_mfma_f32_16x16x32_bf16 v[40:43], v[136:139], v[194:197], v[40:43]
	v_mfma_f32_16x16x32_bf16 v[28:31], v[128:131], v[202:205], v[28:31]
	v_mfma_f32_16x16x32_bf16 v[24:27], v[136:139], v[202:205], v[24:27]
	v_mfma_f32_16x16x32_bf16 v[12:15], v[128:131], v[210:213], v[12:15]
	v_mfma_f32_16x16x32_bf16 v[8:11], v[136:139], v[210:213], v[8:11]
	v_mfma_f32_16x16x32_bf16 v[60:63], v[132:135], v[190:193], v[60:63]
	v_mfma_f32_16x16x32_bf16 v[56:59], v[146:149], v[190:193], v[56:59]
	v_mfma_f32_16x16x32_bf16 v[44:47], v[132:135], v[198:201], v[44:47]
	v_mfma_f32_16x16x32_bf16 v[40:43], v[146:149], v[198:201], v[40:43]
	v_mfma_f32_16x16x32_bf16 v[28:31], v[132:135], v[206:209], v[28:31]
	v_mfma_f32_16x16x32_bf16 v[24:27], v[146:149], v[206:209], v[24:27]
	v_mfma_f32_16x16x32_bf16 v[12:15], v[132:135], v[218:221], v[12:15]
	v_mfma_f32_16x16x32_bf16 v[8:11], v[146:149], v[218:221], v[8:11]
	s_setprio 0
	s_setprio 1
	v_mfma_f32_16x16x32_bf16 v[52:55], v[150:153], v[186:189], v[52:55]
	v_mfma_f32_16x16x32_bf16 v[48:51], v[158:161], v[186:189], v[48:51]
	v_mfma_f32_16x16x32_bf16 v[36:39], v[150:153], v[194:197], v[36:39]
	v_mfma_f32_16x16x32_bf16 v[32:35], v[158:161], v[194:197], v[32:35]
	v_mfma_f32_16x16x32_bf16 v[20:23], v[150:153], v[202:205], v[20:23]
	v_mfma_f32_16x16x32_bf16 v[16:19], v[158:161], v[202:205], v[16:19]
	v_mfma_f32_16x16x32_bf16 v[4:7], v[150:153], v[210:213], v[4:7]
	v_mfma_f32_16x16x32_bf16 v[0:3], v[158:161], v[210:213], v[0:3]
	v_mfma_f32_16x16x32_bf16 v[52:55], v[154:157], v[190:193], v[52:55]
	v_mfma_f32_16x16x32_bf16 v[48:51], v[162:165], v[190:193], v[48:51]
	v_mfma_f32_16x16x32_bf16 v[36:39], v[154:157], v[198:201], v[36:39]
	v_mfma_f32_16x16x32_bf16 v[32:35], v[162:165], v[198:201], v[32:35]
	v_mfma_f32_16x16x32_bf16 v[20:23], v[154:157], v[206:209], v[20:23]
	v_mfma_f32_16x16x32_bf16 v[16:19], v[162:165], v[206:209], v[16:19]
	v_mfma_f32_16x16x32_bf16 v[4:7], v[154:157], v[218:221], v[4:7]
	v_mfma_f32_16x16x32_bf16 v[0:3], v[162:165], v[218:221], v[0:3]
	s_setprio 0
.Lzc0_1j:
	s_barrier
	s_add_i32 s50, 0, 0x18000
	s_add_i32 s51, 0, 0x1c000
	v_add_u32_e32 v146, s50, v215
	v_add_u32_e32 v162, s51, v215
	ds_read_b128 v[128:131], v146
	ds_read_b128 v[132:135], v146 offset:1024
	ds_read_b128 v[136:139], v146 offset:2048
	ds_read_b128 v[146:149], v146 offset:3072
	ds_read_b128 v[150:153], v162
	ds_read_b128 v[154:157], v162 offset:1024
	ds_read_b128 v[158:161], v162 offset:2048
	ds_read_b128 v[162:165], v162 offset:3072
	s_add_u32 s20, s20, 0x100000
	s_addc_u32 s21, s21, 0
	s_mov_b32 m0, s41
	v_lshl_add_u64 v[242:243], s[20:21], 0, v[168:169]
	ds_read_b128 v[186:189], v216 offset:32768
	ds_read_b128 v[190:193], v216 offset:33792
	ds_read_b128 v[194:197], v216 offset:34816
	ds_read_b128 v[198:201], v216 offset:35840
	ds_read_b128 v[202:205], v216 offset:36864
	ds_read_b128 v[206:209], v216 offset:37888
	ds_read_b128 v[210:213], v216 offset:38912
	ds_read_b128 v[218:221], v216 offset:39936
	global_load_lds_dwordx4 v[242:243], off
	v_lshl_add_u64 v[242:243], s[20:21], 0, v[140:141]
	s_mov_b32 m0, s70
	s_nop 0
	global_load_lds_dwordx4 v[242:243], off
	s_waitcnt vmcnt(8)
	s_waitcnt lgkmcnt(0)
	s_barrier
	s_setprio 1
	s_waitcnt lgkmcnt(0)
	v_mfma_f32_16x16x32_bf16 v[124:127], v[128:131], v[186:189], v[124:127]
	v_mfma_f32_16x16x32_bf16 v[120:123], v[136:139], v[186:189], v[120:123]
	v_mfma_f32_16x16x32_bf16 v[108:111], v[128:131], v[194:197], v[108:111]
	v_mfma_f32_16x16x32_bf16 v[104:107], v[136:139], v[194:197], v[104:107]
	v_mfma_f32_16x16x32_bf16 v[92:95], v[128:131], v[202:205], v[92:95]
	v_mfma_f32_16x16x32_bf16 v[88:91], v[136:139], v[202:205], v[88:91]
	v_mfma_f32_16x16x32_bf16 v[76:79], v[128:131], v[210:213], v[76:79]
	v_mfma_f32_16x16x32_bf16 v[72:75], v[136:139], v[210:213], v[72:75]
	v_mfma_f32_16x16x32_bf16 v[124:127], v[132:135], v[190:193], v[124:127]
	v_mfma_f32_16x16x32_bf16 v[120:123], v[146:149], v[190:193], v[120:123]
	v_mfma_f32_16x16x32_bf16 v[108:111], v[132:135], v[198:201], v[108:111]
	v_mfma_f32_16x16x32_bf16 v[104:107], v[146:149], v[198:201], v[104:107]
	v_mfma_f32_16x16x32_bf16 v[92:95], v[132:135], v[206:209], v[92:95]
	v_mfma_f32_16x16x32_bf16 v[88:91], v[146:149], v[206:209], v[88:91]
	v_mfma_f32_16x16x32_bf16 v[76:79], v[132:135], v[218:221], v[76:79]
	v_mfma_f32_16x16x32_bf16 v[72:75], v[146:149], v[218:221], v[72:75]
	s_setprio 0
	s_setprio 1
	v_mfma_f32_16x16x32_bf16 v[116:119], v[150:153], v[186:189], v[116:119]
	v_mfma_f32_16x16x32_bf16 v[112:115], v[158:161], v[186:189], v[112:115]
	v_mfma_f32_16x16x32_bf16 v[100:103], v[150:153], v[194:197], v[100:103]
	v_mfma_f32_16x16x32_bf16 v[96:99], v[158:161], v[194:197], v[96:99]
	v_mfma_f32_16x16x32_bf16 v[84:87], v[150:153], v[202:205], v[84:87]
	v_mfma_f32_16x16x32_bf16 v[80:83], v[158:161], v[202:205], v[80:83]
	v_mfma_f32_16x16x32_bf16 v[68:71], v[150:153], v[210:213], v[68:71]
	v_mfma_f32_16x16x32_bf16 v[64:67], v[158:161], v[210:213], v[64:67]
	v_mfma_f32_16x16x32_bf16 v[116:119], v[154:157], v[190:193], v[116:119]
	v_mfma_f32_16x16x32_bf16 v[112:115], v[162:165], v[190:193], v[112:115]
	v_mfma_f32_16x16x32_bf16 v[100:103], v[154:157], v[198:201], v[100:103]
	v_mfma_f32_16x16x32_bf16 v[96:99], v[162:165], v[198:201], v[96:99]
	v_mfma_f32_16x16x32_bf16 v[84:87], v[154:157], v[206:209], v[84:87]
	v_mfma_f32_16x16x32_bf16 v[80:83], v[162:165], v[206:209], v[80:83]
	v_mfma_f32_16x16x32_bf16 v[68:71], v[154:157], v[218:221], v[68:71]
	v_mfma_f32_16x16x32_bf16 v[64:67], v[162:165], v[218:221], v[64:67]
	s_setprio 0
	s_barrier
	s_add_i32 s20, s50, s26
	v_lshl_add_u64 v[166:167], v[166:167], 0, s[28:29]
	s_mov_b32 m0, s20
	ds_read_b128 v[186:189], v216 offset:49152
	ds_read_b128 v[190:193], v216 offset:50176
	ds_read_b128 v[194:197], v216 offset:51200
	ds_read_b128 v[198:201], v216 offset:52224
	ds_read_b128 v[202:205], v216 offset:53248
	ds_read_b128 v[206:209], v216 offset:54272
	ds_read_b128 v[210:213], v216 offset:55296
	ds_read_b128 v[218:221], v216 offset:56320
	global_load_lds_dwordx4 v[166:167], off
	s_add_i32 m0, s20, 0x2000
	s_add_u32 s2, s2, 0x100080
	v_lshl_add_u64 v[166:167], v[222:223], 0, s[28:29]
	s_addc_u32 s3, s3, 0
	s_add_i32 s20, s51, s26
	global_load_lds_dwordx4 v[166:167], off
	v_lshl_add_u64 v[166:167], s[2:3], 0, v[168:169]
	s_mov_b32 m0, s20
	s_nop 0
	global_load_lds_dwordx4 v[166:167], off
	v_lshl_add_u64 v[166:167], s[2:3], 0, v[140:141]
	s_add_i32 m0, s20, 0x2000
	s_nop 0
	global_load_lds_dwordx4 v[166:167], off
	v_lshl_add_u64 v[166:167], v[234:235], 0, s[28:29]
	s_mov_b32 m0, s76
	s_nop 0
	global_load_lds_dwordx4 v[166:167], off
	v_lshl_add_u64 v[166:167], v[236:237], 0, s[28:29]
	s_mov_b32 m0, s77
	s_nop 0
	global_load_lds_dwordx4 v[166:167], off
	s_waitcnt vmcnt(8)
	s_waitcnt lgkmcnt(0)
	s_barrier
	s_setprio 1
	s_waitcnt lgkmcnt(0)
	v_mfma_f32_16x16x32_bf16 v[60:63], v[128:131], v[186:189], v[60:63]
	v_mfma_f32_16x16x32_bf16 v[56:59], v[136:139], v[186:189], v[56:59]
	v_mfma_f32_16x16x32_bf16 v[44:47], v[128:131], v[194:197], v[44:47]
	v_mfma_f32_16x16x32_bf16 v[40:43], v[136:139], v[194:197], v[40:43]
	v_mfma_f32_16x16x32_bf16 v[28:31], v[128:131], v[202:205], v[28:31]
	v_mfma_f32_16x16x32_bf16 v[24:27], v[136:139], v[202:205], v[24:27]
	v_mfma_f32_16x16x32_bf16 v[12:15], v[128:131], v[210:213], v[12:15]
	v_mfma_f32_16x16x32_bf16 v[8:11], v[136:139], v[210:213], v[8:11]
	v_mfma_f32_16x16x32_bf16 v[60:63], v[132:135], v[190:193], v[60:63]
	v_mfma_f32_16x16x32_bf16 v[56:59], v[146:149], v[190:193], v[56:59]
	v_mfma_f32_16x16x32_bf16 v[44:47], v[132:135], v[198:201], v[44:47]
	v_mfma_f32_16x16x32_bf16 v[40:43], v[146:149], v[198:201], v[40:43]
	v_mfma_f32_16x16x32_bf16 v[28:31], v[132:135], v[206:209], v[28:31]
	v_mfma_f32_16x16x32_bf16 v[24:27], v[146:149], v[206:209], v[24:27]
	v_mfma_f32_16x16x32_bf16 v[12:15], v[132:135], v[218:221], v[12:15]
	v_mfma_f32_16x16x32_bf16 v[8:11], v[146:149], v[218:221], v[8:11]
	s_setprio 0
	s_setprio 1
	v_mfma_f32_16x16x32_bf16 v[52:55], v[150:153], v[186:189], v[52:55]
	v_mfma_f32_16x16x32_bf16 v[48:51], v[158:161], v[186:189], v[48:51]
	v_mfma_f32_16x16x32_bf16 v[36:39], v[150:153], v[194:197], v[36:39]
	v_mfma_f32_16x16x32_bf16 v[32:35], v[158:161], v[194:197], v[32:35]
	v_mfma_f32_16x16x32_bf16 v[20:23], v[150:153], v[202:205], v[20:23]
	v_mfma_f32_16x16x32_bf16 v[16:19], v[158:161], v[202:205], v[16:19]
	v_mfma_f32_16x16x32_bf16 v[4:7], v[150:153], v[210:213], v[4:7]
	v_mfma_f32_16x16x32_bf16 v[0:3], v[158:161], v[210:213], v[0:3]
	v_mfma_f32_16x16x32_bf16 v[52:55], v[154:157], v[190:193], v[52:55]
	v_mfma_f32_16x16x32_bf16 v[48:51], v[162:165], v[190:193], v[48:51]
	v_mfma_f32_16x16x32_bf16 v[36:39], v[154:157], v[198:201], v[36:39]
	v_mfma_f32_16x16x32_bf16 v[32:35], v[162:165], v[198:201], v[32:35]
	v_mfma_f32_16x16x32_bf16 v[20:23], v[154:157], v[206:209], v[20:23]
	v_mfma_f32_16x16x32_bf16 v[16:19], v[162:165], v[206:209], v[16:19]
	v_mfma_f32_16x16x32_bf16 v[4:7], v[154:157], v[218:221], v[4:7]
	v_mfma_f32_16x16x32_bf16 v[0:3], v[162:165], v[218:221], v[0:3]
	s_setprio 0
	s_barrier
	s_add_u32 s0, s0, 0x100
	s_addc_u32 s1, s1, 0
	s_add_u32 s46, s46, 0x100
	s_addc_u32 s47, s47, 0
	s_cmp_ge_i32 s53, s73
	s_mov_b32 s2, s53
	s_mov_b32 s32, 0
	s_cbranch_scc0 .LBB0_42

.Lzc1_0:
	s_setprio 1
	s_waitcnt lgkmcnt(0)
	v_mfma_f32_16x16x32_bf16 v[124:127], v[128:131], v[186:189], 0
	v_mfma_f32_16x16x32_bf16 v[120:123], v[142:145], v[186:189], 0
	v_mfma_f32_16x16x32_bf16 v[108:111], v[128:131], v[194:197], 0
	v_mfma_f32_16x16x32_bf16 v[104:107], v[142:145], v[194:197], 0
	v_mfma_f32_16x16x32_bf16 v[92:95], v[128:131], v[202:205], 0
	v_mfma_f32_16x16x32_bf16 v[88:91], v[142:145], v[202:205], 0
	v_mfma_f32_16x16x32_bf16 v[76:79], v[128:131], v[210:213], 0
	v_mfma_f32_16x16x32_bf16 v[72:75], v[142:145], v[210:213], 0
	v_mfma_f32_16x16x32_bf16 v[124:127], v[132:135], v[190:193], v[124:127]
	v_mfma_f32_16x16x32_bf16 v[120:123], v[146:149], v[190:193], v[120:123]
	v_mfma_f32_16x16x32_bf16 v[108:111], v[132:135], v[198:201], v[108:111]
	v_mfma_f32_16x16x32_bf16 v[104:107], v[146:149], v[198:201], v[104:107]
	v_mfma_f32_16x16x32_bf16 v[92:95], v[132:135], v[206:209], v[92:95]
	v_mfma_f32_16x16x32_bf16 v[88:91], v[146:149], v[206:209], v[88:91]
	v_mfma_f32_16x16x32_bf16 v[76:79], v[132:135], v[214:217], v[76:79]
	v_mfma_f32_16x16x32_bf16 v[72:75], v[146:149], v[214:217], v[72:75]
	s_setprio 0
	s_setprio 1
	v_mfma_f32_16x16x32_bf16 v[116:119], v[150:153], v[186:189], 0
	v_mfma_f32_16x16x32_bf16 v[112:115], v[158:161], v[186:189], 0
	v_mfma_f32_16x16x32_bf16 v[100:103], v[150:153], v[194:197], 0
	v_mfma_f32_16x16x32_bf16 v[96:99], v[158:161], v[194:197], 0
	v_mfma_f32_16x16x32_bf16 v[84:87], v[150:153], v[202:205], 0
	v_mfma_f32_16x16x32_bf16 v[80:83], v[158:161], v[202:205], 0
	v_mfma_f32_16x16x32_bf16 v[68:71], v[150:153], v[210:213], 0
	v_mfma_f32_16x16x32_bf16 v[64:67], v[158:161], v[210:213], 0
	v_mfma_f32_16x16x32_bf16 v[116:119], v[154:157], v[190:193], v[116:119]
	v_mfma_f32_16x16x32_bf16 v[112:115], v[162:165], v[190:193], v[112:115]
	v_mfma_f32_16x16x32_bf16 v[100:103], v[154:157], v[198:201], v[100:103]
	v_mfma_f32_16x16x32_bf16 v[96:99], v[162:165], v[198:201], v[96:99]
	v_mfma_f32_16x16x32_bf16 v[84:87], v[154:157], v[206:209], v[84:87]
	v_mfma_f32_16x16x32_bf16 v[80:83], v[162:165], v[206:209], v[80:83]
	v_mfma_f32_16x16x32_bf16 v[68:71], v[154:157], v[214:217], v[68:71]
	v_mfma_f32_16x16x32_bf16 v[64:67], v[162:165], v[214:217], v[64:67]
	s_setprio 0
	s_branch .Lzc1_0j
.Lzc1_1:
	s_setprio 1
	s_waitcnt lgkmcnt(0)
	v_mfma_f32_16x16x32_bf16 v[60:63], v[128:131], v[186:189], 0
	v_mfma_f32_16x16x32_bf16 v[56:59], v[142:145], v[186:189], 0
	v_mfma_f32_16x16x32_bf16 v[44:47], v[128:131], v[194:197], 0
	v_mfma_f32_16x16x32_bf16 v[40:43], v[142:145], v[194:197], 0
	v_mfma_f32_16x16x32_bf16 v[28:31], v[128:131], v[202:205], 0
	v_mfma_f32_16x16x32_bf16 v[24:27], v[142:145], v[202:205], 0
	v_mfma_f32_16x16x32_bf16 v[12:15], v[128:131], v[210:213], 0
	v_mfma_f32_16x16x32_bf16 v[8:11], v[142:145], v[210:213], 0
	v_mfma_f32_16x16x32_bf16 v[60:63], v[132:135], v[190:193], v[60:63]
	v_mfma_f32_16x16x32_bf16 v[56:59], v[146:149], v[190:193], v[56:59]
	v_mfma_f32_16x16x32_bf16 v[44:47], v[132:135], v[198:201], v[44:47]
	v_mfma_f32_16x16x32_bf16 v[40:43], v[146:149], v[198:201], v[40:43]
	v_mfma_f32_16x16x32_bf16 v[28:31], v[132:135], v[206:209], v[28:31]
	v_mfma_f32_16x16x32_bf16 v[24:27], v[146:149], v[206:209], v[24:27]
	v_mfma_f32_16x16x32_bf16 v[12:15], v[132:135], v[214:217], v[12:15]
	v_mfma_f32_16x16x32_bf16 v[8:11], v[146:149], v[214:217], v[8:11]
	s_setprio 0
	s_setprio 1
	v_mfma_f32_16x16x32_bf16 v[52:55], v[150:153], v[186:189], 0
	v_mfma_f32_16x16x32_bf16 v[48:51], v[158:161], v[186:189], 0
	v_mfma_f32_16x16x32_bf16 v[36:39], v[150:153], v[194:197], 0
	v_mfma_f32_16x16x32_bf16 v[32:35], v[158:161], v[194:197], 0
	v_mfma_f32_16x16x32_bf16 v[20:23], v[150:153], v[202:205], 0
	v_mfma_f32_16x16x32_bf16 v[16:19], v[158:161], v[202:205], 0
	v_mfma_f32_16x16x32_bf16 v[4:7], v[150:153], v[210:213], 0
	v_mfma_f32_16x16x32_bf16 v[0:3], v[158:161], v[210:213], 0
	v_mfma_f32_16x16x32_bf16 v[52:55], v[154:157], v[190:193], v[52:55]
	v_mfma_f32_16x16x32_bf16 v[48:51], v[162:165], v[190:193], v[48:51]
	v_mfma_f32_16x16x32_bf16 v[36:39], v[154:157], v[198:201], v[36:39]
	v_mfma_f32_16x16x32_bf16 v[32:35], v[162:165], v[198:201], v[32:35]
	v_mfma_f32_16x16x32_bf16 v[20:23], v[154:157], v[206:209], v[20:23]
	v_mfma_f32_16x16x32_bf16 v[16:19], v[162:165], v[206:209], v[16:19]
	v_mfma_f32_16x16x32_bf16 v[4:7], v[154:157], v[214:217], v[4:7]
	v_mfma_f32_16x16x32_bf16 v[0:3], v[162:165], v[214:217], v[0:3]
	s_setprio 0
	s_branch .Lzc1_1j

.LBB0_88:
	s_ashr_i32 s61, s60, 31
	s_lshl_b64 s[20:21], s[60:61], 21
	s_add_u32 s64, s24, s20
	s_addc_u32 s65, s25, s21
	s_ashr_i32 s63, s62, 31
	s_lshl_b64 s[20:21], s[62:63], 21
	v_readlane_b32 s22, v254, 54
	s_add_u32 s66, s22, s20
	v_readlane_b32 s20, v254, 62
	s_addc_u32 s67, s20, s21
	s_andn2_b64 vcc, exec, s[42:43]
	s_waitcnt lgkmcnt(0)
	s_cbranch_vccnz .Lzc1_skip
	s_and_b64 s[20:21], s[38:39], exec
	s_mov_b64 s[68:69], s[42:43]
	s_cselect_b32 s22, s65, s1
	s_cselect_b32 s23, s64, s0
	s_cselect_b32 s34, s67, s3
	s_cselect_b32 s42, s66, s2
	s_add_u32 s0, s0, 0x100080
	s_addc_u32 s1, s1, 0
	s_add_u32 s43, s2, 0x100
	s_addc_u32 s44, s3, 0
	s_mov_b32 s2, 0
	s_mov_b32 s32, 1
.LBB0_90:
	s_add_i32 s45, s2, 2
	s_add_u32 s3, s0, 0xfff00080
	s_addc_u32 s20, s1, -1
	s_add_i32 s46, 0, 0x10000
	s_cmp_eq_u32 s74, s2
	s_cselect_b32 s21, s22, s20
	s_cselect_b32 s20, s23, s3
	s_cselect_b32 s3, s34, s44
	s_cselect_b32 s2, s42, s43
	s_add_i32 s50, 0, 0x14000
	v_add_u32_e32 v146, s46, v219
	v_add_u32_e32 v162, s50, v219
	ds_read_b128 v[128:131], v146
	ds_read_b128 v[132:135], v146 offset:1024
	ds_read_b128 v[142:145], v146 offset:2048
	ds_read_b128 v[146:149], v146 offset:3072
	ds_read_b128 v[150:153], v162
	ds_read_b128 v[154:157], v162 offset:1024
	ds_read_b128 v[158:161], v162 offset:2048
	ds_read_b128 v[162:165], v162 offset:3072
	v_lshl_add_u64 v[166:167], s[0:1], 0, v[138:139]
	s_add_i32 m0, s27, 0xc000
	ds_read_b128 v[186:189], v220
	ds_read_b128 v[190:193], v220 offset:1024
	ds_read_b128 v[194:197], v220 offset:2048
	ds_read_b128 v[198:201], v220 offset:3072
	ds_read_b128 v[202:205], v220 offset:4096
	ds_read_b128 v[206:209], v220 offset:5120
	ds_read_b128 v[210:213], v220 offset:6144
	ds_read_b128 v[214:217], v220 offset:7168
	global_load_lds_dwordx4 v[166:167], off
	v_lshl_add_u64 v[166:167], s[0:1], 0, v[140:141]
	s_add_i32 m0, s27, 0xe000
	s_nop 0
	global_load_lds_dwordx4 v[166:167], off
	s_waitcnt vmcnt(8)
	s_waitcnt lgkmcnt(0)
	s_barrier
	s_cmp_lg_u32 s32, 0
	s_cbranch_scc1 .Lzc1_0
	s_setprio 1
	s_waitcnt lgkmcnt(0)
	v_mfma_f32_16x16x32_bf16 v[124:127], v[128:131], v[186:189], v[124:127]
	v_mfma_f32_16x16x32_bf16 v[120:123], v[142:145], v[186:189], v[120:123]
	v_mfma_f32_16x16x32_bf16 v[108:111], v[128:131], v[194:197], v[108:111]
	v_mfma_f32_16x16x32_bf16 v[104:107], v[142:145], v[194:197], v[104:107]
	v_mfma_f32_16x16x32_bf16 v[92:95], v[128:131], v[202:205], v[92:95]
	v_mfma_f32_16x16x32_bf16 v[88:91], v[142:145], v[202:205], v[88:91]
	v_mfma_f32_16x16x32_bf16 v[76:79], v[128:131], v[210:213], v[76:79]
	v_mfma_f32_16x16x32_bf16 v[72:75], v[142:145], v[210:213], v[72:75]
	v_mfma_f32_16x16x32_bf16 v[124:127], v[132:135], v[190:193], v[124:127]
	v_mfma_f32_16x16x32_bf16 v[120:123], v[146:149], v[190:193], v[120:123]
	v_mfma_f32_16x16x32_bf16 v[108:111], v[132:135], v[198:201], v[108:111]
	v_mfma_f32_16x16x32_bf16 v[104:107], v[146:149], v[198:201], v[104:107]
	v_mfma_f32_16x16x32_bf16 v[92:95], v[132:135], v[206:209], v[92:95]
	v_mfma_f32_16x16x32_bf16 v[88:91], v[146:149], v[206:209], v[88:91]
	v_mfma_f32_16x16x32_bf16 v[76:79], v[132:135], v[214:217], v[76:79]
	v_mfma_f32_16x16x32_bf16 v[72:75], v[146:149], v[214:217], v[72:75]
	s_setprio 0
	s_setprio 1
	v_mfma_f32_16x16x32_bf16 v[116:119], v[150:153], v[186:189], v[116:119]
	v_mfma_f32_16x16x32_bf16 v[112:115], v[158:161], v[186:189], v[112:115]
	v_mfma_f32_16x16x32_bf16 v[100:103], v[150:153], v[194:197], v[100:103]
	v_mfma_f32_16x16x32_bf16 v[96:99], v[158:161], v[194:197], v[96:99]
	v_mfma_f32_16x16x32_bf16 v[84:87], v[150:153], v[202:205], v[84:87]
	v_mfma_f32_16x16x32_bf16 v[80:83], v[158:161], v[202:205], v[80:83]
	v_mfma_f32_16x16x32_bf16 v[68:71], v[150:153], v[210:213], v[68:71]
	v_mfma_f32_16x16x32_bf16 v[64:67], v[158:161], v[210:213], v[64:67]
	v_mfma_f32_16x16x32_bf16 v[116:119], v[154:157], v[190:193], v[116:119]
	v_mfma_f32_16x16x32_bf16 v[112:115], v[162:165], v[190:193], v[112:115]
	v_mfma_f32_16x16x32_bf16 v[100:103], v[154:157], v[198:201], v[100:103]
	v_mfma_f32_16x16x32_bf16 v[96:99], v[162:165], v[198:201], v[96:99]
	v_mfma_f32_16x16x32_bf16 v[84:87], v[154:157], v[206:209], v[84:87]
	v_mfma_f32_16x16x32_bf16 v[80:83], v[162:165], v[206:209], v[80:83]
	v_mfma_f32_16x16x32_bf16 v[68:71], v[154:157], v[214:217], v[68:71]
	v_mfma_f32_16x16x32_bf16 v[64:67], v[162:165], v[214:217], v[64:67]
	s_setprio 0
.Lzc1_0j:
	s_barrier
	s_add_i32 s46, s46, s26
	v_lshl_add_u64 v[166:167], s[2:3], 0, v[168:169]
	s_mov_b32 m0, s46
	ds_read_b128 v[186:189], v220 offset:16384
	ds_read_b128 v[190:193], v220 offset:17408
	ds_read_b128 v[194:197], v220 offset:18432
	ds_read_b128 v[198:201], v220 offset:19456
	ds_read_b128 v[202:205], v220 offset:20480
	ds_read_b128 v[206:209], v220 offset:21504
	ds_read_b128 v[210:213], v220 offset:22528
	ds_read_b128 v[214:217], v220 offset:23552
	global_load_lds_dwordx4 v[166:167], off
	s_add_i32 m0, s46, 0x2000
	s_add_u32 s46, s2, 0x100000
	v_lshl_add_u64 v[222:223], s[2:3], 0, v[136:137]
	s_addc_u32 s47, s3, 0
	s_add_i32 s50, s50, s26
	global_load_lds_dwordx4 v[222:223], off
	v_lshl_add_u64 v[234:235], s[46:47], 0, v[168:169]
	s_mov_b32 m0, s50
	v_lshl_add_u64 v[236:237], s[20:21], 0, v[136:137]
	global_load_lds_dwordx4 v[234:235], off
	v_lshl_add_u64 v[234:235], s[46:47], 0, v[136:137]
	s_add_i32 m0, s50, 0x2000
	s_nop 0
	global_load_lds_dwordx4 v[234:235], off
	v_lshl_add_u64 v[234:235], s[20:21], 0, v[168:169]
	s_mov_b32 m0, s27
	s_nop 0
	global_load_lds_dwordx4 v[234:235], off
	s_mov_b32 m0, s41
	s_nop 0
	global_load_lds_dwordx4 v[236:237], off
	s_waitcnt vmcnt(8)
	s_waitcnt lgkmcnt(0)
	s_barrier
	s_cmp_lg_u32 s32, 0
	s_cbranch_scc1 .Lzc1_1
	s_setprio 1
	s_waitcnt lgkmcnt(0)
	v_mfma_f32_16x16x32_bf16 v[60:63], v[128:131], v[186:189], v[60:63]
	v_mfma_f32_16x16x32_bf16 v[56:59], v[142:145], v[186:189], v[56:59]
	v_mfma_f32_16x16x32_bf16 v[44:47], v[128:131], v[194:197], v[44:47]
	v_mfma_f32_16x16x32_bf16 v[40:43], v[142:145], v[194:197], v[40:43]
	v_mfma_f32_16x16x32_bf16 v[28:31], v[128:131], v[202:205], v[28:31]
	v_mfma_f32_16x16x32_bf16 v[24:27], v[142:145], v[202:205], v[24:27]
	v_mfma_f32_16x16x32_bf16 v[12:15], v[128:131], v[210:213], v[12:15]
	v_mfma_f32_16x16x32_bf16 v[8:11], v[142:145], v[210:213], v[8:11]
	v_mfma_f32_16x16x32_bf16 v[60:63], v[132:135], v[190:193], v[60:63]
	v_mfma_f32_16x16x32_bf16 v[56:59], v[146:149], v[190:193], v[56:59]
	v_mfma_f32_16x16x32_bf16 v[44:47], v[132:135], v[198:201], v[44:47]
	v_mfma_f32_16x16x32_bf16 v[40:43], v[146:149], v[198:201], v[40:43]
	v_mfma_f32_16x16x32_bf16 v[28:31], v[132:135], v[206:209], v[28:31]
	v_mfma_f32_16x16x32_bf16 v[24:27], v[146:149], v[206:209], v[24:27]
	v_mfma_f32_16x16x32_bf16 v[12:15], v[132:135], v[214:217], v[12:15]
	v_mfma_f32_16x16x32_bf16 v[8:11], v[146:149], v[214:217], v[8:11]
	s_setprio 0
	s_setprio 1
	v_mfma_f32_16x16x32_bf16 v[52:55], v[150:153], v[186:189], v[52:55]
	v_mfma_f32_16x16x32_bf16 v[48:51], v[158:161], v[186:189], v[48:51]
	v_mfma_f32_16x16x32_bf16 v[36:39], v[150:153], v[194:197], v[36:39]
	v_mfma_f32_16x16x32_bf16 v[32:35], v[158:161], v[194:197], v[32:35]
	v_mfma_f32_16x16x32_bf16 v[20:23], v[150:153], v[202:205], v[20:23]
	v_mfma_f32_16x16x32_bf16 v[16:19], v[158:161], v[202:205], v[16:19]
	v_mfma_f32_16x16x32_bf16 v[4:7], v[150:153], v[210:213], v[4:7]
	v_mfma_f32_16x16x32_bf16 v[0:3], v[158:161], v[210:213], v[0:3]
	v_mfma_f32_16x16x32_bf16 v[52:55], v[154:157], v[190:193], v[52:55]
	v_mfma_f32_16x16x32_bf16 v[48:51], v[162:165], v[190:193], v[48:51]
	v_mfma_f32_16x16x32_bf16 v[36:39], v[154:157], v[198:201], v[36:39]
	v_mfma_f32_16x16x32_bf16 v[32:35], v[162:165], v[198:201], v[32:35]
	v_mfma_f32_16x16x32_bf16 v[20:23], v[154:157], v[206:209], v[20:23]
	v_mfma_f32_16x16x32_bf16 v[16:19], v[162:165], v[206:209], v[16:19]
	v_mfma_f32_16x16x32_bf16 v[4:7], v[154:157], v[214:217], v[4:7]
	v_mfma_f32_16x16x32_bf16 v[0:3], v[162:165], v[214:217], v[0:3]
	s_setprio 0
.Lzc1_1j:
	s_barrier
	s_add_i32 s46, 0, 0x18000
	s_add_i32 s47, 0, 0x1c000
	v_add_u32_e32 v146, s46, v219
	v_add_u32_e32 v162, s47, v219
	ds_read_b128 v[128:131], v146
	ds_read_b128 v[132:135], v146 offset:1024
	ds_read_b128 v[142:145], v146 offset:2048
	ds_read_b128 v[146:149], v146 offset:3072
	ds_read_b128 v[150:153], v162
	ds_read_b128 v[154:157], v162 offset:1024
	ds_read_b128 v[158:161], v162 offset:2048
	ds_read_b128 v[162:165], v162 offset:3072
	s_add_u32 s20, s20, 0x100000
	s_addc_u32 s21, s21, 0
	s_mov_b32 m0, s70
	v_lshl_add_u64 v[242:243], s[20:21], 0, v[168:169]
	ds_read_b128 v[186:189], v220 offset:32768
	ds_read_b128 v[190:193], v220 offset:33792
	ds_read_b128 v[194:197], v220 offset:34816
	ds_read_b128 v[198:201], v220 offset:35840
	ds_read_b128 v[202:205], v220 offset:36864
	ds_read_b128 v[206:209], v220 offset:37888
	ds_read_b128 v[210:213], v220 offset:38912
	ds_read_b128 v[214:217], v220 offset:39936
	global_load_lds_dwordx4 v[242:243], off
	v_lshl_add_u64 v[242:243], s[20:21], 0, v[136:137]
	s_mov_b32 m0, s71
	s_nop 0
	global_load_lds_dwordx4 v[242:243], off
	s_waitcnt vmcnt(8)
	s_waitcnt lgkmcnt(0)
	s_barrier
	s_setprio 1
	s_waitcnt lgkmcnt(0)
	v_mfma_f32_16x16x32_bf16 v[124:127], v[128:131], v[186:189], v[124:127]
	v_mfma_f32_16x16x32_bf16 v[120:123], v[142:145], v[186:189], v[120:123]
	v_mfma_f32_16x16x32_bf16 v[108:111], v[128:131], v[194:197], v[108:111]
	v_mfma_f32_16x16x32_bf16 v[104:107], v[142:145], v[194:197], v[104:107]
	v_mfma_f32_16x16x32_bf16 v[92:95], v[128:131], v[202:205], v[92:95]
	v_mfma_f32_16x16x32_bf16 v[88:91], v[142:145], v[202:205], v[88:91]
	v_mfma_f32_16x16x32_bf16 v[76:79], v[128:131], v[210:213], v[76:79]
	v_mfma_f32_16x16x32_bf16 v[72:75], v[142:145], v[210:213], v[72:75]
	v_mfma_f32_16x16x32_bf16 v[124:127], v[132:135], v[190:193], v[124:127]
	v_mfma_f32_16x16x32_bf16 v[120:123], v[146:149], v[190:193], v[120:123]
	v_mfma_f32_16x16x32_bf16 v[108:111], v[132:135], v[198:201], v[108:111]
	v_mfma_f32_16x16x32_bf16 v[104:107], v[146:149], v[198:201], v[104:107]
	v_mfma_f32_16x16x32_bf16 v[92:95], v[132:135], v[206:209], v[92:95]
	v_mfma_f32_16x16x32_bf16 v[88:91], v[146:149], v[206:209], v[88:91]
	v_mfma_f32_16x16x32_bf16 v[76:79], v[132:135], v[214:217], v[76:79]
	v_mfma_f32_16x16x32_bf16 v[72:75], v[146:149], v[214:217], v[72:75]
	s_setprio 0
	s_setprio 1
	v_mfma_f32_16x16x32_bf16 v[116:119], v[150:153], v[186:189], v[116:119]
	v_mfma_f32_16x16x32_bf16 v[112:115], v[158:161], v[186:189], v[112:115]
	v_mfma_f32_16x16x32_bf16 v[100:103], v[150:153], v[194:197], v[100:103]
	v_mfma_f32_16x16x32_bf16 v[96:99], v[158:161], v[194:197], v[96:99]
	v_mfma_f32_16x16x32_bf16 v[84:87], v[150:153], v[202:205], v[84:87]
	v_mfma_f32_16x16x32_bf16 v[80:83], v[158:161], v[202:205], v[80:83]
	v_mfma_f32_16x16x32_bf16 v[68:71], v[150:153], v[210:213], v[68:71]
	v_mfma_f32_16x16x32_bf16 v[64:67], v[158:161], v[210:213], v[64:67]
	v_mfma_f32_16x16x32_bf16 v[116:119], v[154:157], v[190:193], v[116:119]
	v_mfma_f32_16x16x32_bf16 v[112:115], v[162:165], v[190:193], v[112:115]
	v_mfma_f32_16x16x32_bf16 v[100:103], v[154:157], v[198:201], v[100:103]
	v_mfma_f32_16x16x32_bf16 v[96:99], v[162:165], v[198:201], v[96:99]
	v_mfma_f32_16x16x32_bf16 v[84:87], v[154:157], v[206:209], v[84:87]
	v_mfma_f32_16x16x32_bf16 v[80:83], v[162:165], v[206:209], v[80:83]
	v_mfma_f32_16x16x32_bf16 v[68:71], v[154:157], v[214:217], v[68:71]
	v_mfma_f32_16x16x32_bf16 v[64:67], v[162:165], v[214:217], v[64:67]
	s_setprio 0
	s_barrier
	s_add_i32 s20, s46, s26
	v_lshl_add_u64 v[166:167], v[166:167], 0, s[28:29]
	s_mov_b32 m0, s20
	ds_read_b128 v[186:189], v220 offset:49152
	ds_read_b128 v[190:193], v220 offset:50176
	ds_read_b128 v[194:197], v220 offset:51200
	ds_read_b128 v[198:201], v220 offset:52224
	ds_read_b128 v[202:205], v220 offset:53248
	ds_read_b128 v[206:209], v220 offset:54272
	ds_read_b128 v[210:213], v220 offset:55296
	ds_read_b128 v[214:217], v220 offset:56320
	global_load_lds_dwordx4 v[166:167], off
	s_add_i32 m0, s20, 0x2000
	s_add_u32 s2, s2, 0x100080
	v_lshl_add_u64 v[166:167], v[222:223], 0, s[28:29]
	s_addc_u32 s3, s3, 0
	s_add_i32 s20, s47, s26
	global_load_lds_dwordx4 v[166:167], off
	v_lshl_add_u64 v[166:167], s[2:3], 0, v[168:169]
	s_mov_b32 m0, s20
	s_nop 0
	global_load_lds_dwordx4 v[166:167], off
	v_lshl_add_u64 v[166:167], s[2:3], 0, v[136:137]
	s_add_i32 m0, s20, 0x2000
	s_nop 0
	global_load_lds_dwordx4 v[166:167], off
	v_lshl_add_u64 v[166:167], v[234:235], 0, s[28:29]
	s_mov_b32 m0, s48
	s_nop 0
	global_load_lds_dwordx4 v[166:167], off
	v_lshl_add_u64 v[166:167], v[236:237], 0, s[28:29]
	s_mov_b32 m0, s49
	s_nop 0
	global_load_lds_dwordx4 v[166:167], off
	s_waitcnt vmcnt(8)
	s_waitcnt lgkmcnt(0)
	s_barrier
	s_setprio 1
	s_waitcnt lgkmcnt(0)
	v_mfma_f32_16x16x32_bf16 v[60:63], v[128:131], v[186:189], v[60:63]
	v_mfma_f32_16x16x32_bf16 v[56:59], v[142:145], v[186:189], v[56:59]
	v_mfma_f32_16x16x32_bf16 v[44:47], v[128:131], v[194:197], v[44:47]
	v_mfma_f32_16x16x32_bf16 v[40:43], v[142:145], v[194:197], v[40:43]
	v_mfma_f32_16x16x32_bf16 v[28:31], v[128:131], v[202:205], v[28:31]
	v_mfma_f32_16x16x32_bf16 v[24:27], v[142:145], v[202:205], v[24:27]
	v_mfma_f32_16x16x32_bf16 v[12:15], v[128:131], v[210:213], v[12:15]
	v_mfma_f32_16x16x32_bf16 v[8:11], v[142:145], v[210:213], v[8:11]
	v_mfma_f32_16x16x32_bf16 v[60:63], v[132:135], v[190:193], v[60:63]
	v_mfma_f32_16x16x32_bf16 v[56:59], v[146:149], v[190:193], v[56:59]
	v_mfma_f32_16x16x32_bf16 v[44:47], v[132:135], v[198:201], v[44:47]
	v_mfma_f32_16x16x32_bf16 v[40:43], v[146:149], v[198:201], v[40:43]
	v_mfma_f32_16x16x32_bf16 v[28:31], v[132:135], v[206:209], v[28:31]
	v_mfma_f32_16x16x32_bf16 v[24:27], v[146:149], v[206:209], v[24:27]
	v_mfma_f32_16x16x32_bf16 v[12:15], v[132:135], v[214:217], v[12:15]
	v_mfma_f32_16x16x32_bf16 v[8:11], v[146:149], v[214:217], v[8:11]
	s_setprio 0
	s_setprio 1
	v_mfma_f32_16x16x32_bf16 v[52:55], v[150:153], v[186:189], v[52:55]
	v_mfma_f32_16x16x32_bf16 v[48:51], v[158:161], v[186:189], v[48:51]
	v_mfma_f32_16x16x32_bf16 v[36:39], v[150:153], v[194:197], v[36:39]
	v_mfma_f32_16x16x32_bf16 v[32:35], v[158:161], v[194:197], v[32:35]
	v_mfma_f32_16x16x32_bf16 v[20:23], v[150:153], v[202:205], v[20:23]
	v_mfma_f32_16x16x32_bf16 v[16:19], v[158:161], v[202:205], v[16:19]
	v_mfma_f32_16x16x32_bf16 v[4:7], v[150:153], v[210:213], v[4:7]
	v_mfma_f32_16x16x32_bf16 v[0:3], v[158:161], v[210:213], v[0:3]
	v_mfma_f32_16x16x32_bf16 v[52:55], v[154:157], v[190:193], v[52:55]
	v_mfma_f32_16x16x32_bf16 v[48:51], v[162:165], v[190:193], v[48:51]
	v_mfma_f32_16x16x32_bf16 v[36:39], v[154:157], v[198:201], v[36:39]
	v_mfma_f32_16x16x32_bf16 v[32:35], v[162:165], v[198:201], v[32:35]
	v_mfma_f32_16x16x32_bf16 v[20:23], v[154:157], v[206:209], v[20:23]
	v_mfma_f32_16x16x32_bf16 v[16:19], v[162:165], v[206:209], v[16:19]
	v_mfma_f32_16x16x32_bf16 v[4:7], v[154:157], v[214:217], v[4:7]
	v_mfma_f32_16x16x32_bf16 v[0:3], v[162:165], v[214:217], v[0:3]
	s_setprio 0
	s_barrier
	s_add_u32 s0, s0, 0x100
	s_addc_u32 s1, s1, 0
	s_add_u32 s43, s43, 0x100
	s_addc_u32 s44, s44, 0
	s_cmp_ge_i32 s45, s73
	s_mov_b32 s2, s45
	s_mov_b32 s32, 0
	s_cbranch_scc0 .LBB0_90
	s_mov_b64 s[42:43], s[68:69]

.Lzc2_0:
	s_setprio 1
	s_waitcnt lgkmcnt(0)
	v_mfma_f32_16x16x32_bf16 v[152:155], v[64:67], v[160:163], 0
	v_mfma_f32_16x16x32_bf16 v[156:159], v[72:75], v[160:163], 0
	v_mfma_f32_16x16x32_bf16 v[136:139], v[64:67], v[196:199], 0
	v_mfma_f32_16x16x32_bf16 v[140:143], v[72:75], v[196:199], 0
	v_mfma_f32_16x16x32_bf16 v[120:123], v[64:67], v[204:207], 0
	v_mfma_f32_16x16x32_bf16 v[124:127], v[72:75], v[204:207], 0
	v_mfma_f32_16x16x32_bf16 v[104:107], v[64:67], v[216:219], 0
	v_mfma_f32_16x16x32_bf16 v[108:111], v[72:75], v[216:219], 0
	v_mfma_f32_16x16x32_bf16 v[152:155], v[68:71], v[164:167], v[152:155]
	v_mfma_f32_16x16x32_bf16 v[156:159], v[76:79], v[164:167], v[156:159]
	v_mfma_f32_16x16x32_bf16 v[136:139], v[68:71], v[200:203], v[136:139]
	v_mfma_f32_16x16x32_bf16 v[140:143], v[76:79], v[200:203], v[140:143]
	v_mfma_f32_16x16x32_bf16 v[120:123], v[68:71], v[212:215], v[120:123]
	v_mfma_f32_16x16x32_bf16 v[124:127], v[76:79], v[212:215], v[124:127]
	v_mfma_f32_16x16x32_bf16 v[104:107], v[68:71], v[220:223], v[104:107]
	v_mfma_f32_16x16x32_bf16 v[108:111], v[76:79], v[220:223], v[108:111]
	s_setprio 0
	s_setprio 1
	v_mfma_f32_16x16x32_bf16 v[144:147], v[88:91], v[160:163], 0
	v_mfma_f32_16x16x32_bf16 v[148:151], v[96:99], v[160:163], 0
	v_mfma_f32_16x16x32_bf16 v[128:131], v[88:91], v[196:199], 0
	v_mfma_f32_16x16x32_bf16 v[132:135], v[96:99], v[196:199], 0
	v_mfma_f32_16x16x32_bf16 v[112:115], v[88:91], v[204:207], 0
	v_mfma_f32_16x16x32_bf16 v[116:119], v[96:99], v[204:207], 0
	v_mfma_f32_16x16x32_bf16 v[80:83], v[88:91], v[216:219], 0
	v_mfma_f32_16x16x32_bf16 v[84:87], v[96:99], v[216:219], 0
	v_mfma_f32_16x16x32_bf16 v[144:147], v[92:95], v[164:167], v[144:147]
	v_mfma_f32_16x16x32_bf16 v[148:151], v[100:103], v[164:167], v[148:151]
	v_mfma_f32_16x16x32_bf16 v[128:131], v[92:95], v[200:203], v[128:131]
	v_mfma_f32_16x16x32_bf16 v[132:135], v[100:103], v[200:203], v[132:135]
	v_mfma_f32_16x16x32_bf16 v[112:115], v[92:95], v[212:215], v[112:115]
	v_mfma_f32_16x16x32_bf16 v[116:119], v[100:103], v[212:215], v[116:119]
	v_mfma_f32_16x16x32_bf16 v[80:83], v[92:95], v[220:223], v[80:83]
	v_mfma_f32_16x16x32_bf16 v[84:87], v[100:103], v[220:223], v[84:87]
	s_setprio 0
	s_branch .Lzc2_0j
.Lzc2_1:
	s_setprio 1
	s_waitcnt lgkmcnt(0)
	v_mfma_f32_16x16x32_bf16 v[56:59], v[64:67], v[160:163], 0
	v_mfma_f32_16x16x32_bf16 v[60:63], v[72:75], v[160:163], 0
	v_mfma_f32_16x16x32_bf16 v[40:43], v[64:67], v[196:199], 0
	v_mfma_f32_16x16x32_bf16 v[44:47], v[72:75], v[196:199], 0
	v_mfma_f32_16x16x32_bf16 v[24:27], v[64:67], v[204:207], 0
	v_mfma_f32_16x16x32_bf16 v[28:31], v[72:75], v[204:207], 0
	v_mfma_f32_16x16x32_bf16 v[8:11], v[64:67], v[216:219], 0
	v_mfma_f32_16x16x32_bf16 v[12:15], v[72:75], v[216:219], 0
	v_mfma_f32_16x16x32_bf16 v[56:59], v[68:71], v[164:167], v[56:59]
	v_mfma_f32_16x16x32_bf16 v[60:63], v[76:79], v[164:167], v[60:63]
	v_mfma_f32_16x16x32_bf16 v[40:43], v[68:71], v[200:203], v[40:43]
	v_mfma_f32_16x16x32_bf16 v[44:47], v[76:79], v[200:203], v[44:47]
	v_mfma_f32_16x16x32_bf16 v[24:27], v[68:71], v[212:215], v[24:27]
	v_mfma_f32_16x16x32_bf16 v[28:31], v[76:79], v[212:215], v[28:31]
	v_mfma_f32_16x16x32_bf16 v[8:11], v[68:71], v[220:223], v[8:11]
	v_mfma_f32_16x16x32_bf16 v[12:15], v[76:79], v[220:223], v[12:15]
	s_setprio 0
	s_setprio 1
	v_mfma_f32_16x16x32_bf16 v[48:51], v[88:91], v[160:163], 0
	v_mfma_f32_16x16x32_bf16 v[52:55], v[96:99], v[160:163], 0
	v_mfma_f32_16x16x32_bf16 v[32:35], v[88:91], v[196:199], 0
	v_mfma_f32_16x16x32_bf16 v[36:39], v[96:99], v[196:199], 0
	v_mfma_f32_16x16x32_bf16 v[16:19], v[88:91], v[204:207], 0
	v_mfma_f32_16x16x32_bf16 v[20:23], v[96:99], v[204:207], 0
	v_mfma_f32_16x16x32_bf16 v[0:3], v[88:91], v[216:219], 0
	v_mfma_f32_16x16x32_bf16 v[4:7], v[96:99], v[216:219], 0
	v_mfma_f32_16x16x32_bf16 v[48:51], v[92:95], v[164:167], v[48:51]
	v_mfma_f32_16x16x32_bf16 v[52:55], v[100:103], v[164:167], v[52:55]
	v_mfma_f32_16x16x32_bf16 v[32:35], v[92:95], v[200:203], v[32:35]
	v_mfma_f32_16x16x32_bf16 v[36:39], v[100:103], v[200:203], v[36:39]
	v_mfma_f32_16x16x32_bf16 v[16:19], v[92:95], v[212:215], v[16:19]
	v_mfma_f32_16x16x32_bf16 v[20:23], v[100:103], v[212:215], v[20:23]
	v_mfma_f32_16x16x32_bf16 v[0:3], v[92:95], v[220:223], v[0:3]
	v_mfma_f32_16x16x32_bf16 v[4:7], v[100:103], v[220:223], v[4:7]
	s_setprio 0
	s_branch .Lzc2_1j
.Lzc2_skip:
	v_mov_b32_e32 v0, 0
	v_mov_b32_e32 v1, 0
	v_mov_b32_e32 v2, 0
	v_mov_b32_e32 v3, 0
	v_mov_b32_e32 v4, 0
	v_mov_b32_e32 v5, 0
	v_mov_b32_e32 v6, 0
	v_mov_b32_e32 v7, 0
	v_mov_b32_e32 v8, 0
	v_mov_b32_e32 v9, 0
	v_mov_b32_e32 v10, 0
	v_mov_b32_e32 v11, 0
	v_mov_b32_e32 v12, 0
	v_mov_b32_e32 v13, 0
	v_mov_b32_e32 v14, 0
	v_mov_b32_e32 v15, 0
	v_mov_b32_e32 v16, 0
	v_mov_b32_e32 v17, 0
	v_mov_b32_e32 v18, 0
	v_mov_b32_e32 v19, 0
	v_mov_b32_e32 v20, 0
	v_mov_b32_e32 v21, 0
	v_mov_b32_e32 v22, 0
	v_mov_b32_e32 v23, 0
	v_mov_b32_e32 v24, 0
	v_mov_b32_e32 v25, 0
	v_mov_b32_e32 v26, 0
	v_mov_b32_e32 v27, 0
	v_mov_b32_e32 v28, 0
	v_mov_b32_e32 v29, 0
	v_mov_b32_e32 v30, 0
	v_mov_b32_e32 v31, 0
	v_mov_b32_e32 v32, 0
	v_mov_b32_e32 v33, 0
	v_mov_b32_e32 v34, 0
	v_mov_b32_e32 v35, 0
	v_mov_b32_e32 v36, 0
	v_mov_b32_e32 v37, 0
	v_mov_b32_e32 v38, 0
	v_mov_b32_e32 v39, 0
	v_mov_b32_e32 v40, 0
	v_mov_b32_e32 v41, 0
	v_mov_b32_e32 v42, 0
	v_mov_b32_e32 v43, 0
	v_mov_b32_e32 v44, 0
	v_mov_b32_e32 v45, 0
	v_mov_b32_e32 v46, 0
	v_mov_b32_e32 v47, 0
	v_mov_b32_e32 v48, 0
	v_mov_b32_e32 v49, 0
	v_mov_b32_e32 v50, 0
	v_mov_b32_e32 v51, 0
	v_mov_b32_e32 v52, 0
	v_mov_b32_e32 v53, 0
	v_mov_b32_e32 v54, 0
	v_mov_b32_e32 v55, 0
	v_mov_b32_e32 v56, 0
	v_mov_b32_e32 v57, 0
	v_mov_b32_e32 v58, 0
	v_mov_b32_e32 v59, 0
	v_mov_b32_e32 v60, 0
	v_mov_b32_e32 v61, 0
	v_mov_b32_e32 v62, 0
	v_mov_b32_e32 v63, 0
	v_mov_b32_e32 v80, 0
	v_mov_b32_e32 v81, 0
	v_mov_b32_e32 v82, 0
	v_mov_b32_e32 v83, 0
	v_mov_b32_e32 v84, 0
	v_mov_b32_e32 v85, 0
	v_mov_b32_e32 v86, 0
	v_mov_b32_e32 v87, 0
	v_mov_b32_e32 v104, 0
	v_mov_b32_e32 v105, 0
	v_mov_b32_e32 v106, 0
	v_mov_b32_e32 v107, 0
	v_mov_b32_e32 v108, 0
	v_mov_b32_e32 v109, 0
	v_mov_b32_e32 v110, 0
	v_mov_b32_e32 v111, 0
	v_mov_b32_e32 v112, 0
	v_mov_b32_e32 v113, 0
	v_mov_b32_e32 v114, 0
	v_mov_b32_e32 v115, 0
	v_mov_b32_e32 v116, 0
	v_mov_b32_e32 v117, 0
	v_mov_b32_e32 v118, 0
	v_mov_b32_e32 v119, 0
	v_mov_b32_e32 v120, 0
	v_mov_b32_e32 v121, 0
	v_mov_b32_e32 v122, 0
	v_mov_b32_e32 v123, 0
	v_mov_b32_e32 v124, 0
	v_mov_b32_e32 v125, 0
	v_mov_b32_e32 v126, 0
	v_mov_b32_e32 v127, 0
	v_mov_b32_e32 v128, 0
	v_mov_b32_e32 v129, 0
	v_mov_b32_e32 v130, 0
	v_mov_b32_e32 v131, 0
	v_mov_b32_e32 v132, 0
	v_mov_b32_e32 v133, 0
	v_mov_b32_e32 v134, 0
	v_mov_b32_e32 v135, 0
	v_mov_b32_e32 v136, 0
	v_mov_b32_e32 v137, 0
	v_mov_b32_e32 v138, 0
	v_mov_b32_e32 v139, 0
	v_mov_b32_e32 v140, 0
	v_mov_b32_e32 v141, 0
	v_mov_b32_e32 v142, 0
	v_mov_b32_e32 v143, 0
	v_mov_b32_e32 v144, 0
	v_mov_b32_e32 v145, 0
	v_mov_b32_e32 v146, 0
	v_mov_b32_e32 v147, 0
	v_mov_b32_e32 v148, 0
	v_mov_b32_e32 v149, 0
	v_mov_b32_e32 v150, 0
	v_mov_b32_e32 v151, 0
	v_mov_b32_e32 v152, 0
	v_mov_b32_e32 v153, 0
	v_mov_b32_e32 v154, 0
	v_mov_b32_e32 v155, 0
	v_mov_b32_e32 v156, 0
	v_mov_b32_e32 v157, 0
	v_mov_b32_e32 v158, 0
	v_mov_b32_e32 v159, 0
	s_branch .LBB0_139

.LBB0_136:
	s_ashr_i32 s65, s64, 31
	s_lshl_b64 s[26:27], s[64:65], 19
	v_readlane_b32 s40, v254, 43
	v_readlane_b32 s41, v254, 44
	s_add_u32 s68, s40, s26
	s_addc_u32 s69, s41, s27
	s_ashr_i32 s67, s66, 31
	s_lshl_b64 s[26:27], s[66:67], 19
	s_add_u32 s70, s34, s26
	s_addc_u32 s71, s72, s27
	s_andn2_b64 vcc, exec, s[60:61]
	s_cbranch_vccnz .Lzc2_skip
	s_and_b64 s[26:27], s[38:39], exec
	s_cselect_b32 s1, s69, s21
	s_cselect_b32 s40, s68, s20
	s_cselect_b32 s41, s71, s23
	s_cselect_b32 s44, s70, s22
	s_add_u32 s20, s20, 0x40080
	s_addc_u32 s21, s21, 0
	s_add_u32 s45, s22, 0x100
	s_addc_u32 s53, s23, 0
	s_mov_b32 s22, 0
	s_mov_b32 s32, 1
.LBB0_138:
	s_add_i32 s65, s22, 2
	s_add_u32 s23, s20, 0xfffc0080
	s_addc_u32 s26, s21, -1
	s_add_i32 s67, 0, 0x10000
	s_cmp_eq_u32 s77, s22
	s_cselect_b32 s27, s1, s26
	s_cselect_b32 s26, s40, s23
	s_cselect_b32 s23, s41, s53
	s_cselect_b32 s22, s44, s45
	s_add_i32 s50, 0, 0x14000
	v_add_u32_e32 v76, s67, v209
	v_add_u32_e32 v100, s50, v209
	ds_read_b128 v[64:67], v76
	ds_read_b128 v[68:71], v76 offset:1024
	ds_read_b128 v[72:75], v76 offset:2048
	ds_read_b128 v[76:79], v76 offset:3072
	ds_read_b128 v[88:91], v100
	ds_read_b128 v[92:95], v100 offset:1024
	ds_read_b128 v[96:99], v100 offset:2048
	ds_read_b128 v[100:103], v100 offset:3072
	v_lshl_add_u64 v[234:235], s[20:21], 0, v[192:193]
	s_add_i32 m0, s3, 0xc000
	ds_read_b128 v[160:163], v210
	ds_read_b128 v[164:167], v210 offset:1024
	ds_read_b128 v[196:199], v210 offset:2048
	ds_read_b128 v[200:203], v210 offset:3072
	ds_read_b128 v[204:207], v210 offset:4096
	ds_read_b128 v[212:215], v210 offset:5120
	ds_read_b128 v[216:219], v210 offset:6144
	ds_read_b128 v[220:223], v210 offset:7168
	global_load_lds_dwordx4 v[234:235], off
	v_lshl_add_u64 v[234:235], s[20:21], 0, v[194:195]
	s_add_i32 m0, s3, 0xe000
	s_nop 0
	global_load_lds_dwordx4 v[234:235], off
	s_waitcnt vmcnt(8)
	s_waitcnt lgkmcnt(0)
	s_barrier
	s_cmp_lg_u32 s32, 0
	s_cbranch_scc1 .Lzc2_0
	s_setprio 1
	s_waitcnt lgkmcnt(0)
	v_mfma_f32_16x16x32_bf16 v[152:155], v[64:67], v[160:163], v[152:155]
	v_mfma_f32_16x16x32_bf16 v[156:159], v[72:75], v[160:163], v[156:159]
	v_mfma_f32_16x16x32_bf16 v[136:139], v[64:67], v[196:199], v[136:139]
	v_mfma_f32_16x16x32_bf16 v[140:143], v[72:75], v[196:199], v[140:143]
	v_mfma_f32_16x16x32_bf16 v[120:123], v[64:67], v[204:207], v[120:123]
	v_mfma_f32_16x16x32_bf16 v[124:127], v[72:75], v[204:207], v[124:127]
	v_mfma_f32_16x16x32_bf16 v[104:107], v[64:67], v[216:219], v[104:107]
	v_mfma_f32_16x16x32_bf16 v[108:111], v[72:75], v[216:219], v[108:111]
	v_mfma_f32_16x16x32_bf16 v[152:155], v[68:71], v[164:167], v[152:155]
	v_mfma_f32_16x16x32_bf16 v[156:159], v[76:79], v[164:167], v[156:159]
	v_mfma_f32_16x16x32_bf16 v[136:139], v[68:71], v[200:203], v[136:139]
	v_mfma_f32_16x16x32_bf16 v[140:143], v[76:79], v[200:203], v[140:143]
	v_mfma_f32_16x16x32_bf16 v[120:123], v[68:71], v[212:215], v[120:123]
	v_mfma_f32_16x16x32_bf16 v[124:127], v[76:79], v[212:215], v[124:127]
	v_mfma_f32_16x16x32_bf16 v[104:107], v[68:71], v[220:223], v[104:107]
	v_mfma_f32_16x16x32_bf16 v[108:111], v[76:79], v[220:223], v[108:111]
	s_setprio 0
	s_setprio 1
	v_mfma_f32_16x16x32_bf16 v[144:147], v[88:91], v[160:163], v[144:147]
	v_mfma_f32_16x16x32_bf16 v[148:151], v[96:99], v[160:163], v[148:151]
	v_mfma_f32_16x16x32_bf16 v[128:131], v[88:91], v[196:199], v[128:131]
	v_mfma_f32_16x16x32_bf16 v[132:135], v[96:99], v[196:199], v[132:135]
	v_mfma_f32_16x16x32_bf16 v[112:115], v[88:91], v[204:207], v[112:115]
	v_mfma_f32_16x16x32_bf16 v[116:119], v[96:99], v[204:207], v[116:119]
	v_mfma_f32_16x16x32_bf16 v[80:83], v[88:91], v[216:219], v[80:83]
	v_mfma_f32_16x16x32_bf16 v[84:87], v[96:99], v[216:219], v[84:87]
	v_mfma_f32_16x16x32_bf16 v[144:147], v[92:95], v[164:167], v[144:147]
	v_mfma_f32_16x16x32_bf16 v[148:151], v[100:103], v[164:167], v[148:151]
	v_mfma_f32_16x16x32_bf16 v[128:131], v[92:95], v[200:203], v[128:131]
	v_mfma_f32_16x16x32_bf16 v[132:135], v[100:103], v[200:203], v[132:135]
	v_mfma_f32_16x16x32_bf16 v[112:115], v[92:95], v[212:215], v[112:115]
	v_mfma_f32_16x16x32_bf16 v[116:119], v[100:103], v[212:215], v[116:119]
	v_mfma_f32_16x16x32_bf16 v[80:83], v[92:95], v[220:223], v[80:83]
	v_mfma_f32_16x16x32_bf16 v[84:87], v[100:103], v[220:223], v[84:87]
	s_setprio 0
.Lzc2_0j:
	s_barrier
	s_add_i32 s51, s67, s73
	v_lshl_add_u64 v[234:235], s[22:23], 0, v[168:169]
	s_mov_b32 m0, s51
	ds_read_b128 v[160:163], v210 offset:16384
	ds_read_b128 v[164:167], v210 offset:17408
	ds_read_b128 v[196:199], v210 offset:18432
	ds_read_b128 v[200:203], v210 offset:19456
	ds_read_b128 v[204:207], v210 offset:20480
	ds_read_b128 v[212:215], v210 offset:21504
	ds_read_b128 v[216:219], v210 offset:22528
	ds_read_b128 v[220:223], v210 offset:23552
	global_load_lds_dwordx4 v[234:235], off
	s_add_i32 m0, s51, 0x2000
	s_add_u32 vcc_lo, s22, 0x40000
	v_lshl_add_u64 v[236:237], s[22:23], 0, v[190:191]
	s_addc_u32 vcc_hi, s23, 0
	s_add_i32 s50, s50, s73
	global_load_lds_dwordx4 v[236:237], off
	v_lshl_add_u64 v[242:243], vcc, 0, v[168:169]
	s_mov_b32 m0, s50
	v_lshl_add_u64 v[244:245], s[26:27], 0, v[188:189]
	global_load_lds_dwordx4 v[242:243], off
	v_lshl_add_u64 v[242:243], vcc, 0, v[190:191]
	s_add_i32 m0, s50, 0x2000
	s_nop 0
	global_load_lds_dwordx4 v[242:243], off
	v_lshl_add_u64 v[242:243], s[26:27], 0, v[186:187]
	s_mov_b32 m0, s3
	s_nop 0
	global_load_lds_dwordx4 v[242:243], off
	s_mov_b32 m0, s74
	s_nop 0
	global_load_lds_dwordx4 v[244:245], off
	s_waitcnt vmcnt(8)
	s_waitcnt lgkmcnt(0)
	s_barrier
	s_cmp_lg_u32 s32, 0
	s_cbranch_scc1 .Lzc2_1
	s_setprio 1
	s_waitcnt lgkmcnt(0)
	v_mfma_f32_16x16x32_bf16 v[56:59], v[64:67], v[160:163], v[56:59]
	v_mfma_f32_16x16x32_bf16 v[60:63], v[72:75], v[160:163], v[60:63]
	v_mfma_f32_16x16x32_bf16 v[40:43], v[64:67], v[196:199], v[40:43]
	v_mfma_f32_16x16x32_bf16 v[44:47], v[72:75], v[196:199], v[44:47]
	v_mfma_f32_16x16x32_bf16 v[24:27], v[64:67], v[204:207], v[24:27]
	v_mfma_f32_16x16x32_bf16 v[28:31], v[72:75], v[204:207], v[28:31]
	v_mfma_f32_16x16x32_bf16 v[8:11], v[64:67], v[216:219], v[8:11]
	v_mfma_f32_16x16x32_bf16 v[12:15], v[72:75], v[216:219], v[12:15]
	v_mfma_f32_16x16x32_bf16 v[56:59], v[68:71], v[164:167], v[56:59]
	v_mfma_f32_16x16x32_bf16 v[60:63], v[76:79], v[164:167], v[60:63]
	v_mfma_f32_16x16x32_bf16 v[40:43], v[68:71], v[200:203], v[40:43]
	v_mfma_f32_16x16x32_bf16 v[44:47], v[76:79], v[200:203], v[44:47]
	v_mfma_f32_16x16x32_bf16 v[24:27], v[68:71], v[212:215], v[24:27]
	v_mfma_f32_16x16x32_bf16 v[28:31], v[76:79], v[212:215], v[28:31]
	v_mfma_f32_16x16x32_bf16 v[8:11], v[68:71], v[220:223], v[8:11]
	v_mfma_f32_16x16x32_bf16 v[12:15], v[76:79], v[220:223], v[12:15]
	s_setprio 0
	s_setprio 1
	v_mfma_f32_16x16x32_bf16 v[48:51], v[88:91], v[160:163], v[48:51]
	v_mfma_f32_16x16x32_bf16 v[52:55], v[96:99], v[160:163], v[52:55]
	v_mfma_f32_16x16x32_bf16 v[32:35], v[88:91], v[196:199], v[32:35]
	v_mfma_f32_16x16x32_bf16 v[36:39], v[96:99], v[196:199], v[36:39]
	v_mfma_f32_16x16x32_bf16 v[16:19], v[88:91], v[204:207], v[16:19]
	v_mfma_f32_16x16x32_bf16 v[20:23], v[96:99], v[204:207], v[20:23]
	v_mfma_f32_16x16x32_bf16 v[0:3], v[88:91], v[216:219], v[0:3]
	v_mfma_f32_16x16x32_bf16 v[4:7], v[96:99], v[216:219], v[4:7]
	v_mfma_f32_16x16x32_bf16 v[48:51], v[92:95], v[164:167], v[48:51]
	v_mfma_f32_16x16x32_bf16 v[52:55], v[100:103], v[164:167], v[52:55]
	v_mfma_f32_16x16x32_bf16 v[32:35], v[92:95], v[200:203], v[32:35]
	v_mfma_f32_16x16x32_bf16 v[36:39], v[100:103], v[200:203], v[36:39]
	v_mfma_f32_16x16x32_bf16 v[16:19], v[92:95], v[212:215], v[16:19]
	v_mfma_f32_16x16x32_bf16 v[20:23], v[100:103], v[212:215], v[20:23]
	v_mfma_f32_16x16x32_bf16 v[0:3], v[92:95], v[220:223], v[0:3]
	v_mfma_f32_16x16x32_bf16 v[4:7], v[100:103], v[220:223], v[4:7]
	s_setprio 0
.Lzc2_1j:
	s_barrier
	s_add_i32 s50, 0, 0x18000
	s_add_i32 s51, 0, 0x1c000
	v_add_u32_e32 v76, s50, v209
	v_add_u32_e32 v100, s51, v209
	ds_read_b128 v[64:67], v76
	ds_read_b128 v[68:71], v76 offset:1024
	ds_read_b128 v[72:75], v76 offset:2048
	ds_read_b128 v[76:79], v76 offset:3072
	ds_read_b128 v[88:91], v100
	ds_read_b128 v[92:95], v100 offset:1024
	ds_read_b128 v[96:99], v100 offset:2048
	ds_read_b128 v[100:103], v100 offset:3072
	s_add_u32 s26, s26, 0x40000
	s_addc_u32 s27, s27, 0
	s_mov_b32 m0, s75
	v_lshl_add_u64 v[246:247], s[26:27], 0, v[186:187]
	ds_read_b128 v[160:163], v210 offset:32768
	ds_read_b128 v[164:167], v210 offset:33792
	ds_read_b128 v[196:199], v210 offset:34816
	ds_read_b128 v[200:203], v210 offset:35840
	ds_read_b128 v[204:207], v210 offset:36864
	ds_read_b128 v[212:215], v210 offset:37888
	ds_read_b128 v[216:219], v210 offset:38912
	ds_read_b128 v[220:223], v210 offset:39936
	global_load_lds_dwordx4 v[246:247], off
	v_lshl_add_u64 v[246:247], s[26:27], 0, v[188:189]
	s_mov_b32 m0, s76
	s_nop 0
	global_load_lds_dwordx4 v[246:247], off
	s_waitcnt vmcnt(8)
	s_waitcnt lgkmcnt(0)
	s_barrier
	s_setprio 1
	s_waitcnt lgkmcnt(0)
	v_mfma_f32_16x16x32_bf16 v[152:155], v[64:67], v[160:163], v[152:155]
	v_mfma_f32_16x16x32_bf16 v[156:159], v[72:75], v[160:163], v[156:159]
	v_mfma_f32_16x16x32_bf16 v[136:139], v[64:67], v[196:199], v[136:139]
	v_mfma_f32_16x16x32_bf16 v[140:143], v[72:75], v[196:199], v[140:143]
	v_mfma_f32_16x16x32_bf16 v[120:123], v[64:67], v[204:207], v[120:123]
	v_mfma_f32_16x16x32_bf16 v[124:127], v[72:75], v[204:207], v[124:127]
	v_mfma_f32_16x16x32_bf16 v[104:107], v[64:67], v[216:219], v[104:107]
	v_mfma_f32_16x16x32_bf16 v[108:111], v[72:75], v[216:219], v[108:111]
	v_mfma_f32_16x16x32_bf16 v[152:155], v[68:71], v[164:167], v[152:155]
	v_mfma_f32_16x16x32_bf16 v[156:159], v[76:79], v[164:167], v[156:159]
	v_mfma_f32_16x16x32_bf16 v[136:139], v[68:71], v[200:203], v[136:139]
	v_mfma_f32_16x16x32_bf16 v[140:143], v[76:79], v[200:203], v[140:143]
	v_mfma_f32_16x16x32_bf16 v[120:123], v[68:71], v[212:215], v[120:123]
	v_mfma_f32_16x16x32_bf16 v[124:127], v[76:79], v[212:215], v[124:127]
	v_mfma_f32_16x16x32_bf16 v[104:107], v[68:71], v[220:223], v[104:107]
	v_mfma_f32_16x16x32_bf16 v[108:111], v[76:79], v[220:223], v[108:111]
	s_setprio 0
	s_setprio 1
	v_mfma_f32_16x16x32_bf16 v[144:147], v[88:91], v[160:163], v[144:147]
	v_mfma_f32_16x16x32_bf16 v[148:151], v[96:99], v[160:163], v[148:151]
	v_mfma_f32_16x16x32_bf16 v[128:131], v[88:91], v[196:199], v[128:131]
	v_mfma_f32_16x16x32_bf16 v[132:135], v[96:99], v[196:199], v[132:135]
	v_mfma_f32_16x16x32_bf16 v[112:115], v[88:91], v[204:207], v[112:115]
	v_mfma_f32_16x16x32_bf16 v[116:119], v[96:99], v[204:207], v[116:119]
	v_mfma_f32_16x16x32_bf16 v[80:83], v[88:91], v[216:219], v[80:83]
	v_mfma_f32_16x16x32_bf16 v[84:87], v[96:99], v[216:219], v[84:87]
	v_mfma_f32_16x16x32_bf16 v[144:147], v[92:95], v[164:167], v[144:147]
	v_mfma_f32_16x16x32_bf16 v[148:151], v[100:103], v[164:167], v[148:151]
	v_mfma_f32_16x16x32_bf16 v[128:131], v[92:95], v[200:203], v[128:131]
	v_mfma_f32_16x16x32_bf16 v[132:135], v[100:103], v[200:203], v[132:135]
	v_mfma_f32_16x16x32_bf16 v[112:115], v[92:95], v[212:215], v[112:115]
	v_mfma_f32_16x16x32_bf16 v[116:119], v[100:103], v[212:215], v[116:119]
	v_mfma_f32_16x16x32_bf16 v[80:83], v[92:95], v[220:223], v[80:83]
	v_mfma_f32_16x16x32_bf16 v[84:87], v[100:103], v[220:223], v[84:87]
	s_setprio 0
	s_barrier
	s_add_i32 s26, s50, s73
	v_lshl_add_u64 v[234:235], v[234:235], 0, s[28:29]
	s_mov_b32 m0, s26
	ds_read_b128 v[160:163], v210 offset:49152
	ds_read_b128 v[164:167], v210 offset:50176
	ds_read_b128 v[196:199], v210 offset:51200
	ds_read_b128 v[200:203], v210 offset:52224
	ds_read_b128 v[204:207], v210 offset:53248
	ds_read_b128 v[212:215], v210 offset:54272
	ds_read_b128 v[216:219], v210 offset:55296
	ds_read_b128 v[220:223], v210 offset:56320
	global_load_lds_dwordx4 v[234:235], off
	s_add_i32 m0, s26, 0x2000
	s_add_u32 s22, s22, 0x40080
	v_lshl_add_u64 v[234:235], v[236:237], 0, s[28:29]
	s_addc_u32 s23, s23, 0
	s_add_i32 s26, s51, s73
	global_load_lds_dwordx4 v[234:235], off
	v_lshl_add_u64 v[234:235], s[22:23], 0, v[168:169]
	s_mov_b32 m0, s26
	s_nop 0
	global_load_lds_dwordx4 v[234:235], off
	v_lshl_add_u64 v[234:235], s[22:23], 0, v[190:191]
	s_add_i32 m0, s26, 0x2000
	s_nop 0
	global_load_lds_dwordx4 v[234:235], off
	v_lshl_add_u64 v[234:235], v[242:243], 0, s[28:29]
	s_mov_b32 m0, s46
	s_nop 0
	global_load_lds_dwordx4 v[234:235], off
	v_lshl_add_u64 v[234:235], v[244:245], 0, s[28:29]
	s_mov_b32 m0, s47
	s_nop 0
	global_load_lds_dwordx4 v[234:235], off
	s_waitcnt vmcnt(8)
	s_waitcnt lgkmcnt(0)
	s_barrier
	s_setprio 1
	s_waitcnt lgkmcnt(0)
	v_mfma_f32_16x16x32_bf16 v[56:59], v[64:67], v[160:163], v[56:59]
	v_mfma_f32_16x16x32_bf16 v[60:63], v[72:75], v[160:163], v[60:63]
	v_mfma_f32_16x16x32_bf16 v[40:43], v[64:67], v[196:199], v[40:43]
	v_mfma_f32_16x16x32_bf16 v[44:47], v[72:75], v[196:199], v[44:47]
	v_mfma_f32_16x16x32_bf16 v[24:27], v[64:67], v[204:207], v[24:27]
	v_mfma_f32_16x16x32_bf16 v[28:31], v[72:75], v[204:207], v[28:31]
	v_mfma_f32_16x16x32_bf16 v[8:11], v[64:67], v[216:219], v[8:11]
	v_mfma_f32_16x16x32_bf16 v[12:15], v[72:75], v[216:219], v[12:15]
	v_mfma_f32_16x16x32_bf16 v[56:59], v[68:71], v[164:167], v[56:59]
	v_mfma_f32_16x16x32_bf16 v[60:63], v[76:79], v[164:167], v[60:63]
	v_mfma_f32_16x16x32_bf16 v[40:43], v[68:71], v[200:203], v[40:43]
	v_mfma_f32_16x16x32_bf16 v[44:47], v[76:79], v[200:203], v[44:47]
	v_mfma_f32_16x16x32_bf16 v[24:27], v[68:71], v[212:215], v[24:27]
	v_mfma_f32_16x16x32_bf16 v[28:31], v[76:79], v[212:215], v[28:31]
	v_mfma_f32_16x16x32_bf16 v[8:11], v[68:71], v[220:223], v[8:11]
	v_mfma_f32_16x16x32_bf16 v[12:15], v[76:79], v[220:223], v[12:15]
	s_setprio 0
	s_setprio 1
	v_mfma_f32_16x16x32_bf16 v[48:51], v[88:91], v[160:163], v[48:51]
	v_mfma_f32_16x16x32_bf16 v[52:55], v[96:99], v[160:163], v[52:55]
	v_mfma_f32_16x16x32_bf16 v[32:35], v[88:91], v[196:199], v[32:35]
	v_mfma_f32_16x16x32_bf16 v[36:39], v[96:99], v[196:199], v[36:39]
	v_mfma_f32_16x16x32_bf16 v[16:19], v[88:91], v[204:207], v[16:19]
	v_mfma_f32_16x16x32_bf16 v[20:23], v[96:99], v[204:207], v[20:23]
	v_mfma_f32_16x16x32_bf16 v[0:3], v[88:91], v[216:219], v[0:3]
	v_mfma_f32_16x16x32_bf16 v[4:7], v[96:99], v[216:219], v[4:7]
	v_mfma_f32_16x16x32_bf16 v[48:51], v[92:95], v[164:167], v[48:51]
	v_mfma_f32_16x16x32_bf16 v[52:55], v[100:103], v[164:167], v[52:55]
	v_mfma_f32_16x16x32_bf16 v[32:35], v[92:95], v[200:203], v[32:35]
	v_mfma_f32_16x16x32_bf16 v[36:39], v[100:103], v[200:203], v[36:39]
	v_mfma_f32_16x16x32_bf16 v[16:19], v[92:95], v[212:215], v[16:19]
	v_mfma_f32_16x16x32_bf16 v[20:23], v[100:103], v[212:215], v[20:23]
	v_mfma_f32_16x16x32_bf16 v[0:3], v[92:95], v[220:223], v[0:3]
	v_mfma_f32_16x16x32_bf16 v[4:7], v[100:103], v[220:223], v[4:7]
	s_setprio 0
	s_barrier
	s_add_u32 s20, s20, 0x100
	s_addc_u32 s21, s21, 0
	s_add_u32 s45, s45, 0x100
	s_addc_u32 s53, s53, 0
	s_cmp_ge_i32 s65, s42
	s_mov_b32 s22, s65
	s_mov_b32 s32, 0
	s_cbranch_scc0 .LBB0_138

.LBB0_197:
	s_ashr_i32 s61, s60, 31
	s_lshl_b64 s[20:21], s[60:61], 19
	v_readlane_b32 s41, v254, 57
	s_add_u32 s64, s41, s20
	v_readlane_b32 s20, v254, 59
	s_addc_u32 s65, s20, s21
	s_ashr_i32 s63, s62, 31
	s_lshl_b64 s[20:21], s[62:63], 19
	s_add_u32 s66, s22, s20
	s_addc_u32 s67, s23, s21
	s_andn2_b64 vcc, exec, s[56:57]
	s_waitcnt lgkmcnt(0)
	s_cbranch_vccnz .Lzc3_skip
	s_and_b64 s[20:21], s[38:39], exec
	s_cselect_b32 s41, s65, s1
	s_cselect_b32 s42, s64, s0
	s_cselect_b32 s43, s67, s3
	s_cselect_b32 s44, s66, s2
	s_add_u32 s0, s0, 0x40080
	s_addc_u32 s1, s1, 0
	s_add_u32 s45, s2, 0x100
	s_addc_u32 s46, s3, 0
	s_mov_b32 s2, 0
	s_mov_b32 s32, 1
.LBB0_199:
	s_add_i32 s47, s2, 2
	s_add_u32 s3, s0, 0xfffc0080
	s_addc_u32 s20, s1, -1
	s_add_i32 s61, 0, 0x10000
	s_cmp_eq_u32 s77, s2
	s_cselect_b32 s21, s41, s20
	s_cselect_b32 s20, s42, s3
	s_cselect_b32 s3, s43, s46
	s_cselect_b32 s2, s44, s45
	s_add_i32 s63, 0, 0x14000
	v_add_u32_e32 v146, s61, v219
	v_add_u32_e32 v162, s63, v219
	ds_read_b128 v[128:131], v146
	ds_read_b128 v[132:135], v146 offset:1024
	ds_read_b128 v[142:145], v146 offset:2048
	ds_read_b128 v[146:149], v146 offset:3072
	ds_read_b128 v[150:153], v162
	ds_read_b128 v[154:157], v162 offset:1024
	ds_read_b128 v[158:161], v162 offset:2048
	ds_read_b128 v[162:165], v162 offset:3072
	v_lshl_add_u64 v[166:167], s[0:1], 0, v[138:139]
	s_add_i32 m0, s25, 0xc000
	ds_read_b128 v[186:189], v220
	ds_read_b128 v[190:193], v220 offset:1024
	ds_read_b128 v[194:197], v220 offset:2048
	ds_read_b128 v[198:201], v220 offset:3072
	ds_read_b128 v[202:205], v220 offset:4096
	ds_read_b128 v[206:209], v220 offset:5120
	ds_read_b128 v[210:213], v220 offset:6144
	ds_read_b128 v[214:217], v220 offset:7168
	global_load_lds_dwordx4 v[166:167], off
	v_lshl_add_u64 v[166:167], s[0:1], 0, v[140:141]
	s_add_i32 m0, s25, 0xe000
	s_nop 0
	global_load_lds_dwordx4 v[166:167], off
	s_waitcnt vmcnt(8)
	s_waitcnt lgkmcnt(0)
	s_barrier
	s_cmp_lg_u32 s32, 0
	s_cbranch_scc1 .Lzc3_0
	s_setprio 1
	s_waitcnt lgkmcnt(0)
	v_mfma_f32_16x16x32_bf16 v[124:127], v[128:131], v[186:189], v[124:127]
	v_mfma_f32_16x16x32_bf16 v[120:123], v[142:145], v[186:189], v[120:123]
	v_mfma_f32_16x16x32_bf16 v[108:111], v[128:131], v[194:197], v[108:111]
	v_mfma_f32_16x16x32_bf16 v[104:107], v[142:145], v[194:197], v[104:107]
	v_mfma_f32_16x16x32_bf16 v[92:95], v[128:131], v[202:205], v[92:95]
	v_mfma_f32_16x16x32_bf16 v[88:91], v[142:145], v[202:205], v[88:91]
	v_mfma_f32_16x16x32_bf16 v[76:79], v[128:131], v[210:213], v[76:79]
	v_mfma_f32_16x16x32_bf16 v[72:75], v[142:145], v[210:213], v[72:75]
	v_mfma_f32_16x16x32_bf16 v[124:127], v[132:135], v[190:193], v[124:127]
	v_mfma_f32_16x16x32_bf16 v[120:123], v[146:149], v[190:193], v[120:123]
	v_mfma_f32_16x16x32_bf16 v[108:111], v[132:135], v[198:201], v[108:111]
	v_mfma_f32_16x16x32_bf16 v[104:107], v[146:149], v[198:201], v[104:107]
	v_mfma_f32_16x16x32_bf16 v[92:95], v[132:135], v[206:209], v[92:95]
	v_mfma_f32_16x16x32_bf16 v[88:91], v[146:149], v[206:209], v[88:91]
	v_mfma_f32_16x16x32_bf16 v[76:79], v[132:135], v[214:217], v[76:79]
	v_mfma_f32_16x16x32_bf16 v[72:75], v[146:149], v[214:217], v[72:75]
	s_setprio 0
	s_setprio 1
	v_mfma_f32_16x16x32_bf16 v[116:119], v[150:153], v[186:189], v[116:119]
	v_mfma_f32_16x16x32_bf16 v[112:115], v[158:161], v[186:189], v[112:115]
	v_mfma_f32_16x16x32_bf16 v[100:103], v[150:153], v[194:197], v[100:103]
	v_mfma_f32_16x16x32_bf16 v[96:99], v[158:161], v[194:197], v[96:99]
	v_mfma_f32_16x16x32_bf16 v[84:87], v[150:153], v[202:205], v[84:87]
	v_mfma_f32_16x16x32_bf16 v[80:83], v[158:161], v[202:205], v[80:83]
	v_mfma_f32_16x16x32_bf16 v[68:71], v[150:153], v[210:213], v[68:71]
	v_mfma_f32_16x16x32_bf16 v[64:67], v[158:161], v[210:213], v[64:67]
	v_mfma_f32_16x16x32_bf16 v[116:119], v[154:157], v[190:193], v[116:119]
	v_mfma_f32_16x16x32_bf16 v[112:115], v[162:165], v[190:193], v[112:115]
	v_mfma_f32_16x16x32_bf16 v[100:103], v[154:157], v[198:201], v[100:103]
	v_mfma_f32_16x16x32_bf16 v[96:99], v[162:165], v[198:201], v[96:99]
	v_mfma_f32_16x16x32_bf16 v[84:87], v[154:157], v[206:209], v[84:87]
	v_mfma_f32_16x16x32_bf16 v[80:83], v[162:165], v[206:209], v[80:83]
	v_mfma_f32_16x16x32_bf16 v[68:71], v[154:157], v[214:217], v[68:71]
	v_mfma_f32_16x16x32_bf16 v[64:67], v[162:165], v[214:217], v[64:67]
	s_setprio 0
.Lzc3_0j:
	s_barrier
	s_add_i32 s61, s61, s26
	v_lshl_add_u64 v[166:167], s[2:3], 0, v[168:169]
	s_mov_b32 m0, s61
	ds_read_b128 v[186:189], v220 offset:16384
	ds_read_b128 v[190:193], v220 offset:17408
	ds_read_b128 v[194:197], v220 offset:18432
	ds_read_b128 v[198:201], v220 offset:19456
	ds_read_b128 v[202:205], v220 offset:20480
	ds_read_b128 v[206:209], v220 offset:21504
	ds_read_b128 v[210:213], v220 offset:22528
	ds_read_b128 v[214:217], v220 offset:23552
	global_load_lds_dwordx4 v[166:167], off
	s_add_i32 m0, s61, 0x2000
	s_add_u32 s68, s2, 0x40000
	v_lshl_add_u64 v[222:223], s[2:3], 0, v[136:137]
	s_addc_u32 s69, s3, 0
	s_add_i32 s61, s63, s26
	global_load_lds_dwordx4 v[222:223], off
	v_lshl_add_u64 v[234:235], s[68:69], 0, v[168:169]
	s_mov_b32 m0, s61
	v_lshl_add_u64 v[236:237], s[20:21], 0, v[136:137]
	global_load_lds_dwordx4 v[234:235], off
	v_lshl_add_u64 v[234:235], s[68:69], 0, v[136:137]
	s_add_i32 m0, s61, 0x2000
	s_nop 0
	global_load_lds_dwordx4 v[234:235], off
	v_lshl_add_u64 v[234:235], s[20:21], 0, v[168:169]
	s_mov_b32 m0, s25
	s_nop 0
	global_load_lds_dwordx4 v[234:235], off
	s_mov_b32 m0, s27
	s_nop 0
	global_load_lds_dwordx4 v[236:237], off
	s_waitcnt vmcnt(8)
	s_waitcnt lgkmcnt(0)
	s_barrier
	s_cmp_lg_u32 s32, 0
	s_cbranch_scc1 .Lzc3_1
	s_setprio 1
	s_waitcnt lgkmcnt(0)
	v_mfma_f32_16x16x32_bf16 v[60:63], v[128:131], v[186:189], v[60:63]
	v_mfma_f32_16x16x32_bf16 v[56:59], v[142:145], v[186:189], v[56:59]
	v_mfma_f32_16x16x32_bf16 v[44:47], v[128:131], v[194:197], v[44:47]
	v_mfma_f32_16x16x32_bf16 v[40:43], v[142:145], v[194:197], v[40:43]
	v_mfma_f32_16x16x32_bf16 v[28:31], v[128:131], v[202:205], v[28:31]
	v_mfma_f32_16x16x32_bf16 v[24:27], v[142:145], v[202:205], v[24:27]
	v_mfma_f32_16x16x32_bf16 v[12:15], v[128:131], v[210:213], v[12:15]
	v_mfma_f32_16x16x32_bf16 v[8:11], v[142:145], v[210:213], v[8:11]
	v_mfma_f32_16x16x32_bf16 v[60:63], v[132:135], v[190:193], v[60:63]
	v_mfma_f32_16x16x32_bf16 v[56:59], v[146:149], v[190:193], v[56:59]
	v_mfma_f32_16x16x32_bf16 v[44:47], v[132:135], v[198:201], v[44:47]
	v_mfma_f32_16x16x32_bf16 v[40:43], v[146:149], v[198:201], v[40:43]
	v_mfma_f32_16x16x32_bf16 v[28:31], v[132:135], v[206:209], v[28:31]
	v_mfma_f32_16x16x32_bf16 v[24:27], v[146:149], v[206:209], v[24:27]
	v_mfma_f32_16x16x32_bf16 v[12:15], v[132:135], v[214:217], v[12:15]
	v_mfma_f32_16x16x32_bf16 v[8:11], v[146:149], v[214:217], v[8:11]
	s_setprio 0
	s_setprio 1
	v_mfma_f32_16x16x32_bf16 v[52:55], v[150:153], v[186:189], v[52:55]
	v_mfma_f32_16x16x32_bf16 v[48:51], v[158:161], v[186:189], v[48:51]
	v_mfma_f32_16x16x32_bf16 v[36:39], v[150:153], v[194:197], v[36:39]
	v_mfma_f32_16x16x32_bf16 v[32:35], v[158:161], v[194:197], v[32:35]
	v_mfma_f32_16x16x32_bf16 v[20:23], v[150:153], v[202:205], v[20:23]
	v_mfma_f32_16x16x32_bf16 v[16:19], v[158:161], v[202:205], v[16:19]
	v_mfma_f32_16x16x32_bf16 v[4:7], v[150:153], v[210:213], v[4:7]
	v_mfma_f32_16x16x32_bf16 v[0:3], v[158:161], v[210:213], v[0:3]
	v_mfma_f32_16x16x32_bf16 v[52:55], v[154:157], v[190:193], v[52:55]
	v_mfma_f32_16x16x32_bf16 v[48:51], v[162:165], v[190:193], v[48:51]
	v_mfma_f32_16x16x32_bf16 v[36:39], v[154:157], v[198:201], v[36:39]
	v_mfma_f32_16x16x32_bf16 v[32:35], v[162:165], v[198:201], v[32:35]
	v_mfma_f32_16x16x32_bf16 v[20:23], v[154:157], v[206:209], v[20:23]
	v_mfma_f32_16x16x32_bf16 v[16:19], v[162:165], v[206:209], v[16:19]
	v_mfma_f32_16x16x32_bf16 v[4:7], v[154:157], v[214:217], v[4:7]
	v_mfma_f32_16x16x32_bf16 v[0:3], v[162:165], v[214:217], v[0:3]
	s_setprio 0
.Lzc3_1j:
	s_barrier
	s_add_i32 s61, 0, 0x18000
	s_add_i32 s63, 0, 0x1c000
	v_add_u32_e32 v146, s61, v219
	v_add_u32_e32 v162, s63, v219
	ds_read_b128 v[128:131], v146
	ds_read_b128 v[132:135], v146 offset:1024
	ds_read_b128 v[142:145], v146 offset:2048
	ds_read_b128 v[146:149], v146 offset:3072
	ds_read_b128 v[150:153], v162
	ds_read_b128 v[154:157], v162 offset:1024
	ds_read_b128 v[158:161], v162 offset:2048
	ds_read_b128 v[162:165], v162 offset:3072
	s_add_u32 s20, s20, 0x40000
	s_addc_u32 s21, s21, 0
	s_mov_b32 m0, s70
	v_lshl_add_u64 v[242:243], s[20:21], 0, v[168:169]
	ds_read_b128 v[186:189], v220 offset:32768
	ds_read_b128 v[190:193], v220 offset:33792
	ds_read_b128 v[194:197], v220 offset:34816
	ds_read_b128 v[198:201], v220 offset:35840
	ds_read_b128 v[202:205], v220 offset:36864
	ds_read_b128 v[206:209], v220 offset:37888
	ds_read_b128 v[210:213], v220 offset:38912
	ds_read_b128 v[214:217], v220 offset:39936
	global_load_lds_dwordx4 v[242:243], off
	v_lshl_add_u64 v[242:243], s[20:21], 0, v[136:137]
	s_mov_b32 m0, s71
	s_nop 0
	global_load_lds_dwordx4 v[242:243], off
	s_waitcnt vmcnt(8)
	s_waitcnt lgkmcnt(0)
	s_barrier
	s_setprio 1
	s_waitcnt lgkmcnt(0)
	v_mfma_f32_16x16x32_bf16 v[124:127], v[128:131], v[186:189], v[124:127]
	v_mfma_f32_16x16x32_bf16 v[120:123], v[142:145], v[186:189], v[120:123]
	v_mfma_f32_16x16x32_bf16 v[108:111], v[128:131], v[194:197], v[108:111]
	v_mfma_f32_16x16x32_bf16 v[104:107], v[142:145], v[194:197], v[104:107]
	v_mfma_f32_16x16x32_bf16 v[92:95], v[128:131], v[202:205], v[92:95]
	v_mfma_f32_16x16x32_bf16 v[88:91], v[142:145], v[202:205], v[88:91]
	v_mfma_f32_16x16x32_bf16 v[76:79], v[128:131], v[210:213], v[76:79]
	v_mfma_f32_16x16x32_bf16 v[72:75], v[142:145], v[210:213], v[72:75]
	v_mfma_f32_16x16x32_bf16 v[124:127], v[132:135], v[190:193], v[124:127]
	v_mfma_f32_16x16x32_bf16 v[120:123], v[146:149], v[190:193], v[120:123]
	v_mfma_f32_16x16x32_bf16 v[108:111], v[132:135], v[198:201], v[108:111]
	v_mfma_f32_16x16x32_bf16 v[104:107], v[146:149], v[198:201], v[104:107]
	v_mfma_f32_16x16x32_bf16 v[92:95], v[132:135], v[206:209], v[92:95]
	v_mfma_f32_16x16x32_bf16 v[88:91], v[146:149], v[206:209], v[88:91]
	v_mfma_f32_16x16x32_bf16 v[76:79], v[132:135], v[214:217], v[76:79]
	v_mfma_f32_16x16x32_bf16 v[72:75], v[146:149], v[214:217], v[72:75]
	s_setprio 0
	s_setprio 1
	v_mfma_f32_16x16x32_bf16 v[116:119], v[150:153], v[186:189], v[116:119]
	v_mfma_f32_16x16x32_bf16 v[112:115], v[158:161], v[186:189], v[112:115]
	v_mfma_f32_16x16x32_bf16 v[100:103], v[150:153], v[194:197], v[100:103]
	v_mfma_f32_16x16x32_bf16 v[96:99], v[158:161], v[194:197], v[96:99]
	v_mfma_f32_16x16x32_bf16 v[84:87], v[150:153], v[202:205], v[84:87]
	v_mfma_f32_16x16x32_bf16 v[80:83], v[158:161], v[202:205], v[80:83]
	v_mfma_f32_16x16x32_bf16 v[68:71], v[150:153], v[210:213], v[68:71]
	v_mfma_f32_16x16x32_bf16 v[64:67], v[158:161], v[210:213], v[64:67]
	v_mfma_f32_16x16x32_bf16 v[116:119], v[154:157], v[190:193], v[116:119]
	v_mfma_f32_16x16x32_bf16 v[112:115], v[162:165], v[190:193], v[112:115]
	v_mfma_f32_16x16x32_bf16 v[100:103], v[154:157], v[198:201], v[100:103]
	v_mfma_f32_16x16x32_bf16 v[96:99], v[162:165], v[198:201], v[96:99]
	v_mfma_f32_16x16x32_bf16 v[84:87], v[154:157], v[206:209], v[84:87]
	v_mfma_f32_16x16x32_bf16 v[80:83], v[162:165], v[206:209], v[80:83]
	v_mfma_f32_16x16x32_bf16 v[68:71], v[154:157], v[214:217], v[68:71]
	v_mfma_f32_16x16x32_bf16 v[64:67], v[162:165], v[214:217], v[64:67]
	s_setprio 0
	s_barrier
	s_add_i32 s20, s61, s26
	v_lshl_add_u64 v[166:167], v[166:167], 0, s[28:29]
	s_mov_b32 m0, s20
	ds_read_b128 v[186:189], v220 offset:49152
	ds_read_b128 v[190:193], v220 offset:50176
	ds_read_b128 v[194:197], v220 offset:51200
	ds_read_b128 v[198:201], v220 offset:52224
	ds_read_b128 v[202:205], v220 offset:53248
	ds_read_b128 v[206:209], v220 offset:54272
	ds_read_b128 v[210:213], v220 offset:55296
	ds_read_b128 v[214:217], v220 offset:56320
	global_load_lds_dwordx4 v[166:167], off
	s_add_i32 m0, s20, 0x2000
	s_add_u32 s2, s2, 0x40080
	v_lshl_add_u64 v[166:167], v[222:223], 0, s[28:29]
	s_addc_u32 s3, s3, 0
	s_add_i32 s20, s63, s26
	global_load_lds_dwordx4 v[166:167], off
	v_lshl_add_u64 v[166:167], s[2:3], 0, v[168:169]
	s_mov_b32 m0, s20
	s_nop 0
	global_load_lds_dwordx4 v[166:167], off
	v_lshl_add_u64 v[166:167], s[2:3], 0, v[136:137]
	s_add_i32 m0, s20, 0x2000
	s_nop 0
	global_load_lds_dwordx4 v[166:167], off
	v_lshl_add_u64 v[166:167], v[234:235], 0, s[28:29]
	s_mov_b32 m0, s74
	s_nop 0
	global_load_lds_dwordx4 v[166:167], off
	v_lshl_add_u64 v[166:167], v[236:237], 0, s[28:29]
	s_mov_b32 m0, s75
	s_nop 0
	global_load_lds_dwordx4 v[166:167], off
	s_waitcnt vmcnt(8)
	s_waitcnt lgkmcnt(0)
	s_barrier
	s_setprio 1
	s_waitcnt lgkmcnt(0)
	v_mfma_f32_16x16x32_bf16 v[60:63], v[128:131], v[186:189], v[60:63]
	v_mfma_f32_16x16x32_bf16 v[56:59], v[142:145], v[186:189], v[56:59]
	v_mfma_f32_16x16x32_bf16 v[44:47], v[128:131], v[194:197], v[44:47]
	v_mfma_f32_16x16x32_bf16 v[40:43], v[142:145], v[194:197], v[40:43]
	v_mfma_f32_16x16x32_bf16 v[28:31], v[128:131], v[202:205], v[28:31]
	v_mfma_f32_16x16x32_bf16 v[24:27], v[142:145], v[202:205], v[24:27]
	v_mfma_f32_16x16x32_bf16 v[12:15], v[128:131], v[210:213], v[12:15]
	v_mfma_f32_16x16x32_bf16 v[8:11], v[142:145], v[210:213], v[8:11]
	v_mfma_f32_16x16x32_bf16 v[60:63], v[132:135], v[190:193], v[60:63]
	v_mfma_f32_16x16x32_bf16 v[56:59], v[146:149], v[190:193], v[56:59]
	v_mfma_f32_16x16x32_bf16 v[44:47], v[132:135], v[198:201], v[44:47]
	v_mfma_f32_16x16x32_bf16 v[40:43], v[146:149], v[198:201], v[40:43]
	v_mfma_f32_16x16x32_bf16 v[28:31], v[132:135], v[206:209], v[28:31]
	v_mfma_f32_16x16x32_bf16 v[24:27], v[146:149], v[206:209], v[24:27]
	v_mfma_f32_16x16x32_bf16 v[12:15], v[132:135], v[214:217], v[12:15]
	v_mfma_f32_16x16x32_bf16 v[8:11], v[146:149], v[214:217], v[8:11]
	s_setprio 0
	s_setprio 1
	v_mfma_f32_16x16x32_bf16 v[52:55], v[150:153], v[186:189], v[52:55]
	v_mfma_f32_16x16x32_bf16 v[48:51], v[158:161], v[186:189], v[48:51]
	v_mfma_f32_16x16x32_bf16 v[36:39], v[150:153], v[194:197], v[36:39]
	v_mfma_f32_16x16x32_bf16 v[32:35], v[158:161], v[194:197], v[32:35]
	v_mfma_f32_16x16x32_bf16 v[20:23], v[150:153], v[202:205], v[20:23]
	v_mfma_f32_16x16x32_bf16 v[16:19], v[158:161], v[202:205], v[16:19]
	v_mfma_f32_16x16x32_bf16 v[4:7], v[150:153], v[210:213], v[4:7]
	v_mfma_f32_16x16x32_bf16 v[0:3], v[158:161], v[210:213], v[0:3]
	v_mfma_f32_16x16x32_bf16 v[52:55], v[154:157], v[190:193], v[52:55]
	v_mfma_f32_16x16x32_bf16 v[48:51], v[162:165], v[190:193], v[48:51]
	v_mfma_f32_16x16x32_bf16 v[36:39], v[154:157], v[198:201], v[36:39]
	v_mfma_f32_16x16x32_bf16 v[32:35], v[162:165], v[198:201], v[32:35]
	v_mfma_f32_16x16x32_bf16 v[20:23], v[154:157], v[206:209], v[20:23]
	v_mfma_f32_16x16x32_bf16 v[16:19], v[162:165], v[206:209], v[16:19]
	v_mfma_f32_16x16x32_bf16 v[4:7], v[154:157], v[214:217], v[4:7]
	v_mfma_f32_16x16x32_bf16 v[0:3], v[162:165], v[214:217], v[0:3]
	s_setprio 0
	s_barrier
	s_add_u32 s0, s0, 0x100
	s_addc_u32 s1, s1, 0
	s_add_u32 s45, s45, 0x100
	s_addc_u32 s46, s46, 0
	s_cmp_ge_i32 s47, s52
	s_mov_b32 s2, s47
	s_mov_b32 s32, 0
	s_cbranch_scc0 .LBB0_199

.Lzc4_0:
	s_setprio 1
	s_waitcnt lgkmcnt(0)
	v_mfma_f32_16x16x32_bf16 v[124:127], v[138:141], v[194:197], 0
	v_mfma_f32_16x16x32_bf16 v[120:123], v[150:153], v[194:197], 0
	v_mfma_f32_16x16x32_bf16 v[108:111], v[138:141], v[202:205], 0
	v_mfma_f32_16x16x32_bf16 v[104:107], v[150:153], v[202:205], 0
	v_mfma_f32_16x16x32_bf16 v[92:95], v[138:141], v[210:213], 0
	v_mfma_f32_16x16x32_bf16 v[88:91], v[150:153], v[210:213], 0
	v_mfma_f32_16x16x32_bf16 v[76:79], v[138:141], v[218:221], 0
	v_mfma_f32_16x16x32_bf16 v[72:75], v[150:153], v[218:221], 0
	v_mfma_f32_16x16x32_bf16 v[124:127], v[142:145], v[198:201], v[124:127]
	v_mfma_f32_16x16x32_bf16 v[120:123], v[154:157], v[198:201], v[120:123]
	v_mfma_f32_16x16x32_bf16 v[108:111], v[142:145], v[206:209], v[108:111]
	v_mfma_f32_16x16x32_bf16 v[104:107], v[154:157], v[206:209], v[104:107]
	v_mfma_f32_16x16x32_bf16 v[92:95], v[142:145], v[214:217], v[92:95]
	v_mfma_f32_16x16x32_bf16 v[88:91], v[154:157], v[214:217], v[88:91]
	v_mfma_f32_16x16x32_bf16 v[76:79], v[142:145], v[242:245], v[76:79]
	v_mfma_f32_16x16x32_bf16 v[72:75], v[154:157], v[242:245], v[72:75]
	s_setprio 0
	s_setprio 1
	v_mfma_f32_16x16x32_bf16 v[116:119], v[158:161], v[194:197], 0
	v_mfma_f32_16x16x32_bf16 v[112:115], v[186:189], v[194:197], 0
	v_mfma_f32_16x16x32_bf16 v[100:103], v[158:161], v[202:205], 0
	v_mfma_f32_16x16x32_bf16 v[96:99], v[186:189], v[202:205], 0
	v_mfma_f32_16x16x32_bf16 v[84:87], v[158:161], v[210:213], 0
	v_mfma_f32_16x16x32_bf16 v[80:83], v[186:189], v[210:213], 0
	v_mfma_f32_16x16x32_bf16 v[68:71], v[158:161], v[218:221], 0
	v_mfma_f32_16x16x32_bf16 v[64:67], v[186:189], v[218:221], 0
	v_mfma_f32_16x16x32_bf16 v[116:119], v[162:165], v[198:201], v[116:119]
	v_mfma_f32_16x16x32_bf16 v[112:115], v[190:193], v[198:201], v[112:115]
	v_mfma_f32_16x16x32_bf16 v[100:103], v[162:165], v[206:209], v[100:103]
	v_mfma_f32_16x16x32_bf16 v[96:99], v[190:193], v[206:209], v[96:99]
	v_mfma_f32_16x16x32_bf16 v[84:87], v[162:165], v[214:217], v[84:87]
	v_mfma_f32_16x16x32_bf16 v[80:83], v[190:193], v[214:217], v[80:83]
	v_mfma_f32_16x16x32_bf16 v[68:71], v[162:165], v[242:245], v[68:71]
	v_mfma_f32_16x16x32_bf16 v[64:67], v[190:193], v[242:245], v[64:67]
	s_setprio 0
	s_branch .Lzc4_0j
.Lzc4_1:
	s_setprio 1
	s_waitcnt lgkmcnt(0)
	v_mfma_f32_16x16x32_bf16 v[60:63], v[138:141], v[194:197], 0
	v_mfma_f32_16x16x32_bf16 v[56:59], v[150:153], v[194:197], 0
	v_mfma_f32_16x16x32_bf16 v[44:47], v[138:141], v[202:205], 0
	v_mfma_f32_16x16x32_bf16 v[40:43], v[150:153], v[202:205], 0
	v_mfma_f32_16x16x32_bf16 v[28:31], v[138:141], v[210:213], 0
	v_mfma_f32_16x16x32_bf16 v[24:27], v[150:153], v[210:213], 0
	v_mfma_f32_16x16x32_bf16 v[12:15], v[138:141], v[218:221], 0
	v_mfma_f32_16x16x32_bf16 v[8:11], v[150:153], v[218:221], 0
	v_mfma_f32_16x16x32_bf16 v[60:63], v[142:145], v[198:201], v[60:63]
	v_mfma_f32_16x16x32_bf16 v[56:59], v[154:157], v[198:201], v[56:59]
	v_mfma_f32_16x16x32_bf16 v[44:47], v[142:145], v[206:209], v[44:47]
	v_mfma_f32_16x16x32_bf16 v[40:43], v[154:157], v[206:209], v[40:43]
	v_mfma_f32_16x16x32_bf16 v[28:31], v[142:145], v[214:217], v[28:31]
	v_mfma_f32_16x16x32_bf16 v[24:27], v[154:157], v[214:217], v[24:27]
	v_mfma_f32_16x16x32_bf16 v[12:15], v[142:145], v[242:245], v[12:15]
	v_mfma_f32_16x16x32_bf16 v[8:11], v[154:157], v[242:245], v[8:11]
	s_setprio 0
	s_setprio 1
	v_mfma_f32_16x16x32_bf16 v[52:55], v[158:161], v[194:197], 0
	v_mfma_f32_16x16x32_bf16 v[48:51], v[186:189], v[194:197], 0
	v_mfma_f32_16x16x32_bf16 v[36:39], v[158:161], v[202:205], 0
	v_mfma_f32_16x16x32_bf16 v[32:35], v[186:189], v[202:205], 0
	v_mfma_f32_16x16x32_bf16 v[20:23], v[158:161], v[210:213], 0
	v_mfma_f32_16x16x32_bf16 v[16:19], v[186:189], v[210:213], 0
	v_mfma_f32_16x16x32_bf16 v[4:7], v[158:161], v[218:221], 0
	v_mfma_f32_16x16x32_bf16 v[0:3], v[186:189], v[218:221], 0
	v_mfma_f32_16x16x32_bf16 v[52:55], v[162:165], v[198:201], v[52:55]
	v_mfma_f32_16x16x32_bf16 v[48:51], v[190:193], v[198:201], v[48:51]
	v_mfma_f32_16x16x32_bf16 v[36:39], v[162:165], v[206:209], v[36:39]
	v_mfma_f32_16x16x32_bf16 v[32:35], v[190:193], v[206:209], v[32:35]
	v_mfma_f32_16x16x32_bf16 v[20:23], v[162:165], v[214:217], v[20:23]
	v_mfma_f32_16x16x32_bf16 v[16:19], v[190:193], v[214:217], v[16:19]
	v_mfma_f32_16x16x32_bf16 v[4:7], v[162:165], v[242:245], v[4:7]
	v_mfma_f32_16x16x32_bf16 v[0:3], v[190:193], v[242:245], v[0:3]
	s_setprio 0
	s_branch .Lzc4_1j

.LBB0_248:
	s_andn2_b64 vcc, exec, s[20:21]
	s_cbranch_vccnz .Lzc4_skip
	s_add_u32 s0, s64, 0x40080
	s_addc_u32 s1, s65, 0
	s_add_u32 s3, s62, 0x100
	s_addc_u32 s27, s63, 0
	s_mov_b32 s41, 0
	s_mov_b32 s32, 1
.LBB0_250:
	s_add_i32 s53, s41, 2
	s_add_u32 s59, s0, 0xfffc0080
	s_addc_u32 s61, s1, -1
	s_add_i32 s79, 0, 0x10000
	s_cmp_eq_u32 s73, s41
	s_cselect_b32 s65, s55, s61
	s_cselect_b32 s64, s54, s59
	s_cselect_b32 s63, s57, s27
	s_cselect_b32 s62, s56, s3
	s_add_i32 s41, 0, 0x14000
	v_add_u32_e32 v154, s79, v148
	v_add_u32_e32 v166, s41, v148
	ds_read_b128 v[138:141], v154
	ds_read_b128 v[142:145], v154 offset:1024
	ds_read_b128 v[150:153], v154 offset:2048
	ds_read_b128 v[154:157], v154 offset:3072
	ds_read_b128 v[158:161], v166
	ds_read_b128 v[162:165], v166 offset:1024
	s_waitcnt vmcnt(0)
	ds_read_b128 v[186:189], v166 offset:2048
	ds_read_b128 v[190:193], v166 offset:3072
	v_lshl_add_u64 v[166:167], s[0:1], 0, v[134:135]
	s_add_i32 m0, s46, 0xc000
	ds_read_b128 v[194:197], v149
	ds_read_b128 v[198:201], v149 offset:1024
	ds_read_b128 v[202:205], v149 offset:2048
	ds_read_b128 v[206:209], v149 offset:3072
	ds_read_b128 v[210:213], v149 offset:4096
	ds_read_b128 v[214:217], v149 offset:5120
	ds_read_b128 v[218:221], v149 offset:6144
	ds_read_b128 v[242:245], v149 offset:7168
	global_load_lds_dwordx4 v[166:167], off
	v_lshl_add_u64 v[166:167], s[0:1], 0, v[136:137]
	s_add_i32 m0, s46, 0xe000
	s_nop 0
	global_load_lds_dwordx4 v[166:167], off
	s_waitcnt vmcnt(8)
	s_waitcnt lgkmcnt(0)
	s_barrier
	s_cmp_lg_u32 s32, 0
	s_cbranch_scc1 .Lzc4_0
	s_setprio 1
	s_waitcnt lgkmcnt(0)
	v_mfma_f32_16x16x32_bf16 v[124:127], v[138:141], v[194:197], v[124:127]
	v_mfma_f32_16x16x32_bf16 v[120:123], v[150:153], v[194:197], v[120:123]
	v_mfma_f32_16x16x32_bf16 v[108:111], v[138:141], v[202:205], v[108:111]
	v_mfma_f32_16x16x32_bf16 v[104:107], v[150:153], v[202:205], v[104:107]
	v_mfma_f32_16x16x32_bf16 v[92:95], v[138:141], v[210:213], v[92:95]
	v_mfma_f32_16x16x32_bf16 v[88:91], v[150:153], v[210:213], v[88:91]
	v_mfma_f32_16x16x32_bf16 v[76:79], v[138:141], v[218:221], v[76:79]
	v_mfma_f32_16x16x32_bf16 v[72:75], v[150:153], v[218:221], v[72:75]
	v_mfma_f32_16x16x32_bf16 v[124:127], v[142:145], v[198:201], v[124:127]
	v_mfma_f32_16x16x32_bf16 v[120:123], v[154:157], v[198:201], v[120:123]
	v_mfma_f32_16x16x32_bf16 v[108:111], v[142:145], v[206:209], v[108:111]
	v_mfma_f32_16x16x32_bf16 v[104:107], v[154:157], v[206:209], v[104:107]
	v_mfma_f32_16x16x32_bf16 v[92:95], v[142:145], v[214:217], v[92:95]
	v_mfma_f32_16x16x32_bf16 v[88:91], v[154:157], v[214:217], v[88:91]
	v_mfma_f32_16x16x32_bf16 v[76:79], v[142:145], v[242:245], v[76:79]
	v_mfma_f32_16x16x32_bf16 v[72:75], v[154:157], v[242:245], v[72:75]
	s_setprio 0
	s_setprio 1
	v_mfma_f32_16x16x32_bf16 v[116:119], v[158:161], v[194:197], v[116:119]
	v_mfma_f32_16x16x32_bf16 v[112:115], v[186:189], v[194:197], v[112:115]
	v_mfma_f32_16x16x32_bf16 v[100:103], v[158:161], v[202:205], v[100:103]
	v_mfma_f32_16x16x32_bf16 v[96:99], v[186:189], v[202:205], v[96:99]
	v_mfma_f32_16x16x32_bf16 v[84:87], v[158:161], v[210:213], v[84:87]
	v_mfma_f32_16x16x32_bf16 v[80:83], v[186:189], v[210:213], v[80:83]
	v_mfma_f32_16x16x32_bf16 v[68:71], v[158:161], v[218:221], v[68:71]
	v_mfma_f32_16x16x32_bf16 v[64:67], v[186:189], v[218:221], v[64:67]
	v_mfma_f32_16x16x32_bf16 v[116:119], v[162:165], v[198:201], v[116:119]
	v_mfma_f32_16x16x32_bf16 v[112:115], v[190:193], v[198:201], v[112:115]
	v_mfma_f32_16x16x32_bf16 v[100:103], v[162:165], v[206:209], v[100:103]
	v_mfma_f32_16x16x32_bf16 v[96:99], v[190:193], v[206:209], v[96:99]
	v_mfma_f32_16x16x32_bf16 v[84:87], v[162:165], v[214:217], v[84:87]
	v_mfma_f32_16x16x32_bf16 v[80:83], v[190:193], v[214:217], v[80:83]
	v_mfma_f32_16x16x32_bf16 v[68:71], v[162:165], v[242:245], v[68:71]
	v_mfma_f32_16x16x32_bf16 v[64:67], v[190:193], v[242:245], v[64:67]
	s_setprio 0
.Lzc4_0j:
	s_barrier
	s_add_i32 s59, s79, s45
	v_lshl_add_u64 v[166:167], s[62:63], 0, v[168:169]
	s_mov_b32 m0, s59
	ds_read_b128 v[194:197], v149 offset:16384
	ds_read_b128 v[198:201], v149 offset:17408
	ds_read_b128 v[202:205], v149 offset:18432
	ds_read_b128 v[206:209], v149 offset:19456
	ds_read_b128 v[210:213], v149 offset:20480
	ds_read_b128 v[214:217], v149 offset:21504
	ds_read_b128 v[218:221], v149 offset:22528
	ds_read_b128 v[242:245], v149 offset:23552
	global_load_lds_dwordx4 v[166:167], off
	s_add_i32 m0, s59, 0x2000
	s_add_u32 vcc_lo, s62, 0x10000
	v_lshl_add_u64 v[222:223], s[62:63], 0, v[132:133]
	s_addc_u32 vcc_hi, s63, 0
	s_add_i32 s41, s41, s45
	global_load_lds_dwordx4 v[222:223], off
	v_lshl_add_u64 v[234:235], vcc, 0, v[168:169]
	s_mov_b32 m0, s41
	v_lshl_add_u64 v[236:237], s[64:65], 0, v[130:131]
	global_load_lds_dwordx4 v[234:235], off
	v_lshl_add_u64 v[234:235], vcc, 0, v[132:133]
	s_add_i32 m0, s41, 0x2000
	s_nop 0
	global_load_lds_dwordx4 v[234:235], off
	v_lshl_add_u64 v[234:235], s[64:65], 0, v[128:129]
	s_mov_b32 m0, s46
	s_nop 0
	global_load_lds_dwordx4 v[234:235], off
	s_mov_b32 m0, s47
	s_nop 0
	global_load_lds_dwordx4 v[236:237], off
	s_waitcnt vmcnt(8)
	s_waitcnt lgkmcnt(0)
	s_barrier
	s_cmp_lg_u32 s32, 0
	s_cbranch_scc1 .Lzc4_1
	s_setprio 1
	s_waitcnt lgkmcnt(0)
	v_mfma_f32_16x16x32_bf16 v[60:63], v[138:141], v[194:197], v[60:63]
	v_mfma_f32_16x16x32_bf16 v[56:59], v[150:153], v[194:197], v[56:59]
	v_mfma_f32_16x16x32_bf16 v[44:47], v[138:141], v[202:205], v[44:47]
	v_mfma_f32_16x16x32_bf16 v[40:43], v[150:153], v[202:205], v[40:43]
	v_mfma_f32_16x16x32_bf16 v[28:31], v[138:141], v[210:213], v[28:31]
	v_mfma_f32_16x16x32_bf16 v[24:27], v[150:153], v[210:213], v[24:27]
	v_mfma_f32_16x16x32_bf16 v[12:15], v[138:141], v[218:221], v[12:15]
	v_mfma_f32_16x16x32_bf16 v[8:11], v[150:153], v[218:221], v[8:11]
	v_mfma_f32_16x16x32_bf16 v[60:63], v[142:145], v[198:201], v[60:63]
	v_mfma_f32_16x16x32_bf16 v[56:59], v[154:157], v[198:201], v[56:59]
	v_mfma_f32_16x16x32_bf16 v[44:47], v[142:145], v[206:209], v[44:47]
	v_mfma_f32_16x16x32_bf16 v[40:43], v[154:157], v[206:209], v[40:43]
	v_mfma_f32_16x16x32_bf16 v[28:31], v[142:145], v[214:217], v[28:31]
	v_mfma_f32_16x16x32_bf16 v[24:27], v[154:157], v[214:217], v[24:27]
	v_mfma_f32_16x16x32_bf16 v[12:15], v[142:145], v[242:245], v[12:15]
	v_mfma_f32_16x16x32_bf16 v[8:11], v[154:157], v[242:245], v[8:11]
	s_setprio 0
	s_setprio 1
	v_mfma_f32_16x16x32_bf16 v[52:55], v[158:161], v[194:197], v[52:55]
	v_mfma_f32_16x16x32_bf16 v[48:51], v[186:189], v[194:197], v[48:51]
	v_mfma_f32_16x16x32_bf16 v[36:39], v[158:161], v[202:205], v[36:39]
	v_mfma_f32_16x16x32_bf16 v[32:35], v[186:189], v[202:205], v[32:35]
	v_mfma_f32_16x16x32_bf16 v[20:23], v[158:161], v[210:213], v[20:23]
	v_mfma_f32_16x16x32_bf16 v[16:19], v[186:189], v[210:213], v[16:19]
	v_mfma_f32_16x16x32_bf16 v[4:7], v[158:161], v[218:221], v[4:7]
	v_mfma_f32_16x16x32_bf16 v[0:3], v[186:189], v[218:221], v[0:3]
	v_mfma_f32_16x16x32_bf16 v[52:55], v[162:165], v[198:201], v[52:55]
	v_mfma_f32_16x16x32_bf16 v[48:51], v[190:193], v[198:201], v[48:51]
	v_mfma_f32_16x16x32_bf16 v[36:39], v[162:165], v[206:209], v[36:39]
	v_mfma_f32_16x16x32_bf16 v[32:35], v[190:193], v[206:209], v[32:35]
	v_mfma_f32_16x16x32_bf16 v[20:23], v[162:165], v[214:217], v[20:23]
	v_mfma_f32_16x16x32_bf16 v[16:19], v[190:193], v[214:217], v[16:19]
	v_mfma_f32_16x16x32_bf16 v[4:7], v[162:165], v[242:245], v[4:7]
	v_mfma_f32_16x16x32_bf16 v[0:3], v[190:193], v[242:245], v[0:3]
	s_setprio 0
.Lzc4_1j:
	s_barrier
	s_add_i32 s41, 0, 0x18000
	s_add_i32 s59, 0, 0x1c000
	v_add_u32_e32 v154, s41, v148
	v_add_u32_e32 v174, s59, v148
	ds_read_b128 v[138:141], v154
	ds_read_b128 v[142:145], v154 offset:1024
	ds_read_b128 v[150:153], v154 offset:2048
	ds_read_b128 v[154:157], v154 offset:3072
	ds_read_b128 v[158:161], v174
	ds_read_b128 v[162:165], v174 offset:1024
	ds_read_b128 v[186:189], v174 offset:2048
	ds_read_b128 v[190:193], v174 offset:3072
	s_add_u32 s64, s64, 0x40000
	s_addc_u32 s65, s65, 0
	s_mov_b32 m0, s66
	v_lshl_add_u64 v[246:247], s[64:65], 0, v[128:129]
	ds_read_b128 v[194:197], v149 offset:32768
	ds_read_b128 v[198:201], v149 offset:33792
	ds_read_b128 v[202:205], v149 offset:34816
	ds_read_b128 v[206:209], v149 offset:35840
	ds_read_b128 v[210:213], v149 offset:36864
	ds_read_b128 v[214:217], v149 offset:37888
	ds_read_b128 v[218:221], v149 offset:38912
	ds_read_b128 v[242:245], v149 offset:39936
	global_load_lds_dwordx4 v[246:247], off
	v_lshl_add_u64 v[246:247], s[64:65], 0, v[130:131]
	s_mov_b32 m0, s67
	s_nop 0
	global_load_lds_dwordx4 v[246:247], off
	s_waitcnt vmcnt(8)
	s_waitcnt lgkmcnt(0)
	s_barrier
	s_setprio 1
	s_waitcnt lgkmcnt(0)
	v_mfma_f32_16x16x32_bf16 v[124:127], v[138:141], v[194:197], v[124:127]
	v_mfma_f32_16x16x32_bf16 v[120:123], v[150:153], v[194:197], v[120:123]
	v_mfma_f32_16x16x32_bf16 v[108:111], v[138:141], v[202:205], v[108:111]
	v_mfma_f32_16x16x32_bf16 v[104:107], v[150:153], v[202:205], v[104:107]
	v_mfma_f32_16x16x32_bf16 v[92:95], v[138:141], v[210:213], v[92:95]
	v_mfma_f32_16x16x32_bf16 v[88:91], v[150:153], v[210:213], v[88:91]
	v_mfma_f32_16x16x32_bf16 v[76:79], v[138:141], v[218:221], v[76:79]
	v_mfma_f32_16x16x32_bf16 v[72:75], v[150:153], v[218:221], v[72:75]
	v_mfma_f32_16x16x32_bf16 v[124:127], v[142:145], v[198:201], v[124:127]
	v_mfma_f32_16x16x32_bf16 v[120:123], v[154:157], v[198:201], v[120:123]
	v_mfma_f32_16x16x32_bf16 v[108:111], v[142:145], v[206:209], v[108:111]
	v_mfma_f32_16x16x32_bf16 v[104:107], v[154:157], v[206:209], v[104:107]
	v_mfma_f32_16x16x32_bf16 v[92:95], v[142:145], v[214:217], v[92:95]
	v_mfma_f32_16x16x32_bf16 v[88:91], v[154:157], v[214:217], v[88:91]
	v_mfma_f32_16x16x32_bf16 v[76:79], v[142:145], v[242:245], v[76:79]
	v_mfma_f32_16x16x32_bf16 v[72:75], v[154:157], v[242:245], v[72:75]
	s_setprio 0
	s_setprio 1
	v_mfma_f32_16x16x32_bf16 v[116:119], v[158:161], v[194:197], v[116:119]
	v_mfma_f32_16x16x32_bf16 v[112:115], v[186:189], v[194:197], v[112:115]
	v_mfma_f32_16x16x32_bf16 v[100:103], v[158:161], v[202:205], v[100:103]
	v_mfma_f32_16x16x32_bf16 v[96:99], v[186:189], v[202:205], v[96:99]
	v_mfma_f32_16x16x32_bf16 v[84:87], v[158:161], v[210:213], v[84:87]
	v_mfma_f32_16x16x32_bf16 v[80:83], v[186:189], v[210:213], v[80:83]
	v_mfma_f32_16x16x32_bf16 v[68:71], v[158:161], v[218:221], v[68:71]
	v_mfma_f32_16x16x32_bf16 v[64:67], v[186:189], v[218:221], v[64:67]
	v_mfma_f32_16x16x32_bf16 v[116:119], v[162:165], v[198:201], v[116:119]
	v_mfma_f32_16x16x32_bf16 v[112:115], v[190:193], v[198:201], v[112:115]
	v_mfma_f32_16x16x32_bf16 v[100:103], v[162:165], v[206:209], v[100:103]
	v_mfma_f32_16x16x32_bf16 v[96:99], v[190:193], v[206:209], v[96:99]
	v_mfma_f32_16x16x32_bf16 v[84:87], v[162:165], v[214:217], v[84:87]
	v_mfma_f32_16x16x32_bf16 v[80:83], v[190:193], v[214:217], v[80:83]
	v_mfma_f32_16x16x32_bf16 v[68:71], v[162:165], v[242:245], v[68:71]
	v_mfma_f32_16x16x32_bf16 v[64:67], v[190:193], v[242:245], v[64:67]
	s_setprio 0
	s_barrier
	s_add_i32 s41, s41, s45
	v_lshl_add_u64 v[166:167], v[166:167], 0, s[28:29]
	s_mov_b32 m0, s41
	ds_read_b128 v[194:197], v149 offset:49152
	ds_read_b128 v[198:201], v149 offset:50176
	ds_read_b128 v[202:205], v149 offset:51200
	ds_read_b128 v[206:209], v149 offset:52224
	ds_read_b128 v[210:213], v149 offset:53248
	ds_read_b128 v[214:217], v149 offset:54272
	ds_read_b128 v[218:221], v149 offset:55296
	ds_read_b128 v[242:245], v149 offset:56320
	global_load_lds_dwordx4 v[166:167], off
	s_add_i32 m0, s41, 0x2000
	s_add_u32 s62, s62, 0x10080
	v_lshl_add_u64 v[166:167], v[222:223], 0, s[28:29]
	s_addc_u32 s63, s63, 0
	s_add_i32 s41, s59, s45
	global_load_lds_dwordx4 v[166:167], off
	v_lshl_add_u64 v[166:167], s[62:63], 0, v[168:169]
	s_mov_b32 m0, s41
	s_nop 0
	global_load_lds_dwordx4 v[166:167], off
	v_lshl_add_u64 v[166:167], s[62:63], 0, v[132:133]
	s_add_i32 m0, s41, 0x2000
	s_nop 0
	global_load_lds_dwordx4 v[166:167], off
	v_lshl_add_u64 v[166:167], v[234:235], 0, s[28:29]
	s_mov_b32 m0, s71
	s_nop 0
	global_load_lds_dwordx4 v[166:167], off
	v_lshl_add_u64 v[166:167], v[236:237], 0, s[28:29]
	s_mov_b32 m0, s72
	s_nop 0
	global_load_lds_dwordx4 v[166:167], off
	s_waitcnt vmcnt(8)
	s_waitcnt lgkmcnt(0)
	s_barrier
	s_setprio 1
	s_waitcnt lgkmcnt(0)
	v_mfma_f32_16x16x32_bf16 v[60:63], v[138:141], v[194:197], v[60:63]
	v_mfma_f32_16x16x32_bf16 v[56:59], v[150:153], v[194:197], v[56:59]
	v_mfma_f32_16x16x32_bf16 v[44:47], v[138:141], v[202:205], v[44:47]
	v_mfma_f32_16x16x32_bf16 v[40:43], v[150:153], v[202:205], v[40:43]
	v_mfma_f32_16x16x32_bf16 v[28:31], v[138:141], v[210:213], v[28:31]
	v_mfma_f32_16x16x32_bf16 v[24:27], v[150:153], v[210:213], v[24:27]
	v_mfma_f32_16x16x32_bf16 v[12:15], v[138:141], v[218:221], v[12:15]
	v_mfma_f32_16x16x32_bf16 v[8:11], v[150:153], v[218:221], v[8:11]
	v_mfma_f32_16x16x32_bf16 v[60:63], v[142:145], v[198:201], v[60:63]
	v_mfma_f32_16x16x32_bf16 v[56:59], v[154:157], v[198:201], v[56:59]
	v_mfma_f32_16x16x32_bf16 v[44:47], v[142:145], v[206:209], v[44:47]
	v_mfma_f32_16x16x32_bf16 v[40:43], v[154:157], v[206:209], v[40:43]
	v_mfma_f32_16x16x32_bf16 v[28:31], v[142:145], v[214:217], v[28:31]
	v_mfma_f32_16x16x32_bf16 v[24:27], v[154:157], v[214:217], v[24:27]
	v_mfma_f32_16x16x32_bf16 v[12:15], v[142:145], v[242:245], v[12:15]
	v_mfma_f32_16x16x32_bf16 v[8:11], v[154:157], v[242:245], v[8:11]
	s_setprio 0
	s_setprio 1
	v_mfma_f32_16x16x32_bf16 v[52:55], v[158:161], v[194:197], v[52:55]
	v_mfma_f32_16x16x32_bf16 v[48:51], v[186:189], v[194:197], v[48:51]
	v_mfma_f32_16x16x32_bf16 v[36:39], v[158:161], v[202:205], v[36:39]
	v_mfma_f32_16x16x32_bf16 v[32:35], v[186:189], v[202:205], v[32:35]
	v_mfma_f32_16x16x32_bf16 v[20:23], v[158:161], v[210:213], v[20:23]
	v_mfma_f32_16x16x32_bf16 v[16:19], v[186:189], v[210:213], v[16:19]
	v_mfma_f32_16x16x32_bf16 v[4:7], v[158:161], v[218:221], v[4:7]
	v_mfma_f32_16x16x32_bf16 v[0:3], v[186:189], v[218:221], v[0:3]
	v_mfma_f32_16x16x32_bf16 v[52:55], v[162:165], v[198:201], v[52:55]
	v_mfma_f32_16x16x32_bf16 v[48:51], v[190:193], v[198:201], v[48:51]
	v_mfma_f32_16x16x32_bf16 v[36:39], v[162:165], v[206:209], v[36:39]
	v_mfma_f32_16x16x32_bf16 v[32:35], v[190:193], v[206:209], v[32:35]
	v_mfma_f32_16x16x32_bf16 v[20:23], v[162:165], v[214:217], v[20:23]
	v_mfma_f32_16x16x32_bf16 v[16:19], v[190:193], v[214:217], v[16:19]
	v_mfma_f32_16x16x32_bf16 v[4:7], v[162:165], v[242:245], v[4:7]
	v_mfma_f32_16x16x32_bf16 v[0:3], v[190:193], v[242:245], v[0:3]
	s_setprio 0
	s_barrier
	s_add_u32 s0, s0, 0x100
	s_addc_u32 s1, s1, 0
	s_add_u32 s3, s3, 0x100
	s_addc_u32 s27, s27, 0
	s_cmp_ge_i32 s53, s68
	s_mov_b32 s41, s53
	s_mov_b32 s32, 0
	s_cbranch_scc0 .LBB0_250

.Lzc5_0:
	s_setprio 1
	s_waitcnt lgkmcnt(0)
	v_mfma_f32_16x16x32_bf16 v[124:127], v[138:141], v[194:197], 0
	v_mfma_f32_16x16x32_bf16 v[120:123], v[150:153], v[194:197], 0
	v_mfma_f32_16x16x32_bf16 v[108:111], v[138:141], v[202:205], 0
	v_mfma_f32_16x16x32_bf16 v[104:107], v[150:153], v[202:205], 0
	v_mfma_f32_16x16x32_bf16 v[92:95], v[138:141], v[210:213], 0
	v_mfma_f32_16x16x32_bf16 v[88:91], v[150:153], v[210:213], 0
	v_mfma_f32_16x16x32_bf16 v[76:79], v[138:141], v[218:221], 0
	v_mfma_f32_16x16x32_bf16 v[72:75], v[150:153], v[218:221], 0
	v_mfma_f32_16x16x32_bf16 v[124:127], v[146:149], v[198:201], v[124:127]
	v_mfma_f32_16x16x32_bf16 v[120:123], v[154:157], v[198:201], v[120:123]
	v_mfma_f32_16x16x32_bf16 v[108:111], v[146:149], v[206:209], v[108:111]
	v_mfma_f32_16x16x32_bf16 v[104:107], v[154:157], v[206:209], v[104:107]
	v_mfma_f32_16x16x32_bf16 v[92:95], v[146:149], v[214:217], v[92:95]
	v_mfma_f32_16x16x32_bf16 v[88:91], v[154:157], v[214:217], v[88:91]
	v_mfma_f32_16x16x32_bf16 v[76:79], v[146:149], v[242:245], v[76:79]
	v_mfma_f32_16x16x32_bf16 v[72:75], v[154:157], v[242:245], v[72:75]
	s_setprio 0
	s_setprio 1
	v_mfma_f32_16x16x32_bf16 v[116:119], v[158:161], v[194:197], 0
	v_mfma_f32_16x16x32_bf16 v[112:115], v[186:189], v[194:197], 0
	v_mfma_f32_16x16x32_bf16 v[100:103], v[158:161], v[202:205], 0
	v_mfma_f32_16x16x32_bf16 v[96:99], v[186:189], v[202:205], 0
	v_mfma_f32_16x16x32_bf16 v[84:87], v[158:161], v[210:213], 0
	v_mfma_f32_16x16x32_bf16 v[80:83], v[186:189], v[210:213], 0
	v_mfma_f32_16x16x32_bf16 v[68:71], v[158:161], v[218:221], 0
	v_mfma_f32_16x16x32_bf16 v[64:67], v[186:189], v[218:221], 0
	v_mfma_f32_16x16x32_bf16 v[116:119], v[162:165], v[198:201], v[116:119]
	v_mfma_f32_16x16x32_bf16 v[112:115], v[190:193], v[198:201], v[112:115]
	v_mfma_f32_16x16x32_bf16 v[100:103], v[162:165], v[206:209], v[100:103]
	v_mfma_f32_16x16x32_bf16 v[96:99], v[190:193], v[206:209], v[96:99]
	v_mfma_f32_16x16x32_bf16 v[84:87], v[162:165], v[214:217], v[84:87]
	v_mfma_f32_16x16x32_bf16 v[80:83], v[190:193], v[214:217], v[80:83]
	v_mfma_f32_16x16x32_bf16 v[68:71], v[162:165], v[242:245], v[68:71]
	v_mfma_f32_16x16x32_bf16 v[64:67], v[190:193], v[242:245], v[64:67]
	s_setprio 0
	s_branch .Lzc5_0j
.Lzc5_1:
	s_setprio 1
	s_waitcnt lgkmcnt(0)
	v_mfma_f32_16x16x32_bf16 v[60:63], v[138:141], v[194:197], 0
	v_mfma_f32_16x16x32_bf16 v[56:59], v[150:153], v[194:197], 0
	v_mfma_f32_16x16x32_bf16 v[44:47], v[138:141], v[202:205], 0
	v_mfma_f32_16x16x32_bf16 v[40:43], v[150:153], v[202:205], 0
	v_mfma_f32_16x16x32_bf16 v[28:31], v[138:141], v[210:213], 0
	v_mfma_f32_16x16x32_bf16 v[24:27], v[150:153], v[210:213], 0
	v_mfma_f32_16x16x32_bf16 v[12:15], v[138:141], v[218:221], 0
	v_mfma_f32_16x16x32_bf16 v[8:11], v[150:153], v[218:221], 0
	v_mfma_f32_16x16x32_bf16 v[60:63], v[146:149], v[198:201], v[60:63]
	v_mfma_f32_16x16x32_bf16 v[56:59], v[154:157], v[198:201], v[56:59]
	v_mfma_f32_16x16x32_bf16 v[44:47], v[146:149], v[206:209], v[44:47]
	v_mfma_f32_16x16x32_bf16 v[40:43], v[154:157], v[206:209], v[40:43]
	v_mfma_f32_16x16x32_bf16 v[28:31], v[146:149], v[214:217], v[28:31]
	v_mfma_f32_16x16x32_bf16 v[24:27], v[154:157], v[214:217], v[24:27]
	v_mfma_f32_16x16x32_bf16 v[12:15], v[146:149], v[242:245], v[12:15]
	v_mfma_f32_16x16x32_bf16 v[8:11], v[154:157], v[242:245], v[8:11]
	s_setprio 0
	s_setprio 1
	v_mfma_f32_16x16x32_bf16 v[52:55], v[158:161], v[194:197], 0
	v_mfma_f32_16x16x32_bf16 v[48:51], v[186:189], v[194:197], 0
	v_mfma_f32_16x16x32_bf16 v[36:39], v[158:161], v[202:205], 0
	v_mfma_f32_16x16x32_bf16 v[32:35], v[186:189], v[202:205], 0
	v_mfma_f32_16x16x32_bf16 v[20:23], v[158:161], v[210:213], 0
	v_mfma_f32_16x16x32_bf16 v[16:19], v[186:189], v[210:213], 0
	v_mfma_f32_16x16x32_bf16 v[4:7], v[158:161], v[218:221], 0
	v_mfma_f32_16x16x32_bf16 v[0:3], v[186:189], v[218:221], 0
	v_mfma_f32_16x16x32_bf16 v[52:55], v[162:165], v[198:201], v[52:55]
	v_mfma_f32_16x16x32_bf16 v[48:51], v[190:193], v[198:201], v[48:51]
	v_mfma_f32_16x16x32_bf16 v[36:39], v[162:165], v[206:209], v[36:39]
	v_mfma_f32_16x16x32_bf16 v[32:35], v[190:193], v[206:209], v[32:35]
	v_mfma_f32_16x16x32_bf16 v[20:23], v[162:165], v[214:217], v[20:23]
	v_mfma_f32_16x16x32_bf16 v[16:19], v[190:193], v[214:217], v[16:19]
	v_mfma_f32_16x16x32_bf16 v[4:7], v[162:165], v[242:245], v[4:7]
	v_mfma_f32_16x16x32_bf16 v[0:3], v[190:193], v[242:245], v[0:3]
	s_setprio 0
	s_branch .Lzc5_1j

.LBB0_315:
	s_andn2_b64 vcc, exec, s[48:49]
	s_cbranch_vccnz .Lzc5_skip
	s_add_u32 s2, s2, 0x40080
	s_addc_u32 s3, s3, 0
	s_add_u32 s55, s20, 0x100
	s_addc_u32 s57, s21, 0
	s_mov_b32 s20, 0
	s_mov_b32 s32, 1
.LBB0_317:
	s_add_i32 s59, s20, 2
	s_add_u32 s21, s2, 0xfffc0080
	s_addc_u32 s22, s3, -1
	s_add_i32 s65, 0, 0x10000
	s_cmp_eq_u32 s74, s20
	s_cselect_b32 s23, s1, s22
	s_cselect_b32 s22, s0, s21
	s_cselect_b32 s21, s61, s57
	s_cselect_b32 s20, s60, s55
	s_add_i32 s67, 0, 0x14000
	v_add_u32_e32 v154, s65, v144
	v_add_u32_e32 v166, s67, v144
	ds_read_b128 v[138:141], v154
	ds_read_b128 v[146:149], v154 offset:1024
	ds_read_b128 v[150:153], v154 offset:2048
	ds_read_b128 v[154:157], v154 offset:3072
	ds_read_b128 v[158:161], v166
	ds_read_b128 v[162:165], v166 offset:1024
	s_waitcnt vmcnt(0)
	ds_read_b128 v[186:189], v166 offset:2048
	ds_read_b128 v[190:193], v166 offset:3072
	v_lshl_add_u64 v[166:167], s[2:3], 0, v[134:135]
	s_add_i32 m0, s42, 0xc000
	ds_read_b128 v[194:197], v145
	ds_read_b128 v[198:201], v145 offset:1024
	ds_read_b128 v[202:205], v145 offset:2048
	ds_read_b128 v[206:209], v145 offset:3072
	ds_read_b128 v[210:213], v145 offset:4096
	ds_read_b128 v[214:217], v145 offset:5120
	ds_read_b128 v[218:221], v145 offset:6144
	ds_read_b128 v[242:245], v145 offset:7168
	global_load_lds_dwordx4 v[166:167], off
	v_lshl_add_u64 v[166:167], s[2:3], 0, v[136:137]
	s_add_i32 m0, s42, 0xe000
	s_nop 0
	global_load_lds_dwordx4 v[166:167], off
	s_waitcnt vmcnt(8)
	s_waitcnt lgkmcnt(0)
	s_barrier
	s_cmp_lg_u32 s32, 0
	s_cbranch_scc1 .Lzc5_0
	s_setprio 1
	s_waitcnt lgkmcnt(0)
	v_mfma_f32_16x16x32_bf16 v[124:127], v[138:141], v[194:197], v[124:127]
	v_mfma_f32_16x16x32_bf16 v[120:123], v[150:153], v[194:197], v[120:123]
	v_mfma_f32_16x16x32_bf16 v[108:111], v[138:141], v[202:205], v[108:111]
	v_mfma_f32_16x16x32_bf16 v[104:107], v[150:153], v[202:205], v[104:107]
	v_mfma_f32_16x16x32_bf16 v[92:95], v[138:141], v[210:213], v[92:95]
	v_mfma_f32_16x16x32_bf16 v[88:91], v[150:153], v[210:213], v[88:91]
	v_mfma_f32_16x16x32_bf16 v[76:79], v[138:141], v[218:221], v[76:79]
	v_mfma_f32_16x16x32_bf16 v[72:75], v[150:153], v[218:221], v[72:75]
	v_mfma_f32_16x16x32_bf16 v[124:127], v[146:149], v[198:201], v[124:127]
	v_mfma_f32_16x16x32_bf16 v[120:123], v[154:157], v[198:201], v[120:123]
	v_mfma_f32_16x16x32_bf16 v[108:111], v[146:149], v[206:209], v[108:111]
	v_mfma_f32_16x16x32_bf16 v[104:107], v[154:157], v[206:209], v[104:107]
	v_mfma_f32_16x16x32_bf16 v[92:95], v[146:149], v[214:217], v[92:95]
	v_mfma_f32_16x16x32_bf16 v[88:91], v[154:157], v[214:217], v[88:91]
	v_mfma_f32_16x16x32_bf16 v[76:79], v[146:149], v[242:245], v[76:79]
	v_mfma_f32_16x16x32_bf16 v[72:75], v[154:157], v[242:245], v[72:75]
	s_setprio 0
	s_setprio 1
	v_mfma_f32_16x16x32_bf16 v[116:119], v[158:161], v[194:197], v[116:119]
	v_mfma_f32_16x16x32_bf16 v[112:115], v[186:189], v[194:197], v[112:115]
	v_mfma_f32_16x16x32_bf16 v[100:103], v[158:161], v[202:205], v[100:103]
	v_mfma_f32_16x16x32_bf16 v[96:99], v[186:189], v[202:205], v[96:99]
	v_mfma_f32_16x16x32_bf16 v[84:87], v[158:161], v[210:213], v[84:87]
	v_mfma_f32_16x16x32_bf16 v[80:83], v[186:189], v[210:213], v[80:83]
	v_mfma_f32_16x16x32_bf16 v[68:71], v[158:161], v[218:221], v[68:71]
	v_mfma_f32_16x16x32_bf16 v[64:67], v[186:189], v[218:221], v[64:67]
	v_mfma_f32_16x16x32_bf16 v[116:119], v[162:165], v[198:201], v[116:119]
	v_mfma_f32_16x16x32_bf16 v[112:115], v[190:193], v[198:201], v[112:115]
	v_mfma_f32_16x16x32_bf16 v[100:103], v[162:165], v[206:209], v[100:103]
	v_mfma_f32_16x16x32_bf16 v[96:99], v[190:193], v[206:209], v[96:99]
	v_mfma_f32_16x16x32_bf16 v[84:87], v[162:165], v[214:217], v[84:87]
	v_mfma_f32_16x16x32_bf16 v[80:83], v[190:193], v[214:217], v[80:83]
	v_mfma_f32_16x16x32_bf16 v[68:71], v[162:165], v[242:245], v[68:71]
	v_mfma_f32_16x16x32_bf16 v[64:67], v[190:193], v[242:245], v[64:67]
	s_setprio 0
.Lzc5_0j:
	s_barrier
	s_add_i32 s65, s65, s34
	v_lshl_add_u64 v[166:167], s[20:21], 0, v[168:169]
	s_mov_b32 m0, s65
	ds_read_b128 v[194:197], v145 offset:16384
	ds_read_b128 v[198:201], v145 offset:17408
	ds_read_b128 v[202:205], v145 offset:18432
	ds_read_b128 v[206:209], v145 offset:19456
	ds_read_b128 v[210:213], v145 offset:20480
	ds_read_b128 v[214:217], v145 offset:21504
	ds_read_b128 v[218:221], v145 offset:22528
	ds_read_b128 v[242:245], v145 offset:23552
	global_load_lds_dwordx4 v[166:167], off
	s_add_i32 m0, s65, 0x2000
	s_add_u32 vcc_lo, s20, 0x40000
	v_lshl_add_u64 v[222:223], s[20:21], 0, v[132:133]
	s_addc_u32 vcc_hi, s21, 0
	s_add_i32 s65, s67, s34
	global_load_lds_dwordx4 v[222:223], off
	v_lshl_add_u64 v[234:235], vcc, 0, v[168:169]
	s_mov_b32 m0, s65
	v_lshl_add_u64 v[236:237], s[22:23], 0, v[130:131]
	global_load_lds_dwordx4 v[234:235], off
	v_lshl_add_u64 v[234:235], vcc, 0, v[132:133]
	s_add_i32 m0, s65, 0x2000
	s_nop 0
	global_load_lds_dwordx4 v[234:235], off
	v_lshl_add_u64 v[234:235], s[22:23], 0, v[128:129]
	s_mov_b32 m0, s42
	s_nop 0
	global_load_lds_dwordx4 v[234:235], off
	s_mov_b32 m0, s43
	s_nop 0
	global_load_lds_dwordx4 v[236:237], off
	s_waitcnt vmcnt(8)
	s_waitcnt lgkmcnt(0)
	s_barrier
	s_cmp_lg_u32 s32, 0
	s_cbranch_scc1 .Lzc5_1
	s_setprio 1
	s_waitcnt lgkmcnt(0)
	v_mfma_f32_16x16x32_bf16 v[60:63], v[138:141], v[194:197], v[60:63]
	v_mfma_f32_16x16x32_bf16 v[56:59], v[150:153], v[194:197], v[56:59]
	v_mfma_f32_16x16x32_bf16 v[44:47], v[138:141], v[202:205], v[44:47]
	v_mfma_f32_16x16x32_bf16 v[40:43], v[150:153], v[202:205], v[40:43]
	v_mfma_f32_16x16x32_bf16 v[28:31], v[138:141], v[210:213], v[28:31]
	v_mfma_f32_16x16x32_bf16 v[24:27], v[150:153], v[210:213], v[24:27]
	v_mfma_f32_16x16x32_bf16 v[12:15], v[138:141], v[218:221], v[12:15]
	v_mfma_f32_16x16x32_bf16 v[8:11], v[150:153], v[218:221], v[8:11]
	v_mfma_f32_16x16x32_bf16 v[60:63], v[146:149], v[198:201], v[60:63]
	v_mfma_f32_16x16x32_bf16 v[56:59], v[154:157], v[198:201], v[56:59]
	v_mfma_f32_16x16x32_bf16 v[44:47], v[146:149], v[206:209], v[44:47]
	v_mfma_f32_16x16x32_bf16 v[40:43], v[154:157], v[206:209], v[40:43]
	v_mfma_f32_16x16x32_bf16 v[28:31], v[146:149], v[214:217], v[28:31]
	v_mfma_f32_16x16x32_bf16 v[24:27], v[154:157], v[214:217], v[24:27]
	v_mfma_f32_16x16x32_bf16 v[12:15], v[146:149], v[242:245], v[12:15]
	v_mfma_f32_16x16x32_bf16 v[8:11], v[154:157], v[242:245], v[8:11]
	s_setprio 0
	s_setprio 1
	v_mfma_f32_16x16x32_bf16 v[52:55], v[158:161], v[194:197], v[52:55]
	v_mfma_f32_16x16x32_bf16 v[48:51], v[186:189], v[194:197], v[48:51]
	v_mfma_f32_16x16x32_bf16 v[36:39], v[158:161], v[202:205], v[36:39]
	v_mfma_f32_16x16x32_bf16 v[32:35], v[186:189], v[202:205], v[32:35]
	v_mfma_f32_16x16x32_bf16 v[20:23], v[158:161], v[210:213], v[20:23]
	v_mfma_f32_16x16x32_bf16 v[16:19], v[186:189], v[210:213], v[16:19]
	v_mfma_f32_16x16x32_bf16 v[4:7], v[158:161], v[218:221], v[4:7]
	v_mfma_f32_16x16x32_bf16 v[0:3], v[186:189], v[218:221], v[0:3]
	v_mfma_f32_16x16x32_bf16 v[52:55], v[162:165], v[198:201], v[52:55]
	v_mfma_f32_16x16x32_bf16 v[48:51], v[190:193], v[198:201], v[48:51]
	v_mfma_f32_16x16x32_bf16 v[36:39], v[162:165], v[206:209], v[36:39]
	v_mfma_f32_16x16x32_bf16 v[32:35], v[190:193], v[206:209], v[32:35]
	v_mfma_f32_16x16x32_bf16 v[20:23], v[162:165], v[214:217], v[20:23]
	v_mfma_f32_16x16x32_bf16 v[16:19], v[190:193], v[214:217], v[16:19]
	v_mfma_f32_16x16x32_bf16 v[4:7], v[162:165], v[242:245], v[4:7]
	v_mfma_f32_16x16x32_bf16 v[0:3], v[190:193], v[242:245], v[0:3]
	s_setprio 0
.Lzc5_1j:
	s_barrier
	s_add_i32 s65, 0, 0x18000
	s_add_i32 s67, 0, 0x1c000
	v_add_u32_e32 v154, s65, v144
	v_add_u32_e32 v174, s67, v144
	ds_read_b128 v[138:141], v154
	ds_read_b128 v[146:149], v154 offset:1024
	ds_read_b128 v[150:153], v154 offset:2048
	ds_read_b128 v[154:157], v154 offset:3072
	ds_read_b128 v[158:161], v174
	ds_read_b128 v[162:165], v174 offset:1024
	ds_read_b128 v[186:189], v174 offset:2048
	ds_read_b128 v[190:193], v174 offset:3072
	s_add_u32 s22, s22, 0x40000
	s_addc_u32 s23, s23, 0
	s_mov_b32 m0, s46
	v_lshl_add_u64 v[246:247], s[22:23], 0, v[128:129]
	ds_read_b128 v[194:197], v145 offset:32768
	ds_read_b128 v[198:201], v145 offset:33792
	ds_read_b128 v[202:205], v145 offset:34816
	ds_read_b128 v[206:209], v145 offset:35840
	ds_read_b128 v[210:213], v145 offset:36864
	ds_read_b128 v[214:217], v145 offset:37888
	ds_read_b128 v[218:221], v145 offset:38912
	ds_read_b128 v[242:245], v145 offset:39936
	global_load_lds_dwordx4 v[246:247], off
	v_lshl_add_u64 v[246:247], s[22:23], 0, v[130:131]
	s_mov_b32 m0, s47
	s_nop 0
	global_load_lds_dwordx4 v[246:247], off
	s_waitcnt vmcnt(8)
	s_waitcnt lgkmcnt(0)
	s_barrier
	s_setprio 1
	s_waitcnt lgkmcnt(0)
	v_mfma_f32_16x16x32_bf16 v[124:127], v[138:141], v[194:197], v[124:127]
	v_mfma_f32_16x16x32_bf16 v[120:123], v[150:153], v[194:197], v[120:123]
	v_mfma_f32_16x16x32_bf16 v[108:111], v[138:141], v[202:205], v[108:111]
	v_mfma_f32_16x16x32_bf16 v[104:107], v[150:153], v[202:205], v[104:107]
	v_mfma_f32_16x16x32_bf16 v[92:95], v[138:141], v[210:213], v[92:95]
	v_mfma_f32_16x16x32_bf16 v[88:91], v[150:153], v[210:213], v[88:91]
	v_mfma_f32_16x16x32_bf16 v[76:79], v[138:141], v[218:221], v[76:79]
	v_mfma_f32_16x16x32_bf16 v[72:75], v[150:153], v[218:221], v[72:75]
	v_mfma_f32_16x16x32_bf16 v[124:127], v[146:149], v[198:201], v[124:127]
	v_mfma_f32_16x16x32_bf16 v[120:123], v[154:157], v[198:201], v[120:123]
	v_mfma_f32_16x16x32_bf16 v[108:111], v[146:149], v[206:209], v[108:111]
	v_mfma_f32_16x16x32_bf16 v[104:107], v[154:157], v[206:209], v[104:107]
	v_mfma_f32_16x16x32_bf16 v[92:95], v[146:149], v[214:217], v[92:95]
	v_mfma_f32_16x16x32_bf16 v[88:91], v[154:157], v[214:217], v[88:91]
	v_mfma_f32_16x16x32_bf16 v[76:79], v[146:149], v[242:245], v[76:79]
	v_mfma_f32_16x16x32_bf16 v[72:75], v[154:157], v[242:245], v[72:75]
	s_setprio 0
	s_setprio 1
	v_mfma_f32_16x16x32_bf16 v[116:119], v[158:161], v[194:197], v[116:119]
	v_mfma_f32_16x16x32_bf16 v[112:115], v[186:189], v[194:197], v[112:115]
	v_mfma_f32_16x16x32_bf16 v[100:103], v[158:161], v[202:205], v[100:103]
	v_mfma_f32_16x16x32_bf16 v[96:99], v[186:189], v[202:205], v[96:99]
	v_mfma_f32_16x16x32_bf16 v[84:87], v[158:161], v[210:213], v[84:87]
	v_mfma_f32_16x16x32_bf16 v[80:83], v[186:189], v[210:213], v[80:83]
	v_mfma_f32_16x16x32_bf16 v[68:71], v[158:161], v[218:221], v[68:71]
	v_mfma_f32_16x16x32_bf16 v[64:67], v[186:189], v[218:221], v[64:67]
	v_mfma_f32_16x16x32_bf16 v[116:119], v[162:165], v[198:201], v[116:119]
	v_mfma_f32_16x16x32_bf16 v[112:115], v[190:193], v[198:201], v[112:115]
	v_mfma_f32_16x16x32_bf16 v[100:103], v[162:165], v[206:209], v[100:103]
	v_mfma_f32_16x16x32_bf16 v[96:99], v[190:193], v[206:209], v[96:99]
	v_mfma_f32_16x16x32_bf16 v[84:87], v[162:165], v[214:217], v[84:87]
	v_mfma_f32_16x16x32_bf16 v[80:83], v[190:193], v[214:217], v[80:83]
	v_mfma_f32_16x16x32_bf16 v[68:71], v[162:165], v[242:245], v[68:71]
	v_mfma_f32_16x16x32_bf16 v[64:67], v[190:193], v[242:245], v[64:67]
	s_setprio 0
	s_barrier
	s_add_i32 s22, s65, s34
	v_lshl_add_u64 v[166:167], v[166:167], 0, s[28:29]
	s_mov_b32 m0, s22
	ds_read_b128 v[194:197], v145 offset:49152
	ds_read_b128 v[198:201], v145 offset:50176
	ds_read_b128 v[202:205], v145 offset:51200
	ds_read_b128 v[206:209], v145 offset:52224
	ds_read_b128 v[210:213], v145 offset:53248
	ds_read_b128 v[214:217], v145 offset:54272
	ds_read_b128 v[218:221], v145 offset:55296
	ds_read_b128 v[242:245], v145 offset:56320
	global_load_lds_dwordx4 v[166:167], off
	s_add_i32 m0, s22, 0x2000
	s_add_u32 s20, s20, 0x40080
	v_lshl_add_u64 v[166:167], v[222:223], 0, s[28:29]
	s_addc_u32 s21, s21, 0
	s_add_i32 s22, s67, s34
	global_load_lds_dwordx4 v[166:167], off
	v_lshl_add_u64 v[166:167], s[20:21], 0, v[168:169]
	s_mov_b32 m0, s22
	s_nop 0
	global_load_lds_dwordx4 v[166:167], off
	v_lshl_add_u64 v[166:167], s[20:21], 0, v[132:133]
	s_add_i32 m0, s22, 0x2000
	s_nop 0
	global_load_lds_dwordx4 v[166:167], off
	v_lshl_add_u64 v[166:167], v[234:235], 0, s[28:29]
	s_mov_b32 m0, s72
	s_nop 0
	global_load_lds_dwordx4 v[166:167], off
	v_lshl_add_u64 v[166:167], v[236:237], 0, s[28:29]
	s_mov_b32 m0, s73
	s_nop 0
	global_load_lds_dwordx4 v[166:167], off
	s_waitcnt vmcnt(8)
	s_waitcnt lgkmcnt(0)
	s_barrier
	s_setprio 1
	s_waitcnt lgkmcnt(0)
	v_mfma_f32_16x16x32_bf16 v[60:63], v[138:141], v[194:197], v[60:63]
	v_mfma_f32_16x16x32_bf16 v[56:59], v[150:153], v[194:197], v[56:59]
	v_mfma_f32_16x16x32_bf16 v[44:47], v[138:141], v[202:205], v[44:47]
	v_mfma_f32_16x16x32_bf16 v[40:43], v[150:153], v[202:205], v[40:43]
	v_mfma_f32_16x16x32_bf16 v[28:31], v[138:141], v[210:213], v[28:31]
	v_mfma_f32_16x16x32_bf16 v[24:27], v[150:153], v[210:213], v[24:27]
	v_mfma_f32_16x16x32_bf16 v[12:15], v[138:141], v[218:221], v[12:15]
	v_mfma_f32_16x16x32_bf16 v[8:11], v[150:153], v[218:221], v[8:11]
	v_mfma_f32_16x16x32_bf16 v[60:63], v[146:149], v[198:201], v[60:63]
	v_mfma_f32_16x16x32_bf16 v[56:59], v[154:157], v[198:201], v[56:59]
	v_mfma_f32_16x16x32_bf16 v[44:47], v[146:149], v[206:209], v[44:47]
	v_mfma_f32_16x16x32_bf16 v[40:43], v[154:157], v[206:209], v[40:43]
	v_mfma_f32_16x16x32_bf16 v[28:31], v[146:149], v[214:217], v[28:31]
	v_mfma_f32_16x16x32_bf16 v[24:27], v[154:157], v[214:217], v[24:27]
	v_mfma_f32_16x16x32_bf16 v[12:15], v[146:149], v[242:245], v[12:15]
	v_mfma_f32_16x16x32_bf16 v[8:11], v[154:157], v[242:245], v[8:11]
	s_setprio 0
	s_setprio 1
	v_mfma_f32_16x16x32_bf16 v[52:55], v[158:161], v[194:197], v[52:55]
	v_mfma_f32_16x16x32_bf16 v[48:51], v[186:189], v[194:197], v[48:51]
	v_mfma_f32_16x16x32_bf16 v[36:39], v[158:161], v[202:205], v[36:39]
	v_mfma_f32_16x16x32_bf16 v[32:35], v[186:189], v[202:205], v[32:35]
	v_mfma_f32_16x16x32_bf16 v[20:23], v[158:161], v[210:213], v[20:23]
	v_mfma_f32_16x16x32_bf16 v[16:19], v[186:189], v[210:213], v[16:19]
	v_mfma_f32_16x16x32_bf16 v[4:7], v[158:161], v[218:221], v[4:7]
	v_mfma_f32_16x16x32_bf16 v[0:3], v[186:189], v[218:221], v[0:3]
	v_mfma_f32_16x16x32_bf16 v[52:55], v[162:165], v[198:201], v[52:55]
	v_mfma_f32_16x16x32_bf16 v[48:51], v[190:193], v[198:201], v[48:51]
	v_mfma_f32_16x16x32_bf16 v[36:39], v[162:165], v[206:209], v[36:39]
	v_mfma_f32_16x16x32_bf16 v[32:35], v[190:193], v[206:209], v[32:35]
	v_mfma_f32_16x16x32_bf16 v[20:23], v[162:165], v[214:217], v[20:23]
	v_mfma_f32_16x16x32_bf16 v[16:19], v[190:193], v[214:217], v[16:19]
	v_mfma_f32_16x16x32_bf16 v[4:7], v[162:165], v[242:245], v[4:7]
	v_mfma_f32_16x16x32_bf16 v[0:3], v[190:193], v[242:245], v[0:3]
	s_setprio 0
	s_barrier
	s_add_u32 s2, s2, 0x100
	s_addc_u32 s3, s3, 0
	s_add_u32 s55, s55, 0x100
	s_addc_u32 s57, s57, 0
	s_cmp_ge_i32 s59, s69
	s_mov_b32 s20, s59
	s_mov_b32 s32, 0
	s_cbranch_scc0 .LBB0_317

.Lzc6_0:
	s_setprio 1
	s_waitcnt lgkmcnt(0)
	v_mfma_f32_16x16x32_bf16 v[156:159], v[72:75], v[160:163], 0
	v_mfma_f32_16x16x32_bf16 v[152:155], v[84:87], v[160:163], 0
	v_mfma_f32_16x16x32_bf16 v[140:143], v[72:75], v[196:199], 0
	v_mfma_f32_16x16x32_bf16 v[136:139], v[84:87], v[196:199], 0
	v_mfma_f32_16x16x32_bf16 v[124:127], v[72:75], v[204:207], 0
	v_mfma_f32_16x16x32_bf16 v[120:123], v[84:87], v[204:207], 0
	v_mfma_f32_16x16x32_bf16 v[92:95], v[72:75], v[218:221], 0
	v_mfma_f32_16x16x32_bf16 v[80:83], v[84:87], v[218:221], 0
	v_mfma_f32_16x16x32_bf16 v[156:159], v[76:79], v[164:167], v[156:159]
	v_mfma_f32_16x16x32_bf16 v[152:155], v[88:91], v[164:167], v[152:155]
	v_mfma_f32_16x16x32_bf16 v[140:143], v[76:79], v[200:203], v[140:143]
	v_mfma_f32_16x16x32_bf16 v[136:139], v[88:91], v[200:203], v[136:139]
	v_mfma_f32_16x16x32_bf16 v[124:127], v[76:79], v[214:217], v[124:127]
	v_mfma_f32_16x16x32_bf16 v[120:123], v[88:91], v[214:217], v[120:123]
	v_mfma_f32_16x16x32_bf16 v[92:95], v[76:79], v[242:245], v[92:95]
	v_mfma_f32_16x16x32_bf16 v[80:83], v[88:91], v[242:245], v[80:83]
	s_setprio 0
	s_setprio 1
	v_mfma_f32_16x16x32_bf16 v[148:151], v[96:99], v[160:163], 0
	v_mfma_f32_16x16x32_bf16 v[144:147], v[104:107], v[160:163], 0
	v_mfma_f32_16x16x32_bf16 v[132:135], v[96:99], v[196:199], 0
	v_mfma_f32_16x16x32_bf16 v[128:131], v[104:107], v[196:199], 0
	v_mfma_f32_16x16x32_bf16 v[116:119], v[96:99], v[204:207], 0
	v_mfma_f32_16x16x32_bf16 v[112:115], v[104:107], v[204:207], 0
	v_mfma_f32_16x16x32_bf16 v[68:71], v[96:99], v[218:221], 0
	v_mfma_f32_16x16x32_bf16 v[64:67], v[104:107], v[218:221], 0
	v_mfma_f32_16x16x32_bf16 v[148:151], v[100:103], v[164:167], v[148:151]
	v_mfma_f32_16x16x32_bf16 v[144:147], v[108:111], v[164:167], v[144:147]
	v_mfma_f32_16x16x32_bf16 v[132:135], v[100:103], v[200:203], v[132:135]
	v_mfma_f32_16x16x32_bf16 v[128:131], v[108:111], v[200:203], v[128:131]
	v_mfma_f32_16x16x32_bf16 v[116:119], v[100:103], v[214:217], v[116:119]
	v_mfma_f32_16x16x32_bf16 v[112:115], v[108:111], v[214:217], v[112:115]
	v_mfma_f32_16x16x32_bf16 v[68:71], v[100:103], v[242:245], v[68:71]
	v_mfma_f32_16x16x32_bf16 v[64:67], v[108:111], v[242:245], v[64:67]
	s_setprio 0
	s_branch .Lzc6_0j
.Lzc6_1:
	s_setprio 1
	s_waitcnt lgkmcnt(0)
	v_mfma_f32_16x16x32_bf16 v[60:63], v[72:75], v[160:163], 0
	v_mfma_f32_16x16x32_bf16 v[56:59], v[84:87], v[160:163], 0
	v_mfma_f32_16x16x32_bf16 v[44:47], v[72:75], v[196:199], 0
	v_mfma_f32_16x16x32_bf16 v[40:43], v[84:87], v[196:199], 0
	v_mfma_f32_16x16x32_bf16 v[28:31], v[72:75], v[204:207], 0
	v_mfma_f32_16x16x32_bf16 v[24:27], v[84:87], v[204:207], 0
	v_mfma_f32_16x16x32_bf16 v[12:15], v[72:75], v[218:221], 0
	v_mfma_f32_16x16x32_bf16 v[8:11], v[84:87], v[218:221], 0
	v_mfma_f32_16x16x32_bf16 v[60:63], v[76:79], v[164:167], v[60:63]
	v_mfma_f32_16x16x32_bf16 v[56:59], v[88:91], v[164:167], v[56:59]
	v_mfma_f32_16x16x32_bf16 v[44:47], v[76:79], v[200:203], v[44:47]
	v_mfma_f32_16x16x32_bf16 v[40:43], v[88:91], v[200:203], v[40:43]
	v_mfma_f32_16x16x32_bf16 v[28:31], v[76:79], v[214:217], v[28:31]
	v_mfma_f32_16x16x32_bf16 v[24:27], v[88:91], v[214:217], v[24:27]
	v_mfma_f32_16x16x32_bf16 v[12:15], v[76:79], v[242:245], v[12:15]
	v_mfma_f32_16x16x32_bf16 v[8:11], v[88:91], v[242:245], v[8:11]
	s_setprio 0
	s_setprio 1
	v_mfma_f32_16x16x32_bf16 v[52:55], v[96:99], v[160:163], 0
	v_mfma_f32_16x16x32_bf16 v[48:51], v[104:107], v[160:163], 0
	v_mfma_f32_16x16x32_bf16 v[36:39], v[96:99], v[196:199], 0
	v_mfma_f32_16x16x32_bf16 v[32:35], v[104:107], v[196:199], 0
	v_mfma_f32_16x16x32_bf16 v[20:23], v[96:99], v[204:207], 0
	v_mfma_f32_16x16x32_bf16 v[16:19], v[104:107], v[204:207], 0
	v_mfma_f32_16x16x32_bf16 v[4:7], v[96:99], v[218:221], 0
	v_mfma_f32_16x16x32_bf16 v[0:3], v[104:107], v[218:221], 0
	v_mfma_f32_16x16x32_bf16 v[52:55], v[100:103], v[164:167], v[52:55]
	v_mfma_f32_16x16x32_bf16 v[48:51], v[108:111], v[164:167], v[48:51]
	v_mfma_f32_16x16x32_bf16 v[36:39], v[100:103], v[200:203], v[36:39]
	v_mfma_f32_16x16x32_bf16 v[32:35], v[108:111], v[200:203], v[32:35]
	v_mfma_f32_16x16x32_bf16 v[20:23], v[100:103], v[214:217], v[20:23]
	v_mfma_f32_16x16x32_bf16 v[16:19], v[108:111], v[214:217], v[16:19]
	v_mfma_f32_16x16x32_bf16 v[4:7], v[100:103], v[242:245], v[4:7]
	v_mfma_f32_16x16x32_bf16 v[0:3], v[108:111], v[242:245], v[0:3]
	s_setprio 0
	s_branch .Lzc6_1j
.Lzc6_skip:
	v_mov_b32_e32 v0, 0
	v_mov_b32_e32 v1, 0
	v_mov_b32_e32 v2, 0
	v_mov_b32_e32 v3, 0
	v_mov_b32_e32 v4, 0
	v_mov_b32_e32 v5, 0
	v_mov_b32_e32 v6, 0
	v_mov_b32_e32 v7, 0
	v_mov_b32_e32 v8, 0
	v_mov_b32_e32 v9, 0
	v_mov_b32_e32 v10, 0
	v_mov_b32_e32 v11, 0
	v_mov_b32_e32 v12, 0
	v_mov_b32_e32 v13, 0
	v_mov_b32_e32 v14, 0
	v_mov_b32_e32 v15, 0
	v_mov_b32_e32 v16, 0
	v_mov_b32_e32 v17, 0
	v_mov_b32_e32 v18, 0
	v_mov_b32_e32 v19, 0
	v_mov_b32_e32 v20, 0
	v_mov_b32_e32 v21, 0
	v_mov_b32_e32 v22, 0
	v_mov_b32_e32 v23, 0
	v_mov_b32_e32 v24, 0
	v_mov_b32_e32 v25, 0
	v_mov_b32_e32 v26, 0
	v_mov_b32_e32 v27, 0
	v_mov_b32_e32 v28, 0
	v_mov_b32_e32 v29, 0
	v_mov_b32_e32 v30, 0
	v_mov_b32_e32 v31, 0
	v_mov_b32_e32 v32, 0
	v_mov_b32_e32 v33, 0
	v_mov_b32_e32 v34, 0
	v_mov_b32_e32 v35, 0
	v_mov_b32_e32 v36, 0
	v_mov_b32_e32 v37, 0
	v_mov_b32_e32 v38, 0
	v_mov_b32_e32 v39, 0
	v_mov_b32_e32 v40, 0
	v_mov_b32_e32 v41, 0
	v_mov_b32_e32 v42, 0
	v_mov_b32_e32 v43, 0
	v_mov_b32_e32 v44, 0
	v_mov_b32_e32 v45, 0
	v_mov_b32_e32 v46, 0
	v_mov_b32_e32 v47, 0
	v_mov_b32_e32 v48, 0
	v_mov_b32_e32 v49, 0
	v_mov_b32_e32 v50, 0
	v_mov_b32_e32 v51, 0
	v_mov_b32_e32 v52, 0
	v_mov_b32_e32 v53, 0
	v_mov_b32_e32 v54, 0
	v_mov_b32_e32 v55, 0
	v_mov_b32_e32 v56, 0
	v_mov_b32_e32 v57, 0
	v_mov_b32_e32 v58, 0
	v_mov_b32_e32 v59, 0
	v_mov_b32_e32 v60, 0
	v_mov_b32_e32 v61, 0
	v_mov_b32_e32 v62, 0
	v_mov_b32_e32 v63, 0
	v_mov_b32_e32 v64, 0
	v_mov_b32_e32 v65, 0
	v_mov_b32_e32 v66, 0
	v_mov_b32_e32 v67, 0
	v_mov_b32_e32 v68, 0
	v_mov_b32_e32 v69, 0
	v_mov_b32_e32 v70, 0
	v_mov_b32_e32 v71, 0
	v_mov_b32_e32 v80, 0
	v_mov_b32_e32 v81, 0
	v_mov_b32_e32 v82, 0
	v_mov_b32_e32 v83, 0
	v_mov_b32_e32 v92, 0
	v_mov_b32_e32 v93, 0
	v_mov_b32_e32 v94, 0
	v_mov_b32_e32 v95, 0
	v_mov_b32_e32 v112, 0
	v_mov_b32_e32 v113, 0
	v_mov_b32_e32 v114, 0
	v_mov_b32_e32 v115, 0
	v_mov_b32_e32 v116, 0
	v_mov_b32_e32 v117, 0
	v_mov_b32_e32 v118, 0
	v_mov_b32_e32 v119, 0
	v_mov_b32_e32 v120, 0
	v_mov_b32_e32 v121, 0
	v_mov_b32_e32 v122, 0
	v_mov_b32_e32 v123, 0
	v_mov_b32_e32 v124, 0
	v_mov_b32_e32 v125, 0
	v_mov_b32_e32 v126, 0
	v_mov_b32_e32 v127, 0
	v_mov_b32_e32 v128, 0
	v_mov_b32_e32 v129, 0
	v_mov_b32_e32 v130, 0
	v_mov_b32_e32 v131, 0
	v_mov_b32_e32 v132, 0
	v_mov_b32_e32 v133, 0
	v_mov_b32_e32 v134, 0
	v_mov_b32_e32 v135, 0
	v_mov_b32_e32 v136, 0
	v_mov_b32_e32 v137, 0
	v_mov_b32_e32 v138, 0
	v_mov_b32_e32 v139, 0
	v_mov_b32_e32 v140, 0
	v_mov_b32_e32 v141, 0
	v_mov_b32_e32 v142, 0
	v_mov_b32_e32 v143, 0
	v_mov_b32_e32 v144, 0
	v_mov_b32_e32 v145, 0
	v_mov_b32_e32 v146, 0
	v_mov_b32_e32 v147, 0
	v_mov_b32_e32 v148, 0
	v_mov_b32_e32 v149, 0
	v_mov_b32_e32 v150, 0
	v_mov_b32_e32 v151, 0
	v_mov_b32_e32 v152, 0
	v_mov_b32_e32 v153, 0
	v_mov_b32_e32 v154, 0
	v_mov_b32_e32 v155, 0
	v_mov_b32_e32 v156, 0
	v_mov_b32_e32 v157, 0
	v_mov_b32_e32 v158, 0
	v_mov_b32_e32 v159, 0
	s_branch .LBB0_379

.LBB0_376:
	s_ashr_i32 s63, s62, 31
	s_lshl_b64 s[26:27], s[62:63], 19
	v_readlane_b32 s40, v254, 43
	v_readlane_b32 s41, v254, 44
	s_add_u32 s66, s40, s26
	s_addc_u32 s67, s41, s27
	s_ashr_i32 s65, s64, 31
	s_lshl_b64 s[26:27], s[64:65], 19
	s_add_u32 s68, s34, s26
	s_addc_u32 s69, s42, s27
	s_andn2_b64 vcc, exec, s[58:59]
	s_cbranch_vccnz .Lzc6_skip
	s_and_b64 s[26:27], s[38:39], exec
	s_cselect_b32 s1, s67, s21
	s_cselect_b32 s40, s66, s20
	s_cselect_b32 s41, s69, s23
	s_cselect_b32 s44, s68, s22
	s_add_u32 s20, s20, 0x40080
	s_addc_u32 s21, s21, 0
	s_add_u32 s45, s22, 0x100
	s_addc_u32 s63, s23, 0
	s_mov_b32 s22, 0
	s_mov_b32 s32, 1
.LBB0_378:
	s_add_i32 s65, s22, 2
	s_add_u32 s23, s20, 0xfffc0080
	s_addc_u32 s26, s21, -1
	s_add_i32 s79, 0, 0x10000
	s_cmp_eq_u32 s76, s22
	s_cselect_b32 s27, s1, s26
	s_cselect_b32 s26, s40, s23
	s_cselect_b32 s23, s41, s63
	s_cselect_b32 s22, s44, s45
	s_add_i32 s48, 0, 0x14000
	v_add_u32_e32 v88, s79, v211
	v_add_u32_e32 v108, s48, v211
	ds_read_b128 v[72:75], v88
	ds_read_b128 v[76:79], v88 offset:1024
	ds_read_b128 v[84:87], v88 offset:2048
	ds_read_b128 v[88:91], v88 offset:3072
	ds_read_b128 v[96:99], v108
	ds_read_b128 v[100:103], v108 offset:1024
	ds_read_b128 v[104:107], v108 offset:2048
	ds_read_b128 v[108:111], v108 offset:3072
	v_lshl_add_u64 v[208:209], s[20:21], 0, v[192:193]
	s_add_i32 m0, s3, 0xc000
	ds_read_b128 v[160:163], v212
	ds_read_b128 v[164:167], v212 offset:1024
	ds_read_b128 v[196:199], v212 offset:2048
	ds_read_b128 v[200:203], v212 offset:3072
	ds_read_b128 v[204:207], v212 offset:4096
	ds_read_b128 v[214:217], v212 offset:5120
	ds_read_b128 v[218:221], v212 offset:6144
	ds_read_b128 v[242:245], v212 offset:7168
	global_load_lds_dwordx4 v[208:209], off
	v_lshl_add_u64 v[208:209], s[20:21], 0, v[194:195]
	s_add_i32 m0, s3, 0xe000
	s_nop 0
	global_load_lds_dwordx4 v[208:209], off
	s_waitcnt vmcnt(8)
	s_waitcnt lgkmcnt(0)
	s_barrier
	s_cmp_lg_u32 s32, 0
	s_cbranch_scc1 .Lzc6_0
	s_setprio 1
	s_waitcnt lgkmcnt(0)
	v_mfma_f32_16x16x32_bf16 v[156:159], v[72:75], v[160:163], v[156:159]
	v_mfma_f32_16x16x32_bf16 v[152:155], v[84:87], v[160:163], v[152:155]
	v_mfma_f32_16x16x32_bf16 v[140:143], v[72:75], v[196:199], v[140:143]
	v_mfma_f32_16x16x32_bf16 v[136:139], v[84:87], v[196:199], v[136:139]
	v_mfma_f32_16x16x32_bf16 v[124:127], v[72:75], v[204:207], v[124:127]
	v_mfma_f32_16x16x32_bf16 v[120:123], v[84:87], v[204:207], v[120:123]
	v_mfma_f32_16x16x32_bf16 v[92:95], v[72:75], v[218:221], v[92:95]
	v_mfma_f32_16x16x32_bf16 v[80:83], v[84:87], v[218:221], v[80:83]
	v_mfma_f32_16x16x32_bf16 v[156:159], v[76:79], v[164:167], v[156:159]
	v_mfma_f32_16x16x32_bf16 v[152:155], v[88:91], v[164:167], v[152:155]
	v_mfma_f32_16x16x32_bf16 v[140:143], v[76:79], v[200:203], v[140:143]
	v_mfma_f32_16x16x32_bf16 v[136:139], v[88:91], v[200:203], v[136:139]
	v_mfma_f32_16x16x32_bf16 v[124:127], v[76:79], v[214:217], v[124:127]
	v_mfma_f32_16x16x32_bf16 v[120:123], v[88:91], v[214:217], v[120:123]
	v_mfma_f32_16x16x32_bf16 v[92:95], v[76:79], v[242:245], v[92:95]
	v_mfma_f32_16x16x32_bf16 v[80:83], v[88:91], v[242:245], v[80:83]
	s_setprio 0
	s_setprio 1
	v_mfma_f32_16x16x32_bf16 v[148:151], v[96:99], v[160:163], v[148:151]
	v_mfma_f32_16x16x32_bf16 v[144:147], v[104:107], v[160:163], v[144:147]
	v_mfma_f32_16x16x32_bf16 v[132:135], v[96:99], v[196:199], v[132:135]
	v_mfma_f32_16x16x32_bf16 v[128:131], v[104:107], v[196:199], v[128:131]
	v_mfma_f32_16x16x32_bf16 v[116:119], v[96:99], v[204:207], v[116:119]
	v_mfma_f32_16x16x32_bf16 v[112:115], v[104:107], v[204:207], v[112:115]
	v_mfma_f32_16x16x32_bf16 v[68:71], v[96:99], v[218:221], v[68:71]
	v_mfma_f32_16x16x32_bf16 v[64:67], v[104:107], v[218:221], v[64:67]
	v_mfma_f32_16x16x32_bf16 v[148:151], v[100:103], v[164:167], v[148:151]
	v_mfma_f32_16x16x32_bf16 v[144:147], v[108:111], v[164:167], v[144:147]
	v_mfma_f32_16x16x32_bf16 v[132:135], v[100:103], v[200:203], v[132:135]
	v_mfma_f32_16x16x32_bf16 v[128:131], v[108:111], v[200:203], v[128:131]
	v_mfma_f32_16x16x32_bf16 v[116:119], v[100:103], v[214:217], v[116:119]
	v_mfma_f32_16x16x32_bf16 v[112:115], v[108:111], v[214:217], v[112:115]
	v_mfma_f32_16x16x32_bf16 v[68:71], v[100:103], v[242:245], v[68:71]
	v_mfma_f32_16x16x32_bf16 v[64:67], v[108:111], v[242:245], v[64:67]
	s_setprio 0
.Lzc6_0j:
	s_barrier
	s_add_i32 s49, s79, s43
	v_lshl_add_u64 v[208:209], s[22:23], 0, v[168:169]
	s_mov_b32 m0, s49
	ds_read_b128 v[160:163], v212 offset:16384
	ds_read_b128 v[164:167], v212 offset:17408
	ds_read_b128 v[196:199], v212 offset:18432
	ds_read_b128 v[200:203], v212 offset:19456
	ds_read_b128 v[204:207], v212 offset:20480
	ds_read_b128 v[214:217], v212 offset:21504
	ds_read_b128 v[218:221], v212 offset:22528
	ds_read_b128 v[242:245], v212 offset:23552
	global_load_lds_dwordx4 v[208:209], off
	s_add_i32 m0, s49, 0x2000
	s_add_u32 vcc_lo, s22, 0x40000
	v_lshl_add_u64 v[222:223], s[22:23], 0, v[190:191]
	s_addc_u32 vcc_hi, s23, 0
	s_add_i32 s48, s48, s43
	global_load_lds_dwordx4 v[222:223], off
	v_lshl_add_u64 v[234:235], vcc, 0, v[168:169]
	s_mov_b32 m0, s48
	v_lshl_add_u64 v[236:237], s[26:27], 0, v[188:189]
	global_load_lds_dwordx4 v[234:235], off
	v_lshl_add_u64 v[234:235], vcc, 0, v[190:191]
	s_add_i32 m0, s48, 0x2000
	s_nop 0
	global_load_lds_dwordx4 v[234:235], off
	v_lshl_add_u64 v[234:235], s[26:27], 0, v[186:187]
	s_mov_b32 m0, s3
	s_nop 0
	global_load_lds_dwordx4 v[234:235], off
	s_mov_b32 m0, s46
	s_nop 0
	global_load_lds_dwordx4 v[236:237], off
	s_waitcnt vmcnt(8)
	s_waitcnt lgkmcnt(0)
	s_barrier
	s_cmp_lg_u32 s32, 0
	s_cbranch_scc1 .Lzc6_1
	s_setprio 1
	s_waitcnt lgkmcnt(0)
	v_mfma_f32_16x16x32_bf16 v[60:63], v[72:75], v[160:163], v[60:63]
	v_mfma_f32_16x16x32_bf16 v[56:59], v[84:87], v[160:163], v[56:59]
	v_mfma_f32_16x16x32_bf16 v[44:47], v[72:75], v[196:199], v[44:47]
	v_mfma_f32_16x16x32_bf16 v[40:43], v[84:87], v[196:199], v[40:43]
	v_mfma_f32_16x16x32_bf16 v[28:31], v[72:75], v[204:207], v[28:31]
	v_mfma_f32_16x16x32_bf16 v[24:27], v[84:87], v[204:207], v[24:27]
	v_mfma_f32_16x16x32_bf16 v[12:15], v[72:75], v[218:221], v[12:15]
	v_mfma_f32_16x16x32_bf16 v[8:11], v[84:87], v[218:221], v[8:11]
	v_mfma_f32_16x16x32_bf16 v[60:63], v[76:79], v[164:167], v[60:63]
	v_mfma_f32_16x16x32_bf16 v[56:59], v[88:91], v[164:167], v[56:59]
	v_mfma_f32_16x16x32_bf16 v[44:47], v[76:79], v[200:203], v[44:47]
	v_mfma_f32_16x16x32_bf16 v[40:43], v[88:91], v[200:203], v[40:43]
	v_mfma_f32_16x16x32_bf16 v[28:31], v[76:79], v[214:217], v[28:31]
	v_mfma_f32_16x16x32_bf16 v[24:27], v[88:91], v[214:217], v[24:27]
	v_mfma_f32_16x16x32_bf16 v[12:15], v[76:79], v[242:245], v[12:15]
	v_mfma_f32_16x16x32_bf16 v[8:11], v[88:91], v[242:245], v[8:11]
	s_setprio 0
	s_setprio 1
	v_mfma_f32_16x16x32_bf16 v[52:55], v[96:99], v[160:163], v[52:55]
	v_mfma_f32_16x16x32_bf16 v[48:51], v[104:107], v[160:163], v[48:51]
	v_mfma_f32_16x16x32_bf16 v[36:39], v[96:99], v[196:199], v[36:39]
	v_mfma_f32_16x16x32_bf16 v[32:35], v[104:107], v[196:199], v[32:35]
	v_mfma_f32_16x16x32_bf16 v[20:23], v[96:99], v[204:207], v[20:23]
	v_mfma_f32_16x16x32_bf16 v[16:19], v[104:107], v[204:207], v[16:19]
	v_mfma_f32_16x16x32_bf16 v[4:7], v[96:99], v[218:221], v[4:7]
	v_mfma_f32_16x16x32_bf16 v[0:3], v[104:107], v[218:221], v[0:3]
	v_mfma_f32_16x16x32_bf16 v[52:55], v[100:103], v[164:167], v[52:55]
	v_mfma_f32_16x16x32_bf16 v[48:51], v[108:111], v[164:167], v[48:51]
	v_mfma_f32_16x16x32_bf16 v[36:39], v[100:103], v[200:203], v[36:39]
	v_mfma_f32_16x16x32_bf16 v[32:35], v[108:111], v[200:203], v[32:35]
	v_mfma_f32_16x16x32_bf16 v[20:23], v[100:103], v[214:217], v[20:23]
	v_mfma_f32_16x16x32_bf16 v[16:19], v[108:111], v[214:217], v[16:19]
	v_mfma_f32_16x16x32_bf16 v[4:7], v[100:103], v[242:245], v[4:7]
	v_mfma_f32_16x16x32_bf16 v[0:3], v[108:111], v[242:245], v[0:3]
	s_setprio 0
.Lzc6_1j:
	s_barrier
	s_add_i32 s48, 0, 0x18000
	s_add_i32 s49, 0, 0x1c000
	v_add_u32_e32 v88, s48, v211
	v_add_u32_e32 v108, s49, v211
	ds_read_b128 v[72:75], v88
	ds_read_b128 v[76:79], v88 offset:1024
	ds_read_b128 v[84:87], v88 offset:2048
	ds_read_b128 v[88:91], v88 offset:3072
	ds_read_b128 v[96:99], v108
	ds_read_b128 v[100:103], v108 offset:1024
	ds_read_b128 v[104:107], v108 offset:2048
	ds_read_b128 v[108:111], v108 offset:3072
	s_add_u32 s26, s26, 0x40000
	s_addc_u32 s27, s27, 0
	s_mov_b32 m0, s47
	v_lshl_add_u64 v[246:247], s[26:27], 0, v[186:187]
	ds_read_b128 v[160:163], v212 offset:32768
	ds_read_b128 v[164:167], v212 offset:33792
	ds_read_b128 v[196:199], v212 offset:34816
	ds_read_b128 v[200:203], v212 offset:35840
	ds_read_b128 v[204:207], v212 offset:36864
	ds_read_b128 v[214:217], v212 offset:37888
	ds_read_b128 v[218:221], v212 offset:38912
	ds_read_b128 v[242:245], v212 offset:39936
	global_load_lds_dwordx4 v[246:247], off
	v_lshl_add_u64 v[246:247], s[26:27], 0, v[188:189]
	s_mov_b32 m0, s70
	s_nop 0
	global_load_lds_dwordx4 v[246:247], off
	s_waitcnt vmcnt(8)
	s_waitcnt lgkmcnt(0)
	s_barrier
	s_setprio 1
	s_waitcnt lgkmcnt(0)
	v_mfma_f32_16x16x32_bf16 v[156:159], v[72:75], v[160:163], v[156:159]
	v_mfma_f32_16x16x32_bf16 v[152:155], v[84:87], v[160:163], v[152:155]
	v_mfma_f32_16x16x32_bf16 v[140:143], v[72:75], v[196:199], v[140:143]
	v_mfma_f32_16x16x32_bf16 v[136:139], v[84:87], v[196:199], v[136:139]
	v_mfma_f32_16x16x32_bf16 v[124:127], v[72:75], v[204:207], v[124:127]
	v_mfma_f32_16x16x32_bf16 v[120:123], v[84:87], v[204:207], v[120:123]
	v_mfma_f32_16x16x32_bf16 v[92:95], v[72:75], v[218:221], v[92:95]
	v_mfma_f32_16x16x32_bf16 v[80:83], v[84:87], v[218:221], v[80:83]
	v_mfma_f32_16x16x32_bf16 v[156:159], v[76:79], v[164:167], v[156:159]
	v_mfma_f32_16x16x32_bf16 v[152:155], v[88:91], v[164:167], v[152:155]
	v_mfma_f32_16x16x32_bf16 v[140:143], v[76:79], v[200:203], v[140:143]
	v_mfma_f32_16x16x32_bf16 v[136:139], v[88:91], v[200:203], v[136:139]
	v_mfma_f32_16x16x32_bf16 v[124:127], v[76:79], v[214:217], v[124:127]
	v_mfma_f32_16x16x32_bf16 v[120:123], v[88:91], v[214:217], v[120:123]
	v_mfma_f32_16x16x32_bf16 v[92:95], v[76:79], v[242:245], v[92:95]
	v_mfma_f32_16x16x32_bf16 v[80:83], v[88:91], v[242:245], v[80:83]
	s_setprio 0
	s_setprio 1
	v_mfma_f32_16x16x32_bf16 v[148:151], v[96:99], v[160:163], v[148:151]
	v_mfma_f32_16x16x32_bf16 v[144:147], v[104:107], v[160:163], v[144:147]
	v_mfma_f32_16x16x32_bf16 v[132:135], v[96:99], v[196:199], v[132:135]
	v_mfma_f32_16x16x32_bf16 v[128:131], v[104:107], v[196:199], v[128:131]
	v_mfma_f32_16x16x32_bf16 v[116:119], v[96:99], v[204:207], v[116:119]
	v_mfma_f32_16x16x32_bf16 v[112:115], v[104:107], v[204:207], v[112:115]
	v_mfma_f32_16x16x32_bf16 v[68:71], v[96:99], v[218:221], v[68:71]
	v_mfma_f32_16x16x32_bf16 v[64:67], v[104:107], v[218:221], v[64:67]
	v_mfma_f32_16x16x32_bf16 v[148:151], v[100:103], v[164:167], v[148:151]
	v_mfma_f32_16x16x32_bf16 v[144:147], v[108:111], v[164:167], v[144:147]
	v_mfma_f32_16x16x32_bf16 v[132:135], v[100:103], v[200:203], v[132:135]
	v_mfma_f32_16x16x32_bf16 v[128:131], v[108:111], v[200:203], v[128:131]
	v_mfma_f32_16x16x32_bf16 v[116:119], v[100:103], v[214:217], v[116:119]
	v_mfma_f32_16x16x32_bf16 v[112:115], v[108:111], v[214:217], v[112:115]
	v_mfma_f32_16x16x32_bf16 v[68:71], v[100:103], v[242:245], v[68:71]
	v_mfma_f32_16x16x32_bf16 v[64:67], v[108:111], v[242:245], v[64:67]
	s_setprio 0
	s_barrier
	s_add_i32 s26, s48, s43
	v_lshl_add_u64 v[208:209], v[208:209], 0, s[28:29]
	s_mov_b32 m0, s26
	ds_read_b128 v[160:163], v212 offset:49152
	ds_read_b128 v[164:167], v212 offset:50176
	ds_read_b128 v[196:199], v212 offset:51200
	ds_read_b128 v[200:203], v212 offset:52224
	ds_read_b128 v[204:207], v212 offset:53248
	ds_read_b128 v[214:217], v212 offset:54272
	ds_read_b128 v[218:221], v212 offset:55296
	ds_read_b128 v[242:245], v212 offset:56320
	global_load_lds_dwordx4 v[208:209], off
	s_add_i32 m0, s26, 0x2000
	s_add_u32 s22, s22, 0x40080
	v_lshl_add_u64 v[208:209], v[222:223], 0, s[28:29]
	s_addc_u32 s23, s23, 0
	s_add_i32 s26, s49, s43
	global_load_lds_dwordx4 v[208:209], off
	v_lshl_add_u64 v[208:209], s[22:23], 0, v[168:169]
	s_mov_b32 m0, s26
	s_nop 0
	global_load_lds_dwordx4 v[208:209], off
	v_lshl_add_u64 v[208:209], s[22:23], 0, v[190:191]
	s_add_i32 m0, s26, 0x2000
	s_nop 0
	global_load_lds_dwordx4 v[208:209], off
	v_lshl_add_u64 v[208:209], v[234:235], 0, s[28:29]
	s_mov_b32 m0, s74
	s_nop 0
	global_load_lds_dwordx4 v[208:209], off
	v_lshl_add_u64 v[208:209], v[236:237], 0, s[28:29]
	s_mov_b32 m0, s75
	s_nop 0
	global_load_lds_dwordx4 v[208:209], off
	s_waitcnt vmcnt(8)
	s_waitcnt lgkmcnt(0)
	s_barrier
	s_setprio 1
	s_waitcnt lgkmcnt(0)
	v_mfma_f32_16x16x32_bf16 v[60:63], v[72:75], v[160:163], v[60:63]
	v_mfma_f32_16x16x32_bf16 v[56:59], v[84:87], v[160:163], v[56:59]
	v_mfma_f32_16x16x32_bf16 v[44:47], v[72:75], v[196:199], v[44:47]
	v_mfma_f32_16x16x32_bf16 v[40:43], v[84:87], v[196:199], v[40:43]
	v_mfma_f32_16x16x32_bf16 v[28:31], v[72:75], v[204:207], v[28:31]
	v_mfma_f32_16x16x32_bf16 v[24:27], v[84:87], v[204:207], v[24:27]
	v_mfma_f32_16x16x32_bf16 v[12:15], v[72:75], v[218:221], v[12:15]
	v_mfma_f32_16x16x32_bf16 v[8:11], v[84:87], v[218:221], v[8:11]
	v_mfma_f32_16x16x32_bf16 v[60:63], v[76:79], v[164:167], v[60:63]
	v_mfma_f32_16x16x32_bf16 v[56:59], v[88:91], v[164:167], v[56:59]
	v_mfma_f32_16x16x32_bf16 v[44:47], v[76:79], v[200:203], v[44:47]
	v_mfma_f32_16x16x32_bf16 v[40:43], v[88:91], v[200:203], v[40:43]
	v_mfma_f32_16x16x32_bf16 v[28:31], v[76:79], v[214:217], v[28:31]
	v_mfma_f32_16x16x32_bf16 v[24:27], v[88:91], v[214:217], v[24:27]
	v_mfma_f32_16x16x32_bf16 v[12:15], v[76:79], v[242:245], v[12:15]
	v_mfma_f32_16x16x32_bf16 v[8:11], v[88:91], v[242:245], v[8:11]
	s_setprio 0
	s_setprio 1
	v_mfma_f32_16x16x32_bf16 v[52:55], v[96:99], v[160:163], v[52:55]
	v_mfma_f32_16x16x32_bf16 v[48:51], v[104:107], v[160:163], v[48:51]
	v_mfma_f32_16x16x32_bf16 v[36:39], v[96:99], v[196:199], v[36:39]
	v_mfma_f32_16x16x32_bf16 v[32:35], v[104:107], v[196:199], v[32:35]
	v_mfma_f32_16x16x32_bf16 v[20:23], v[96:99], v[204:207], v[20:23]
	v_mfma_f32_16x16x32_bf16 v[16:19], v[104:107], v[204:207], v[16:19]
	v_mfma_f32_16x16x32_bf16 v[4:7], v[96:99], v[218:221], v[4:7]
	v_mfma_f32_16x16x32_bf16 v[0:3], v[104:107], v[218:221], v[0:3]
	v_mfma_f32_16x16x32_bf16 v[52:55], v[100:103], v[164:167], v[52:55]
	v_mfma_f32_16x16x32_bf16 v[48:51], v[108:111], v[164:167], v[48:51]
	v_mfma_f32_16x16x32_bf16 v[36:39], v[100:103], v[200:203], v[36:39]
	v_mfma_f32_16x16x32_bf16 v[32:35], v[108:111], v[200:203], v[32:35]
	v_mfma_f32_16x16x32_bf16 v[20:23], v[100:103], v[214:217], v[20:23]
	v_mfma_f32_16x16x32_bf16 v[16:19], v[108:111], v[214:217], v[16:19]
	v_mfma_f32_16x16x32_bf16 v[4:7], v[100:103], v[242:245], v[4:7]
	v_mfma_f32_16x16x32_bf16 v[0:3], v[108:111], v[242:245], v[0:3]
	s_setprio 0
	s_barrier
	s_add_u32 s20, s20, 0x100
	s_addc_u32 s21, s21, 0
	s_add_u32 s45, s45, 0x100
	s_addc_u32 s63, s63, 0
	s_cmp_ge_i32 s65, s71
	s_mov_b32 s22, s65
	s_mov_b32 s32, 0
	s_cbranch_scc0 .LBB0_378

.LBB0_442:
	s_ashr_i32 s51, s50, 31
	s_lshl_b64 s[20:21], s[50:51], 19
	v_readlane_b32 s42, v254, 57
	v_readlane_b32 s43, v254, 58
	s_add_u32 s54, s42, s20
	s_addc_u32 s55, s43, s21
	s_ashr_i32 s53, s52, 31
	s_lshl_b64 s[20:21], s[52:53], 19
	s_add_u32 s56, s34, s20
	s_addc_u32 s57, s60, s21
	s_andn2_b64 vcc, exec, s[46:47]
	s_waitcnt lgkmcnt(0)
	s_cbranch_vccnz .Lzc7_skip
	s_and_b64 s[20:21], s[38:39], exec
	s_cselect_b32 s41, s55, s1
	s_cselect_b32 s42, s54, s0
	s_cselect_b32 s43, s57, s3
	s_cselect_b32 s51, s56, s2
	s_add_u32 s0, s0, 0x40080
	s_addc_u32 s1, s1, 0
	s_add_u32 s53, s2, 0x100
	s_addc_u32 s58, s3, 0
	s_mov_b32 s2, 0
	s_mov_b32 s32, 1
.LBB0_444:
	s_add_i32 s59, s2, 2
	s_add_u32 s3, s0, 0xfffc0080
	s_addc_u32 s20, s1, -1
	s_add_i32 s74, 0, 0x10000
	s_cmp_eq_u32 s68, s2
	s_cselect_b32 s21, s41, s20
	s_cselect_b32 s20, s42, s3
	s_cselect_b32 s3, s43, s58
	s_cselect_b32 s2, s51, s53
	s_add_i32 s76, 0, 0x14000
	v_add_u32_e32 v146, s74, v219
	v_add_u32_e32 v162, s76, v219
	ds_read_b128 v[128:131], v146
	ds_read_b128 v[132:135], v146 offset:1024
	ds_read_b128 v[142:145], v146 offset:2048
	ds_read_b128 v[146:149], v146 offset:3072
	ds_read_b128 v[150:153], v162
	ds_read_b128 v[154:157], v162 offset:1024
	ds_read_b128 v[158:161], v162 offset:2048
	ds_read_b128 v[162:165], v162 offset:3072
	v_lshl_add_u64 v[166:167], s[0:1], 0, v[138:139]
	s_add_i32 m0, s23, 0xc000
	ds_read_b128 v[186:189], v220
	ds_read_b128 v[190:193], v220 offset:1024
	ds_read_b128 v[194:197], v220 offset:2048
	ds_read_b128 v[198:201], v220 offset:3072
	ds_read_b128 v[202:205], v220 offset:4096
	ds_read_b128 v[206:209], v220 offset:5120
	ds_read_b128 v[210:213], v220 offset:6144
	ds_read_b128 v[214:217], v220 offset:7168
	global_load_lds_dwordx4 v[166:167], off
	v_lshl_add_u64 v[166:167], s[0:1], 0, v[140:141]
	s_add_i32 m0, s23, 0xe000
	s_nop 0
	global_load_lds_dwordx4 v[166:167], off
	s_waitcnt vmcnt(8)
	s_waitcnt lgkmcnt(0)
	s_barrier
	s_cmp_lg_u32 s32, 0
	s_cbranch_scc1 .Lzc7_0
	s_setprio 1
	s_waitcnt lgkmcnt(0)
	v_mfma_f32_16x16x32_bf16 v[124:127], v[128:131], v[186:189], v[124:127]
	v_mfma_f32_16x16x32_bf16 v[120:123], v[142:145], v[186:189], v[120:123]
	v_mfma_f32_16x16x32_bf16 v[108:111], v[128:131], v[194:197], v[108:111]
	v_mfma_f32_16x16x32_bf16 v[104:107], v[142:145], v[194:197], v[104:107]
	v_mfma_f32_16x16x32_bf16 v[92:95], v[128:131], v[202:205], v[92:95]
	v_mfma_f32_16x16x32_bf16 v[88:91], v[142:145], v[202:205], v[88:91]
	v_mfma_f32_16x16x32_bf16 v[76:79], v[128:131], v[210:213], v[76:79]
	v_mfma_f32_16x16x32_bf16 v[72:75], v[142:145], v[210:213], v[72:75]
	v_mfma_f32_16x16x32_bf16 v[124:127], v[132:135], v[190:193], v[124:127]
	v_mfma_f32_16x16x32_bf16 v[120:123], v[146:149], v[190:193], v[120:123]
	v_mfma_f32_16x16x32_bf16 v[108:111], v[132:135], v[198:201], v[108:111]
	v_mfma_f32_16x16x32_bf16 v[104:107], v[146:149], v[198:201], v[104:107]
	v_mfma_f32_16x16x32_bf16 v[92:95], v[132:135], v[206:209], v[92:95]
	v_mfma_f32_16x16x32_bf16 v[88:91], v[146:149], v[206:209], v[88:91]
	v_mfma_f32_16x16x32_bf16 v[76:79], v[132:135], v[214:217], v[76:79]
	v_mfma_f32_16x16x32_bf16 v[72:75], v[146:149], v[214:217], v[72:75]
	s_setprio 0
	s_setprio 1
	v_mfma_f32_16x16x32_bf16 v[116:119], v[150:153], v[186:189], v[116:119]
	v_mfma_f32_16x16x32_bf16 v[112:115], v[158:161], v[186:189], v[112:115]
	v_mfma_f32_16x16x32_bf16 v[100:103], v[150:153], v[194:197], v[100:103]
	v_mfma_f32_16x16x32_bf16 v[96:99], v[158:161], v[194:197], v[96:99]
	v_mfma_f32_16x16x32_bf16 v[84:87], v[150:153], v[202:205], v[84:87]
	v_mfma_f32_16x16x32_bf16 v[80:83], v[158:161], v[202:205], v[80:83]
	v_mfma_f32_16x16x32_bf16 v[68:71], v[150:153], v[210:213], v[68:71]
	v_mfma_f32_16x16x32_bf16 v[64:67], v[158:161], v[210:213], v[64:67]
	v_mfma_f32_16x16x32_bf16 v[116:119], v[154:157], v[190:193], v[116:119]
	v_mfma_f32_16x16x32_bf16 v[112:115], v[162:165], v[190:193], v[112:115]
	v_mfma_f32_16x16x32_bf16 v[100:103], v[154:157], v[198:201], v[100:103]
	v_mfma_f32_16x16x32_bf16 v[96:99], v[162:165], v[198:201], v[96:99]
	v_mfma_f32_16x16x32_bf16 v[84:87], v[154:157], v[206:209], v[84:87]
	v_mfma_f32_16x16x32_bf16 v[80:83], v[162:165], v[206:209], v[80:83]
	v_mfma_f32_16x16x32_bf16 v[68:71], v[154:157], v[214:217], v[68:71]
	v_mfma_f32_16x16x32_bf16 v[64:67], v[162:165], v[214:217], v[64:67]
	s_setprio 0
.Lzc7_0j:
	s_barrier
	s_add_i32 s74, s74, s22
	v_lshl_add_u64 v[166:167], s[2:3], 0, v[168:169]
	s_mov_b32 m0, s74
	ds_read_b128 v[186:189], v220 offset:16384
	ds_read_b128 v[190:193], v220 offset:17408
	ds_read_b128 v[194:197], v220 offset:18432
	ds_read_b128 v[198:201], v220 offset:19456
	ds_read_b128 v[202:205], v220 offset:20480
	ds_read_b128 v[206:209], v220 offset:21504
	ds_read_b128 v[210:213], v220 offset:22528
	ds_read_b128 v[214:217], v220 offset:23552
	global_load_lds_dwordx4 v[166:167], off
	s_add_i32 m0, s74, 0x2000
	s_add_u32 s74, s2, 0x40000
	v_lshl_add_u64 v[222:223], s[2:3], 0, v[136:137]
	s_addc_u32 s75, s3, 0
	s_add_i32 s76, s76, s22
	global_load_lds_dwordx4 v[222:223], off
	v_lshl_add_u64 v[234:235], s[74:75], 0, v[168:169]
	s_mov_b32 m0, s76
	v_lshl_add_u64 v[236:237], s[20:21], 0, v[136:137]
	global_load_lds_dwordx4 v[234:235], off
	v_lshl_add_u64 v[234:235], s[74:75], 0, v[136:137]
	s_add_i32 m0, s76, 0x2000
	s_nop 0
	global_load_lds_dwordx4 v[234:235], off
	v_lshl_add_u64 v[234:235], s[20:21], 0, v[168:169]
	s_mov_b32 m0, s23
	s_nop 0
	global_load_lds_dwordx4 v[234:235], off
	s_mov_b32 m0, s25
	s_nop 0
	global_load_lds_dwordx4 v[236:237], off
	s_waitcnt vmcnt(8)
	s_waitcnt lgkmcnt(0)
	s_barrier
	s_cmp_lg_u32 s32, 0
	s_cbranch_scc1 .Lzc7_1
	s_setprio 1
	s_waitcnt lgkmcnt(0)
	v_mfma_f32_16x16x32_bf16 v[60:63], v[128:131], v[186:189], v[60:63]
	v_mfma_f32_16x16x32_bf16 v[56:59], v[142:145], v[186:189], v[56:59]
	v_mfma_f32_16x16x32_bf16 v[44:47], v[128:131], v[194:197], v[44:47]
	v_mfma_f32_16x16x32_bf16 v[40:43], v[142:145], v[194:197], v[40:43]
	v_mfma_f32_16x16x32_bf16 v[28:31], v[128:131], v[202:205], v[28:31]
	v_mfma_f32_16x16x32_bf16 v[24:27], v[142:145], v[202:205], v[24:27]
	v_mfma_f32_16x16x32_bf16 v[12:15], v[128:131], v[210:213], v[12:15]
	v_mfma_f32_16x16x32_bf16 v[8:11], v[142:145], v[210:213], v[8:11]
	v_mfma_f32_16x16x32_bf16 v[60:63], v[132:135], v[190:193], v[60:63]
	v_mfma_f32_16x16x32_bf16 v[56:59], v[146:149], v[190:193], v[56:59]
	v_mfma_f32_16x16x32_bf16 v[44:47], v[132:135], v[198:201], v[44:47]
	v_mfma_f32_16x16x32_bf16 v[40:43], v[146:149], v[198:201], v[40:43]
	v_mfma_f32_16x16x32_bf16 v[28:31], v[132:135], v[206:209], v[28:31]
	v_mfma_f32_16x16x32_bf16 v[24:27], v[146:149], v[206:209], v[24:27]
	v_mfma_f32_16x16x32_bf16 v[12:15], v[132:135], v[214:217], v[12:15]
	v_mfma_f32_16x16x32_bf16 v[8:11], v[146:149], v[214:217], v[8:11]
	s_setprio 0
	s_setprio 1
	v_mfma_f32_16x16x32_bf16 v[52:55], v[150:153], v[186:189], v[52:55]
	v_mfma_f32_16x16x32_bf16 v[48:51], v[158:161], v[186:189], v[48:51]
	v_mfma_f32_16x16x32_bf16 v[36:39], v[150:153], v[194:197], v[36:39]
	v_mfma_f32_16x16x32_bf16 v[32:35], v[158:161], v[194:197], v[32:35]
	v_mfma_f32_16x16x32_bf16 v[20:23], v[150:153], v[202:205], v[20:23]
	v_mfma_f32_16x16x32_bf16 v[16:19], v[158:161], v[202:205], v[16:19]
	v_mfma_f32_16x16x32_bf16 v[4:7], v[150:153], v[210:213], v[4:7]
	v_mfma_f32_16x16x32_bf16 v[0:3], v[158:161], v[210:213], v[0:3]
	v_mfma_f32_16x16x32_bf16 v[52:55], v[154:157], v[190:193], v[52:55]
	v_mfma_f32_16x16x32_bf16 v[48:51], v[162:165], v[190:193], v[48:51]
	v_mfma_f32_16x16x32_bf16 v[36:39], v[154:157], v[198:201], v[36:39]
	v_mfma_f32_16x16x32_bf16 v[32:35], v[162:165], v[198:201], v[32:35]
	v_mfma_f32_16x16x32_bf16 v[20:23], v[154:157], v[206:209], v[20:23]
	v_mfma_f32_16x16x32_bf16 v[16:19], v[162:165], v[206:209], v[16:19]
	v_mfma_f32_16x16x32_bf16 v[4:7], v[154:157], v[214:217], v[4:7]
	v_mfma_f32_16x16x32_bf16 v[0:3], v[162:165], v[214:217], v[0:3]
	s_setprio 0
.Lzc7_1j:
	s_barrier
	s_add_i32 s74, 0, 0x18000
	s_add_i32 s75, 0, 0x1c000
	v_add_u32_e32 v146, s74, v219
	v_add_u32_e32 v162, s75, v219
	ds_read_b128 v[128:131], v146
	ds_read_b128 v[132:135], v146 offset:1024
	ds_read_b128 v[142:145], v146 offset:2048
	ds_read_b128 v[146:149], v146 offset:3072
	ds_read_b128 v[150:153], v162
	ds_read_b128 v[154:157], v162 offset:1024
	ds_read_b128 v[158:161], v162 offset:2048
	ds_read_b128 v[162:165], v162 offset:3072
	s_add_u32 s20, s20, 0x40000
	s_addc_u32 s21, s21, 0
	s_mov_b32 m0, s61
	v_lshl_add_u64 v[242:243], s[20:21], 0, v[168:169]
	ds_read_b128 v[186:189], v220 offset:32768
	ds_read_b128 v[190:193], v220 offset:33792
	ds_read_b128 v[194:197], v220 offset:34816
	ds_read_b128 v[198:201], v220 offset:35840
	ds_read_b128 v[202:205], v220 offset:36864
	ds_read_b128 v[206:209], v220 offset:37888
	ds_read_b128 v[210:213], v220 offset:38912
	ds_read_b128 v[214:217], v220 offset:39936
	global_load_lds_dwordx4 v[242:243], off
	v_lshl_add_u64 v[242:243], s[20:21], 0, v[136:137]
	s_mov_b32 m0, s62
	s_nop 0
	global_load_lds_dwordx4 v[242:243], off
	s_waitcnt vmcnt(8)
	s_waitcnt lgkmcnt(0)
	s_barrier
	s_setprio 1
	s_waitcnt lgkmcnt(0)
	v_mfma_f32_16x16x32_bf16 v[124:127], v[128:131], v[186:189], v[124:127]
	v_mfma_f32_16x16x32_bf16 v[120:123], v[142:145], v[186:189], v[120:123]
	v_mfma_f32_16x16x32_bf16 v[108:111], v[128:131], v[194:197], v[108:111]
	v_mfma_f32_16x16x32_bf16 v[104:107], v[142:145], v[194:197], v[104:107]
	v_mfma_f32_16x16x32_bf16 v[92:95], v[128:131], v[202:205], v[92:95]
	v_mfma_f32_16x16x32_bf16 v[88:91], v[142:145], v[202:205], v[88:91]
	v_mfma_f32_16x16x32_bf16 v[76:79], v[128:131], v[210:213], v[76:79]
	v_mfma_f32_16x16x32_bf16 v[72:75], v[142:145], v[210:213], v[72:75]
	v_mfma_f32_16x16x32_bf16 v[124:127], v[132:135], v[190:193], v[124:127]
	v_mfma_f32_16x16x32_bf16 v[120:123], v[146:149], v[190:193], v[120:123]
	v_mfma_f32_16x16x32_bf16 v[108:111], v[132:135], v[198:201], v[108:111]
	v_mfma_f32_16x16x32_bf16 v[104:107], v[146:149], v[198:201], v[104:107]
	v_mfma_f32_16x16x32_bf16 v[92:95], v[132:135], v[206:209], v[92:95]
	v_mfma_f32_16x16x32_bf16 v[88:91], v[146:149], v[206:209], v[88:91]
	v_mfma_f32_16x16x32_bf16 v[76:79], v[132:135], v[214:217], v[76:79]
	v_mfma_f32_16x16x32_bf16 v[72:75], v[146:149], v[214:217], v[72:75]
	s_setprio 0
	s_setprio 1
	v_mfma_f32_16x16x32_bf16 v[116:119], v[150:153], v[186:189], v[116:119]
	v_mfma_f32_16x16x32_bf16 v[112:115], v[158:161], v[186:189], v[112:115]
	v_mfma_f32_16x16x32_bf16 v[100:103], v[150:153], v[194:197], v[100:103]
	v_mfma_f32_16x16x32_bf16 v[96:99], v[158:161], v[194:197], v[96:99]
	v_mfma_f32_16x16x32_bf16 v[84:87], v[150:153], v[202:205], v[84:87]
	v_mfma_f32_16x16x32_bf16 v[80:83], v[158:161], v[202:205], v[80:83]
	v_mfma_f32_16x16x32_bf16 v[68:71], v[150:153], v[210:213], v[68:71]
	v_mfma_f32_16x16x32_bf16 v[64:67], v[158:161], v[210:213], v[64:67]
	v_mfma_f32_16x16x32_bf16 v[116:119], v[154:157], v[190:193], v[116:119]
	v_mfma_f32_16x16x32_bf16 v[112:115], v[162:165], v[190:193], v[112:115]
	v_mfma_f32_16x16x32_bf16 v[100:103], v[154:157], v[198:201], v[100:103]
	v_mfma_f32_16x16x32_bf16 v[96:99], v[162:165], v[198:201], v[96:99]
	v_mfma_f32_16x16x32_bf16 v[84:87], v[154:157], v[206:209], v[84:87]
	v_mfma_f32_16x16x32_bf16 v[80:83], v[162:165], v[206:209], v[80:83]
	v_mfma_f32_16x16x32_bf16 v[68:71], v[154:157], v[214:217], v[68:71]
	v_mfma_f32_16x16x32_bf16 v[64:67], v[162:165], v[214:217], v[64:67]
	s_setprio 0
	s_barrier
	s_add_i32 s20, s74, s22
	v_lshl_add_u64 v[166:167], v[166:167], 0, s[28:29]
	s_mov_b32 m0, s20
	ds_read_b128 v[186:189], v220 offset:49152
	ds_read_b128 v[190:193], v220 offset:50176
	ds_read_b128 v[194:197], v220 offset:51200
	ds_read_b128 v[198:201], v220 offset:52224
	ds_read_b128 v[202:205], v220 offset:53248
	ds_read_b128 v[206:209], v220 offset:54272
	ds_read_b128 v[210:213], v220 offset:55296
	ds_read_b128 v[214:217], v220 offset:56320
	global_load_lds_dwordx4 v[166:167], off
	s_add_i32 m0, s20, 0x2000
	s_add_u32 s2, s2, 0x40080
	v_lshl_add_u64 v[166:167], v[222:223], 0, s[28:29]
	s_addc_u32 s3, s3, 0
	s_add_i32 s20, s75, s22
	global_load_lds_dwordx4 v[166:167], off
	v_lshl_add_u64 v[166:167], s[2:3], 0, v[168:169]
	s_mov_b32 m0, s20
	s_nop 0
	global_load_lds_dwordx4 v[166:167], off
	v_lshl_add_u64 v[166:167], s[2:3], 0, v[136:137]
	s_add_i32 m0, s20, 0x2000
	s_nop 0
	global_load_lds_dwordx4 v[166:167], off
	v_lshl_add_u64 v[166:167], v[234:235], 0, s[28:29]
	s_mov_b32 m0, s66
	s_nop 0
	global_load_lds_dwordx4 v[166:167], off
	v_lshl_add_u64 v[166:167], v[236:237], 0, s[28:29]
	s_mov_b32 m0, s67
	s_nop 0
	global_load_lds_dwordx4 v[166:167], off
	s_waitcnt vmcnt(8)
	s_waitcnt lgkmcnt(0)
	s_barrier
	s_setprio 1
	s_waitcnt lgkmcnt(0)
	v_mfma_f32_16x16x32_bf16 v[60:63], v[128:131], v[186:189], v[60:63]
	v_mfma_f32_16x16x32_bf16 v[56:59], v[142:145], v[186:189], v[56:59]
	v_mfma_f32_16x16x32_bf16 v[44:47], v[128:131], v[194:197], v[44:47]
	v_mfma_f32_16x16x32_bf16 v[40:43], v[142:145], v[194:197], v[40:43]
	v_mfma_f32_16x16x32_bf16 v[28:31], v[128:131], v[202:205], v[28:31]
	v_mfma_f32_16x16x32_bf16 v[24:27], v[142:145], v[202:205], v[24:27]
	v_mfma_f32_16x16x32_bf16 v[12:15], v[128:131], v[210:213], v[12:15]
	v_mfma_f32_16x16x32_bf16 v[8:11], v[142:145], v[210:213], v[8:11]
	v_mfma_f32_16x16x32_bf16 v[60:63], v[132:135], v[190:193], v[60:63]
	v_mfma_f32_16x16x32_bf16 v[56:59], v[146:149], v[190:193], v[56:59]
	v_mfma_f32_16x16x32_bf16 v[44:47], v[132:135], v[198:201], v[44:47]
	v_mfma_f32_16x16x32_bf16 v[40:43], v[146:149], v[198:201], v[40:43]
	v_mfma_f32_16x16x32_bf16 v[28:31], v[132:135], v[206:209], v[28:31]
	v_mfma_f32_16x16x32_bf16 v[24:27], v[146:149], v[206:209], v[24:27]
	v_mfma_f32_16x16x32_bf16 v[12:15], v[132:135], v[214:217], v[12:15]
	v_mfma_f32_16x16x32_bf16 v[8:11], v[146:149], v[214:217], v[8:11]
	s_setprio 0
	s_setprio 1
	v_mfma_f32_16x16x32_bf16 v[52:55], v[150:153], v[186:189], v[52:55]
	v_mfma_f32_16x16x32_bf16 v[48:51], v[158:161], v[186:189], v[48:51]
	v_mfma_f32_16x16x32_bf16 v[36:39], v[150:153], v[194:197], v[36:39]
	v_mfma_f32_16x16x32_bf16 v[32:35], v[158:161], v[194:197], v[32:35]
	v_mfma_f32_16x16x32_bf16 v[20:23], v[150:153], v[202:205], v[20:23]
	v_mfma_f32_16x16x32_bf16 v[16:19], v[158:161], v[202:205], v[16:19]
	v_mfma_f32_16x16x32_bf16 v[4:7], v[150:153], v[210:213], v[4:7]
	v_mfma_f32_16x16x32_bf16 v[0:3], v[158:161], v[210:213], v[0:3]
	v_mfma_f32_16x16x32_bf16 v[52:55], v[154:157], v[190:193], v[52:55]
	v_mfma_f32_16x16x32_bf16 v[48:51], v[162:165], v[190:193], v[48:51]
	v_mfma_f32_16x16x32_bf16 v[36:39], v[154:157], v[198:201], v[36:39]
	v_mfma_f32_16x16x32_bf16 v[32:35], v[162:165], v[198:201], v[32:35]
	v_mfma_f32_16x16x32_bf16 v[20:23], v[154:157], v[206:209], v[20:23]
	v_mfma_f32_16x16x32_bf16 v[16:19], v[162:165], v[206:209], v[16:19]
	v_mfma_f32_16x16x32_bf16 v[4:7], v[154:157], v[214:217], v[4:7]
	v_mfma_f32_16x16x32_bf16 v[0:3], v[162:165], v[214:217], v[0:3]
	s_setprio 0
	s_barrier
	s_add_u32 s0, s0, 0x100
	s_addc_u32 s1, s1, 0
	s_add_u32 s53, s53, 0x100
	s_addc_u32 s58, s58, 0
	s_cmp_ge_i32 s59, s63
	s_mov_b32 s2, s59
	s_mov_b32 s32, 0
	s_cbranch_scc0 .LBB0_444

.Lzc8_0:
	s_setprio 1
	s_waitcnt lgkmcnt(0)
	v_mfma_f32_16x16x32_bf16 v[124:127], v[134:137], v[186:189], 0
	v_mfma_f32_16x16x32_bf16 v[120:123], v[142:145], v[186:189], 0
	v_mfma_f32_16x16x32_bf16 v[108:111], v[134:137], v[198:201], 0
	v_mfma_f32_16x16x32_bf16 v[104:107], v[142:145], v[198:201], 0
	v_mfma_f32_16x16x32_bf16 v[92:95], v[134:137], v[206:209], 0
	v_mfma_f32_16x16x32_bf16 v[88:91], v[142:145], v[206:209], 0
	v_mfma_f32_16x16x32_bf16 v[76:79], v[134:137], v[214:217], 0
	v_mfma_f32_16x16x32_bf16 v[72:75], v[142:145], v[214:217], 0
	v_mfma_f32_16x16x32_bf16 v[124:127], v[138:141], v[190:193], v[124:127]
	v_mfma_f32_16x16x32_bf16 v[120:123], v[146:149], v[190:193], v[120:123]
	v_mfma_f32_16x16x32_bf16 v[108:111], v[138:141], v[202:205], v[108:111]
	v_mfma_f32_16x16x32_bf16 v[104:107], v[146:149], v[202:205], v[104:107]
	v_mfma_f32_16x16x32_bf16 v[92:95], v[138:141], v[210:213], v[92:95]
	v_mfma_f32_16x16x32_bf16 v[88:91], v[146:149], v[210:213], v[88:91]
	v_mfma_f32_16x16x32_bf16 v[76:79], v[138:141], v[218:221], v[76:79]
	v_mfma_f32_16x16x32_bf16 v[72:75], v[146:149], v[218:221], v[72:75]
	s_setprio 0
	s_setprio 1
	v_mfma_f32_16x16x32_bf16 v[116:119], v[150:153], v[186:189], 0
	v_mfma_f32_16x16x32_bf16 v[112:115], v[158:161], v[186:189], 0
	v_mfma_f32_16x16x32_bf16 v[100:103], v[150:153], v[198:201], 0
	v_mfma_f32_16x16x32_bf16 v[96:99], v[158:161], v[198:201], 0
	v_mfma_f32_16x16x32_bf16 v[84:87], v[150:153], v[206:209], 0
	v_mfma_f32_16x16x32_bf16 v[80:83], v[158:161], v[206:209], 0
	v_mfma_f32_16x16x32_bf16 v[68:71], v[150:153], v[214:217], 0
	v_mfma_f32_16x16x32_bf16 v[64:67], v[158:161], v[214:217], 0
	v_mfma_f32_16x16x32_bf16 v[116:119], v[154:157], v[190:193], v[116:119]
	v_mfma_f32_16x16x32_bf16 v[112:115], v[162:165], v[190:193], v[112:115]
	v_mfma_f32_16x16x32_bf16 v[100:103], v[154:157], v[202:205], v[100:103]
	v_mfma_f32_16x16x32_bf16 v[96:99], v[162:165], v[202:205], v[96:99]
	v_mfma_f32_16x16x32_bf16 v[84:87], v[154:157], v[210:213], v[84:87]
	v_mfma_f32_16x16x32_bf16 v[80:83], v[162:165], v[210:213], v[80:83]
	v_mfma_f32_16x16x32_bf16 v[68:71], v[154:157], v[218:221], v[68:71]
	v_mfma_f32_16x16x32_bf16 v[64:67], v[162:165], v[218:221], v[64:67]
	s_setprio 0
	s_branch .Lzc8_0j
.Lzc8_1:
	s_setprio 1
	s_waitcnt lgkmcnt(0)
	v_mfma_f32_16x16x32_bf16 v[60:63], v[134:137], v[186:189], 0
	v_mfma_f32_16x16x32_bf16 v[56:59], v[142:145], v[186:189], 0
	v_mfma_f32_16x16x32_bf16 v[44:47], v[134:137], v[198:201], 0
	v_mfma_f32_16x16x32_bf16 v[40:43], v[142:145], v[198:201], 0
	v_mfma_f32_16x16x32_bf16 v[28:31], v[134:137], v[206:209], 0
	v_mfma_f32_16x16x32_bf16 v[24:27], v[142:145], v[206:209], 0
	v_mfma_f32_16x16x32_bf16 v[12:15], v[134:137], v[214:217], 0
	v_mfma_f32_16x16x32_bf16 v[8:11], v[142:145], v[214:217], 0
	v_mfma_f32_16x16x32_bf16 v[60:63], v[138:141], v[190:193], v[60:63]
	v_mfma_f32_16x16x32_bf16 v[56:59], v[146:149], v[190:193], v[56:59]
	v_mfma_f32_16x16x32_bf16 v[44:47], v[138:141], v[202:205], v[44:47]
	v_mfma_f32_16x16x32_bf16 v[40:43], v[146:149], v[202:205], v[40:43]
	v_mfma_f32_16x16x32_bf16 v[28:31], v[138:141], v[210:213], v[28:31]
	v_mfma_f32_16x16x32_bf16 v[24:27], v[146:149], v[210:213], v[24:27]
	v_mfma_f32_16x16x32_bf16 v[12:15], v[138:141], v[218:221], v[12:15]
	v_mfma_f32_16x16x32_bf16 v[8:11], v[146:149], v[218:221], v[8:11]
	s_setprio 0
	s_setprio 1
	v_mfma_f32_16x16x32_bf16 v[52:55], v[150:153], v[186:189], 0
	v_mfma_f32_16x16x32_bf16 v[48:51], v[158:161], v[186:189], 0
	v_mfma_f32_16x16x32_bf16 v[36:39], v[150:153], v[198:201], 0
	v_mfma_f32_16x16x32_bf16 v[32:35], v[158:161], v[198:201], 0
	v_mfma_f32_16x16x32_bf16 v[20:23], v[150:153], v[206:209], 0
	v_mfma_f32_16x16x32_bf16 v[16:19], v[158:161], v[206:209], 0
	v_mfma_f32_16x16x32_bf16 v[4:7], v[150:153], v[214:217], 0
	v_mfma_f32_16x16x32_bf16 v[0:3], v[158:161], v[214:217], 0
	v_mfma_f32_16x16x32_bf16 v[52:55], v[154:157], v[190:193], v[52:55]
	v_mfma_f32_16x16x32_bf16 v[48:51], v[162:165], v[190:193], v[48:51]
	v_mfma_f32_16x16x32_bf16 v[36:39], v[154:157], v[202:205], v[36:39]
	v_mfma_f32_16x16x32_bf16 v[32:35], v[162:165], v[202:205], v[32:35]
	v_mfma_f32_16x16x32_bf16 v[20:23], v[154:157], v[210:213], v[20:23]
	v_mfma_f32_16x16x32_bf16 v[16:19], v[162:165], v[210:213], v[16:19]
	v_mfma_f32_16x16x32_bf16 v[4:7], v[154:157], v[218:221], v[4:7]
	v_mfma_f32_16x16x32_bf16 v[0:3], v[162:165], v[218:221], v[0:3]
	s_setprio 0
	s_branch .Lzc8_1j

.LBB0_489:
	s_ashr_i32 s49, s48, 31
	s_lshl_b64 s[22:23], s[48:49], 19
	v_readlane_b32 s40, v254, 57
	v_readlane_b32 s41, v254, 58
	s_add_u32 s52, s40, s22
	s_addc_u32 s53, s41, s23
	s_ashr_i32 s51, s50, 31
	s_lshl_b64 s[22:23], s[50:51], 19
	s_add_u32 s54, s34, s22
	s_addc_u32 s55, s60, s23
	s_andn2_b64 vcc, exec, s[44:45]
	s_waitcnt lgkmcnt(0)
	s_cbranch_vccnz .Lzc8_skip
	s_and_b64 s[22:23], s[38:39], exec
	s_cselect_b32 s1, s53, s3
	s_cselect_b32 s25, s52, s2
	s_cselect_b32 s40, s55, s21
	s_cselect_b32 s41, s54, s20
	s_add_u32 s2, s2, 0x40080
	s_addc_u32 s3, s3, 0
	s_add_u32 s49, s20, 0x100
	s_addc_u32 s51, s21, 0
	s_mov_b32 s20, 0
	s_mov_b32 s32, 1
.LBB0_491:
	s_add_i32 s73, s20, 2
	s_add_u32 s21, s2, 0xfffc0080
	s_addc_u32 s22, s3, -1
	s_add_i32 s74, 0, 0x10000
	s_cmp_eq_u32 s67, s20
	s_cselect_b32 s23, s1, s22
	s_cselect_b32 s22, s25, s21
	s_cselect_b32 s21, s40, s51
	s_cselect_b32 s20, s41, s49
	s_add_i32 s76, 0, 0x14000
	v_add_u32_e32 v146, s74, v195
	v_add_u32_e32 v162, s76, v195
	ds_read_b128 v[134:137], v146
	ds_read_b128 v[138:141], v146 offset:1024
	ds_read_b128 v[142:145], v146 offset:2048
	ds_read_b128 v[146:149], v146 offset:3072
	ds_read_b128 v[150:153], v162
	ds_read_b128 v[154:157], v162 offset:1024
	ds_read_b128 v[158:161], v162 offset:2048
	ds_read_b128 v[162:165], v162 offset:3072
	v_lshl_add_u64 v[166:167], s[2:3], 0, v[130:131]
	s_add_i32 m0, s57, 0xc000
	s_waitcnt vmcnt(0)
	ds_read_b128 v[186:189], v196
	ds_read_b128 v[190:193], v196 offset:1024
	ds_read_b128 v[198:201], v196 offset:2048
	ds_read_b128 v[202:205], v196 offset:3072
	ds_read_b128 v[206:209], v196 offset:4096
	ds_read_b128 v[210:213], v196 offset:5120
	ds_read_b128 v[214:217], v196 offset:6144
	ds_read_b128 v[218:221], v196 offset:7168
	global_load_lds_dwordx4 v[166:167], off
	v_lshl_add_u64 v[166:167], s[2:3], 0, v[132:133]
	s_add_i32 m0, s57, 0xe000
	s_nop 0
	global_load_lds_dwordx4 v[166:167], off
	s_waitcnt vmcnt(8)
	s_waitcnt lgkmcnt(0)
	s_barrier
	s_cmp_lg_u32 s32, 0
	s_cbranch_scc1 .Lzc8_0
	s_setprio 1
	s_waitcnt lgkmcnt(0)
	v_mfma_f32_16x16x32_bf16 v[124:127], v[134:137], v[186:189], v[124:127]
	v_mfma_f32_16x16x32_bf16 v[120:123], v[142:145], v[186:189], v[120:123]
	v_mfma_f32_16x16x32_bf16 v[108:111], v[134:137], v[198:201], v[108:111]
	v_mfma_f32_16x16x32_bf16 v[104:107], v[142:145], v[198:201], v[104:107]
	v_mfma_f32_16x16x32_bf16 v[92:95], v[134:137], v[206:209], v[92:95]
	v_mfma_f32_16x16x32_bf16 v[88:91], v[142:145], v[206:209], v[88:91]
	v_mfma_f32_16x16x32_bf16 v[76:79], v[134:137], v[214:217], v[76:79]
	v_mfma_f32_16x16x32_bf16 v[72:75], v[142:145], v[214:217], v[72:75]
	v_mfma_f32_16x16x32_bf16 v[124:127], v[138:141], v[190:193], v[124:127]
	v_mfma_f32_16x16x32_bf16 v[120:123], v[146:149], v[190:193], v[120:123]
	v_mfma_f32_16x16x32_bf16 v[108:111], v[138:141], v[202:205], v[108:111]
	v_mfma_f32_16x16x32_bf16 v[104:107], v[146:149], v[202:205], v[104:107]
	v_mfma_f32_16x16x32_bf16 v[92:95], v[138:141], v[210:213], v[92:95]
	v_mfma_f32_16x16x32_bf16 v[88:91], v[146:149], v[210:213], v[88:91]
	v_mfma_f32_16x16x32_bf16 v[76:79], v[138:141], v[218:221], v[76:79]
	v_mfma_f32_16x16x32_bf16 v[72:75], v[146:149], v[218:221], v[72:75]
	s_setprio 0
	s_setprio 1
	v_mfma_f32_16x16x32_bf16 v[116:119], v[150:153], v[186:189], v[116:119]
	v_mfma_f32_16x16x32_bf16 v[112:115], v[158:161], v[186:189], v[112:115]
	v_mfma_f32_16x16x32_bf16 v[100:103], v[150:153], v[198:201], v[100:103]
	v_mfma_f32_16x16x32_bf16 v[96:99], v[158:161], v[198:201], v[96:99]
	v_mfma_f32_16x16x32_bf16 v[84:87], v[150:153], v[206:209], v[84:87]
	v_mfma_f32_16x16x32_bf16 v[80:83], v[158:161], v[206:209], v[80:83]
	v_mfma_f32_16x16x32_bf16 v[68:71], v[150:153], v[214:217], v[68:71]
	v_mfma_f32_16x16x32_bf16 v[64:67], v[158:161], v[214:217], v[64:67]
	v_mfma_f32_16x16x32_bf16 v[116:119], v[154:157], v[190:193], v[116:119]
	v_mfma_f32_16x16x32_bf16 v[112:115], v[162:165], v[190:193], v[112:115]
	v_mfma_f32_16x16x32_bf16 v[100:103], v[154:157], v[202:205], v[100:103]
	v_mfma_f32_16x16x32_bf16 v[96:99], v[162:165], v[202:205], v[96:99]
	v_mfma_f32_16x16x32_bf16 v[84:87], v[154:157], v[210:213], v[84:87]
	v_mfma_f32_16x16x32_bf16 v[80:83], v[162:165], v[210:213], v[80:83]
	v_mfma_f32_16x16x32_bf16 v[68:71], v[154:157], v[218:221], v[68:71]
	v_mfma_f32_16x16x32_bf16 v[64:67], v[162:165], v[218:221], v[64:67]
	s_setprio 0
.Lzc8_0j:
	s_barrier
	s_add_i32 s74, s74, s56
	v_lshl_add_u64 v[166:167], s[20:21], 0, v[168:169]
	s_mov_b32 m0, s74
	ds_read_b128 v[186:189], v196 offset:16384
	ds_read_b128 v[190:193], v196 offset:17408
	ds_read_b128 v[198:201], v196 offset:18432
	ds_read_b128 v[202:205], v196 offset:19456
	ds_read_b128 v[206:209], v196 offset:20480
	ds_read_b128 v[210:213], v196 offset:21504
	ds_read_b128 v[214:217], v196 offset:22528
	ds_read_b128 v[218:221], v196 offset:23552
	global_load_lds_dwordx4 v[166:167], off
	s_add_i32 m0, s74, 0x2000
	s_add_u32 s74, s20, 0x40000
	v_lshl_add_u64 v[222:223], s[20:21], 0, v[128:129]
	s_addc_u32 s75, s21, 0
	s_add_i32 s76, s76, s56
	global_load_lds_dwordx4 v[222:223], off
	v_lshl_add_u64 v[234:235], s[74:75], 0, v[168:169]
	s_mov_b32 m0, s76
	v_lshl_add_u64 v[236:237], s[22:23], 0, v[128:129]
	global_load_lds_dwordx4 v[234:235], off
	v_lshl_add_u64 v[234:235], s[74:75], 0, v[128:129]
	s_add_i32 m0, s76, 0x2000
	s_nop 0
	global_load_lds_dwordx4 v[234:235], off
	v_lshl_add_u64 v[234:235], s[22:23], 0, v[168:169]
	s_mov_b32 m0, s57
	s_nop 0
	global_load_lds_dwordx4 v[234:235], off
	s_mov_b32 m0, s58
	s_nop 0
	global_load_lds_dwordx4 v[236:237], off
	s_waitcnt vmcnt(8)
	s_waitcnt lgkmcnt(0)
	s_barrier
	s_cmp_lg_u32 s32, 0
	s_cbranch_scc1 .Lzc8_1
	s_setprio 1
	s_waitcnt lgkmcnt(0)
	v_mfma_f32_16x16x32_bf16 v[60:63], v[134:137], v[186:189], v[60:63]
	v_mfma_f32_16x16x32_bf16 v[56:59], v[142:145], v[186:189], v[56:59]
	v_mfma_f32_16x16x32_bf16 v[44:47], v[134:137], v[198:201], v[44:47]
	v_mfma_f32_16x16x32_bf16 v[40:43], v[142:145], v[198:201], v[40:43]
	v_mfma_f32_16x16x32_bf16 v[28:31], v[134:137], v[206:209], v[28:31]
	v_mfma_f32_16x16x32_bf16 v[24:27], v[142:145], v[206:209], v[24:27]
	v_mfma_f32_16x16x32_bf16 v[12:15], v[134:137], v[214:217], v[12:15]
	v_mfma_f32_16x16x32_bf16 v[8:11], v[142:145], v[214:217], v[8:11]
	v_mfma_f32_16x16x32_bf16 v[60:63], v[138:141], v[190:193], v[60:63]
	v_mfma_f32_16x16x32_bf16 v[56:59], v[146:149], v[190:193], v[56:59]
	v_mfma_f32_16x16x32_bf16 v[44:47], v[138:141], v[202:205], v[44:47]
	v_mfma_f32_16x16x32_bf16 v[40:43], v[146:149], v[202:205], v[40:43]
	v_mfma_f32_16x16x32_bf16 v[28:31], v[138:141], v[210:213], v[28:31]
	v_mfma_f32_16x16x32_bf16 v[24:27], v[146:149], v[210:213], v[24:27]
	v_mfma_f32_16x16x32_bf16 v[12:15], v[138:141], v[218:221], v[12:15]
	v_mfma_f32_16x16x32_bf16 v[8:11], v[146:149], v[218:221], v[8:11]
	s_setprio 0
	s_setprio 1
	v_mfma_f32_16x16x32_bf16 v[52:55], v[150:153], v[186:189], v[52:55]
	v_mfma_f32_16x16x32_bf16 v[48:51], v[158:161], v[186:189], v[48:51]
	v_mfma_f32_16x16x32_bf16 v[36:39], v[150:153], v[198:201], v[36:39]
	v_mfma_f32_16x16x32_bf16 v[32:35], v[158:161], v[198:201], v[32:35]
	v_mfma_f32_16x16x32_bf16 v[20:23], v[150:153], v[206:209], v[20:23]
	v_mfma_f32_16x16x32_bf16 v[16:19], v[158:161], v[206:209], v[16:19]
	v_mfma_f32_16x16x32_bf16 v[4:7], v[150:153], v[214:217], v[4:7]
	v_mfma_f32_16x16x32_bf16 v[0:3], v[158:161], v[214:217], v[0:3]
	v_mfma_f32_16x16x32_bf16 v[52:55], v[154:157], v[190:193], v[52:55]
	v_mfma_f32_16x16x32_bf16 v[48:51], v[162:165], v[190:193], v[48:51]
	v_mfma_f32_16x16x32_bf16 v[36:39], v[154:157], v[202:205], v[36:39]
	v_mfma_f32_16x16x32_bf16 v[32:35], v[162:165], v[202:205], v[32:35]
	v_mfma_f32_16x16x32_bf16 v[20:23], v[154:157], v[210:213], v[20:23]
	v_mfma_f32_16x16x32_bf16 v[16:19], v[162:165], v[210:213], v[16:19]
	v_mfma_f32_16x16x32_bf16 v[4:7], v[154:157], v[218:221], v[4:7]
	v_mfma_f32_16x16x32_bf16 v[0:3], v[162:165], v[218:221], v[0:3]
	s_setprio 0
.Lzc8_1j:
	s_barrier
	s_add_i32 s74, 0, 0x18000
	s_add_i32 s75, 0, 0x1c000
	v_add_u32_e32 v146, s74, v195
	v_add_u32_e32 v162, s75, v195
	ds_read_b128 v[134:137], v146
	ds_read_b128 v[138:141], v146 offset:1024
	ds_read_b128 v[142:145], v146 offset:2048
	ds_read_b128 v[146:149], v146 offset:3072
	ds_read_b128 v[150:153], v162
	ds_read_b128 v[154:157], v162 offset:1024
	ds_read_b128 v[158:161], v162 offset:2048
	ds_read_b128 v[162:165], v162 offset:3072
	s_add_u32 s22, s22, 0x40000
	s_addc_u32 s23, s23, 0
	s_mov_b32 m0, s59
	v_lshl_add_u64 v[242:243], s[22:23], 0, v[168:169]
	ds_read_b128 v[186:189], v196 offset:32768
	ds_read_b128 v[190:193], v196 offset:33792
	ds_read_b128 v[198:201], v196 offset:34816
	ds_read_b128 v[202:205], v196 offset:35840
	ds_read_b128 v[206:209], v196 offset:36864
	ds_read_b128 v[210:213], v196 offset:37888
	ds_read_b128 v[214:217], v196 offset:38912
	ds_read_b128 v[218:221], v196 offset:39936
	global_load_lds_dwordx4 v[242:243], off
	v_lshl_add_u64 v[242:243], s[22:23], 0, v[128:129]
	s_mov_b32 m0, s61
	s_nop 0
	global_load_lds_dwordx4 v[242:243], off
	s_waitcnt vmcnt(8)
	s_waitcnt lgkmcnt(0)
	s_barrier
	s_setprio 1
	s_waitcnt lgkmcnt(0)
	v_mfma_f32_16x16x32_bf16 v[124:127], v[134:137], v[186:189], v[124:127]
	v_mfma_f32_16x16x32_bf16 v[120:123], v[142:145], v[186:189], v[120:123]
	v_mfma_f32_16x16x32_bf16 v[108:111], v[134:137], v[198:201], v[108:111]
	v_mfma_f32_16x16x32_bf16 v[104:107], v[142:145], v[198:201], v[104:107]
	v_mfma_f32_16x16x32_bf16 v[92:95], v[134:137], v[206:209], v[92:95]
	v_mfma_f32_16x16x32_bf16 v[88:91], v[142:145], v[206:209], v[88:91]
	v_mfma_f32_16x16x32_bf16 v[76:79], v[134:137], v[214:217], v[76:79]
	v_mfma_f32_16x16x32_bf16 v[72:75], v[142:145], v[214:217], v[72:75]
	v_mfma_f32_16x16x32_bf16 v[124:127], v[138:141], v[190:193], v[124:127]
	v_mfma_f32_16x16x32_bf16 v[120:123], v[146:149], v[190:193], v[120:123]
	v_mfma_f32_16x16x32_bf16 v[108:111], v[138:141], v[202:205], v[108:111]
	v_mfma_f32_16x16x32_bf16 v[104:107], v[146:149], v[202:205], v[104:107]
	v_mfma_f32_16x16x32_bf16 v[92:95], v[138:141], v[210:213], v[92:95]
	v_mfma_f32_16x16x32_bf16 v[88:91], v[146:149], v[210:213], v[88:91]
	v_mfma_f32_16x16x32_bf16 v[76:79], v[138:141], v[218:221], v[76:79]
	v_mfma_f32_16x16x32_bf16 v[72:75], v[146:149], v[218:221], v[72:75]
	s_setprio 0
	s_setprio 1
	v_mfma_f32_16x16x32_bf16 v[116:119], v[150:153], v[186:189], v[116:119]
	v_mfma_f32_16x16x32_bf16 v[112:115], v[158:161], v[186:189], v[112:115]
	v_mfma_f32_16x16x32_bf16 v[100:103], v[150:153], v[198:201], v[100:103]
	v_mfma_f32_16x16x32_bf16 v[96:99], v[158:161], v[198:201], v[96:99]
	v_mfma_f32_16x16x32_bf16 v[84:87], v[150:153], v[206:209], v[84:87]
	v_mfma_f32_16x16x32_bf16 v[80:83], v[158:161], v[206:209], v[80:83]
	v_mfma_f32_16x16x32_bf16 v[68:71], v[150:153], v[214:217], v[68:71]
	v_mfma_f32_16x16x32_bf16 v[64:67], v[158:161], v[214:217], v[64:67]
	v_mfma_f32_16x16x32_bf16 v[116:119], v[154:157], v[190:193], v[116:119]
	v_mfma_f32_16x16x32_bf16 v[112:115], v[162:165], v[190:193], v[112:115]
	v_mfma_f32_16x16x32_bf16 v[100:103], v[154:157], v[202:205], v[100:103]
	v_mfma_f32_16x16x32_bf16 v[96:99], v[162:165], v[202:205], v[96:99]
	v_mfma_f32_16x16x32_bf16 v[84:87], v[154:157], v[210:213], v[84:87]
	v_mfma_f32_16x16x32_bf16 v[80:83], v[162:165], v[210:213], v[80:83]
	v_mfma_f32_16x16x32_bf16 v[68:71], v[154:157], v[218:221], v[68:71]
	v_mfma_f32_16x16x32_bf16 v[64:67], v[162:165], v[218:221], v[64:67]
	s_setprio 0
	s_barrier
	s_add_i32 s22, s74, s56
	v_lshl_add_u64 v[166:167], v[166:167], 0, s[28:29]
	s_mov_b32 m0, s22
	ds_read_b128 v[186:189], v196 offset:49152
	ds_read_b128 v[190:193], v196 offset:50176
	ds_read_b128 v[198:201], v196 offset:51200
	ds_read_b128 v[202:205], v196 offset:52224
	ds_read_b128 v[206:209], v196 offset:53248
	ds_read_b128 v[210:213], v196 offset:54272
	ds_read_b128 v[214:217], v196 offset:55296
	ds_read_b128 v[218:221], v196 offset:56320
	global_load_lds_dwordx4 v[166:167], off
	s_add_i32 m0, s22, 0x2000
	s_add_u32 s20, s20, 0x40080
	v_lshl_add_u64 v[166:167], v[222:223], 0, s[28:29]
	s_addc_u32 s21, s21, 0
	s_add_i32 s22, s75, s56
	global_load_lds_dwordx4 v[166:167], off
	v_lshl_add_u64 v[166:167], s[20:21], 0, v[168:169]
	s_mov_b32 m0, s22
	s_nop 0
	global_load_lds_dwordx4 v[166:167], off
	v_lshl_add_u64 v[166:167], s[20:21], 0, v[128:129]
	s_add_i32 m0, s22, 0x2000
	s_nop 0
	global_load_lds_dwordx4 v[166:167], off
	v_lshl_add_u64 v[166:167], v[234:235], 0, s[28:29]
	s_mov_b32 m0, s65
	s_nop 0
	global_load_lds_dwordx4 v[166:167], off
	v_lshl_add_u64 v[166:167], v[236:237], 0, s[28:29]
	s_mov_b32 m0, s66
	s_nop 0
	global_load_lds_dwordx4 v[166:167], off
	s_waitcnt vmcnt(8)
	s_waitcnt lgkmcnt(0)
	s_barrier
	s_setprio 1
	s_waitcnt lgkmcnt(0)
	v_mfma_f32_16x16x32_bf16 v[60:63], v[134:137], v[186:189], v[60:63]
	v_mfma_f32_16x16x32_bf16 v[56:59], v[142:145], v[186:189], v[56:59]
	v_mfma_f32_16x16x32_bf16 v[44:47], v[134:137], v[198:201], v[44:47]
	v_mfma_f32_16x16x32_bf16 v[40:43], v[142:145], v[198:201], v[40:43]
	v_mfma_f32_16x16x32_bf16 v[28:31], v[134:137], v[206:209], v[28:31]
	v_mfma_f32_16x16x32_bf16 v[24:27], v[142:145], v[206:209], v[24:27]
	v_mfma_f32_16x16x32_bf16 v[12:15], v[134:137], v[214:217], v[12:15]
	v_mfma_f32_16x16x32_bf16 v[8:11], v[142:145], v[214:217], v[8:11]
	v_mfma_f32_16x16x32_bf16 v[60:63], v[138:141], v[190:193], v[60:63]
	v_mfma_f32_16x16x32_bf16 v[56:59], v[146:149], v[190:193], v[56:59]
	v_mfma_f32_16x16x32_bf16 v[44:47], v[138:141], v[202:205], v[44:47]
	v_mfma_f32_16x16x32_bf16 v[40:43], v[146:149], v[202:205], v[40:43]
	v_mfma_f32_16x16x32_bf16 v[28:31], v[138:141], v[210:213], v[28:31]
	v_mfma_f32_16x16x32_bf16 v[24:27], v[146:149], v[210:213], v[24:27]
	v_mfma_f32_16x16x32_bf16 v[12:15], v[138:141], v[218:221], v[12:15]
	v_mfma_f32_16x16x32_bf16 v[8:11], v[146:149], v[218:221], v[8:11]
	s_setprio 0
	s_setprio 1
	v_mfma_f32_16x16x32_bf16 v[52:55], v[150:153], v[186:189], v[52:55]
	v_mfma_f32_16x16x32_bf16 v[48:51], v[158:161], v[186:189], v[48:51]
	v_mfma_f32_16x16x32_bf16 v[36:39], v[150:153], v[198:201], v[36:39]
	v_mfma_f32_16x16x32_bf16 v[32:35], v[158:161], v[198:201], v[32:35]
	v_mfma_f32_16x16x32_bf16 v[20:23], v[150:153], v[206:209], v[20:23]
	v_mfma_f32_16x16x32_bf16 v[16:19], v[158:161], v[206:209], v[16:19]
	v_mfma_f32_16x16x32_bf16 v[4:7], v[150:153], v[214:217], v[4:7]
	v_mfma_f32_16x16x32_bf16 v[0:3], v[158:161], v[214:217], v[0:3]
	v_mfma_f32_16x16x32_bf16 v[52:55], v[154:157], v[190:193], v[52:55]
	v_mfma_f32_16x16x32_bf16 v[48:51], v[162:165], v[190:193], v[48:51]
	v_mfma_f32_16x16x32_bf16 v[36:39], v[154:157], v[202:205], v[36:39]
	v_mfma_f32_16x16x32_bf16 v[32:35], v[162:165], v[202:205], v[32:35]
	v_mfma_f32_16x16x32_bf16 v[20:23], v[154:157], v[210:213], v[20:23]
	v_mfma_f32_16x16x32_bf16 v[16:19], v[162:165], v[210:213], v[16:19]
	v_mfma_f32_16x16x32_bf16 v[4:7], v[154:157], v[218:221], v[4:7]
	v_mfma_f32_16x16x32_bf16 v[0:3], v[162:165], v[218:221], v[0:3]
	s_setprio 0
	s_barrier
	s_add_u32 s2, s2, 0x100
	s_addc_u32 s3, s3, 0
	s_add_u32 s49, s49, 0x100
	s_addc_u32 s51, s51, 0
	s_cmp_ge_i32 s73, s62
	s_mov_b32 s20, s73
	s_mov_b32 s32, 0
	s_cbranch_scc0 .LBB0_491

.Lzc9_0:
	s_setprio 1
	s_waitcnt lgkmcnt(0)
	v_mfma_f32_16x16x32_bf16 v[124:127], v[146:149], v[198:201], 0
	v_mfma_f32_16x16x32_bf16 v[120:123], v[154:157], v[198:201], 0
	v_mfma_f32_16x16x32_bf16 v[108:111], v[146:149], v[206:209], 0
	v_mfma_f32_16x16x32_bf16 v[104:107], v[154:157], v[206:209], 0
	v_mfma_f32_16x16x32_bf16 v[92:95], v[146:149], v[214:217], 0
	v_mfma_f32_16x16x32_bf16 v[88:91], v[154:157], v[214:217], 0
	v_mfma_f32_16x16x32_bf16 v[76:79], v[146:149], v[242:245], 0
	v_mfma_f32_16x16x32_bf16 v[72:75], v[154:157], v[242:245], 0
	v_mfma_f32_16x16x32_bf16 v[124:127], v[150:153], v[202:205], v[124:127]
	v_mfma_f32_16x16x32_bf16 v[120:123], v[158:161], v[202:205], v[120:123]
	v_mfma_f32_16x16x32_bf16 v[108:111], v[150:153], v[210:213], v[108:111]
	v_mfma_f32_16x16x32_bf16 v[104:107], v[158:161], v[210:213], v[104:107]
	v_mfma_f32_16x16x32_bf16 v[92:95], v[150:153], v[218:221], v[92:95]
	v_mfma_f32_16x16x32_bf16 v[88:91], v[158:161], v[218:221], v[88:91]
	v_mfma_f32_16x16x32_bf16 v[76:79], v[150:153], v[246:249], v[76:79]
	v_mfma_f32_16x16x32_bf16 v[72:75], v[158:161], v[246:249], v[72:75]
	s_setprio 0
	s_setprio 1
	v_mfma_f32_16x16x32_bf16 v[116:119], v[162:165], v[198:201], 0
	v_mfma_f32_16x16x32_bf16 v[112:115], v[190:193], v[198:201], 0
	v_mfma_f32_16x16x32_bf16 v[100:103], v[162:165], v[206:209], 0
	v_mfma_f32_16x16x32_bf16 v[96:99], v[190:193], v[206:209], 0
	v_mfma_f32_16x16x32_bf16 v[84:87], v[162:165], v[214:217], 0
	v_mfma_f32_16x16x32_bf16 v[80:83], v[190:193], v[214:217], 0
	v_mfma_f32_16x16x32_bf16 v[68:71], v[162:165], v[242:245], 0
	v_mfma_f32_16x16x32_bf16 v[64:67], v[190:193], v[242:245], 0
	v_mfma_f32_16x16x32_bf16 v[116:119], v[186:189], v[202:205], v[116:119]
	v_mfma_f32_16x16x32_bf16 v[112:115], v[194:197], v[202:205], v[112:115]
	v_mfma_f32_16x16x32_bf16 v[100:103], v[186:189], v[210:213], v[100:103]
	v_mfma_f32_16x16x32_bf16 v[96:99], v[194:197], v[210:213], v[96:99]
	v_mfma_f32_16x16x32_bf16 v[84:87], v[186:189], v[218:221], v[84:87]
	v_mfma_f32_16x16x32_bf16 v[80:83], v[194:197], v[218:221], v[80:83]
	v_mfma_f32_16x16x32_bf16 v[68:71], v[186:189], v[246:249], v[68:71]
	v_mfma_f32_16x16x32_bf16 v[64:67], v[194:197], v[246:249], v[64:67]
	s_setprio 0
	s_branch .Lzc9_0j
.Lzc9_1:
	s_setprio 1
	s_waitcnt lgkmcnt(0)
	v_mfma_f32_16x16x32_bf16 v[60:63], v[146:149], v[198:201], 0
	v_mfma_f32_16x16x32_bf16 v[56:59], v[154:157], v[198:201], 0
	v_mfma_f32_16x16x32_bf16 v[44:47], v[146:149], v[206:209], 0
	v_mfma_f32_16x16x32_bf16 v[40:43], v[154:157], v[206:209], 0
	v_mfma_f32_16x16x32_bf16 v[28:31], v[146:149], v[214:217], 0
	v_mfma_f32_16x16x32_bf16 v[24:27], v[154:157], v[214:217], 0
	v_mfma_f32_16x16x32_bf16 v[12:15], v[146:149], v[242:245], 0
	v_mfma_f32_16x16x32_bf16 v[8:11], v[154:157], v[242:245], 0
	v_mfma_f32_16x16x32_bf16 v[60:63], v[150:153], v[202:205], v[60:63]
	v_mfma_f32_16x16x32_bf16 v[56:59], v[158:161], v[202:205], v[56:59]
	v_mfma_f32_16x16x32_bf16 v[44:47], v[150:153], v[210:213], v[44:47]
	v_mfma_f32_16x16x32_bf16 v[40:43], v[158:161], v[210:213], v[40:43]
	v_mfma_f32_16x16x32_bf16 v[28:31], v[150:153], v[218:221], v[28:31]
	v_mfma_f32_16x16x32_bf16 v[24:27], v[158:161], v[218:221], v[24:27]
	v_mfma_f32_16x16x32_bf16 v[12:15], v[150:153], v[246:249], v[12:15]
	v_mfma_f32_16x16x32_bf16 v[8:11], v[158:161], v[246:249], v[8:11]
	s_setprio 0
	s_setprio 1
	v_mfma_f32_16x16x32_bf16 v[52:55], v[162:165], v[198:201], 0
	v_mfma_f32_16x16x32_bf16 v[48:51], v[190:193], v[198:201], 0
	v_mfma_f32_16x16x32_bf16 v[36:39], v[162:165], v[206:209], 0
	v_mfma_f32_16x16x32_bf16 v[32:35], v[190:193], v[206:209], 0
	v_mfma_f32_16x16x32_bf16 v[20:23], v[162:165], v[214:217], 0
	v_mfma_f32_16x16x32_bf16 v[16:19], v[190:193], v[214:217], 0
	v_mfma_f32_16x16x32_bf16 v[0:3], v[162:165], v[242:245], 0
	v_mfma_f32_16x16x32_bf16 v[4:7], v[190:193], v[242:245], 0
	v_mfma_f32_16x16x32_bf16 v[52:55], v[186:189], v[202:205], v[52:55]
	v_mfma_f32_16x16x32_bf16 v[48:51], v[194:197], v[202:205], v[48:51]
	v_mfma_f32_16x16x32_bf16 v[36:39], v[186:189], v[210:213], v[36:39]
	v_mfma_f32_16x16x32_bf16 v[32:35], v[194:197], v[210:213], v[32:35]
	v_mfma_f32_16x16x32_bf16 v[20:23], v[186:189], v[218:221], v[20:23]
	v_mfma_f32_16x16x32_bf16 v[16:19], v[194:197], v[218:221], v[16:19]
	v_mfma_f32_16x16x32_bf16 v[0:3], v[186:189], v[246:249], v[0:3]
	v_mfma_f32_16x16x32_bf16 v[4:7], v[194:197], v[246:249], v[4:7]
	s_setprio 0
	s_branch .Lzc9_1j

.LBB0_535:
	s_ashr_i32 s47, s46, 31
	s_lshl_b64 s[22:23], s[46:47], 19
	s_add_u32 s48, s52, s22
	s_addc_u32 s49, s53, s23
	s_andn2_b64 vcc, exec, s[42:43]
	s_cbranch_vccnz .Lzc9_skip
	s_and_b64 s[22:23], s[38:39], exec
	s_cselect_b32 s3, s49, s21
	s_cselect_b32 s47, s48, s20
	s_add_u32 s66, s20, 0x100
	s_addc_u32 s67, s21, 0
	s_add_u32 s20, s20, 0x40080
	s_addc_u32 s21, s21, 0
	v_lshl_add_u64 v[138:139], s[20:21], 0, v[134:135]
	v_lshl_add_u64 v[140:141], s[20:21], 0, v[136:137]
	s_mov_b32 s26, 0
	s_mov_b64 s[20:21], 0
	s_mov_b32 s32, 1
.LBB0_537:
	s_add_i32 s68, s26, 2
	s_add_u32 s22, s20, 0x100
	s_addc_u32 s23, s21, 0
	s_add_u32 s27, s66, s20
	s_addc_u32 s50, s67, s21
	s_add_i32 s69, 0, 0x10000
	s_cmp_eq_u32 s64, s26
	s_cselect_b32 s26, 0, s22
	s_cselect_b32 s51, s3, s50
	s_cselect_b32 s50, s47, s27
	s_cselect_b32 s27, 0, s23
	s_add_u32 s26, s0, s26
	s_addc_u32 s27, s1, s27
	s_add_i32 s70, 0, 0x14000
	v_add_u32_e32 v158, s69, v144
	v_add_u32_e32 v166, s70, v144
	ds_read_b128 v[146:149], v158
	ds_read_b128 v[150:153], v158 offset:1024
	ds_read_b128 v[154:157], v158 offset:2048
	ds_read_b128 v[158:161], v158 offset:3072
	ds_read_b128 v[162:165], v166
	s_waitcnt vmcnt(0)
	ds_read_b128 v[186:189], v166 offset:1024
	ds_read_b128 v[190:193], v166 offset:2048
	ds_read_b128 v[194:197], v166 offset:3072
	v_lshl_add_u64 v[166:167], v[138:139], 0, s[20:21]
	s_add_i32 m0, s55, 0xc000
	ds_read_b128 v[198:201], v145
	ds_read_b128 v[202:205], v145 offset:1024
	ds_read_b128 v[206:209], v145 offset:2048
	ds_read_b128 v[210:213], v145 offset:3072
	ds_read_b128 v[214:217], v145 offset:4096
	ds_read_b128 v[218:221], v145 offset:5120
	ds_read_b128 v[242:245], v145 offset:6144
	ds_read_b128 v[246:249], v145 offset:7168
	global_load_lds_dwordx4 v[166:167], off
	v_lshl_add_u64 v[166:167], v[140:141], 0, s[20:21]
	s_add_i32 m0, s55, 0xe000
	s_nop 0
	global_load_lds_dwordx4 v[166:167], off
	s_waitcnt vmcnt(8)
	s_waitcnt lgkmcnt(0)
	s_barrier
	s_cmp_lg_u32 s32, 0
	s_cbranch_scc1 .Lzc9_0
	s_setprio 1
	s_waitcnt lgkmcnt(0)
	v_mfma_f32_16x16x32_bf16 v[124:127], v[146:149], v[198:201], v[124:127]
	v_mfma_f32_16x16x32_bf16 v[120:123], v[154:157], v[198:201], v[120:123]
	v_mfma_f32_16x16x32_bf16 v[108:111], v[146:149], v[206:209], v[108:111]
	v_mfma_f32_16x16x32_bf16 v[104:107], v[154:157], v[206:209], v[104:107]
	v_mfma_f32_16x16x32_bf16 v[92:95], v[146:149], v[214:217], v[92:95]
	v_mfma_f32_16x16x32_bf16 v[88:91], v[154:157], v[214:217], v[88:91]
	v_mfma_f32_16x16x32_bf16 v[76:79], v[146:149], v[242:245], v[76:79]
	v_mfma_f32_16x16x32_bf16 v[72:75], v[154:157], v[242:245], v[72:75]
	v_mfma_f32_16x16x32_bf16 v[124:127], v[150:153], v[202:205], v[124:127]
	v_mfma_f32_16x16x32_bf16 v[120:123], v[158:161], v[202:205], v[120:123]
	v_mfma_f32_16x16x32_bf16 v[108:111], v[150:153], v[210:213], v[108:111]
	v_mfma_f32_16x16x32_bf16 v[104:107], v[158:161], v[210:213], v[104:107]
	v_mfma_f32_16x16x32_bf16 v[92:95], v[150:153], v[218:221], v[92:95]
	v_mfma_f32_16x16x32_bf16 v[88:91], v[158:161], v[218:221], v[88:91]
	v_mfma_f32_16x16x32_bf16 v[76:79], v[150:153], v[246:249], v[76:79]
	v_mfma_f32_16x16x32_bf16 v[72:75], v[158:161], v[246:249], v[72:75]
	s_setprio 0
	s_setprio 1
	v_mfma_f32_16x16x32_bf16 v[116:119], v[162:165], v[198:201], v[116:119]
	v_mfma_f32_16x16x32_bf16 v[112:115], v[190:193], v[198:201], v[112:115]
	v_mfma_f32_16x16x32_bf16 v[100:103], v[162:165], v[206:209], v[100:103]
	v_mfma_f32_16x16x32_bf16 v[96:99], v[190:193], v[206:209], v[96:99]
	v_mfma_f32_16x16x32_bf16 v[84:87], v[162:165], v[214:217], v[84:87]
	v_mfma_f32_16x16x32_bf16 v[80:83], v[190:193], v[214:217], v[80:83]
	v_mfma_f32_16x16x32_bf16 v[68:71], v[162:165], v[242:245], v[68:71]
	v_mfma_f32_16x16x32_bf16 v[64:67], v[190:193], v[242:245], v[64:67]
	v_mfma_f32_16x16x32_bf16 v[116:119], v[186:189], v[202:205], v[116:119]
	v_mfma_f32_16x16x32_bf16 v[112:115], v[194:197], v[202:205], v[112:115]
	v_mfma_f32_16x16x32_bf16 v[100:103], v[186:189], v[210:213], v[100:103]
	v_mfma_f32_16x16x32_bf16 v[96:99], v[194:197], v[210:213], v[96:99]
	v_mfma_f32_16x16x32_bf16 v[84:87], v[186:189], v[218:221], v[84:87]
	v_mfma_f32_16x16x32_bf16 v[80:83], v[194:197], v[218:221], v[80:83]
	v_mfma_f32_16x16x32_bf16 v[68:71], v[186:189], v[246:249], v[68:71]
	v_mfma_f32_16x16x32_bf16 v[64:67], v[194:197], v[246:249], v[64:67]
	s_setprio 0
.Lzc9_0j:
	s_barrier
	s_add_i32 s20, s69, s54
	v_lshl_add_u64 v[166:167], s[26:27], 0, v[128:129]
	s_mov_b32 m0, s20
	ds_read_b128 v[198:201], v145 offset:16384
	ds_read_b128 v[202:205], v145 offset:17408
	ds_read_b128 v[206:209], v145 offset:18432
	ds_read_b128 v[210:213], v145 offset:19456
	ds_read_b128 v[214:217], v145 offset:20480
	ds_read_b128 v[218:221], v145 offset:21504
	ds_read_b128 v[242:245], v145 offset:22528
	ds_read_b128 v[246:249], v145 offset:23552
	global_load_lds_dwordx4 v[166:167], off
	s_add_i32 m0, s20, 0x2000
	s_add_u32 s20, s26, 0x10000
	v_lshl_add_u64 v[222:223], s[26:27], 0, v[132:133]
	s_addc_u32 s21, s27, 0
	s_add_i32 s69, s70, s54
	global_load_lds_dwordx4 v[222:223], off
	v_lshl_add_u64 v[236:237], s[20:21], 0, v[128:129]
	s_mov_b32 m0, s69
	v_lshl_add_u64 v[250:251], s[50:51], 0, v[130:131]
	global_load_lds_dwordx4 v[236:237], off
	v_lshl_add_u64 v[236:237], s[20:21], 0, v[132:133]
	s_add_i32 m0, s69, 0x2000
	s_nop 0
	global_load_lds_dwordx4 v[236:237], off
	v_lshl_add_u64 v[236:237], s[50:51], 0, v[168:169]
	s_mov_b32 m0, s55
	s_nop 0
	global_load_lds_dwordx4 v[236:237], off
	s_mov_b32 m0, s56
	s_nop 0
	global_load_lds_dwordx4 v[250:251], off
	s_waitcnt vmcnt(8)
	s_waitcnt lgkmcnt(0)
	s_barrier
	s_cmp_lg_u32 s32, 0
	s_cbranch_scc1 .Lzc9_1
	s_setprio 1
	s_waitcnt lgkmcnt(0)
	v_mfma_f32_16x16x32_bf16 v[60:63], v[146:149], v[198:201], v[60:63]
	v_mfma_f32_16x16x32_bf16 v[56:59], v[154:157], v[198:201], v[56:59]
	v_mfma_f32_16x16x32_bf16 v[44:47], v[146:149], v[206:209], v[44:47]
	v_mfma_f32_16x16x32_bf16 v[40:43], v[154:157], v[206:209], v[40:43]
	v_mfma_f32_16x16x32_bf16 v[28:31], v[146:149], v[214:217], v[28:31]
	v_mfma_f32_16x16x32_bf16 v[24:27], v[154:157], v[214:217], v[24:27]
	v_mfma_f32_16x16x32_bf16 v[12:15], v[146:149], v[242:245], v[12:15]
	v_mfma_f32_16x16x32_bf16 v[8:11], v[154:157], v[242:245], v[8:11]
	v_mfma_f32_16x16x32_bf16 v[60:63], v[150:153], v[202:205], v[60:63]
	v_mfma_f32_16x16x32_bf16 v[56:59], v[158:161], v[202:205], v[56:59]
	v_mfma_f32_16x16x32_bf16 v[44:47], v[150:153], v[210:213], v[44:47]
	v_mfma_f32_16x16x32_bf16 v[40:43], v[158:161], v[210:213], v[40:43]
	v_mfma_f32_16x16x32_bf16 v[28:31], v[150:153], v[218:221], v[28:31]
	v_mfma_f32_16x16x32_bf16 v[24:27], v[158:161], v[218:221], v[24:27]
	v_mfma_f32_16x16x32_bf16 v[12:15], v[150:153], v[246:249], v[12:15]
	v_mfma_f32_16x16x32_bf16 v[8:11], v[158:161], v[246:249], v[8:11]
	s_setprio 0
	s_setprio 1
	v_mfma_f32_16x16x32_bf16 v[52:55], v[162:165], v[198:201], v[52:55]
	v_mfma_f32_16x16x32_bf16 v[48:51], v[190:193], v[198:201], v[48:51]
	v_mfma_f32_16x16x32_bf16 v[36:39], v[162:165], v[206:209], v[36:39]
	v_mfma_f32_16x16x32_bf16 v[32:35], v[190:193], v[206:209], v[32:35]
	v_mfma_f32_16x16x32_bf16 v[20:23], v[162:165], v[214:217], v[20:23]
	v_mfma_f32_16x16x32_bf16 v[16:19], v[190:193], v[214:217], v[16:19]
	v_mfma_f32_16x16x32_bf16 v[0:3], v[162:165], v[242:245], v[0:3]
	v_mfma_f32_16x16x32_bf16 v[4:7], v[190:193], v[242:245], v[4:7]
	v_mfma_f32_16x16x32_bf16 v[52:55], v[186:189], v[202:205], v[52:55]
	v_mfma_f32_16x16x32_bf16 v[48:51], v[194:197], v[202:205], v[48:51]
	v_mfma_f32_16x16x32_bf16 v[36:39], v[186:189], v[210:213], v[36:39]
	v_mfma_f32_16x16x32_bf16 v[32:35], v[194:197], v[210:213], v[32:35]
	v_mfma_f32_16x16x32_bf16 v[20:23], v[186:189], v[218:221], v[20:23]
	v_mfma_f32_16x16x32_bf16 v[16:19], v[194:197], v[218:221], v[16:19]
	v_mfma_f32_16x16x32_bf16 v[0:3], v[186:189], v[246:249], v[0:3]
	v_mfma_f32_16x16x32_bf16 v[4:7], v[194:197], v[246:249], v[4:7]
	s_setprio 0
.Lzc9_1j:
	s_barrier
	s_add_i32 s69, 0, 0x18000
	s_add_i32 s70, 0, 0x1c000
	v_add_u32_e32 v158, s69, v144
	v_add_u32_e32 v174, s70, v144
	ds_read_b128 v[146:149], v158
	ds_read_b128 v[150:153], v158 offset:1024
	ds_read_b128 v[154:157], v158 offset:2048
	ds_read_b128 v[158:161], v158 offset:3072
	ds_read_b128 v[162:165], v174
	ds_read_b128 v[186:189], v174 offset:1024
	ds_read_b128 v[190:193], v174 offset:2048
	ds_read_b128 v[194:197], v174 offset:3072
	s_add_u32 s20, s50, 0x40000
	s_addc_u32 s21, s51, 0
	s_mov_b32 m0, s57
	v_lshl_add_u64 v[234:235], s[20:21], 0, v[168:169]
	ds_read_b128 v[198:201], v145 offset:32768
	ds_read_b128 v[202:205], v145 offset:33792
	ds_read_b128 v[206:209], v145 offset:34816
	ds_read_b128 v[210:213], v145 offset:35840
	ds_read_b128 v[214:217], v145 offset:36864
	ds_read_b128 v[218:221], v145 offset:37888
	ds_read_b128 v[242:245], v145 offset:38912
	ds_read_b128 v[246:249], v145 offset:39936
	global_load_lds_dwordx4 v[234:235], off
	v_lshl_add_u64 v[234:235], s[20:21], 0, v[130:131]
	s_mov_b32 m0, s58
	s_nop 0
	global_load_lds_dwordx4 v[234:235], off
	s_waitcnt vmcnt(8)
	s_waitcnt lgkmcnt(0)
	s_barrier
	s_setprio 1
	s_waitcnt lgkmcnt(0)
	v_mfma_f32_16x16x32_bf16 v[124:127], v[146:149], v[198:201], v[124:127]
	v_mfma_f32_16x16x32_bf16 v[120:123], v[154:157], v[198:201], v[120:123]
	v_mfma_f32_16x16x32_bf16 v[108:111], v[146:149], v[206:209], v[108:111]
	v_mfma_f32_16x16x32_bf16 v[104:107], v[154:157], v[206:209], v[104:107]
	v_mfma_f32_16x16x32_bf16 v[92:95], v[146:149], v[214:217], v[92:95]
	v_mfma_f32_16x16x32_bf16 v[88:91], v[154:157], v[214:217], v[88:91]
	v_mfma_f32_16x16x32_bf16 v[76:79], v[146:149], v[242:245], v[76:79]
	v_mfma_f32_16x16x32_bf16 v[72:75], v[154:157], v[242:245], v[72:75]
	v_mfma_f32_16x16x32_bf16 v[124:127], v[150:153], v[202:205], v[124:127]
	v_mfma_f32_16x16x32_bf16 v[120:123], v[158:161], v[202:205], v[120:123]
	v_mfma_f32_16x16x32_bf16 v[108:111], v[150:153], v[210:213], v[108:111]
	v_mfma_f32_16x16x32_bf16 v[104:107], v[158:161], v[210:213], v[104:107]
	v_mfma_f32_16x16x32_bf16 v[92:95], v[150:153], v[218:221], v[92:95]
	v_mfma_f32_16x16x32_bf16 v[88:91], v[158:161], v[218:221], v[88:91]
	v_mfma_f32_16x16x32_bf16 v[76:79], v[150:153], v[246:249], v[76:79]
	v_mfma_f32_16x16x32_bf16 v[72:75], v[158:161], v[246:249], v[72:75]
	s_setprio 0
	s_setprio 1
	v_mfma_f32_16x16x32_bf16 v[116:119], v[162:165], v[198:201], v[116:119]
	v_mfma_f32_16x16x32_bf16 v[112:115], v[190:193], v[198:201], v[112:115]
	v_mfma_f32_16x16x32_bf16 v[100:103], v[162:165], v[206:209], v[100:103]
	v_mfma_f32_16x16x32_bf16 v[96:99], v[190:193], v[206:209], v[96:99]
	v_mfma_f32_16x16x32_bf16 v[84:87], v[162:165], v[214:217], v[84:87]
	v_mfma_f32_16x16x32_bf16 v[80:83], v[190:193], v[214:217], v[80:83]
	v_mfma_f32_16x16x32_bf16 v[68:71], v[162:165], v[242:245], v[68:71]
	v_mfma_f32_16x16x32_bf16 v[64:67], v[190:193], v[242:245], v[64:67]
	v_mfma_f32_16x16x32_bf16 v[116:119], v[186:189], v[202:205], v[116:119]
	v_mfma_f32_16x16x32_bf16 v[112:115], v[194:197], v[202:205], v[112:115]
	v_mfma_f32_16x16x32_bf16 v[100:103], v[186:189], v[210:213], v[100:103]
	v_mfma_f32_16x16x32_bf16 v[96:99], v[194:197], v[210:213], v[96:99]
	v_mfma_f32_16x16x32_bf16 v[84:87], v[186:189], v[218:221], v[84:87]
	v_mfma_f32_16x16x32_bf16 v[80:83], v[194:197], v[218:221], v[80:83]
	v_mfma_f32_16x16x32_bf16 v[68:71], v[186:189], v[246:249], v[68:71]
	v_mfma_f32_16x16x32_bf16 v[64:67], v[194:197], v[246:249], v[64:67]
	s_setprio 0
	s_barrier
	s_add_i32 s20, s69, s54
	v_lshl_add_u64 v[166:167], v[166:167], 0, s[28:29]
	s_mov_b32 m0, s20
	ds_read_b128 v[198:201], v145 offset:49152
	ds_read_b128 v[202:205], v145 offset:50176
	ds_read_b128 v[206:209], v145 offset:51200
	ds_read_b128 v[210:213], v145 offset:52224
	ds_read_b128 v[214:217], v145 offset:53248
	ds_read_b128 v[218:221], v145 offset:54272
	ds_read_b128 v[242:245], v145 offset:55296
	ds_read_b128 v[246:249], v145 offset:56320
	global_load_lds_dwordx4 v[166:167], off
	s_add_i32 m0, s20, 0x2000
	s_add_u32 s20, s26, 0x10080
	v_lshl_add_u64 v[166:167], v[222:223], 0, s[28:29]
	s_addc_u32 s21, s27, 0
	s_add_i32 s26, s70, s54
	global_load_lds_dwordx4 v[166:167], off
	v_lshl_add_u64 v[166:167], s[20:21], 0, v[128:129]
	s_mov_b32 m0, s26
	s_nop 0
	global_load_lds_dwordx4 v[166:167], off
	v_lshl_add_u64 v[166:167], s[20:21], 0, v[132:133]
	s_add_i32 m0, s26, 0x2000
	s_nop 0
	global_load_lds_dwordx4 v[166:167], off
	v_lshl_add_u64 v[166:167], v[236:237], 0, s[28:29]
	s_mov_b32 m0, s62
	s_nop 0
	global_load_lds_dwordx4 v[166:167], off
	v_lshl_add_u64 v[166:167], v[250:251], 0, s[28:29]
	s_mov_b32 m0, s63
	s_nop 0
	global_load_lds_dwordx4 v[166:167], off
	s_waitcnt vmcnt(8)
	s_waitcnt lgkmcnt(0)
	s_barrier
	s_setprio 1
	s_waitcnt lgkmcnt(0)
	v_mfma_f32_16x16x32_bf16 v[60:63], v[146:149], v[198:201], v[60:63]
	v_mfma_f32_16x16x32_bf16 v[56:59], v[154:157], v[198:201], v[56:59]
	v_mfma_f32_16x16x32_bf16 v[44:47], v[146:149], v[206:209], v[44:47]
	v_mfma_f32_16x16x32_bf16 v[40:43], v[154:157], v[206:209], v[40:43]
	v_mfma_f32_16x16x32_bf16 v[28:31], v[146:149], v[214:217], v[28:31]
	v_mfma_f32_16x16x32_bf16 v[24:27], v[154:157], v[214:217], v[24:27]
	v_mfma_f32_16x16x32_bf16 v[12:15], v[146:149], v[242:245], v[12:15]
	v_mfma_f32_16x16x32_bf16 v[8:11], v[154:157], v[242:245], v[8:11]
	v_mfma_f32_16x16x32_bf16 v[60:63], v[150:153], v[202:205], v[60:63]
	v_mfma_f32_16x16x32_bf16 v[56:59], v[158:161], v[202:205], v[56:59]
	v_mfma_f32_16x16x32_bf16 v[44:47], v[150:153], v[210:213], v[44:47]
	v_mfma_f32_16x16x32_bf16 v[40:43], v[158:161], v[210:213], v[40:43]
	v_mfma_f32_16x16x32_bf16 v[28:31], v[150:153], v[218:221], v[28:31]
	v_mfma_f32_16x16x32_bf16 v[24:27], v[158:161], v[218:221], v[24:27]
	v_mfma_f32_16x16x32_bf16 v[12:15], v[150:153], v[246:249], v[12:15]
	v_mfma_f32_16x16x32_bf16 v[8:11], v[158:161], v[246:249], v[8:11]
	s_setprio 0
	s_setprio 1
	v_mfma_f32_16x16x32_bf16 v[52:55], v[162:165], v[198:201], v[52:55]
	v_mfma_f32_16x16x32_bf16 v[48:51], v[190:193], v[198:201], v[48:51]
	v_mfma_f32_16x16x32_bf16 v[36:39], v[162:165], v[206:209], v[36:39]
	v_mfma_f32_16x16x32_bf16 v[32:35], v[190:193], v[206:209], v[32:35]
	v_mfma_f32_16x16x32_bf16 v[20:23], v[162:165], v[214:217], v[20:23]
	v_mfma_f32_16x16x32_bf16 v[16:19], v[190:193], v[214:217], v[16:19]
	v_mfma_f32_16x16x32_bf16 v[0:3], v[162:165], v[242:245], v[0:3]
	v_mfma_f32_16x16x32_bf16 v[4:7], v[190:193], v[242:245], v[4:7]
	v_mfma_f32_16x16x32_bf16 v[52:55], v[186:189], v[202:205], v[52:55]
	v_mfma_f32_16x16x32_bf16 v[48:51], v[194:197], v[202:205], v[48:51]
	v_mfma_f32_16x16x32_bf16 v[36:39], v[186:189], v[210:213], v[36:39]
	v_mfma_f32_16x16x32_bf16 v[32:35], v[194:197], v[210:213], v[32:35]
	v_mfma_f32_16x16x32_bf16 v[20:23], v[186:189], v[218:221], v[20:23]
	v_mfma_f32_16x16x32_bf16 v[16:19], v[194:197], v[218:221], v[16:19]
	v_mfma_f32_16x16x32_bf16 v[0:3], v[186:189], v[246:249], v[0:3]
	v_mfma_f32_16x16x32_bf16 v[4:7], v[194:197], v[246:249], v[4:7]
	s_setprio 0
	s_barrier
	s_cmp_ge_i32 s68, s59
	s_mov_b64 s[20:21], s[22:23]
	s_mov_b32 s26, s68
	s_mov_b32 s32, 0
	s_cbranch_scc0 .LBB0_537
	v_readlane_b32 s78, v254, 17
	v_readlane_b32 s79, v254, 18

.Lzc10_0:
	s_setprio 1
	s_waitcnt lgkmcnt(0)
	v_mfma_f32_16x16x32_bf16 v[124:127], v[144:147], v[194:197], 0
	v_mfma_f32_16x16x32_bf16 v[120:123], v[152:155], v[194:197], 0
	v_mfma_f32_16x16x32_bf16 v[108:111], v[144:147], v[202:205], 0
	v_mfma_f32_16x16x32_bf16 v[104:107], v[152:155], v[202:205], 0
	v_mfma_f32_16x16x32_bf16 v[92:95], v[144:147], v[210:213], 0
	v_mfma_f32_16x16x32_bf16 v[88:91], v[152:155], v[210:213], 0
	v_mfma_f32_16x16x32_bf16 v[76:79], v[144:147], v[218:221], 0
	v_mfma_f32_16x16x32_bf16 v[72:75], v[152:155], v[218:221], 0
	v_mfma_f32_16x16x32_bf16 v[124:127], v[148:151], v[198:201], v[124:127]
	v_mfma_f32_16x16x32_bf16 v[120:123], v[156:159], v[198:201], v[120:123]
	v_mfma_f32_16x16x32_bf16 v[108:111], v[148:151], v[206:209], v[108:111]
	v_mfma_f32_16x16x32_bf16 v[104:107], v[156:159], v[206:209], v[104:107]
	v_mfma_f32_16x16x32_bf16 v[92:95], v[148:151], v[214:217], v[92:95]
	v_mfma_f32_16x16x32_bf16 v[88:91], v[156:159], v[214:217], v[88:91]
	v_mfma_f32_16x16x32_bf16 v[76:79], v[148:151], v[242:245], v[76:79]
	v_mfma_f32_16x16x32_bf16 v[72:75], v[156:159], v[242:245], v[72:75]
	s_setprio 0
	s_setprio 1
	v_mfma_f32_16x16x32_bf16 v[116:119], v[160:163], v[194:197], 0
	v_mfma_f32_16x16x32_bf16 v[112:115], v[186:189], v[194:197], 0
	v_mfma_f32_16x16x32_bf16 v[100:103], v[160:163], v[202:205], 0
	v_mfma_f32_16x16x32_bf16 v[96:99], v[186:189], v[202:205], 0
	v_mfma_f32_16x16x32_bf16 v[84:87], v[160:163], v[210:213], 0
	v_mfma_f32_16x16x32_bf16 v[80:83], v[186:189], v[210:213], 0
	v_mfma_f32_16x16x32_bf16 v[68:71], v[160:163], v[218:221], 0
	v_mfma_f32_16x16x32_bf16 v[64:67], v[186:189], v[218:221], 0
	v_mfma_f32_16x16x32_bf16 v[116:119], v[164:167], v[198:201], v[116:119]
	v_mfma_f32_16x16x32_bf16 v[112:115], v[190:193], v[198:201], v[112:115]
	v_mfma_f32_16x16x32_bf16 v[100:103], v[164:167], v[206:209], v[100:103]
	v_mfma_f32_16x16x32_bf16 v[96:99], v[190:193], v[206:209], v[96:99]
	v_mfma_f32_16x16x32_bf16 v[84:87], v[164:167], v[214:217], v[84:87]
	v_mfma_f32_16x16x32_bf16 v[80:83], v[190:193], v[214:217], v[80:83]
	v_mfma_f32_16x16x32_bf16 v[68:71], v[164:167], v[242:245], v[68:71]
	v_mfma_f32_16x16x32_bf16 v[64:67], v[190:193], v[242:245], v[64:67]
	s_setprio 0
	s_branch .Lzc10_0j
.Lzc10_1:
	s_setprio 1
	s_waitcnt lgkmcnt(0)
	v_mfma_f32_16x16x32_bf16 v[60:63], v[144:147], v[194:197], 0
	v_mfma_f32_16x16x32_bf16 v[56:59], v[152:155], v[194:197], 0
	v_mfma_f32_16x16x32_bf16 v[44:47], v[144:147], v[202:205], 0
	v_mfma_f32_16x16x32_bf16 v[40:43], v[152:155], v[202:205], 0
	v_mfma_f32_16x16x32_bf16 v[28:31], v[144:147], v[210:213], 0
	v_mfma_f32_16x16x32_bf16 v[24:27], v[152:155], v[210:213], 0
	v_mfma_f32_16x16x32_bf16 v[12:15], v[144:147], v[218:221], 0
	v_mfma_f32_16x16x32_bf16 v[8:11], v[152:155], v[218:221], 0
	v_mfma_f32_16x16x32_bf16 v[60:63], v[148:151], v[198:201], v[60:63]
	v_mfma_f32_16x16x32_bf16 v[56:59], v[156:159], v[198:201], v[56:59]
	v_mfma_f32_16x16x32_bf16 v[44:47], v[148:151], v[206:209], v[44:47]
	v_mfma_f32_16x16x32_bf16 v[40:43], v[156:159], v[206:209], v[40:43]
	v_mfma_f32_16x16x32_bf16 v[28:31], v[148:151], v[214:217], v[28:31]
	v_mfma_f32_16x16x32_bf16 v[24:27], v[156:159], v[214:217], v[24:27]
	v_mfma_f32_16x16x32_bf16 v[12:15], v[148:151], v[242:245], v[12:15]
	v_mfma_f32_16x16x32_bf16 v[8:11], v[156:159], v[242:245], v[8:11]
	s_setprio 0
	s_setprio 1
	v_mfma_f32_16x16x32_bf16 v[52:55], v[160:163], v[194:197], 0
	v_mfma_f32_16x16x32_bf16 v[48:51], v[186:189], v[194:197], 0
	v_mfma_f32_16x16x32_bf16 v[36:39], v[160:163], v[202:205], 0
	v_mfma_f32_16x16x32_bf16 v[32:35], v[186:189], v[202:205], 0
	v_mfma_f32_16x16x32_bf16 v[20:23], v[160:163], v[210:213], 0
	v_mfma_f32_16x16x32_bf16 v[16:19], v[186:189], v[210:213], 0
	v_mfma_f32_16x16x32_bf16 v[4:7], v[160:163], v[218:221], 0
	v_mfma_f32_16x16x32_bf16 v[0:3], v[186:189], v[218:221], 0
	v_mfma_f32_16x16x32_bf16 v[52:55], v[164:167], v[198:201], v[52:55]
	v_mfma_f32_16x16x32_bf16 v[48:51], v[190:193], v[198:201], v[48:51]
	v_mfma_f32_16x16x32_bf16 v[36:39], v[164:167], v[206:209], v[36:39]
	v_mfma_f32_16x16x32_bf16 v[32:35], v[190:193], v[206:209], v[32:35]
	v_mfma_f32_16x16x32_bf16 v[20:23], v[164:167], v[214:217], v[20:23]
	v_mfma_f32_16x16x32_bf16 v[16:19], v[190:193], v[214:217], v[16:19]
	v_mfma_f32_16x16x32_bf16 v[4:7], v[164:167], v[242:245], v[4:7]
	v_mfma_f32_16x16x32_bf16 v[0:3], v[190:193], v[242:245], v[0:3]
	s_setprio 0
	s_branch .Lzc10_1j

.LBB0_572:
	s_ashr_i32 s43, s42, 31
	s_ashr_i32 s45, s44, 31
	s_lshl_b64 s[46:47], s[44:45], 18
	s_lshl_b64 s[48:49], s[42:43], 22
	s_add_u32 s3, s78, s48
	s_addc_u32 s21, s79, s49
	s_add_u32 s46, s3, s46
	s_addc_u32 s47, s21, s47
	s_ashr_i32 s3, s67, 31
	s_add_u32 s48, s67, s42
	s_addc_u32 s49, s3, s43
	s_lshl_b64 s[48:49], s[48:49], 18
	s_add_u32 s48, s52, s48
	s_addc_u32 s49, s53, s49
	s_andn2_b64 vcc, exec, s[24:25]
	s_cbranch_vccnz .Lzc10_skip
	s_and_b64 s[50:51], s[38:39], exec
	s_cselect_b32 s3, s47, s23
	s_cselect_b32 s21, s46, s22
	s_cselect_b32 s43, s49, s27
	s_cselect_b32 s45, s48, s26
	s_add_u32 s22, s22, 0x20080
	s_addc_u32 s23, s23, 0
	s_add_u32 s68, s26, 0x100
	s_addc_u32 s69, s27, 0
	s_mov_b32 s26, 0
	s_mov_b32 s32, 1
.LBB0_574:
	s_add_i32 s70, s26, 2
	s_add_u32 s27, s22, 0xfffe0080
	s_addc_u32 s50, s23, -1
	s_add_i32 s71, 0, 0x10000
	s_cmp_eq_u32 s64, s26
	s_cselect_b32 s51, s3, s50
	s_cselect_b32 s50, s21, s27
	s_cselect_b32 s27, s43, s69
	s_cselect_b32 s26, s45, s68
	s_add_i32 s74, 0, 0x14000
	v_add_u32_e32 v156, s71, v142
	v_add_u32_e32 v168, s74, v142
	ds_read_b128 v[144:147], v156
	ds_read_b128 v[148:151], v156 offset:1024
	ds_read_b128 v[152:155], v156 offset:2048
	ds_read_b128 v[156:159], v156 offset:3072
	ds_read_b128 v[160:163], v168
	ds_read_b128 v[164:167], v168 offset:1024
	ds_read_b128 v[186:189], v168 offset:2048
	ds_read_b128 v[190:193], v168 offset:3072
	v_lshl_add_u64 v[222:223], s[22:23], 0, v[136:137]
	s_add_i32 m0, s55, 0xc000
	ds_read_b128 v[194:197], v143
	ds_read_b128 v[198:201], v143 offset:1024
	ds_read_b128 v[202:205], v143 offset:2048
	ds_read_b128 v[206:209], v143 offset:3072
	ds_read_b128 v[210:213], v143 offset:4096
	ds_read_b128 v[214:217], v143 offset:5120
	ds_read_b128 v[218:221], v143 offset:6144
	ds_read_b128 v[242:245], v143 offset:7168
	global_load_lds_dwordx4 v[222:223], off
	v_lshl_add_u64 v[222:223], s[22:23], 0, v[138:139]
	s_add_i32 m0, s55, 0xe000
	s_nop 0
	global_load_lds_dwordx4 v[222:223], off
	s_waitcnt vmcnt(8)
	s_waitcnt lgkmcnt(0)
	s_barrier
	s_cmp_lg_u32 s32, 0
	s_cbranch_scc1 .Lzc10_0
	s_setprio 1
	s_waitcnt lgkmcnt(0)
	v_mfma_f32_16x16x32_bf16 v[124:127], v[144:147], v[194:197], v[124:127]
	v_mfma_f32_16x16x32_bf16 v[120:123], v[152:155], v[194:197], v[120:123]
	v_mfma_f32_16x16x32_bf16 v[108:111], v[144:147], v[202:205], v[108:111]
	v_mfma_f32_16x16x32_bf16 v[104:107], v[152:155], v[202:205], v[104:107]
	v_mfma_f32_16x16x32_bf16 v[92:95], v[144:147], v[210:213], v[92:95]
	v_mfma_f32_16x16x32_bf16 v[88:91], v[152:155], v[210:213], v[88:91]
	v_mfma_f32_16x16x32_bf16 v[76:79], v[144:147], v[218:221], v[76:79]
	v_mfma_f32_16x16x32_bf16 v[72:75], v[152:155], v[218:221], v[72:75]
	v_mfma_f32_16x16x32_bf16 v[124:127], v[148:151], v[198:201], v[124:127]
	v_mfma_f32_16x16x32_bf16 v[120:123], v[156:159], v[198:201], v[120:123]
	v_mfma_f32_16x16x32_bf16 v[108:111], v[148:151], v[206:209], v[108:111]
	v_mfma_f32_16x16x32_bf16 v[104:107], v[156:159], v[206:209], v[104:107]
	v_mfma_f32_16x16x32_bf16 v[92:95], v[148:151], v[214:217], v[92:95]
	v_mfma_f32_16x16x32_bf16 v[88:91], v[156:159], v[214:217], v[88:91]
	v_mfma_f32_16x16x32_bf16 v[76:79], v[148:151], v[242:245], v[76:79]
	v_mfma_f32_16x16x32_bf16 v[72:75], v[156:159], v[242:245], v[72:75]
	s_setprio 0
	s_setprio 1
	v_mfma_f32_16x16x32_bf16 v[116:119], v[160:163], v[194:197], v[116:119]
	v_mfma_f32_16x16x32_bf16 v[112:115], v[186:189], v[194:197], v[112:115]
	v_mfma_f32_16x16x32_bf16 v[100:103], v[160:163], v[202:205], v[100:103]
	v_mfma_f32_16x16x32_bf16 v[96:99], v[186:189], v[202:205], v[96:99]
	v_mfma_f32_16x16x32_bf16 v[84:87], v[160:163], v[210:213], v[84:87]
	v_mfma_f32_16x16x32_bf16 v[80:83], v[186:189], v[210:213], v[80:83]
	v_mfma_f32_16x16x32_bf16 v[68:71], v[160:163], v[218:221], v[68:71]
	v_mfma_f32_16x16x32_bf16 v[64:67], v[186:189], v[218:221], v[64:67]
	v_mfma_f32_16x16x32_bf16 v[116:119], v[164:167], v[198:201], v[116:119]
	v_mfma_f32_16x16x32_bf16 v[112:115], v[190:193], v[198:201], v[112:115]
	v_mfma_f32_16x16x32_bf16 v[100:103], v[164:167], v[206:209], v[100:103]
	v_mfma_f32_16x16x32_bf16 v[96:99], v[190:193], v[206:209], v[96:99]
	v_mfma_f32_16x16x32_bf16 v[84:87], v[164:167], v[214:217], v[84:87]
	v_mfma_f32_16x16x32_bf16 v[80:83], v[190:193], v[214:217], v[80:83]
	v_mfma_f32_16x16x32_bf16 v[68:71], v[164:167], v[242:245], v[68:71]
	v_mfma_f32_16x16x32_bf16 v[64:67], v[190:193], v[242:245], v[64:67]
	s_setprio 0
.Lzc10_0j:
	s_barrier
	s_add_i32 s71, s71, s54
	v_lshl_add_u64 v[222:223], s[26:27], 0, v[130:131]
	s_mov_b32 m0, s71
	ds_read_b128 v[194:197], v143 offset:16384
	ds_read_b128 v[198:201], v143 offset:17408
	ds_read_b128 v[202:205], v143 offset:18432
	ds_read_b128 v[206:209], v143 offset:19456
	ds_read_b128 v[210:213], v143 offset:20480
	ds_read_b128 v[214:217], v143 offset:21504
	ds_read_b128 v[218:221], v143 offset:22528
	ds_read_b128 v[242:245], v143 offset:23552
	global_load_lds_dwordx4 v[222:223], off
	s_add_i32 m0, s71, 0x2000
	s_add_u32 s72, s26, 0x20000
	v_lshl_add_u64 v[236:237], s[26:27], 0, v[134:135]
	s_addc_u32 s73, s27, 0
	s_add_i32 s71, s74, s54
	global_load_lds_dwordx4 v[236:237], off
	v_lshl_add_u64 v[246:247], s[72:73], 0, v[130:131]
	s_mov_b32 m0, s71
	v_lshl_add_u64 v[248:249], s[50:51], 0, v[132:133]
	global_load_lds_dwordx4 v[246:247], off
	v_lshl_add_u64 v[246:247], s[72:73], 0, v[134:135]
	s_add_i32 m0, s71, 0x2000
	s_nop 0
	global_load_lds_dwordx4 v[246:247], off
	v_lshl_add_u64 v[246:247], s[50:51], 0, v[128:129]
	s_mov_b32 m0, s55
	s_nop 0
	global_load_lds_dwordx4 v[246:247], off
	s_mov_b32 m0, s56
	s_nop 0
	global_load_lds_dwordx4 v[248:249], off
	s_waitcnt vmcnt(8)
	s_waitcnt lgkmcnt(0)
	s_barrier
	s_cmp_lg_u32 s32, 0
	s_cbranch_scc1 .Lzc10_1
	s_setprio 1
	s_waitcnt lgkmcnt(0)
	v_mfma_f32_16x16x32_bf16 v[60:63], v[144:147], v[194:197], v[60:63]
	v_mfma_f32_16x16x32_bf16 v[56:59], v[152:155], v[194:197], v[56:59]
	v_mfma_f32_16x16x32_bf16 v[44:47], v[144:147], v[202:205], v[44:47]
	v_mfma_f32_16x16x32_bf16 v[40:43], v[152:155], v[202:205], v[40:43]
	v_mfma_f32_16x16x32_bf16 v[28:31], v[144:147], v[210:213], v[28:31]
	v_mfma_f32_16x16x32_bf16 v[24:27], v[152:155], v[210:213], v[24:27]
	v_mfma_f32_16x16x32_bf16 v[12:15], v[144:147], v[218:221], v[12:15]
	v_mfma_f32_16x16x32_bf16 v[8:11], v[152:155], v[218:221], v[8:11]
	v_mfma_f32_16x16x32_bf16 v[60:63], v[148:151], v[198:201], v[60:63]
	v_mfma_f32_16x16x32_bf16 v[56:59], v[156:159], v[198:201], v[56:59]
	v_mfma_f32_16x16x32_bf16 v[44:47], v[148:151], v[206:209], v[44:47]
	v_mfma_f32_16x16x32_bf16 v[40:43], v[156:159], v[206:209], v[40:43]
	v_mfma_f32_16x16x32_bf16 v[28:31], v[148:151], v[214:217], v[28:31]
	v_mfma_f32_16x16x32_bf16 v[24:27], v[156:159], v[214:217], v[24:27]
	v_mfma_f32_16x16x32_bf16 v[12:15], v[148:151], v[242:245], v[12:15]
	v_mfma_f32_16x16x32_bf16 v[8:11], v[156:159], v[242:245], v[8:11]
	s_setprio 0
	s_setprio 1
	v_mfma_f32_16x16x32_bf16 v[52:55], v[160:163], v[194:197], v[52:55]
	v_mfma_f32_16x16x32_bf16 v[48:51], v[186:189], v[194:197], v[48:51]
	v_mfma_f32_16x16x32_bf16 v[36:39], v[160:163], v[202:205], v[36:39]
	v_mfma_f32_16x16x32_bf16 v[32:35], v[186:189], v[202:205], v[32:35]
	v_mfma_f32_16x16x32_bf16 v[20:23], v[160:163], v[210:213], v[20:23]
	v_mfma_f32_16x16x32_bf16 v[16:19], v[186:189], v[210:213], v[16:19]
	v_mfma_f32_16x16x32_bf16 v[4:7], v[160:163], v[218:221], v[4:7]
	v_mfma_f32_16x16x32_bf16 v[0:3], v[186:189], v[218:221], v[0:3]
	v_mfma_f32_16x16x32_bf16 v[52:55], v[164:167], v[198:201], v[52:55]
	v_mfma_f32_16x16x32_bf16 v[48:51], v[190:193], v[198:201], v[48:51]
	v_mfma_f32_16x16x32_bf16 v[36:39], v[164:167], v[206:209], v[36:39]
	v_mfma_f32_16x16x32_bf16 v[32:35], v[190:193], v[206:209], v[32:35]
	v_mfma_f32_16x16x32_bf16 v[20:23], v[164:167], v[214:217], v[20:23]
	v_mfma_f32_16x16x32_bf16 v[16:19], v[190:193], v[214:217], v[16:19]
	v_mfma_f32_16x16x32_bf16 v[4:7], v[164:167], v[242:245], v[4:7]
	v_mfma_f32_16x16x32_bf16 v[0:3], v[190:193], v[242:245], v[0:3]
	s_setprio 0
.Lzc10_1j:
	s_barrier
	s_add_i32 s71, 0, 0x18000
	s_add_i32 s72, 0, 0x1c000
	v_add_u32_e32 v156, s71, v142
	v_add_u32_e32 v168, s72, v142
	ds_read_b128 v[144:147], v156
	ds_read_b128 v[148:151], v156 offset:1024
	ds_read_b128 v[152:155], v156 offset:2048
	ds_read_b128 v[156:159], v156 offset:3072
	ds_read_b128 v[160:163], v168
	ds_read_b128 v[164:167], v168 offset:1024
	ds_read_b128 v[186:189], v168 offset:2048
	ds_read_b128 v[190:193], v168 offset:3072
	s_add_u32 s50, s50, 0x20000
	s_addc_u32 s51, s51, 0
	s_mov_b32 m0, s57
	v_lshl_add_u64 v[250:251], s[50:51], 0, v[128:129]
	ds_read_b128 v[194:197], v143 offset:32768
	ds_read_b128 v[198:201], v143 offset:33792
	ds_read_b128 v[202:205], v143 offset:34816
	ds_read_b128 v[206:209], v143 offset:35840
	ds_read_b128 v[210:213], v143 offset:36864
	ds_read_b128 v[214:217], v143 offset:37888
	ds_read_b128 v[218:221], v143 offset:38912
	ds_read_b128 v[242:245], v143 offset:39936
	global_load_lds_dwordx4 v[250:251], off
	v_lshl_add_u64 v[250:251], s[50:51], 0, v[132:133]
	s_mov_b32 m0, s58
	s_nop 0
	global_load_lds_dwordx4 v[250:251], off
	s_waitcnt vmcnt(8)
	s_waitcnt lgkmcnt(0)
	s_barrier
	s_setprio 1
	s_waitcnt lgkmcnt(0)
	v_mfma_f32_16x16x32_bf16 v[124:127], v[144:147], v[194:197], v[124:127]
	v_mfma_f32_16x16x32_bf16 v[120:123], v[152:155], v[194:197], v[120:123]
	v_mfma_f32_16x16x32_bf16 v[108:111], v[144:147], v[202:205], v[108:111]
	v_mfma_f32_16x16x32_bf16 v[104:107], v[152:155], v[202:205], v[104:107]
	v_mfma_f32_16x16x32_bf16 v[92:95], v[144:147], v[210:213], v[92:95]
	v_mfma_f32_16x16x32_bf16 v[88:91], v[152:155], v[210:213], v[88:91]
	v_mfma_f32_16x16x32_bf16 v[76:79], v[144:147], v[218:221], v[76:79]
	v_mfma_f32_16x16x32_bf16 v[72:75], v[152:155], v[218:221], v[72:75]
	v_mfma_f32_16x16x32_bf16 v[124:127], v[148:151], v[198:201], v[124:127]
	v_mfma_f32_16x16x32_bf16 v[120:123], v[156:159], v[198:201], v[120:123]
	v_mfma_f32_16x16x32_bf16 v[108:111], v[148:151], v[206:209], v[108:111]
	v_mfma_f32_16x16x32_bf16 v[104:107], v[156:159], v[206:209], v[104:107]
	v_mfma_f32_16x16x32_bf16 v[92:95], v[148:151], v[214:217], v[92:95]
	v_mfma_f32_16x16x32_bf16 v[88:91], v[156:159], v[214:217], v[88:91]
	v_mfma_f32_16x16x32_bf16 v[76:79], v[148:151], v[242:245], v[76:79]
	v_mfma_f32_16x16x32_bf16 v[72:75], v[156:159], v[242:245], v[72:75]
	s_setprio 0
	s_setprio 1
	v_mfma_f32_16x16x32_bf16 v[116:119], v[160:163], v[194:197], v[116:119]
	v_mfma_f32_16x16x32_bf16 v[112:115], v[186:189], v[194:197], v[112:115]
	v_mfma_f32_16x16x32_bf16 v[100:103], v[160:163], v[202:205], v[100:103]
	v_mfma_f32_16x16x32_bf16 v[96:99], v[186:189], v[202:205], v[96:99]
	v_mfma_f32_16x16x32_bf16 v[84:87], v[160:163], v[210:213], v[84:87]
	v_mfma_f32_16x16x32_bf16 v[80:83], v[186:189], v[210:213], v[80:83]
	v_mfma_f32_16x16x32_bf16 v[68:71], v[160:163], v[218:221], v[68:71]
	v_mfma_f32_16x16x32_bf16 v[64:67], v[186:189], v[218:221], v[64:67]
	v_mfma_f32_16x16x32_bf16 v[116:119], v[164:167], v[198:201], v[116:119]
	v_mfma_f32_16x16x32_bf16 v[112:115], v[190:193], v[198:201], v[112:115]
	v_mfma_f32_16x16x32_bf16 v[100:103], v[164:167], v[206:209], v[100:103]
	v_mfma_f32_16x16x32_bf16 v[96:99], v[190:193], v[206:209], v[96:99]
	v_mfma_f32_16x16x32_bf16 v[84:87], v[164:167], v[214:217], v[84:87]
	v_mfma_f32_16x16x32_bf16 v[80:83], v[190:193], v[214:217], v[80:83]
	v_mfma_f32_16x16x32_bf16 v[68:71], v[164:167], v[242:245], v[68:71]
	v_mfma_f32_16x16x32_bf16 v[64:67], v[190:193], v[242:245], v[64:67]
	s_setprio 0
	s_barrier
	s_add_i32 s50, s71, s54
	v_lshl_add_u64 v[222:223], v[222:223], 0, s[28:29]
	s_mov_b32 m0, s50
	ds_read_b128 v[194:197], v143 offset:49152
	ds_read_b128 v[198:201], v143 offset:50176
	ds_read_b128 v[202:205], v143 offset:51200
	ds_read_b128 v[206:209], v143 offset:52224
	ds_read_b128 v[210:213], v143 offset:53248
	ds_read_b128 v[214:217], v143 offset:54272
	ds_read_b128 v[218:221], v143 offset:55296
	ds_read_b128 v[242:245], v143 offset:56320
	global_load_lds_dwordx4 v[222:223], off
	s_add_i32 m0, s50, 0x2000
	s_add_u32 s26, s26, 0x20080
	v_lshl_add_u64 v[222:223], v[236:237], 0, s[28:29]
	s_addc_u32 s27, s27, 0
	s_add_i32 s50, s72, s54
	global_load_lds_dwordx4 v[222:223], off
	v_lshl_add_u64 v[222:223], s[26:27], 0, v[130:131]
	s_mov_b32 m0, s50
	s_nop 0
	global_load_lds_dwordx4 v[222:223], off
	v_lshl_add_u64 v[222:223], s[26:27], 0, v[134:135]
	s_add_i32 m0, s50, 0x2000
	s_nop 0
	global_load_lds_dwordx4 v[222:223], off
	v_lshl_add_u64 v[222:223], v[246:247], 0, s[28:29]
	s_mov_b32 m0, s62
	s_nop 0
	global_load_lds_dwordx4 v[222:223], off
	v_lshl_add_u64 v[222:223], v[248:249], 0, s[28:29]
	s_mov_b32 m0, s63
	s_nop 0
	global_load_lds_dwordx4 v[222:223], off
	s_waitcnt vmcnt(8)
	s_waitcnt lgkmcnt(0)
	s_barrier
	s_setprio 1
	s_waitcnt lgkmcnt(0)
	v_mfma_f32_16x16x32_bf16 v[60:63], v[144:147], v[194:197], v[60:63]
	v_mfma_f32_16x16x32_bf16 v[56:59], v[152:155], v[194:197], v[56:59]
	v_mfma_f32_16x16x32_bf16 v[44:47], v[144:147], v[202:205], v[44:47]
	v_mfma_f32_16x16x32_bf16 v[40:43], v[152:155], v[202:205], v[40:43]
	v_mfma_f32_16x16x32_bf16 v[28:31], v[144:147], v[210:213], v[28:31]
	v_mfma_f32_16x16x32_bf16 v[24:27], v[152:155], v[210:213], v[24:27]
	v_mfma_f32_16x16x32_bf16 v[12:15], v[144:147], v[218:221], v[12:15]
	v_mfma_f32_16x16x32_bf16 v[8:11], v[152:155], v[218:221], v[8:11]
	v_mfma_f32_16x16x32_bf16 v[60:63], v[148:151], v[198:201], v[60:63]
	v_mfma_f32_16x16x32_bf16 v[56:59], v[156:159], v[198:201], v[56:59]
	v_mfma_f32_16x16x32_bf16 v[44:47], v[148:151], v[206:209], v[44:47]
	v_mfma_f32_16x16x32_bf16 v[40:43], v[156:159], v[206:209], v[40:43]
	v_mfma_f32_16x16x32_bf16 v[28:31], v[148:151], v[214:217], v[28:31]
	v_mfma_f32_16x16x32_bf16 v[24:27], v[156:159], v[214:217], v[24:27]
	v_mfma_f32_16x16x32_bf16 v[12:15], v[148:151], v[242:245], v[12:15]
	v_mfma_f32_16x16x32_bf16 v[8:11], v[156:159], v[242:245], v[8:11]
	s_setprio 0
	s_setprio 1
	v_mfma_f32_16x16x32_bf16 v[52:55], v[160:163], v[194:197], v[52:55]
	v_mfma_f32_16x16x32_bf16 v[48:51], v[186:189], v[194:197], v[48:51]
	v_mfma_f32_16x16x32_bf16 v[36:39], v[160:163], v[202:205], v[36:39]
	v_mfma_f32_16x16x32_bf16 v[32:35], v[186:189], v[202:205], v[32:35]
	v_mfma_f32_16x16x32_bf16 v[20:23], v[160:163], v[210:213], v[20:23]
	v_mfma_f32_16x16x32_bf16 v[16:19], v[186:189], v[210:213], v[16:19]
	v_mfma_f32_16x16x32_bf16 v[4:7], v[160:163], v[218:221], v[4:7]
	v_mfma_f32_16x16x32_bf16 v[0:3], v[186:189], v[218:221], v[0:3]
	v_mfma_f32_16x16x32_bf16 v[52:55], v[164:167], v[198:201], v[52:55]
	v_mfma_f32_16x16x32_bf16 v[48:51], v[190:193], v[198:201], v[48:51]
	v_mfma_f32_16x16x32_bf16 v[36:39], v[164:167], v[206:209], v[36:39]
	v_mfma_f32_16x16x32_bf16 v[32:35], v[190:193], v[206:209], v[32:35]
	v_mfma_f32_16x16x32_bf16 v[20:23], v[164:167], v[214:217], v[20:23]
	v_mfma_f32_16x16x32_bf16 v[16:19], v[190:193], v[214:217], v[16:19]
	v_mfma_f32_16x16x32_bf16 v[4:7], v[164:167], v[242:245], v[4:7]
	v_mfma_f32_16x16x32_bf16 v[0:3], v[190:193], v[242:245], v[0:3]
	s_setprio 0
	s_barrier
	s_add_u32 s22, s22, 0x100
	s_addc_u32 s23, s23, 0
	s_add_u32 s68, s68, 0x100
	s_addc_u32 s69, s69, 0
	s_cmp_ge_i32 s70, s59
	s_mov_b32 s26, s70
	s_mov_b32 s32, 0
	s_cbranch_scc0 .LBB0_574

.LBB0_628:
	s_andn2_b64 vcc, exec, s[20:21]
	s_cbranch_vccnz .Lzc11_skip
	s_add_u32 s0, s50, 0x20080
	s_addc_u32 s1, s51, 0
	s_add_u32 s3, s48, 0x100
	s_addc_u32 s27, s49, 0
	s_mov_b32 s41, 0
	s_mov_b32 s32, 1
.LBB0_630:
	s_add_i32 s70, s41, 2
	s_add_u32 s48, s0, 0xfffe0080
	s_addc_u32 s49, s1, -1
	s_add_i32 s71, 0, 0x10000
	s_cmp_eq_u32 s64, s41
	s_cselect_b32 s51, s43, s49
	s_cselect_b32 s50, s42, s48
	s_cselect_b32 s49, s45, s27
	s_cselect_b32 s48, s44, s3
	s_add_i32 s41, 0, 0x14000
	v_add_u32_e32 v154, s71, v148
	v_add_u32_e32 v166, s41, v148
	ds_read_b128 v[138:141], v154
	ds_read_b128 v[142:145], v154 offset:1024
	ds_read_b128 v[150:153], v154 offset:2048
	ds_read_b128 v[154:157], v154 offset:3072
	ds_read_b128 v[158:161], v166
	ds_read_b128 v[162:165], v166 offset:1024
	ds_read_b128 v[186:189], v166 offset:2048
	ds_read_b128 v[190:193], v166 offset:3072
	v_lshl_add_u64 v[166:167], s[0:1], 0, v[134:135]
	s_add_i32 m0, s47, 0xc000
	ds_read_b128 v[194:197], v149
	ds_read_b128 v[198:201], v149 offset:1024
	ds_read_b128 v[202:205], v149 offset:2048
	ds_read_b128 v[206:209], v149 offset:3072
	ds_read_b128 v[210:213], v149 offset:4096
	ds_read_b128 v[214:217], v149 offset:5120
	ds_read_b128 v[218:221], v149 offset:6144
	ds_read_b128 v[242:245], v149 offset:7168
	global_load_lds_dwordx4 v[166:167], off
	v_lshl_add_u64 v[166:167], s[0:1], 0, v[136:137]
	s_add_i32 m0, s47, 0xe000
	s_nop 0
	global_load_lds_dwordx4 v[166:167], off
	s_waitcnt vmcnt(8)
	s_waitcnt lgkmcnt(0)
	s_barrier
	s_cmp_lg_u32 s32, 0
	s_cbranch_scc1 .Lzc11_0
	s_setprio 1
	s_waitcnt lgkmcnt(0)
	v_mfma_f32_16x16x32_bf16 v[124:127], v[138:141], v[194:197], v[124:127]
	v_mfma_f32_16x16x32_bf16 v[120:123], v[150:153], v[194:197], v[120:123]
	v_mfma_f32_16x16x32_bf16 v[108:111], v[138:141], v[202:205], v[108:111]
	v_mfma_f32_16x16x32_bf16 v[104:107], v[150:153], v[202:205], v[104:107]
	v_mfma_f32_16x16x32_bf16 v[92:95], v[138:141], v[210:213], v[92:95]
	v_mfma_f32_16x16x32_bf16 v[88:91], v[150:153], v[210:213], v[88:91]
	v_mfma_f32_16x16x32_bf16 v[76:79], v[138:141], v[218:221], v[76:79]
	v_mfma_f32_16x16x32_bf16 v[72:75], v[150:153], v[218:221], v[72:75]
	v_mfma_f32_16x16x32_bf16 v[124:127], v[142:145], v[198:201], v[124:127]
	v_mfma_f32_16x16x32_bf16 v[120:123], v[154:157], v[198:201], v[120:123]
	v_mfma_f32_16x16x32_bf16 v[108:111], v[142:145], v[206:209], v[108:111]
	v_mfma_f32_16x16x32_bf16 v[104:107], v[154:157], v[206:209], v[104:107]
	v_mfma_f32_16x16x32_bf16 v[92:95], v[142:145], v[214:217], v[92:95]
	v_mfma_f32_16x16x32_bf16 v[88:91], v[154:157], v[214:217], v[88:91]
	v_mfma_f32_16x16x32_bf16 v[76:79], v[142:145], v[242:245], v[76:79]
	v_mfma_f32_16x16x32_bf16 v[72:75], v[154:157], v[242:245], v[72:75]
	s_setprio 0
	s_setprio 1
	v_mfma_f32_16x16x32_bf16 v[116:119], v[158:161], v[194:197], v[116:119]
	v_mfma_f32_16x16x32_bf16 v[112:115], v[186:189], v[194:197], v[112:115]
	v_mfma_f32_16x16x32_bf16 v[100:103], v[158:161], v[202:205], v[100:103]
	v_mfma_f32_16x16x32_bf16 v[96:99], v[186:189], v[202:205], v[96:99]
	v_mfma_f32_16x16x32_bf16 v[84:87], v[158:161], v[210:213], v[84:87]
	v_mfma_f32_16x16x32_bf16 v[80:83], v[186:189], v[210:213], v[80:83]
	v_mfma_f32_16x16x32_bf16 v[68:71], v[158:161], v[218:221], v[68:71]
	v_mfma_f32_16x16x32_bf16 v[64:67], v[186:189], v[218:221], v[64:67]
	v_mfma_f32_16x16x32_bf16 v[116:119], v[162:165], v[198:201], v[116:119]
	v_mfma_f32_16x16x32_bf16 v[112:115], v[190:193], v[198:201], v[112:115]
	v_mfma_f32_16x16x32_bf16 v[100:103], v[162:165], v[206:209], v[100:103]
	v_mfma_f32_16x16x32_bf16 v[96:99], v[190:193], v[206:209], v[96:99]
	v_mfma_f32_16x16x32_bf16 v[84:87], v[162:165], v[214:217], v[84:87]
	v_mfma_f32_16x16x32_bf16 v[80:83], v[190:193], v[214:217], v[80:83]
	v_mfma_f32_16x16x32_bf16 v[68:71], v[162:165], v[242:245], v[68:71]
	v_mfma_f32_16x16x32_bf16 v[64:67], v[190:193], v[242:245], v[64:67]
	s_setprio 0
.Lzc11_0j:
	s_barrier
	s_add_i32 s71, s71, s53
	v_lshl_add_u64 v[166:167], s[48:49], 0, v[168:169]
	s_mov_b32 m0, s71
	ds_read_b128 v[194:197], v149 offset:16384
	ds_read_b128 v[198:201], v149 offset:17408
	ds_read_b128 v[202:205], v149 offset:18432
	ds_read_b128 v[206:209], v149 offset:19456
	ds_read_b128 v[210:213], v149 offset:20480
	ds_read_b128 v[214:217], v149 offset:21504
	ds_read_b128 v[218:221], v149 offset:22528
	ds_read_b128 v[242:245], v149 offset:23552
	global_load_lds_dwordx4 v[166:167], off
	s_add_i32 m0, s71, 0x2000
	s_add_u32 s72, s48, 0x10000
	v_lshl_add_u64 v[222:223], s[48:49], 0, v[132:133]
	s_addc_u32 s73, s49, 0
	s_add_i32 s41, s41, s53
	global_load_lds_dwordx4 v[222:223], off
	v_lshl_add_u64 v[236:237], s[72:73], 0, v[168:169]
	s_mov_b32 m0, s41
	v_lshl_add_u64 v[246:247], s[50:51], 0, v[130:131]
	global_load_lds_dwordx4 v[236:237], off
	v_lshl_add_u64 v[236:237], s[72:73], 0, v[132:133]
	s_add_i32 m0, s41, 0x2000
	s_nop 0
	global_load_lds_dwordx4 v[236:237], off
	v_lshl_add_u64 v[236:237], s[50:51], 0, v[128:129]
	s_mov_b32 m0, s47
	s_nop 0
	global_load_lds_dwordx4 v[236:237], off
	s_mov_b32 m0, s54
	s_nop 0
	global_load_lds_dwordx4 v[246:247], off
	s_waitcnt vmcnt(8)
	s_waitcnt lgkmcnt(0)
	s_barrier
	s_cmp_lg_u32 s32, 0
	s_cbranch_scc1 .Lzc11_1
	s_setprio 1
	s_waitcnt lgkmcnt(0)
	v_mfma_f32_16x16x32_bf16 v[60:63], v[138:141], v[194:197], v[60:63]
	v_mfma_f32_16x16x32_bf16 v[56:59], v[150:153], v[194:197], v[56:59]
	v_mfma_f32_16x16x32_bf16 v[44:47], v[138:141], v[202:205], v[44:47]
	v_mfma_f32_16x16x32_bf16 v[40:43], v[150:153], v[202:205], v[40:43]
	v_mfma_f32_16x16x32_bf16 v[28:31], v[138:141], v[210:213], v[28:31]
	v_mfma_f32_16x16x32_bf16 v[24:27], v[150:153], v[210:213], v[24:27]
	v_mfma_f32_16x16x32_bf16 v[12:15], v[138:141], v[218:221], v[12:15]
	v_mfma_f32_16x16x32_bf16 v[8:11], v[150:153], v[218:221], v[8:11]
	v_mfma_f32_16x16x32_bf16 v[60:63], v[142:145], v[198:201], v[60:63]
	v_mfma_f32_16x16x32_bf16 v[56:59], v[154:157], v[198:201], v[56:59]
	v_mfma_f32_16x16x32_bf16 v[44:47], v[142:145], v[206:209], v[44:47]
	v_mfma_f32_16x16x32_bf16 v[40:43], v[154:157], v[206:209], v[40:43]
	v_mfma_f32_16x16x32_bf16 v[28:31], v[142:145], v[214:217], v[28:31]
	v_mfma_f32_16x16x32_bf16 v[24:27], v[154:157], v[214:217], v[24:27]
	v_mfma_f32_16x16x32_bf16 v[12:15], v[142:145], v[242:245], v[12:15]
	v_mfma_f32_16x16x32_bf16 v[8:11], v[154:157], v[242:245], v[8:11]
	s_setprio 0
	s_setprio 1
	v_mfma_f32_16x16x32_bf16 v[52:55], v[158:161], v[194:197], v[52:55]
	v_mfma_f32_16x16x32_bf16 v[48:51], v[186:189], v[194:197], v[48:51]
	v_mfma_f32_16x16x32_bf16 v[36:39], v[158:161], v[202:205], v[36:39]
	v_mfma_f32_16x16x32_bf16 v[32:35], v[186:189], v[202:205], v[32:35]
	v_mfma_f32_16x16x32_bf16 v[20:23], v[158:161], v[210:213], v[20:23]
	v_mfma_f32_16x16x32_bf16 v[16:19], v[186:189], v[210:213], v[16:19]
	v_mfma_f32_16x16x32_bf16 v[4:7], v[158:161], v[218:221], v[4:7]
	v_mfma_f32_16x16x32_bf16 v[0:3], v[186:189], v[218:221], v[0:3]
	v_mfma_f32_16x16x32_bf16 v[52:55], v[162:165], v[198:201], v[52:55]
	v_mfma_f32_16x16x32_bf16 v[48:51], v[190:193], v[198:201], v[48:51]
	v_mfma_f32_16x16x32_bf16 v[36:39], v[162:165], v[206:209], v[36:39]
	v_mfma_f32_16x16x32_bf16 v[32:35], v[190:193], v[206:209], v[32:35]
	v_mfma_f32_16x16x32_bf16 v[20:23], v[162:165], v[214:217], v[20:23]
	v_mfma_f32_16x16x32_bf16 v[16:19], v[190:193], v[214:217], v[16:19]
	v_mfma_f32_16x16x32_bf16 v[4:7], v[162:165], v[242:245], v[4:7]
	v_mfma_f32_16x16x32_bf16 v[0:3], v[190:193], v[242:245], v[0:3]
	s_setprio 0
.Lzc11_1j:
	s_barrier
	s_add_i32 s41, 0, 0x18000
	s_add_i32 s71, 0, 0x1c000
	v_add_u32_e32 v154, s41, v148
	v_add_u32_e32 v179, s71, v148
	ds_read_b128 v[138:141], v154
	ds_read_b128 v[142:145], v154 offset:1024
	ds_read_b128 v[150:153], v154 offset:2048
	ds_read_b128 v[154:157], v154 offset:3072
	ds_read_b128 v[158:161], v179
	ds_read_b128 v[162:165], v179 offset:1024
	ds_read_b128 v[186:189], v179 offset:2048
	ds_read_b128 v[190:193], v179 offset:3072
	s_add_u32 s50, s50, 0x20000
	s_addc_u32 s51, s51, 0
	s_mov_b32 m0, s55
	v_lshl_add_u64 v[248:249], s[50:51], 0, v[128:129]
	ds_read_b128 v[194:197], v149 offset:32768
	ds_read_b128 v[198:201], v149 offset:33792
	ds_read_b128 v[202:205], v149 offset:34816
	ds_read_b128 v[206:209], v149 offset:35840
	ds_read_b128 v[210:213], v149 offset:36864
	ds_read_b128 v[214:217], v149 offset:37888
	ds_read_b128 v[218:221], v149 offset:38912
	ds_read_b128 v[242:245], v149 offset:39936
	global_load_lds_dwordx4 v[248:249], off
	v_lshl_add_u64 v[248:249], s[50:51], 0, v[130:131]
	s_mov_b32 m0, s56
	s_nop 0
	global_load_lds_dwordx4 v[248:249], off
	s_waitcnt vmcnt(8)
	s_waitcnt lgkmcnt(0)
	s_barrier
	s_setprio 1
	s_waitcnt lgkmcnt(0)
	v_mfma_f32_16x16x32_bf16 v[124:127], v[138:141], v[194:197], v[124:127]
	v_mfma_f32_16x16x32_bf16 v[120:123], v[150:153], v[194:197], v[120:123]
	v_mfma_f32_16x16x32_bf16 v[108:111], v[138:141], v[202:205], v[108:111]
	v_mfma_f32_16x16x32_bf16 v[104:107], v[150:153], v[202:205], v[104:107]
	v_mfma_f32_16x16x32_bf16 v[92:95], v[138:141], v[210:213], v[92:95]
	v_mfma_f32_16x16x32_bf16 v[88:91], v[150:153], v[210:213], v[88:91]
	v_mfma_f32_16x16x32_bf16 v[76:79], v[138:141], v[218:221], v[76:79]
	v_mfma_f32_16x16x32_bf16 v[72:75], v[150:153], v[218:221], v[72:75]
	v_mfma_f32_16x16x32_bf16 v[124:127], v[142:145], v[198:201], v[124:127]
	v_mfma_f32_16x16x32_bf16 v[120:123], v[154:157], v[198:201], v[120:123]
	v_mfma_f32_16x16x32_bf16 v[108:111], v[142:145], v[206:209], v[108:111]
	v_mfma_f32_16x16x32_bf16 v[104:107], v[154:157], v[206:209], v[104:107]
	v_mfma_f32_16x16x32_bf16 v[92:95], v[142:145], v[214:217], v[92:95]
	v_mfma_f32_16x16x32_bf16 v[88:91], v[154:157], v[214:217], v[88:91]
	v_mfma_f32_16x16x32_bf16 v[76:79], v[142:145], v[242:245], v[76:79]
	v_mfma_f32_16x16x32_bf16 v[72:75], v[154:157], v[242:245], v[72:75]
	s_setprio 0
	s_setprio 1
	v_mfma_f32_16x16x32_bf16 v[116:119], v[158:161], v[194:197], v[116:119]
	v_mfma_f32_16x16x32_bf16 v[112:115], v[186:189], v[194:197], v[112:115]
	v_mfma_f32_16x16x32_bf16 v[100:103], v[158:161], v[202:205], v[100:103]
	v_mfma_f32_16x16x32_bf16 v[96:99], v[186:189], v[202:205], v[96:99]
	v_mfma_f32_16x16x32_bf16 v[84:87], v[158:161], v[210:213], v[84:87]
	v_mfma_f32_16x16x32_bf16 v[80:83], v[186:189], v[210:213], v[80:83]
	v_mfma_f32_16x16x32_bf16 v[68:71], v[158:161], v[218:221], v[68:71]
	v_mfma_f32_16x16x32_bf16 v[64:67], v[186:189], v[218:221], v[64:67]
	v_mfma_f32_16x16x32_bf16 v[116:119], v[162:165], v[198:201], v[116:119]
	v_mfma_f32_16x16x32_bf16 v[112:115], v[190:193], v[198:201], v[112:115]
	v_mfma_f32_16x16x32_bf16 v[100:103], v[162:165], v[206:209], v[100:103]
	v_mfma_f32_16x16x32_bf16 v[96:99], v[190:193], v[206:209], v[96:99]
	v_mfma_f32_16x16x32_bf16 v[84:87], v[162:165], v[214:217], v[84:87]
	v_mfma_f32_16x16x32_bf16 v[80:83], v[190:193], v[214:217], v[80:83]
	v_mfma_f32_16x16x32_bf16 v[68:71], v[162:165], v[242:245], v[68:71]
	v_mfma_f32_16x16x32_bf16 v[64:67], v[190:193], v[242:245], v[64:67]
	s_setprio 0
	s_barrier
	s_add_i32 s41, s41, s53
	v_lshl_add_u64 v[166:167], v[166:167], 0, s[28:29]
	s_mov_b32 m0, s41
	ds_read_b128 v[194:197], v149 offset:49152
	ds_read_b128 v[198:201], v149 offset:50176
	ds_read_b128 v[202:205], v149 offset:51200
	ds_read_b128 v[206:209], v149 offset:52224
	ds_read_b128 v[210:213], v149 offset:53248
	ds_read_b128 v[214:217], v149 offset:54272
	ds_read_b128 v[218:221], v149 offset:55296
	ds_read_b128 v[242:245], v149 offset:56320
	global_load_lds_dwordx4 v[166:167], off
	s_add_i32 m0, s41, 0x2000
	s_add_u32 s48, s48, 0x10080
	v_lshl_add_u64 v[166:167], v[222:223], 0, s[28:29]
	s_addc_u32 s49, s49, 0
	s_add_i32 s41, s71, s53
	global_load_lds_dwordx4 v[166:167], off
	v_lshl_add_u64 v[166:167], s[48:49], 0, v[168:169]
	s_mov_b32 m0, s41
	s_nop 0
	global_load_lds_dwordx4 v[166:167], off
	v_lshl_add_u64 v[166:167], s[48:49], 0, v[132:133]
	s_add_i32 m0, s41, 0x2000
	s_nop 0
	global_load_lds_dwordx4 v[166:167], off
	v_lshl_add_u64 v[166:167], v[236:237], 0, s[28:29]
	s_mov_b32 m0, s62
	s_nop 0
	global_load_lds_dwordx4 v[166:167], off
	v_lshl_add_u64 v[166:167], v[246:247], 0, s[28:29]
	s_mov_b32 m0, s63
	s_nop 0
	global_load_lds_dwordx4 v[166:167], off
	s_waitcnt vmcnt(8)
	s_waitcnt lgkmcnt(0)
	s_barrier
	s_setprio 1
	s_waitcnt lgkmcnt(0)
	v_mfma_f32_16x16x32_bf16 v[60:63], v[138:141], v[194:197], v[60:63]
	v_mfma_f32_16x16x32_bf16 v[56:59], v[150:153], v[194:197], v[56:59]
	v_mfma_f32_16x16x32_bf16 v[44:47], v[138:141], v[202:205], v[44:47]
	v_mfma_f32_16x16x32_bf16 v[40:43], v[150:153], v[202:205], v[40:43]
	v_mfma_f32_16x16x32_bf16 v[28:31], v[138:141], v[210:213], v[28:31]
	v_mfma_f32_16x16x32_bf16 v[24:27], v[150:153], v[210:213], v[24:27]
	v_mfma_f32_16x16x32_bf16 v[12:15], v[138:141], v[218:221], v[12:15]
	v_mfma_f32_16x16x32_bf16 v[8:11], v[150:153], v[218:221], v[8:11]
	v_mfma_f32_16x16x32_bf16 v[60:63], v[142:145], v[198:201], v[60:63]
	v_mfma_f32_16x16x32_bf16 v[56:59], v[154:157], v[198:201], v[56:59]
	v_mfma_f32_16x16x32_bf16 v[44:47], v[142:145], v[206:209], v[44:47]
	v_mfma_f32_16x16x32_bf16 v[40:43], v[154:157], v[206:209], v[40:43]
	v_mfma_f32_16x16x32_bf16 v[28:31], v[142:145], v[214:217], v[28:31]
	v_mfma_f32_16x16x32_bf16 v[24:27], v[154:157], v[214:217], v[24:27]
	v_mfma_f32_16x16x32_bf16 v[12:15], v[142:145], v[242:245], v[12:15]
	v_mfma_f32_16x16x32_bf16 v[8:11], v[154:157], v[242:245], v[8:11]
	s_setprio 0
	s_setprio 1
	v_mfma_f32_16x16x32_bf16 v[52:55], v[158:161], v[194:197], v[52:55]
	v_mfma_f32_16x16x32_bf16 v[48:51], v[186:189], v[194:197], v[48:51]
	v_mfma_f32_16x16x32_bf16 v[36:39], v[158:161], v[202:205], v[36:39]
	v_mfma_f32_16x16x32_bf16 v[32:35], v[186:189], v[202:205], v[32:35]
	v_mfma_f32_16x16x32_bf16 v[20:23], v[158:161], v[210:213], v[20:23]
	v_mfma_f32_16x16x32_bf16 v[16:19], v[186:189], v[210:213], v[16:19]
	v_mfma_f32_16x16x32_bf16 v[4:7], v[158:161], v[218:221], v[4:7]
	v_mfma_f32_16x16x32_bf16 v[0:3], v[186:189], v[218:221], v[0:3]
	v_mfma_f32_16x16x32_bf16 v[52:55], v[162:165], v[198:201], v[52:55]
	v_mfma_f32_16x16x32_bf16 v[48:51], v[190:193], v[198:201], v[48:51]
	v_mfma_f32_16x16x32_bf16 v[36:39], v[162:165], v[206:209], v[36:39]
	v_mfma_f32_16x16x32_bf16 v[32:35], v[190:193], v[206:209], v[32:35]
	v_mfma_f32_16x16x32_bf16 v[20:23], v[162:165], v[214:217], v[20:23]
	v_mfma_f32_16x16x32_bf16 v[16:19], v[190:193], v[214:217], v[16:19]
	v_mfma_f32_16x16x32_bf16 v[4:7], v[162:165], v[242:245], v[4:7]
	v_mfma_f32_16x16x32_bf16 v[0:3], v[190:193], v[242:245], v[0:3]
	s_setprio 0
	s_barrier
	s_add_u32 s0, s0, 0x100
	s_addc_u32 s1, s1, 0
	s_add_u32 s3, s3, 0x100
	s_addc_u32 s27, s27, 0
	s_cmp_ge_i32 s70, s59
	s_mov_b32 s41, s70
	s_mov_b32 s32, 0
	s_cbranch_scc0 .LBB0_630

.Lzc12_0:
	s_setprio 1
	s_waitcnt lgkmcnt(0)
	v_mfma_f32_16x16x32_bf16 v[156:159], v[80:83], v[160:163], 0
	v_mfma_f32_16x16x32_bf16 v[152:155], v[88:91], v[160:163], 0
	v_mfma_f32_16x16x32_bf16 v[140:143], v[80:83], v[196:199], 0
	v_mfma_f32_16x16x32_bf16 v[136:139], v[88:91], v[196:199], 0
	v_mfma_f32_16x16x32_bf16 v[124:127], v[80:83], v[204:207], 0
	v_mfma_f32_16x16x32_bf16 v[120:123], v[88:91], v[204:207], 0
	v_mfma_f32_16x16x32_bf16 v[76:79], v[80:83], v[218:221], 0
	v_mfma_f32_16x16x32_bf16 v[72:75], v[88:91], v[218:221], 0
	v_mfma_f32_16x16x32_bf16 v[156:159], v[84:87], v[164:167], v[156:159]
	v_mfma_f32_16x16x32_bf16 v[152:155], v[92:95], v[164:167], v[152:155]
	v_mfma_f32_16x16x32_bf16 v[140:143], v[84:87], v[200:203], v[140:143]
	v_mfma_f32_16x16x32_bf16 v[136:139], v[92:95], v[200:203], v[136:139]
	v_mfma_f32_16x16x32_bf16 v[124:127], v[84:87], v[214:217], v[124:127]
	v_mfma_f32_16x16x32_bf16 v[120:123], v[92:95], v[214:217], v[120:123]
	v_mfma_f32_16x16x32_bf16 v[76:79], v[84:87], v[242:245], v[76:79]
	v_mfma_f32_16x16x32_bf16 v[72:75], v[92:95], v[242:245], v[72:75]
	s_setprio 0
	s_setprio 1
	v_mfma_f32_16x16x32_bf16 v[148:151], v[96:99], v[160:163], 0
	v_mfma_f32_16x16x32_bf16 v[144:147], v[104:107], v[160:163], 0
	v_mfma_f32_16x16x32_bf16 v[132:135], v[96:99], v[196:199], 0
	v_mfma_f32_16x16x32_bf16 v[128:131], v[104:107], v[196:199], 0
	v_mfma_f32_16x16x32_bf16 v[116:119], v[96:99], v[204:207], 0
	v_mfma_f32_16x16x32_bf16 v[112:115], v[104:107], v[204:207], 0
	v_mfma_f32_16x16x32_bf16 v[68:71], v[96:99], v[218:221], 0
	v_mfma_f32_16x16x32_bf16 v[64:67], v[104:107], v[218:221], 0
	v_mfma_f32_16x16x32_bf16 v[148:151], v[100:103], v[164:167], v[148:151]
	v_mfma_f32_16x16x32_bf16 v[144:147], v[108:111], v[164:167], v[144:147]
	v_mfma_f32_16x16x32_bf16 v[132:135], v[100:103], v[200:203], v[132:135]
	v_mfma_f32_16x16x32_bf16 v[128:131], v[108:111], v[200:203], v[128:131]
	v_mfma_f32_16x16x32_bf16 v[116:119], v[100:103], v[214:217], v[116:119]
	v_mfma_f32_16x16x32_bf16 v[112:115], v[108:111], v[214:217], v[112:115]
	v_mfma_f32_16x16x32_bf16 v[68:71], v[100:103], v[242:245], v[68:71]
	v_mfma_f32_16x16x32_bf16 v[64:67], v[108:111], v[242:245], v[64:67]
	s_setprio 0
	s_branch .Lzc12_0j
.Lzc12_1:
	s_setprio 1
	s_waitcnt lgkmcnt(0)
	v_mfma_f32_16x16x32_bf16 v[60:63], v[80:83], v[160:163], 0
	v_mfma_f32_16x16x32_bf16 v[56:59], v[88:91], v[160:163], 0
	v_mfma_f32_16x16x32_bf16 v[44:47], v[80:83], v[196:199], 0
	v_mfma_f32_16x16x32_bf16 v[40:43], v[88:91], v[196:199], 0
	v_mfma_f32_16x16x32_bf16 v[28:31], v[80:83], v[204:207], 0
	v_mfma_f32_16x16x32_bf16 v[24:27], v[88:91], v[204:207], 0
	v_mfma_f32_16x16x32_bf16 v[12:15], v[80:83], v[218:221], 0
	v_mfma_f32_16x16x32_bf16 v[8:11], v[88:91], v[218:221], 0
	v_mfma_f32_16x16x32_bf16 v[60:63], v[84:87], v[164:167], v[60:63]
	v_mfma_f32_16x16x32_bf16 v[56:59], v[92:95], v[164:167], v[56:59]
	v_mfma_f32_16x16x32_bf16 v[44:47], v[84:87], v[200:203], v[44:47]
	v_mfma_f32_16x16x32_bf16 v[40:43], v[92:95], v[200:203], v[40:43]
	v_mfma_f32_16x16x32_bf16 v[28:31], v[84:87], v[214:217], v[28:31]
	v_mfma_f32_16x16x32_bf16 v[24:27], v[92:95], v[214:217], v[24:27]
	v_mfma_f32_16x16x32_bf16 v[12:15], v[84:87], v[242:245], v[12:15]
	v_mfma_f32_16x16x32_bf16 v[8:11], v[92:95], v[242:245], v[8:11]
	s_setprio 0
	s_setprio 1
	v_mfma_f32_16x16x32_bf16 v[52:55], v[96:99], v[160:163], 0
	v_mfma_f32_16x16x32_bf16 v[48:51], v[104:107], v[160:163], 0
	v_mfma_f32_16x16x32_bf16 v[36:39], v[96:99], v[196:199], 0
	v_mfma_f32_16x16x32_bf16 v[32:35], v[104:107], v[196:199], 0
	v_mfma_f32_16x16x32_bf16 v[20:23], v[96:99], v[204:207], 0
	v_mfma_f32_16x16x32_bf16 v[16:19], v[104:107], v[204:207], 0
	v_mfma_f32_16x16x32_bf16 v[4:7], v[96:99], v[218:221], 0
	v_mfma_f32_16x16x32_bf16 v[0:3], v[104:107], v[218:221], 0
	v_mfma_f32_16x16x32_bf16 v[52:55], v[100:103], v[164:167], v[52:55]
	v_mfma_f32_16x16x32_bf16 v[48:51], v[108:111], v[164:167], v[48:51]
	v_mfma_f32_16x16x32_bf16 v[36:39], v[100:103], v[200:203], v[36:39]
	v_mfma_f32_16x16x32_bf16 v[32:35], v[108:111], v[200:203], v[32:35]
	v_mfma_f32_16x16x32_bf16 v[20:23], v[100:103], v[214:217], v[20:23]
	v_mfma_f32_16x16x32_bf16 v[16:19], v[108:111], v[214:217], v[16:19]
	v_mfma_f32_16x16x32_bf16 v[4:7], v[100:103], v[242:245], v[4:7]
	v_mfma_f32_16x16x32_bf16 v[0:3], v[108:111], v[242:245], v[0:3]
	s_setprio 0
	s_branch .Lzc12_1j
.Lzc12_skip:
	v_mov_b32_e32 v0, 0
	v_mov_b32_e32 v1, 0
	v_mov_b32_e32 v2, 0
	v_mov_b32_e32 v3, 0
	v_mov_b32_e32 v4, 0
	v_mov_b32_e32 v5, 0
	v_mov_b32_e32 v6, 0
	v_mov_b32_e32 v7, 0
	v_mov_b32_e32 v8, 0
	v_mov_b32_e32 v9, 0
	v_mov_b32_e32 v10, 0
	v_mov_b32_e32 v11, 0
	v_mov_b32_e32 v12, 0
	v_mov_b32_e32 v13, 0
	v_mov_b32_e32 v14, 0
	v_mov_b32_e32 v15, 0
	v_mov_b32_e32 v16, 0
	v_mov_b32_e32 v17, 0
	v_mov_b32_e32 v18, 0
	v_mov_b32_e32 v19, 0
	v_mov_b32_e32 v20, 0
	v_mov_b32_e32 v21, 0
	v_mov_b32_e32 v22, 0
	v_mov_b32_e32 v23, 0
	v_mov_b32_e32 v24, 0
	v_mov_b32_e32 v25, 0
	v_mov_b32_e32 v26, 0
	v_mov_b32_e32 v27, 0
	v_mov_b32_e32 v28, 0
	v_mov_b32_e32 v29, 0
	v_mov_b32_e32 v30, 0
	v_mov_b32_e32 v31, 0
	v_mov_b32_e32 v32, 0
	v_mov_b32_e32 v33, 0
	v_mov_b32_e32 v34, 0
	v_mov_b32_e32 v35, 0
	v_mov_b32_e32 v36, 0
	v_mov_b32_e32 v37, 0
	v_mov_b32_e32 v38, 0
	v_mov_b32_e32 v39, 0
	v_mov_b32_e32 v40, 0
	v_mov_b32_e32 v41, 0
	v_mov_b32_e32 v42, 0
	v_mov_b32_e32 v43, 0
	v_mov_b32_e32 v44, 0
	v_mov_b32_e32 v45, 0
	v_mov_b32_e32 v46, 0
	v_mov_b32_e32 v47, 0
	v_mov_b32_e32 v48, 0
	v_mov_b32_e32 v49, 0
	v_mov_b32_e32 v50, 0
	v_mov_b32_e32 v51, 0
	v_mov_b32_e32 v52, 0
	v_mov_b32_e32 v53, 0
	v_mov_b32_e32 v54, 0
	v_mov_b32_e32 v55, 0
	v_mov_b32_e32 v56, 0
	v_mov_b32_e32 v57, 0
	v_mov_b32_e32 v58, 0
	v_mov_b32_e32 v59, 0
	v_mov_b32_e32 v60, 0
	v_mov_b32_e32 v61, 0
	v_mov_b32_e32 v62, 0
	v_mov_b32_e32 v63, 0
	v_mov_b32_e32 v64, 0
	v_mov_b32_e32 v65, 0
	v_mov_b32_e32 v66, 0
	v_mov_b32_e32 v67, 0
	v_mov_b32_e32 v68, 0
	v_mov_b32_e32 v69, 0
	v_mov_b32_e32 v70, 0
	v_mov_b32_e32 v71, 0
	v_mov_b32_e32 v72, 0
	v_mov_b32_e32 v73, 0
	v_mov_b32_e32 v74, 0
	v_mov_b32_e32 v75, 0
	v_mov_b32_e32 v76, 0
	v_mov_b32_e32 v77, 0
	v_mov_b32_e32 v78, 0
	v_mov_b32_e32 v79, 0
	v_mov_b32_e32 v112, 0
	v_mov_b32_e32 v113, 0
	v_mov_b32_e32 v114, 0
	v_mov_b32_e32 v115, 0
	v_mov_b32_e32 v116, 0
	v_mov_b32_e32 v117, 0
	v_mov_b32_e32 v118, 0
	v_mov_b32_e32 v119, 0
	v_mov_b32_e32 v120, 0
	v_mov_b32_e32 v121, 0
	v_mov_b32_e32 v122, 0
	v_mov_b32_e32 v123, 0
	v_mov_b32_e32 v124, 0
	v_mov_b32_e32 v125, 0
	v_mov_b32_e32 v126, 0
	v_mov_b32_e32 v127, 0
	v_mov_b32_e32 v128, 0
	v_mov_b32_e32 v129, 0
	v_mov_b32_e32 v130, 0
	v_mov_b32_e32 v131, 0
	v_mov_b32_e32 v132, 0
	v_mov_b32_e32 v133, 0
	v_mov_b32_e32 v134, 0
	v_mov_b32_e32 v135, 0
	v_mov_b32_e32 v136, 0
	v_mov_b32_e32 v137, 0
	v_mov_b32_e32 v138, 0
	v_mov_b32_e32 v139, 0
	v_mov_b32_e32 v140, 0
	v_mov_b32_e32 v141, 0
	v_mov_b32_e32 v142, 0
	v_mov_b32_e32 v143, 0
	v_mov_b32_e32 v144, 0
	v_mov_b32_e32 v145, 0
	v_mov_b32_e32 v146, 0
	v_mov_b32_e32 v147, 0
	v_mov_b32_e32 v148, 0
	v_mov_b32_e32 v149, 0
	v_mov_b32_e32 v150, 0
	v_mov_b32_e32 v151, 0
	v_mov_b32_e32 v152, 0
	v_mov_b32_e32 v153, 0
	v_mov_b32_e32 v154, 0
	v_mov_b32_e32 v155, 0
	v_mov_b32_e32 v156, 0
	v_mov_b32_e32 v157, 0
	v_mov_b32_e32 v158, 0
	v_mov_b32_e32 v159, 0
	s_branch .LBB0_854

.LBB0_851:
	s_ashr_i32 s53, s52, 31
	s_lshl_b64 s[26:27], s[52:53], 19
	v_readlane_b32 s40, v254, 43
	v_readlane_b32 s41, v254, 44
	s_add_u32 s56, s40, s26
	s_addc_u32 s57, s41, s27
	s_ashr_i32 s55, s54, 31
	s_lshl_b64 s[26:27], s[54:55], 19
	v_readlane_b32 s1, v254, 41
	s_add_u32 s58, s1, s26
	v_readlane_b32 s1, v254, 42
	s_addc_u32 s59, s1, s27
	s_andn2_b64 vcc, exec, s[48:49]
	s_cbranch_vccnz .Lzc12_skip
	s_and_b64 s[26:27], s[38:39], exec
	s_cselect_b32 s1, s57, s21
	s_cselect_b32 s40, s56, s20
	s_cselect_b32 s41, s59, s23
	s_cselect_b32 s53, s58, s22
	s_add_u32 s20, s20, 0x40080
	s_addc_u32 s21, s21, 0
	s_add_u32 s55, s22, 0x100
	s_addc_u32 s71, s23, 0
	s_mov_b32 s22, 0
	s_mov_b32 s32, 1
.LBB0_853:
	s_add_i32 s72, s22, 2
	s_add_u32 s23, s20, 0xfffc0080
	s_addc_u32 s26, s21, -1
	s_add_i32 s73, 0, 0x10000
	s_cmp_eq_u32 s68, s22
	s_cselect_b32 s27, s1, s26
	s_cselect_b32 s26, s40, s23
	s_cselect_b32 s23, s41, s71
	s_cselect_b32 s22, s53, s55
	s_add_i32 s76, 0, 0x14000
	v_add_u32_e32 v92, s73, v211
	v_add_u32_e32 v108, s76, v211
	ds_read_b128 v[80:83], v92
	ds_read_b128 v[84:87], v92 offset:1024
	ds_read_b128 v[88:91], v92 offset:2048
	ds_read_b128 v[92:95], v92 offset:3072
	ds_read_b128 v[96:99], v108
	ds_read_b128 v[100:103], v108 offset:1024
	ds_read_b128 v[104:107], v108 offset:2048
	ds_read_b128 v[108:111], v108 offset:3072
	v_lshl_add_u64 v[208:209], s[20:21], 0, v[192:193]
	s_add_i32 m0, s3, 0xc000
	ds_read_b128 v[160:163], v212
	ds_read_b128 v[164:167], v212 offset:1024
	ds_read_b128 v[196:199], v212 offset:2048
	ds_read_b128 v[200:203], v212 offset:3072
	ds_read_b128 v[204:207], v212 offset:4096
	ds_read_b128 v[214:217], v212 offset:5120
	ds_read_b128 v[218:221], v212 offset:6144
	ds_read_b128 v[242:245], v212 offset:7168
	global_load_lds_dwordx4 v[208:209], off
	v_lshl_add_u64 v[208:209], s[20:21], 0, v[194:195]
	s_add_i32 m0, s3, 0xe000
	s_nop 0
	global_load_lds_dwordx4 v[208:209], off
	s_waitcnt vmcnt(8)
	s_waitcnt lgkmcnt(0)
	s_barrier
	s_cmp_lg_u32 s32, 0
	s_cbranch_scc1 .Lzc12_0
	s_setprio 1
	s_waitcnt lgkmcnt(0)
	v_mfma_f32_16x16x32_bf16 v[156:159], v[80:83], v[160:163], v[156:159]
	v_mfma_f32_16x16x32_bf16 v[152:155], v[88:91], v[160:163], v[152:155]
	v_mfma_f32_16x16x32_bf16 v[140:143], v[80:83], v[196:199], v[140:143]
	v_mfma_f32_16x16x32_bf16 v[136:139], v[88:91], v[196:199], v[136:139]
	v_mfma_f32_16x16x32_bf16 v[124:127], v[80:83], v[204:207], v[124:127]
	v_mfma_f32_16x16x32_bf16 v[120:123], v[88:91], v[204:207], v[120:123]
	v_mfma_f32_16x16x32_bf16 v[76:79], v[80:83], v[218:221], v[76:79]
	v_mfma_f32_16x16x32_bf16 v[72:75], v[88:91], v[218:221], v[72:75]
	v_mfma_f32_16x16x32_bf16 v[156:159], v[84:87], v[164:167], v[156:159]
	v_mfma_f32_16x16x32_bf16 v[152:155], v[92:95], v[164:167], v[152:155]
	v_mfma_f32_16x16x32_bf16 v[140:143], v[84:87], v[200:203], v[140:143]
	v_mfma_f32_16x16x32_bf16 v[136:139], v[92:95], v[200:203], v[136:139]
	v_mfma_f32_16x16x32_bf16 v[124:127], v[84:87], v[214:217], v[124:127]
	v_mfma_f32_16x16x32_bf16 v[120:123], v[92:95], v[214:217], v[120:123]
	v_mfma_f32_16x16x32_bf16 v[76:79], v[84:87], v[242:245], v[76:79]
	v_mfma_f32_16x16x32_bf16 v[72:75], v[92:95], v[242:245], v[72:75]
	s_setprio 0
	s_setprio 1
	v_mfma_f32_16x16x32_bf16 v[148:151], v[96:99], v[160:163], v[148:151]
	v_mfma_f32_16x16x32_bf16 v[144:147], v[104:107], v[160:163], v[144:147]
	v_mfma_f32_16x16x32_bf16 v[132:135], v[96:99], v[196:199], v[132:135]
	v_mfma_f32_16x16x32_bf16 v[128:131], v[104:107], v[196:199], v[128:131]
	v_mfma_f32_16x16x32_bf16 v[116:119], v[96:99], v[204:207], v[116:119]
	v_mfma_f32_16x16x32_bf16 v[112:115], v[104:107], v[204:207], v[112:115]
	v_mfma_f32_16x16x32_bf16 v[68:71], v[96:99], v[218:221], v[68:71]
	v_mfma_f32_16x16x32_bf16 v[64:67], v[104:107], v[218:221], v[64:67]
	v_mfma_f32_16x16x32_bf16 v[148:151], v[100:103], v[164:167], v[148:151]
	v_mfma_f32_16x16x32_bf16 v[144:147], v[108:111], v[164:167], v[144:147]
	v_mfma_f32_16x16x32_bf16 v[132:135], v[100:103], v[200:203], v[132:135]
	v_mfma_f32_16x16x32_bf16 v[128:131], v[108:111], v[200:203], v[128:131]
	v_mfma_f32_16x16x32_bf16 v[116:119], v[100:103], v[214:217], v[116:119]
	v_mfma_f32_16x16x32_bf16 v[112:115], v[108:111], v[214:217], v[112:115]
	v_mfma_f32_16x16x32_bf16 v[68:71], v[100:103], v[242:245], v[68:71]
	v_mfma_f32_16x16x32_bf16 v[64:67], v[108:111], v[242:245], v[64:67]
	s_setprio 0
.Lzc12_0j:
	s_barrier
	s_add_i32 s73, s73, s34
	v_lshl_add_u64 v[208:209], s[22:23], 0, v[168:169]
	s_mov_b32 m0, s73
	ds_read_b128 v[160:163], v212 offset:16384
	ds_read_b128 v[164:167], v212 offset:17408
	ds_read_b128 v[196:199], v212 offset:18432
	ds_read_b128 v[200:203], v212 offset:19456
	ds_read_b128 v[204:207], v212 offset:20480
	ds_read_b128 v[214:217], v212 offset:21504
	ds_read_b128 v[218:221], v212 offset:22528
	ds_read_b128 v[242:245], v212 offset:23552
	global_load_lds_dwordx4 v[208:209], off
	s_add_i32 m0, s73, 0x2000
	s_add_u32 s74, s22, 0x40000
	v_lshl_add_u64 v[222:223], s[22:23], 0, v[190:191]
	s_addc_u32 s75, s23, 0
	s_add_i32 s73, s76, s34
	global_load_lds_dwordx4 v[222:223], off
	v_lshl_add_u64 v[236:237], s[74:75], 0, v[168:169]
	s_mov_b32 m0, s73
	v_lshl_add_u64 v[246:247], s[26:27], 0, v[188:189]
	global_load_lds_dwordx4 v[236:237], off
	v_lshl_add_u64 v[236:237], s[74:75], 0, v[190:191]
	s_add_i32 m0, s73, 0x2000
	s_nop 0
	global_load_lds_dwordx4 v[236:237], off
	v_lshl_add_u64 v[236:237], s[26:27], 0, v[186:187]
	s_mov_b32 m0, s3
	s_nop 0
	global_load_lds_dwordx4 v[236:237], off
	s_mov_b32 m0, s60
	s_nop 0
	global_load_lds_dwordx4 v[246:247], off
	s_waitcnt vmcnt(8)
	s_waitcnt lgkmcnt(0)
	s_barrier
	s_cmp_lg_u32 s32, 0
	s_cbranch_scc1 .Lzc12_1
	s_setprio 1
	s_waitcnt lgkmcnt(0)
	v_mfma_f32_16x16x32_bf16 v[60:63], v[80:83], v[160:163], v[60:63]
	v_mfma_f32_16x16x32_bf16 v[56:59], v[88:91], v[160:163], v[56:59]
	v_mfma_f32_16x16x32_bf16 v[44:47], v[80:83], v[196:199], v[44:47]
	v_mfma_f32_16x16x32_bf16 v[40:43], v[88:91], v[196:199], v[40:43]
	v_mfma_f32_16x16x32_bf16 v[28:31], v[80:83], v[204:207], v[28:31]
	v_mfma_f32_16x16x32_bf16 v[24:27], v[88:91], v[204:207], v[24:27]
	v_mfma_f32_16x16x32_bf16 v[12:15], v[80:83], v[218:221], v[12:15]
	v_mfma_f32_16x16x32_bf16 v[8:11], v[88:91], v[218:221], v[8:11]
	v_mfma_f32_16x16x32_bf16 v[60:63], v[84:87], v[164:167], v[60:63]
	v_mfma_f32_16x16x32_bf16 v[56:59], v[92:95], v[164:167], v[56:59]
	v_mfma_f32_16x16x32_bf16 v[44:47], v[84:87], v[200:203], v[44:47]
	v_mfma_f32_16x16x32_bf16 v[40:43], v[92:95], v[200:203], v[40:43]
	v_mfma_f32_16x16x32_bf16 v[28:31], v[84:87], v[214:217], v[28:31]
	v_mfma_f32_16x16x32_bf16 v[24:27], v[92:95], v[214:217], v[24:27]
	v_mfma_f32_16x16x32_bf16 v[12:15], v[84:87], v[242:245], v[12:15]
	v_mfma_f32_16x16x32_bf16 v[8:11], v[92:95], v[242:245], v[8:11]
	s_setprio 0
	s_setprio 1
	v_mfma_f32_16x16x32_bf16 v[52:55], v[96:99], v[160:163], v[52:55]
	v_mfma_f32_16x16x32_bf16 v[48:51], v[104:107], v[160:163], v[48:51]
	v_mfma_f32_16x16x32_bf16 v[36:39], v[96:99], v[196:199], v[36:39]
	v_mfma_f32_16x16x32_bf16 v[32:35], v[104:107], v[196:199], v[32:35]
	v_mfma_f32_16x16x32_bf16 v[20:23], v[96:99], v[204:207], v[20:23]
	v_mfma_f32_16x16x32_bf16 v[16:19], v[104:107], v[204:207], v[16:19]
	v_mfma_f32_16x16x32_bf16 v[4:7], v[96:99], v[218:221], v[4:7]
	v_mfma_f32_16x16x32_bf16 v[0:3], v[104:107], v[218:221], v[0:3]
	v_mfma_f32_16x16x32_bf16 v[52:55], v[100:103], v[164:167], v[52:55]
	v_mfma_f32_16x16x32_bf16 v[48:51], v[108:111], v[164:167], v[48:51]
	v_mfma_f32_16x16x32_bf16 v[36:39], v[100:103], v[200:203], v[36:39]
	v_mfma_f32_16x16x32_bf16 v[32:35], v[108:111], v[200:203], v[32:35]
	v_mfma_f32_16x16x32_bf16 v[20:23], v[100:103], v[214:217], v[20:23]
	v_mfma_f32_16x16x32_bf16 v[16:19], v[108:111], v[214:217], v[16:19]
	v_mfma_f32_16x16x32_bf16 v[4:7], v[100:103], v[242:245], v[4:7]
	v_mfma_f32_16x16x32_bf16 v[0:3], v[108:111], v[242:245], v[0:3]
	s_setprio 0
.Lzc12_1j:
	s_barrier
	s_add_i32 s73, 0, 0x18000
	s_add_i32 s74, 0, 0x1c000
	v_add_u32_e32 v92, s73, v211
	v_add_u32_e32 v108, s74, v211
	ds_read_b128 v[80:83], v92
	ds_read_b128 v[84:87], v92 offset:1024
	ds_read_b128 v[88:91], v92 offset:2048
	ds_read_b128 v[92:95], v92 offset:3072
	ds_read_b128 v[96:99], v108
	ds_read_b128 v[100:103], v108 offset:1024
	ds_read_b128 v[104:107], v108 offset:2048
	ds_read_b128 v[108:111], v108 offset:3072
	s_add_u32 s26, s26, 0x40000
	s_addc_u32 s27, s27, 0
	s_mov_b32 m0, s61
	v_lshl_add_u64 v[248:249], s[26:27], 0, v[186:187]
	ds_read_b128 v[160:163], v212 offset:32768
	ds_read_b128 v[164:167], v212 offset:33792
	ds_read_b128 v[196:199], v212 offset:34816
	ds_read_b128 v[200:203], v212 offset:35840
	ds_read_b128 v[204:207], v212 offset:36864
	ds_read_b128 v[214:217], v212 offset:37888
	ds_read_b128 v[218:221], v212 offset:38912
	ds_read_b128 v[242:245], v212 offset:39936
	global_load_lds_dwordx4 v[248:249], off
	v_lshl_add_u64 v[248:249], s[26:27], 0, v[188:189]
	s_mov_b32 m0, s62
	s_nop 0
	global_load_lds_dwordx4 v[248:249], off
	s_waitcnt vmcnt(8)
	s_waitcnt lgkmcnt(0)
	s_barrier
	s_setprio 1
	s_waitcnt lgkmcnt(0)
	v_mfma_f32_16x16x32_bf16 v[156:159], v[80:83], v[160:163], v[156:159]
	v_mfma_f32_16x16x32_bf16 v[152:155], v[88:91], v[160:163], v[152:155]
	v_mfma_f32_16x16x32_bf16 v[140:143], v[80:83], v[196:199], v[140:143]
	v_mfma_f32_16x16x32_bf16 v[136:139], v[88:91], v[196:199], v[136:139]
	v_mfma_f32_16x16x32_bf16 v[124:127], v[80:83], v[204:207], v[124:127]
	v_mfma_f32_16x16x32_bf16 v[120:123], v[88:91], v[204:207], v[120:123]
	v_mfma_f32_16x16x32_bf16 v[76:79], v[80:83], v[218:221], v[76:79]
	v_mfma_f32_16x16x32_bf16 v[72:75], v[88:91], v[218:221], v[72:75]
	v_mfma_f32_16x16x32_bf16 v[156:159], v[84:87], v[164:167], v[156:159]
	v_mfma_f32_16x16x32_bf16 v[152:155], v[92:95], v[164:167], v[152:155]
	v_mfma_f32_16x16x32_bf16 v[140:143], v[84:87], v[200:203], v[140:143]
	v_mfma_f32_16x16x32_bf16 v[136:139], v[92:95], v[200:203], v[136:139]
	v_mfma_f32_16x16x32_bf16 v[124:127], v[84:87], v[214:217], v[124:127]
	v_mfma_f32_16x16x32_bf16 v[120:123], v[92:95], v[214:217], v[120:123]
	v_mfma_f32_16x16x32_bf16 v[76:79], v[84:87], v[242:245], v[76:79]
	v_mfma_f32_16x16x32_bf16 v[72:75], v[92:95], v[242:245], v[72:75]
	s_setprio 0
	s_setprio 1
	v_mfma_f32_16x16x32_bf16 v[148:151], v[96:99], v[160:163], v[148:151]
	v_mfma_f32_16x16x32_bf16 v[144:147], v[104:107], v[160:163], v[144:147]
	v_mfma_f32_16x16x32_bf16 v[132:135], v[96:99], v[196:199], v[132:135]
	v_mfma_f32_16x16x32_bf16 v[128:131], v[104:107], v[196:199], v[128:131]
	v_mfma_f32_16x16x32_bf16 v[116:119], v[96:99], v[204:207], v[116:119]
	v_mfma_f32_16x16x32_bf16 v[112:115], v[104:107], v[204:207], v[112:115]
	v_mfma_f32_16x16x32_bf16 v[68:71], v[96:99], v[218:221], v[68:71]
	v_mfma_f32_16x16x32_bf16 v[64:67], v[104:107], v[218:221], v[64:67]
	v_mfma_f32_16x16x32_bf16 v[148:151], v[100:103], v[164:167], v[148:151]
	v_mfma_f32_16x16x32_bf16 v[144:147], v[108:111], v[164:167], v[144:147]
	v_mfma_f32_16x16x32_bf16 v[132:135], v[100:103], v[200:203], v[132:135]
	v_mfma_f32_16x16x32_bf16 v[128:131], v[108:111], v[200:203], v[128:131]
	v_mfma_f32_16x16x32_bf16 v[116:119], v[100:103], v[214:217], v[116:119]
	v_mfma_f32_16x16x32_bf16 v[112:115], v[108:111], v[214:217], v[112:115]
	v_mfma_f32_16x16x32_bf16 v[68:71], v[100:103], v[242:245], v[68:71]
	v_mfma_f32_16x16x32_bf16 v[64:67], v[108:111], v[242:245], v[64:67]
	s_setprio 0
	s_barrier
	s_add_i32 s26, s73, s34
	v_lshl_add_u64 v[208:209], v[208:209], 0, s[28:29]
	s_mov_b32 m0, s26
	ds_read_b128 v[160:163], v212 offset:49152
	ds_read_b128 v[164:167], v212 offset:50176
	ds_read_b128 v[196:199], v212 offset:51200
	ds_read_b128 v[200:203], v212 offset:52224
	ds_read_b128 v[204:207], v212 offset:53248
	ds_read_b128 v[214:217], v212 offset:54272
	ds_read_b128 v[218:221], v212 offset:55296
	ds_read_b128 v[242:245], v212 offset:56320
	global_load_lds_dwordx4 v[208:209], off
	s_add_i32 m0, s26, 0x2000
	s_add_u32 s22, s22, 0x40080
	v_lshl_add_u64 v[208:209], v[222:223], 0, s[28:29]
	s_addc_u32 s23, s23, 0
	s_add_i32 s26, s74, s34
	global_load_lds_dwordx4 v[208:209], off
	v_lshl_add_u64 v[208:209], s[22:23], 0, v[168:169]
	s_mov_b32 m0, s26
	s_nop 0
	global_load_lds_dwordx4 v[208:209], off
	v_lshl_add_u64 v[208:209], s[22:23], 0, v[190:191]
	s_add_i32 m0, s26, 0x2000
	s_nop 0
	global_load_lds_dwordx4 v[208:209], off
	v_lshl_add_u64 v[208:209], v[236:237], 0, s[28:29]
	s_mov_b32 m0, s66
	s_nop 0
	global_load_lds_dwordx4 v[208:209], off
	v_lshl_add_u64 v[208:209], v[246:247], 0, s[28:29]
	s_mov_b32 m0, s67
	s_nop 0
	global_load_lds_dwordx4 v[208:209], off
	s_waitcnt vmcnt(8)
	s_waitcnt lgkmcnt(0)
	s_barrier
	s_setprio 1
	s_waitcnt lgkmcnt(0)
	v_mfma_f32_16x16x32_bf16 v[60:63], v[80:83], v[160:163], v[60:63]
	v_mfma_f32_16x16x32_bf16 v[56:59], v[88:91], v[160:163], v[56:59]
	v_mfma_f32_16x16x32_bf16 v[44:47], v[80:83], v[196:199], v[44:47]
	v_mfma_f32_16x16x32_bf16 v[40:43], v[88:91], v[196:199], v[40:43]
	v_mfma_f32_16x16x32_bf16 v[28:31], v[80:83], v[204:207], v[28:31]
	v_mfma_f32_16x16x32_bf16 v[24:27], v[88:91], v[204:207], v[24:27]
	v_mfma_f32_16x16x32_bf16 v[12:15], v[80:83], v[218:221], v[12:15]
	v_mfma_f32_16x16x32_bf16 v[8:11], v[88:91], v[218:221], v[8:11]
	v_mfma_f32_16x16x32_bf16 v[60:63], v[84:87], v[164:167], v[60:63]
	v_mfma_f32_16x16x32_bf16 v[56:59], v[92:95], v[164:167], v[56:59]
	v_mfma_f32_16x16x32_bf16 v[44:47], v[84:87], v[200:203], v[44:47]
	v_mfma_f32_16x16x32_bf16 v[40:43], v[92:95], v[200:203], v[40:43]
	v_mfma_f32_16x16x32_bf16 v[28:31], v[84:87], v[214:217], v[28:31]
	v_mfma_f32_16x16x32_bf16 v[24:27], v[92:95], v[214:217], v[24:27]
	v_mfma_f32_16x16x32_bf16 v[12:15], v[84:87], v[242:245], v[12:15]
	v_mfma_f32_16x16x32_bf16 v[8:11], v[92:95], v[242:245], v[8:11]
	s_setprio 0
	s_setprio 1
	v_mfma_f32_16x16x32_bf16 v[52:55], v[96:99], v[160:163], v[52:55]
	v_mfma_f32_16x16x32_bf16 v[48:51], v[104:107], v[160:163], v[48:51]
	v_mfma_f32_16x16x32_bf16 v[36:39], v[96:99], v[196:199], v[36:39]
	v_mfma_f32_16x16x32_bf16 v[32:35], v[104:107], v[196:199], v[32:35]
	v_mfma_f32_16x16x32_bf16 v[20:23], v[96:99], v[204:207], v[20:23]
	v_mfma_f32_16x16x32_bf16 v[16:19], v[104:107], v[204:207], v[16:19]
	v_mfma_f32_16x16x32_bf16 v[4:7], v[96:99], v[218:221], v[4:7]
	v_mfma_f32_16x16x32_bf16 v[0:3], v[104:107], v[218:221], v[0:3]
	v_mfma_f32_16x16x32_bf16 v[52:55], v[100:103], v[164:167], v[52:55]
	v_mfma_f32_16x16x32_bf16 v[48:51], v[108:111], v[164:167], v[48:51]
	v_mfma_f32_16x16x32_bf16 v[36:39], v[100:103], v[200:203], v[36:39]
	v_mfma_f32_16x16x32_bf16 v[32:35], v[108:111], v[200:203], v[32:35]
	v_mfma_f32_16x16x32_bf16 v[20:23], v[100:103], v[214:217], v[20:23]
	v_mfma_f32_16x16x32_bf16 v[16:19], v[108:111], v[214:217], v[16:19]
	v_mfma_f32_16x16x32_bf16 v[4:7], v[100:103], v[242:245], v[4:7]
	v_mfma_f32_16x16x32_bf16 v[0:3], v[108:111], v[242:245], v[0:3]
	s_setprio 0
	s_barrier
	s_add_u32 s20, s20, 0x100
	s_addc_u32 s21, s21, 0
	s_add_u32 s55, s55, 0x100
	s_addc_u32 s71, s71, 0
	s_cmp_ge_i32 s72, s63
	s_mov_b32 s22, s72
	s_mov_b32 s32, 0
	s_cbranch_scc0 .LBB0_853

.LBB0_914:
	s_ashr_i32 s47, s46, 31
	s_lshl_b64 s[50:51], s[46:47], 19
	s_add_u32 s50, s34, s50
	s_addc_u32 s51, s60, s51
	s_andn2_b64 vcc, exec, s[20:21]
	s_cbranch_vccnz .Lzc13_skip
	s_and_b64 s[58:59], s[58:59], exec
	s_cselect_b32 s1, s51, s55
	s_cselect_b32 s3, s50, s54
	s_add_u32 s54, s54, 0x40080
	s_addc_u32 s55, s55, 0
	s_add_u32 s43, s56, 0x100
	s_addc_u32 s45, s57, 0
	s_mov_b32 s47, 0
	s_mov_b32 s32, 1
.LBB0_916:
	s_add_i32 s76, s47, 2
	s_add_u32 s56, s54, 0xfffc0080
	s_addc_u32 s57, s55, -1
	s_add_i32 s77, 0, 0x10000
	s_cmp_eq_u32 s72, s47
	s_cselect_b32 s59, s1, s57
	s_cselect_b32 s58, s3, s56
	s_cselect_b32 s57, s49, s45
	s_cselect_b32 s56, s48, s43
	s_add_i32 s47, 0, 0x14000
	v_add_u32_e32 v154, s77, v148
	v_add_u32_e32 v166, s47, v148
	ds_read_b128 v[138:141], v154
	ds_read_b128 v[142:145], v154 offset:1024
	ds_read_b128 v[150:153], v154 offset:2048
	ds_read_b128 v[154:157], v154 offset:3072
	ds_read_b128 v[158:161], v166
	ds_read_b128 v[162:165], v166 offset:1024
	ds_read_b128 v[186:189], v166 offset:2048
	ds_read_b128 v[190:193], v166 offset:3072
	v_lshl_add_u64 v[166:167], s[54:55], 0, v[134:135]
	s_add_i32 m0, s53, 0xc000
	ds_read_b128 v[194:197], v149
	ds_read_b128 v[198:201], v149 offset:1024
	ds_read_b128 v[202:205], v149 offset:2048
	ds_read_b128 v[206:209], v149 offset:3072
	ds_read_b128 v[210:213], v149 offset:4096
	ds_read_b128 v[214:217], v149 offset:5120
	ds_read_b128 v[218:221], v149 offset:6144
	ds_read_b128 v[242:245], v149 offset:7168
	global_load_lds_dwordx4 v[166:167], off
	v_lshl_add_u64 v[166:167], s[54:55], 0, v[136:137]
	s_add_i32 m0, s53, 0xe000
	s_nop 0
	global_load_lds_dwordx4 v[166:167], off
	s_waitcnt vmcnt(8)
	s_waitcnt lgkmcnt(0)
	s_barrier
	s_cmp_lg_u32 s32, 0
	s_cbranch_scc1 .Lzc13_0
	s_setprio 1
	s_waitcnt lgkmcnt(0)
	v_mfma_f32_16x16x32_bf16 v[124:127], v[138:141], v[194:197], v[124:127]
	v_mfma_f32_16x16x32_bf16 v[120:123], v[150:153], v[194:197], v[120:123]
	v_mfma_f32_16x16x32_bf16 v[108:111], v[138:141], v[202:205], v[108:111]
	v_mfma_f32_16x16x32_bf16 v[104:107], v[150:153], v[202:205], v[104:107]
	v_mfma_f32_16x16x32_bf16 v[92:95], v[138:141], v[210:213], v[92:95]
	v_mfma_f32_16x16x32_bf16 v[88:91], v[150:153], v[210:213], v[88:91]
	v_mfma_f32_16x16x32_bf16 v[76:79], v[138:141], v[218:221], v[76:79]
	v_mfma_f32_16x16x32_bf16 v[72:75], v[150:153], v[218:221], v[72:75]
	v_mfma_f32_16x16x32_bf16 v[124:127], v[142:145], v[198:201], v[124:127]
	v_mfma_f32_16x16x32_bf16 v[120:123], v[154:157], v[198:201], v[120:123]
	v_mfma_f32_16x16x32_bf16 v[108:111], v[142:145], v[206:209], v[108:111]
	v_mfma_f32_16x16x32_bf16 v[104:107], v[154:157], v[206:209], v[104:107]
	v_mfma_f32_16x16x32_bf16 v[92:95], v[142:145], v[214:217], v[92:95]
	v_mfma_f32_16x16x32_bf16 v[88:91], v[154:157], v[214:217], v[88:91]
	v_mfma_f32_16x16x32_bf16 v[76:79], v[142:145], v[242:245], v[76:79]
	v_mfma_f32_16x16x32_bf16 v[72:75], v[154:157], v[242:245], v[72:75]
	s_setprio 0
	s_setprio 1
	v_mfma_f32_16x16x32_bf16 v[116:119], v[158:161], v[194:197], v[116:119]
	v_mfma_f32_16x16x32_bf16 v[112:115], v[186:189], v[194:197], v[112:115]
	v_mfma_f32_16x16x32_bf16 v[100:103], v[158:161], v[202:205], v[100:103]
	v_mfma_f32_16x16x32_bf16 v[96:99], v[186:189], v[202:205], v[96:99]
	v_mfma_f32_16x16x32_bf16 v[84:87], v[158:161], v[210:213], v[84:87]
	v_mfma_f32_16x16x32_bf16 v[80:83], v[186:189], v[210:213], v[80:83]
	v_mfma_f32_16x16x32_bf16 v[68:71], v[158:161], v[218:221], v[68:71]
	v_mfma_f32_16x16x32_bf16 v[64:67], v[186:189], v[218:221], v[64:67]
	v_mfma_f32_16x16x32_bf16 v[116:119], v[162:165], v[198:201], v[116:119]
	v_mfma_f32_16x16x32_bf16 v[112:115], v[190:193], v[198:201], v[112:115]
	v_mfma_f32_16x16x32_bf16 v[100:103], v[162:165], v[206:209], v[100:103]
	v_mfma_f32_16x16x32_bf16 v[96:99], v[190:193], v[206:209], v[96:99]
	v_mfma_f32_16x16x32_bf16 v[84:87], v[162:165], v[214:217], v[84:87]
	v_mfma_f32_16x16x32_bf16 v[80:83], v[190:193], v[214:217], v[80:83]
	v_mfma_f32_16x16x32_bf16 v[68:71], v[162:165], v[242:245], v[68:71]
	v_mfma_f32_16x16x32_bf16 v[64:67], v[190:193], v[242:245], v[64:67]
	s_setprio 0
.Lzc13_0j:
	s_barrier
	s_add_i32 s77, s77, s63
	v_lshl_add_u64 v[166:167], s[56:57], 0, v[168:169]
	s_mov_b32 m0, s77
	ds_read_b128 v[194:197], v149 offset:16384
	ds_read_b128 v[198:201], v149 offset:17408
	ds_read_b128 v[202:205], v149 offset:18432
	ds_read_b128 v[206:209], v149 offset:19456
	ds_read_b128 v[210:213], v149 offset:20480
	ds_read_b128 v[214:217], v149 offset:21504
	ds_read_b128 v[218:221], v149 offset:22528
	ds_read_b128 v[242:245], v149 offset:23552
	global_load_lds_dwordx4 v[166:167], off
	s_add_i32 m0, s77, 0x2000
	s_add_u32 s78, s56, 0x40000
	v_lshl_add_u64 v[222:223], s[56:57], 0, v[132:133]
	s_addc_u32 s79, s57, 0
	s_add_i32 s47, s47, s63
	global_load_lds_dwordx4 v[222:223], off
	v_lshl_add_u64 v[236:237], s[78:79], 0, v[168:169]
	s_mov_b32 m0, s47
	v_lshl_add_u64 v[246:247], s[58:59], 0, v[130:131]
	global_load_lds_dwordx4 v[236:237], off
	v_lshl_add_u64 v[236:237], s[78:79], 0, v[132:133]
	s_add_i32 m0, s47, 0x2000
	s_nop 0
	global_load_lds_dwordx4 v[236:237], off
	v_lshl_add_u64 v[236:237], s[58:59], 0, v[128:129]
	s_mov_b32 m0, s53
	s_nop 0
	global_load_lds_dwordx4 v[236:237], off
	s_mov_b32 m0, s64
	s_nop 0
	global_load_lds_dwordx4 v[246:247], off
	s_waitcnt vmcnt(8)
	s_waitcnt lgkmcnt(0)
	s_barrier
	s_cmp_lg_u32 s32, 0
	s_cbranch_scc1 .Lzc13_1
	s_setprio 1
	s_waitcnt lgkmcnt(0)
	v_mfma_f32_16x16x32_bf16 v[60:63], v[138:141], v[194:197], v[60:63]
	v_mfma_f32_16x16x32_bf16 v[56:59], v[150:153], v[194:197], v[56:59]
	v_mfma_f32_16x16x32_bf16 v[44:47], v[138:141], v[202:205], v[44:47]
	v_mfma_f32_16x16x32_bf16 v[40:43], v[150:153], v[202:205], v[40:43]
	v_mfma_f32_16x16x32_bf16 v[28:31], v[138:141], v[210:213], v[28:31]
	v_mfma_f32_16x16x32_bf16 v[24:27], v[150:153], v[210:213], v[24:27]
	v_mfma_f32_16x16x32_bf16 v[12:15], v[138:141], v[218:221], v[12:15]
	v_mfma_f32_16x16x32_bf16 v[8:11], v[150:153], v[218:221], v[8:11]
	v_mfma_f32_16x16x32_bf16 v[60:63], v[142:145], v[198:201], v[60:63]
	v_mfma_f32_16x16x32_bf16 v[56:59], v[154:157], v[198:201], v[56:59]
	v_mfma_f32_16x16x32_bf16 v[44:47], v[142:145], v[206:209], v[44:47]
	v_mfma_f32_16x16x32_bf16 v[40:43], v[154:157], v[206:209], v[40:43]
	v_mfma_f32_16x16x32_bf16 v[28:31], v[142:145], v[214:217], v[28:31]
	v_mfma_f32_16x16x32_bf16 v[24:27], v[154:157], v[214:217], v[24:27]
	v_mfma_f32_16x16x32_bf16 v[12:15], v[142:145], v[242:245], v[12:15]
	v_mfma_f32_16x16x32_bf16 v[8:11], v[154:157], v[242:245], v[8:11]
	s_setprio 0
	s_setprio 1
	v_mfma_f32_16x16x32_bf16 v[52:55], v[158:161], v[194:197], v[52:55]
	v_mfma_f32_16x16x32_bf16 v[48:51], v[186:189], v[194:197], v[48:51]
	v_mfma_f32_16x16x32_bf16 v[36:39], v[158:161], v[202:205], v[36:39]
	v_mfma_f32_16x16x32_bf16 v[32:35], v[186:189], v[202:205], v[32:35]
	v_mfma_f32_16x16x32_bf16 v[20:23], v[158:161], v[210:213], v[20:23]
	v_mfma_f32_16x16x32_bf16 v[16:19], v[186:189], v[210:213], v[16:19]
	v_mfma_f32_16x16x32_bf16 v[4:7], v[158:161], v[218:221], v[4:7]
	v_mfma_f32_16x16x32_bf16 v[0:3], v[186:189], v[218:221], v[0:3]
	v_mfma_f32_16x16x32_bf16 v[52:55], v[162:165], v[198:201], v[52:55]
	v_mfma_f32_16x16x32_bf16 v[48:51], v[190:193], v[198:201], v[48:51]
	v_mfma_f32_16x16x32_bf16 v[36:39], v[162:165], v[206:209], v[36:39]
	v_mfma_f32_16x16x32_bf16 v[32:35], v[190:193], v[206:209], v[32:35]
	v_mfma_f32_16x16x32_bf16 v[20:23], v[162:165], v[214:217], v[20:23]
	v_mfma_f32_16x16x32_bf16 v[16:19], v[190:193], v[214:217], v[16:19]
	v_mfma_f32_16x16x32_bf16 v[4:7], v[162:165], v[242:245], v[4:7]
	v_mfma_f32_16x16x32_bf16 v[0:3], v[190:193], v[242:245], v[0:3]
	s_setprio 0
.Lzc13_1j:
	s_barrier
	s_add_i32 s47, 0, 0x18000
	s_add_i32 s77, 0, 0x1c000
	v_add_u32_e32 v154, s47, v148
	v_add_u32_e32 v179, s77, v148
	ds_read_b128 v[138:141], v154
	ds_read_b128 v[142:145], v154 offset:1024
	ds_read_b128 v[150:153], v154 offset:2048
	ds_read_b128 v[154:157], v154 offset:3072
	ds_read_b128 v[158:161], v179
	ds_read_b128 v[162:165], v179 offset:1024
	ds_read_b128 v[186:189], v179 offset:2048
	ds_read_b128 v[190:193], v179 offset:3072
	s_add_u32 s58, s58, 0x40000
	s_addc_u32 s59, s59, 0
	s_mov_b32 m0, s65
	v_lshl_add_u64 v[248:249], s[58:59], 0, v[128:129]
	ds_read_b128 v[194:197], v149 offset:32768
	ds_read_b128 v[198:201], v149 offset:33792
	ds_read_b128 v[202:205], v149 offset:34816
	ds_read_b128 v[206:209], v149 offset:35840
	ds_read_b128 v[210:213], v149 offset:36864
	ds_read_b128 v[214:217], v149 offset:37888
	ds_read_b128 v[218:221], v149 offset:38912
	ds_read_b128 v[242:245], v149 offset:39936
	global_load_lds_dwordx4 v[248:249], off
	v_lshl_add_u64 v[248:249], s[58:59], 0, v[130:131]
	s_mov_b32 m0, s66
	s_nop 0
	global_load_lds_dwordx4 v[248:249], off
	s_waitcnt vmcnt(8)
	s_waitcnt lgkmcnt(0)
	s_barrier
	s_setprio 1
	s_waitcnt lgkmcnt(0)
	v_mfma_f32_16x16x32_bf16 v[124:127], v[138:141], v[194:197], v[124:127]
	v_mfma_f32_16x16x32_bf16 v[120:123], v[150:153], v[194:197], v[120:123]
	v_mfma_f32_16x16x32_bf16 v[108:111], v[138:141], v[202:205], v[108:111]
	v_mfma_f32_16x16x32_bf16 v[104:107], v[150:153], v[202:205], v[104:107]
	v_mfma_f32_16x16x32_bf16 v[92:95], v[138:141], v[210:213], v[92:95]
	v_mfma_f32_16x16x32_bf16 v[88:91], v[150:153], v[210:213], v[88:91]
	v_mfma_f32_16x16x32_bf16 v[76:79], v[138:141], v[218:221], v[76:79]
	v_mfma_f32_16x16x32_bf16 v[72:75], v[150:153], v[218:221], v[72:75]
	v_mfma_f32_16x16x32_bf16 v[124:127], v[142:145], v[198:201], v[124:127]
	v_mfma_f32_16x16x32_bf16 v[120:123], v[154:157], v[198:201], v[120:123]
	v_mfma_f32_16x16x32_bf16 v[108:111], v[142:145], v[206:209], v[108:111]
	v_mfma_f32_16x16x32_bf16 v[104:107], v[154:157], v[206:209], v[104:107]
	v_mfma_f32_16x16x32_bf16 v[92:95], v[142:145], v[214:217], v[92:95]
	v_mfma_f32_16x16x32_bf16 v[88:91], v[154:157], v[214:217], v[88:91]
	v_mfma_f32_16x16x32_bf16 v[76:79], v[142:145], v[242:245], v[76:79]
	v_mfma_f32_16x16x32_bf16 v[72:75], v[154:157], v[242:245], v[72:75]
	s_setprio 0
	s_setprio 1
	v_mfma_f32_16x16x32_bf16 v[116:119], v[158:161], v[194:197], v[116:119]
	v_mfma_f32_16x16x32_bf16 v[112:115], v[186:189], v[194:197], v[112:115]
	v_mfma_f32_16x16x32_bf16 v[100:103], v[158:161], v[202:205], v[100:103]
	v_mfma_f32_16x16x32_bf16 v[96:99], v[186:189], v[202:205], v[96:99]
	v_mfma_f32_16x16x32_bf16 v[84:87], v[158:161], v[210:213], v[84:87]
	v_mfma_f32_16x16x32_bf16 v[80:83], v[186:189], v[210:213], v[80:83]
	v_mfma_f32_16x16x32_bf16 v[68:71], v[158:161], v[218:221], v[68:71]
	v_mfma_f32_16x16x32_bf16 v[64:67], v[186:189], v[218:221], v[64:67]
	v_mfma_f32_16x16x32_bf16 v[116:119], v[162:165], v[198:201], v[116:119]
	v_mfma_f32_16x16x32_bf16 v[112:115], v[190:193], v[198:201], v[112:115]
	v_mfma_f32_16x16x32_bf16 v[100:103], v[162:165], v[206:209], v[100:103]
	v_mfma_f32_16x16x32_bf16 v[96:99], v[190:193], v[206:209], v[96:99]
	v_mfma_f32_16x16x32_bf16 v[84:87], v[162:165], v[214:217], v[84:87]
	v_mfma_f32_16x16x32_bf16 v[80:83], v[190:193], v[214:217], v[80:83]
	v_mfma_f32_16x16x32_bf16 v[68:71], v[162:165], v[242:245], v[68:71]
	v_mfma_f32_16x16x32_bf16 v[64:67], v[190:193], v[242:245], v[64:67]
	s_setprio 0
	s_barrier
	s_add_i32 s47, s47, s63
	v_lshl_add_u64 v[166:167], v[166:167], 0, s[28:29]
	s_mov_b32 m0, s47
	ds_read_b128 v[194:197], v149 offset:49152
	ds_read_b128 v[198:201], v149 offset:50176
	ds_read_b128 v[202:205], v149 offset:51200
	ds_read_b128 v[206:209], v149 offset:52224
	ds_read_b128 v[210:213], v149 offset:53248
	ds_read_b128 v[214:217], v149 offset:54272
	ds_read_b128 v[218:221], v149 offset:55296
	ds_read_b128 v[242:245], v149 offset:56320
	global_load_lds_dwordx4 v[166:167], off
	s_add_i32 m0, s47, 0x2000
	s_add_u32 s56, s56, 0x40080
	v_lshl_add_u64 v[166:167], v[222:223], 0, s[28:29]
	s_addc_u32 s57, s57, 0
	s_add_i32 s47, s77, s63
	global_load_lds_dwordx4 v[166:167], off
	v_lshl_add_u64 v[166:167], s[56:57], 0, v[168:169]
	s_mov_b32 m0, s47
	s_nop 0
	global_load_lds_dwordx4 v[166:167], off
	v_lshl_add_u64 v[166:167], s[56:57], 0, v[132:133]
	s_add_i32 m0, s47, 0x2000
	s_nop 0
	global_load_lds_dwordx4 v[166:167], off
	v_lshl_add_u64 v[166:167], v[236:237], 0, s[28:29]
	s_mov_b32 m0, s70
	s_nop 0
	global_load_lds_dwordx4 v[166:167], off
	v_lshl_add_u64 v[166:167], v[246:247], 0, s[28:29]
	s_mov_b32 m0, s71
	s_nop 0
	global_load_lds_dwordx4 v[166:167], off
	s_waitcnt vmcnt(8)
	s_waitcnt lgkmcnt(0)
	s_barrier
	s_setprio 1
	s_waitcnt lgkmcnt(0)
	v_mfma_f32_16x16x32_bf16 v[60:63], v[138:141], v[194:197], v[60:63]
	v_mfma_f32_16x16x32_bf16 v[56:59], v[150:153], v[194:197], v[56:59]
	v_mfma_f32_16x16x32_bf16 v[44:47], v[138:141], v[202:205], v[44:47]
	v_mfma_f32_16x16x32_bf16 v[40:43], v[150:153], v[202:205], v[40:43]
	v_mfma_f32_16x16x32_bf16 v[28:31], v[138:141], v[210:213], v[28:31]
	v_mfma_f32_16x16x32_bf16 v[24:27], v[150:153], v[210:213], v[24:27]
	v_mfma_f32_16x16x32_bf16 v[12:15], v[138:141], v[218:221], v[12:15]
	v_mfma_f32_16x16x32_bf16 v[8:11], v[150:153], v[218:221], v[8:11]
	v_mfma_f32_16x16x32_bf16 v[60:63], v[142:145], v[198:201], v[60:63]
	v_mfma_f32_16x16x32_bf16 v[56:59], v[154:157], v[198:201], v[56:59]
	v_mfma_f32_16x16x32_bf16 v[44:47], v[142:145], v[206:209], v[44:47]
	v_mfma_f32_16x16x32_bf16 v[40:43], v[154:157], v[206:209], v[40:43]
	v_mfma_f32_16x16x32_bf16 v[28:31], v[142:145], v[214:217], v[28:31]
	v_mfma_f32_16x16x32_bf16 v[24:27], v[154:157], v[214:217], v[24:27]
	v_mfma_f32_16x16x32_bf16 v[12:15], v[142:145], v[242:245], v[12:15]
	v_mfma_f32_16x16x32_bf16 v[8:11], v[154:157], v[242:245], v[8:11]
	s_setprio 0
	s_setprio 1
	v_mfma_f32_16x16x32_bf16 v[52:55], v[158:161], v[194:197], v[52:55]
	v_mfma_f32_16x16x32_bf16 v[48:51], v[186:189], v[194:197], v[48:51]
	v_mfma_f32_16x16x32_bf16 v[36:39], v[158:161], v[202:205], v[36:39]
	v_mfma_f32_16x16x32_bf16 v[32:35], v[186:189], v[202:205], v[32:35]
	v_mfma_f32_16x16x32_bf16 v[20:23], v[158:161], v[210:213], v[20:23]
	v_mfma_f32_16x16x32_bf16 v[16:19], v[186:189], v[210:213], v[16:19]
	v_mfma_f32_16x16x32_bf16 v[4:7], v[158:161], v[218:221], v[4:7]
	v_mfma_f32_16x16x32_bf16 v[0:3], v[186:189], v[218:221], v[0:3]
	v_mfma_f32_16x16x32_bf16 v[52:55], v[162:165], v[198:201], v[52:55]
	v_mfma_f32_16x16x32_bf16 v[48:51], v[190:193], v[198:201], v[48:51]
	v_mfma_f32_16x16x32_bf16 v[36:39], v[162:165], v[206:209], v[36:39]
	v_mfma_f32_16x16x32_bf16 v[32:35], v[190:193], v[206:209], v[32:35]
	v_mfma_f32_16x16x32_bf16 v[20:23], v[162:165], v[214:217], v[20:23]
	v_mfma_f32_16x16x32_bf16 v[16:19], v[190:193], v[214:217], v[16:19]
	v_mfma_f32_16x16x32_bf16 v[4:7], v[162:165], v[242:245], v[4:7]
	v_mfma_f32_16x16x32_bf16 v[0:3], v[190:193], v[242:245], v[0:3]
	s_setprio 0
	s_barrier
	s_add_u32 s54, s54, 0x100
	s_addc_u32 s55, s55, 0
	s_add_u32 s43, s43, 0x100
	s_addc_u32 s45, s45, 0
	s_cmp_ge_i32 s76, s67
	s_mov_b32 s47, s76
	s_mov_b32 s32, 0
	s_cbranch_scc0 .LBB0_916
	s_mov_b32 s76, 0x3fffff80
	v_readlane_b32 s77, v254, 56

.LBB0_978:
	s_andn2_b64 vcc, exec, s[20:21]
	s_cbranch_vccnz .Lzc14_skip
	s_add_u32 s50, s50, 0x40080
	s_addc_u32 s51, s51, 0
	s_add_u32 s1, s52, 0x100
	s_addc_u32 s3, s53, 0
	s_mov_b32 s41, 0
	s_mov_b32 s32, 1
.LBB0_980:
	s_add_i32 s43, s41, 2
	s_add_u32 s49, s50, 0xfffc0080
	s_addc_u32 s52, s51, -1
	s_add_i32 s76, 0, 0x10000
	s_cmp_eq_u32 s69, s41
	s_cselect_b32 s55, s45, s52
	s_cselect_b32 s54, s44, s49
	s_cselect_b32 s53, s47, s3
	s_cselect_b32 s52, s46, s1
	s_add_i32 s41, 0, 0x14000
	v_add_u32_e32 v154, s76, v148
	v_add_u32_e32 v166, s41, v148
	ds_read_b128 v[138:141], v154
	ds_read_b128 v[142:145], v154 offset:1024
	ds_read_b128 v[150:153], v154 offset:2048
	ds_read_b128 v[154:157], v154 offset:3072
	ds_read_b128 v[158:161], v166
	ds_read_b128 v[162:165], v166 offset:1024
	ds_read_b128 v[186:189], v166 offset:2048
	ds_read_b128 v[190:193], v166 offset:3072
	v_lshl_add_u64 v[166:167], s[50:51], 0, v[134:135]
	s_add_i32 m0, s59, 0xc000
	ds_read_b128 v[194:197], v149
	ds_read_b128 v[198:201], v149 offset:1024
	ds_read_b128 v[202:205], v149 offset:2048
	ds_read_b128 v[206:209], v149 offset:3072
	ds_read_b128 v[210:213], v149 offset:4096
	ds_read_b128 v[214:217], v149 offset:5120
	ds_read_b128 v[218:221], v149 offset:6144
	ds_read_b128 v[242:245], v149 offset:7168
	global_load_lds_dwordx4 v[166:167], off
	v_lshl_add_u64 v[166:167], s[50:51], 0, v[136:137]
	s_add_i32 m0, s59, 0xe000
	s_nop 0
	global_load_lds_dwordx4 v[166:167], off
	s_waitcnt vmcnt(8)
	s_waitcnt lgkmcnt(0)
	s_barrier
	s_cmp_lg_u32 s32, 0
	s_cbranch_scc1 .Lzc14_0
	s_setprio 1
	s_waitcnt lgkmcnt(0)
	v_mfma_f32_16x16x32_bf16 v[124:127], v[138:141], v[194:197], v[124:127]
	v_mfma_f32_16x16x32_bf16 v[120:123], v[150:153], v[194:197], v[120:123]
	v_mfma_f32_16x16x32_bf16 v[108:111], v[138:141], v[202:205], v[108:111]
	v_mfma_f32_16x16x32_bf16 v[104:107], v[150:153], v[202:205], v[104:107]
	v_mfma_f32_16x16x32_bf16 v[92:95], v[138:141], v[210:213], v[92:95]
	v_mfma_f32_16x16x32_bf16 v[88:91], v[150:153], v[210:213], v[88:91]
	v_mfma_f32_16x16x32_bf16 v[76:79], v[138:141], v[218:221], v[76:79]
	v_mfma_f32_16x16x32_bf16 v[72:75], v[150:153], v[218:221], v[72:75]
	v_mfma_f32_16x16x32_bf16 v[124:127], v[142:145], v[198:201], v[124:127]
	v_mfma_f32_16x16x32_bf16 v[120:123], v[154:157], v[198:201], v[120:123]
	v_mfma_f32_16x16x32_bf16 v[108:111], v[142:145], v[206:209], v[108:111]
	v_mfma_f32_16x16x32_bf16 v[104:107], v[154:157], v[206:209], v[104:107]
	v_mfma_f32_16x16x32_bf16 v[92:95], v[142:145], v[214:217], v[92:95]
	v_mfma_f32_16x16x32_bf16 v[88:91], v[154:157], v[214:217], v[88:91]
	v_mfma_f32_16x16x32_bf16 v[76:79], v[142:145], v[242:245], v[76:79]
	v_mfma_f32_16x16x32_bf16 v[72:75], v[154:157], v[242:245], v[72:75]
	s_setprio 0
	s_setprio 1
	v_mfma_f32_16x16x32_bf16 v[116:119], v[158:161], v[194:197], v[116:119]
	v_mfma_f32_16x16x32_bf16 v[112:115], v[186:189], v[194:197], v[112:115]
	v_mfma_f32_16x16x32_bf16 v[100:103], v[158:161], v[202:205], v[100:103]
	v_mfma_f32_16x16x32_bf16 v[96:99], v[186:189], v[202:205], v[96:99]
	v_mfma_f32_16x16x32_bf16 v[84:87], v[158:161], v[210:213], v[84:87]
	v_mfma_f32_16x16x32_bf16 v[80:83], v[186:189], v[210:213], v[80:83]
	v_mfma_f32_16x16x32_bf16 v[68:71], v[158:161], v[218:221], v[68:71]
	v_mfma_f32_16x16x32_bf16 v[64:67], v[186:189], v[218:221], v[64:67]
	v_mfma_f32_16x16x32_bf16 v[116:119], v[162:165], v[198:201], v[116:119]
	v_mfma_f32_16x16x32_bf16 v[112:115], v[190:193], v[198:201], v[112:115]
	v_mfma_f32_16x16x32_bf16 v[100:103], v[162:165], v[206:209], v[100:103]
	v_mfma_f32_16x16x32_bf16 v[96:99], v[190:193], v[206:209], v[96:99]
	v_mfma_f32_16x16x32_bf16 v[84:87], v[162:165], v[214:217], v[84:87]
	v_mfma_f32_16x16x32_bf16 v[80:83], v[190:193], v[214:217], v[80:83]
	v_mfma_f32_16x16x32_bf16 v[68:71], v[162:165], v[242:245], v[68:71]
	v_mfma_f32_16x16x32_bf16 v[64:67], v[190:193], v[242:245], v[64:67]
	s_setprio 0
.Lzc14_0j:
	s_barrier
	s_add_i32 s49, s76, s58
	v_lshl_add_u64 v[166:167], s[52:53], 0, v[168:169]
	s_mov_b32 m0, s49
	ds_read_b128 v[194:197], v149 offset:16384
	ds_read_b128 v[198:201], v149 offset:17408
	ds_read_b128 v[202:205], v149 offset:18432
	ds_read_b128 v[206:209], v149 offset:19456
	ds_read_b128 v[210:213], v149 offset:20480
	ds_read_b128 v[214:217], v149 offset:21504
	ds_read_b128 v[218:221], v149 offset:22528
	ds_read_b128 v[242:245], v149 offset:23552
	global_load_lds_dwordx4 v[166:167], off
	s_add_i32 m0, s49, 0x2000
	s_add_u32 s76, s52, 0x40000
	v_lshl_add_u64 v[222:223], s[52:53], 0, v[132:133]
	s_addc_u32 s77, s53, 0
	s_add_i32 s41, s41, s58
	global_load_lds_dwordx4 v[222:223], off
	v_lshl_add_u64 v[236:237], s[76:77], 0, v[168:169]
	s_mov_b32 m0, s41
	v_lshl_add_u64 v[246:247], s[54:55], 0, v[130:131]
	global_load_lds_dwordx4 v[236:237], off
	v_lshl_add_u64 v[236:237], s[76:77], 0, v[132:133]
	s_add_i32 m0, s41, 0x2000
	s_nop 0
	global_load_lds_dwordx4 v[236:237], off
	v_lshl_add_u64 v[236:237], s[54:55], 0, v[128:129]
	s_mov_b32 m0, s59
	s_nop 0
	global_load_lds_dwordx4 v[236:237], off
	s_mov_b32 m0, s61
	s_nop 0
	global_load_lds_dwordx4 v[246:247], off
	s_waitcnt vmcnt(8)
	s_waitcnt lgkmcnt(0)
	s_barrier
	s_cmp_lg_u32 s32, 0
	s_cbranch_scc1 .Lzc14_1
	s_setprio 1
	s_waitcnt lgkmcnt(0)
	v_mfma_f32_16x16x32_bf16 v[60:63], v[138:141], v[194:197], v[60:63]
	v_mfma_f32_16x16x32_bf16 v[56:59], v[150:153], v[194:197], v[56:59]
	v_mfma_f32_16x16x32_bf16 v[44:47], v[138:141], v[202:205], v[44:47]
	v_mfma_f32_16x16x32_bf16 v[40:43], v[150:153], v[202:205], v[40:43]
	v_mfma_f32_16x16x32_bf16 v[28:31], v[138:141], v[210:213], v[28:31]
	v_mfma_f32_16x16x32_bf16 v[24:27], v[150:153], v[210:213], v[24:27]
	v_mfma_f32_16x16x32_bf16 v[12:15], v[138:141], v[218:221], v[12:15]
	v_mfma_f32_16x16x32_bf16 v[8:11], v[150:153], v[218:221], v[8:11]
	v_mfma_f32_16x16x32_bf16 v[60:63], v[142:145], v[198:201], v[60:63]
	v_mfma_f32_16x16x32_bf16 v[56:59], v[154:157], v[198:201], v[56:59]
	v_mfma_f32_16x16x32_bf16 v[44:47], v[142:145], v[206:209], v[44:47]
	v_mfma_f32_16x16x32_bf16 v[40:43], v[154:157], v[206:209], v[40:43]
	v_mfma_f32_16x16x32_bf16 v[28:31], v[142:145], v[214:217], v[28:31]
	v_mfma_f32_16x16x32_bf16 v[24:27], v[154:157], v[214:217], v[24:27]
	v_mfma_f32_16x16x32_bf16 v[12:15], v[142:145], v[242:245], v[12:15]
	v_mfma_f32_16x16x32_bf16 v[8:11], v[154:157], v[242:245], v[8:11]
	s_setprio 0
	s_setprio 1
	v_mfma_f32_16x16x32_bf16 v[52:55], v[158:161], v[194:197], v[52:55]
	v_mfma_f32_16x16x32_bf16 v[48:51], v[186:189], v[194:197], v[48:51]
	v_mfma_f32_16x16x32_bf16 v[36:39], v[158:161], v[202:205], v[36:39]
	v_mfma_f32_16x16x32_bf16 v[32:35], v[186:189], v[202:205], v[32:35]
	v_mfma_f32_16x16x32_bf16 v[20:23], v[158:161], v[210:213], v[20:23]
	v_mfma_f32_16x16x32_bf16 v[16:19], v[186:189], v[210:213], v[16:19]
	v_mfma_f32_16x16x32_bf16 v[4:7], v[158:161], v[218:221], v[4:7]
	v_mfma_f32_16x16x32_bf16 v[0:3], v[186:189], v[218:221], v[0:3]
	v_mfma_f32_16x16x32_bf16 v[52:55], v[162:165], v[198:201], v[52:55]
	v_mfma_f32_16x16x32_bf16 v[48:51], v[190:193], v[198:201], v[48:51]
	v_mfma_f32_16x16x32_bf16 v[36:39], v[162:165], v[206:209], v[36:39]
	v_mfma_f32_16x16x32_bf16 v[32:35], v[190:193], v[206:209], v[32:35]
	v_mfma_f32_16x16x32_bf16 v[20:23], v[162:165], v[214:217], v[20:23]
	v_mfma_f32_16x16x32_bf16 v[16:19], v[190:193], v[214:217], v[16:19]
	v_mfma_f32_16x16x32_bf16 v[4:7], v[162:165], v[242:245], v[4:7]
	v_mfma_f32_16x16x32_bf16 v[0:3], v[190:193], v[242:245], v[0:3]
	s_setprio 0
.Lzc14_1j:
	s_barrier
	s_add_i32 s41, 0, 0x18000
	s_add_i32 s49, 0, 0x1c000
	v_add_u32_e32 v154, s41, v148
	v_add_u32_e32 v179, s49, v148
	ds_read_b128 v[138:141], v154
	ds_read_b128 v[142:145], v154 offset:1024
	ds_read_b128 v[150:153], v154 offset:2048
	ds_read_b128 v[154:157], v154 offset:3072
	ds_read_b128 v[158:161], v179
	ds_read_b128 v[162:165], v179 offset:1024
	ds_read_b128 v[186:189], v179 offset:2048
	ds_read_b128 v[190:193], v179 offset:3072
	s_add_u32 s54, s54, 0x40000
	s_addc_u32 s55, s55, 0
	s_mov_b32 m0, s62
	v_lshl_add_u64 v[248:249], s[54:55], 0, v[128:129]
	ds_read_b128 v[194:197], v149 offset:32768
	ds_read_b128 v[198:201], v149 offset:33792
	ds_read_b128 v[202:205], v149 offset:34816
	ds_read_b128 v[206:209], v149 offset:35840
	ds_read_b128 v[210:213], v149 offset:36864
	ds_read_b128 v[214:217], v149 offset:37888
	ds_read_b128 v[218:221], v149 offset:38912
	ds_read_b128 v[242:245], v149 offset:39936
	global_load_lds_dwordx4 v[248:249], off
	v_lshl_add_u64 v[248:249], s[54:55], 0, v[130:131]
	s_mov_b32 m0, s63
	s_nop 0
	global_load_lds_dwordx4 v[248:249], off
	s_waitcnt vmcnt(8)
	s_waitcnt lgkmcnt(0)
	s_barrier
	s_setprio 1
	s_waitcnt lgkmcnt(0)
	v_mfma_f32_16x16x32_bf16 v[124:127], v[138:141], v[194:197], v[124:127]
	v_mfma_f32_16x16x32_bf16 v[120:123], v[150:153], v[194:197], v[120:123]
	v_mfma_f32_16x16x32_bf16 v[108:111], v[138:141], v[202:205], v[108:111]
	v_mfma_f32_16x16x32_bf16 v[104:107], v[150:153], v[202:205], v[104:107]
	v_mfma_f32_16x16x32_bf16 v[92:95], v[138:141], v[210:213], v[92:95]
	v_mfma_f32_16x16x32_bf16 v[88:91], v[150:153], v[210:213], v[88:91]
	v_mfma_f32_16x16x32_bf16 v[76:79], v[138:141], v[218:221], v[76:79]
	v_mfma_f32_16x16x32_bf16 v[72:75], v[150:153], v[218:221], v[72:75]
	v_mfma_f32_16x16x32_bf16 v[124:127], v[142:145], v[198:201], v[124:127]
	v_mfma_f32_16x16x32_bf16 v[120:123], v[154:157], v[198:201], v[120:123]
	v_mfma_f32_16x16x32_bf16 v[108:111], v[142:145], v[206:209], v[108:111]
	v_mfma_f32_16x16x32_bf16 v[104:107], v[154:157], v[206:209], v[104:107]
	v_mfma_f32_16x16x32_bf16 v[92:95], v[142:145], v[214:217], v[92:95]
	v_mfma_f32_16x16x32_bf16 v[88:91], v[154:157], v[214:217], v[88:91]
	v_mfma_f32_16x16x32_bf16 v[76:79], v[142:145], v[242:245], v[76:79]
	v_mfma_f32_16x16x32_bf16 v[72:75], v[154:157], v[242:245], v[72:75]
	s_setprio 0
	s_setprio 1
	v_mfma_f32_16x16x32_bf16 v[116:119], v[158:161], v[194:197], v[116:119]
	v_mfma_f32_16x16x32_bf16 v[112:115], v[186:189], v[194:197], v[112:115]
	v_mfma_f32_16x16x32_bf16 v[100:103], v[158:161], v[202:205], v[100:103]
	v_mfma_f32_16x16x32_bf16 v[96:99], v[186:189], v[202:205], v[96:99]
	v_mfma_f32_16x16x32_bf16 v[84:87], v[158:161], v[210:213], v[84:87]
	v_mfma_f32_16x16x32_bf16 v[80:83], v[186:189], v[210:213], v[80:83]
	v_mfma_f32_16x16x32_bf16 v[68:71], v[158:161], v[218:221], v[68:71]
	v_mfma_f32_16x16x32_bf16 v[64:67], v[186:189], v[218:221], v[64:67]
	v_mfma_f32_16x16x32_bf16 v[116:119], v[162:165], v[198:201], v[116:119]
	v_mfma_f32_16x16x32_bf16 v[112:115], v[190:193], v[198:201], v[112:115]
	v_mfma_f32_16x16x32_bf16 v[100:103], v[162:165], v[206:209], v[100:103]
	v_mfma_f32_16x16x32_bf16 v[96:99], v[190:193], v[206:209], v[96:99]
	v_mfma_f32_16x16x32_bf16 v[84:87], v[162:165], v[214:217], v[84:87]
	v_mfma_f32_16x16x32_bf16 v[80:83], v[190:193], v[214:217], v[80:83]
	v_mfma_f32_16x16x32_bf16 v[68:71], v[162:165], v[242:245], v[68:71]
	v_mfma_f32_16x16x32_bf16 v[64:67], v[190:193], v[242:245], v[64:67]
	s_setprio 0
	s_barrier
	s_add_i32 s41, s41, s58
	v_lshl_add_u64 v[166:167], v[166:167], 0, s[28:29]
	s_mov_b32 m0, s41
	ds_read_b128 v[194:197], v149 offset:49152
	ds_read_b128 v[198:201], v149 offset:50176
	ds_read_b128 v[202:205], v149 offset:51200
	ds_read_b128 v[206:209], v149 offset:52224
	ds_read_b128 v[210:213], v149 offset:53248
	ds_read_b128 v[214:217], v149 offset:54272
	ds_read_b128 v[218:221], v149 offset:55296
	ds_read_b128 v[242:245], v149 offset:56320
	global_load_lds_dwordx4 v[166:167], off
	s_add_i32 m0, s41, 0x2000
	s_add_u32 s52, s52, 0x40080
	v_lshl_add_u64 v[166:167], v[222:223], 0, s[28:29]
	s_addc_u32 s53, s53, 0
	s_add_i32 s41, s49, s58
	global_load_lds_dwordx4 v[166:167], off
	v_lshl_add_u64 v[166:167], s[52:53], 0, v[168:169]
	s_mov_b32 m0, s41
	s_nop 0
	global_load_lds_dwordx4 v[166:167], off
	v_lshl_add_u64 v[166:167], s[52:53], 0, v[132:133]
	s_add_i32 m0, s41, 0x2000
	s_nop 0
	global_load_lds_dwordx4 v[166:167], off
	v_lshl_add_u64 v[166:167], v[236:237], 0, s[28:29]
	s_mov_b32 m0, s67
	s_nop 0
	global_load_lds_dwordx4 v[166:167], off
	v_lshl_add_u64 v[166:167], v[246:247], 0, s[28:29]
	s_mov_b32 m0, s68
	s_nop 0
	global_load_lds_dwordx4 v[166:167], off
	s_waitcnt vmcnt(8)
	s_waitcnt lgkmcnt(0)
	s_barrier
	s_setprio 1
	s_waitcnt lgkmcnt(0)
	v_mfma_f32_16x16x32_bf16 v[60:63], v[138:141], v[194:197], v[60:63]
	v_mfma_f32_16x16x32_bf16 v[56:59], v[150:153], v[194:197], v[56:59]
	v_mfma_f32_16x16x32_bf16 v[44:47], v[138:141], v[202:205], v[44:47]
	v_mfma_f32_16x16x32_bf16 v[40:43], v[150:153], v[202:205], v[40:43]
	v_mfma_f32_16x16x32_bf16 v[28:31], v[138:141], v[210:213], v[28:31]
	v_mfma_f32_16x16x32_bf16 v[24:27], v[150:153], v[210:213], v[24:27]
	v_mfma_f32_16x16x32_bf16 v[12:15], v[138:141], v[218:221], v[12:15]
	v_mfma_f32_16x16x32_bf16 v[8:11], v[150:153], v[218:221], v[8:11]
	v_mfma_f32_16x16x32_bf16 v[60:63], v[142:145], v[198:201], v[60:63]
	v_mfma_f32_16x16x32_bf16 v[56:59], v[154:157], v[198:201], v[56:59]
	v_mfma_f32_16x16x32_bf16 v[44:47], v[142:145], v[206:209], v[44:47]
	v_mfma_f32_16x16x32_bf16 v[40:43], v[154:157], v[206:209], v[40:43]
	v_mfma_f32_16x16x32_bf16 v[28:31], v[142:145], v[214:217], v[28:31]
	v_mfma_f32_16x16x32_bf16 v[24:27], v[154:157], v[214:217], v[24:27]
	v_mfma_f32_16x16x32_bf16 v[12:15], v[142:145], v[242:245], v[12:15]
	v_mfma_f32_16x16x32_bf16 v[8:11], v[154:157], v[242:245], v[8:11]
	s_setprio 0
	s_setprio 1
	v_mfma_f32_16x16x32_bf16 v[52:55], v[158:161], v[194:197], v[52:55]
	v_mfma_f32_16x16x32_bf16 v[48:51], v[186:189], v[194:197], v[48:51]
	v_mfma_f32_16x16x32_bf16 v[36:39], v[158:161], v[202:205], v[36:39]
	v_mfma_f32_16x16x32_bf16 v[32:35], v[186:189], v[202:205], v[32:35]
	v_mfma_f32_16x16x32_bf16 v[20:23], v[158:161], v[210:213], v[20:23]
	v_mfma_f32_16x16x32_bf16 v[16:19], v[186:189], v[210:213], v[16:19]
	v_mfma_f32_16x16x32_bf16 v[4:7], v[158:161], v[218:221], v[4:7]
	v_mfma_f32_16x16x32_bf16 v[0:3], v[186:189], v[218:221], v[0:3]
	v_mfma_f32_16x16x32_bf16 v[52:55], v[162:165], v[198:201], v[52:55]
	v_mfma_f32_16x16x32_bf16 v[48:51], v[190:193], v[198:201], v[48:51]
	v_mfma_f32_16x16x32_bf16 v[36:39], v[162:165], v[206:209], v[36:39]
	v_mfma_f32_16x16x32_bf16 v[32:35], v[190:193], v[206:209], v[32:35]
	v_mfma_f32_16x16x32_bf16 v[20:23], v[162:165], v[214:217], v[20:23]
	v_mfma_f32_16x16x32_bf16 v[16:19], v[190:193], v[214:217], v[16:19]
	v_mfma_f32_16x16x32_bf16 v[4:7], v[162:165], v[242:245], v[4:7]
	v_mfma_f32_16x16x32_bf16 v[0:3], v[190:193], v[242:245], v[0:3]
	s_setprio 0
	s_barrier
	s_add_u32 s50, s50, 0x100
	s_addc_u32 s51, s51, 0
	s_add_u32 s1, s1, 0x100
	s_addc_u32 s3, s3, 0
	s_cmp_ge_i32 s43, s64
	s_mov_b32 s41, s43
	s_mov_b32 s32, 0
	s_cbranch_scc0 .LBB0_980
	v_readlane_b32 s77, v254, 56

.Lzc15_0:
	s_setprio 1
	s_waitcnt lgkmcnt(0)
	v_mfma_f32_16x16x32_bf16 v[124:127], v[138:141], v[194:197], 0
	v_mfma_f32_16x16x32_bf16 v[120:123], v[152:155], v[194:197], 0
	v_mfma_f32_16x16x32_bf16 v[108:111], v[138:141], v[202:205], 0
	v_mfma_f32_16x16x32_bf16 v[104:107], v[152:155], v[202:205], 0
	v_mfma_f32_16x16x32_bf16 v[92:95], v[138:141], v[210:213], 0
	v_mfma_f32_16x16x32_bf16 v[88:91], v[152:155], v[210:213], 0
	v_mfma_f32_16x16x32_bf16 v[76:79], v[138:141], v[218:221], 0
	v_mfma_f32_16x16x32_bf16 v[72:75], v[152:155], v[218:221], 0
	v_mfma_f32_16x16x32_bf16 v[124:127], v[148:151], v[198:201], v[124:127]
	v_mfma_f32_16x16x32_bf16 v[120:123], v[156:159], v[198:201], v[120:123]
	v_mfma_f32_16x16x32_bf16 v[108:111], v[148:151], v[206:209], v[108:111]
	v_mfma_f32_16x16x32_bf16 v[104:107], v[156:159], v[206:209], v[104:107]
	v_mfma_f32_16x16x32_bf16 v[92:95], v[148:151], v[214:217], v[92:95]
	v_mfma_f32_16x16x32_bf16 v[88:91], v[156:159], v[214:217], v[88:91]
	v_mfma_f32_16x16x32_bf16 v[76:79], v[148:151], v[242:245], v[76:79]
	v_mfma_f32_16x16x32_bf16 v[72:75], v[156:159], v[242:245], v[72:75]
	s_setprio 0
	s_setprio 1
	v_mfma_f32_16x16x32_bf16 v[116:119], v[160:163], v[194:197], 0
	v_mfma_f32_16x16x32_bf16 v[112:115], v[186:189], v[194:197], 0
	v_mfma_f32_16x16x32_bf16 v[100:103], v[160:163], v[202:205], 0
	v_mfma_f32_16x16x32_bf16 v[96:99], v[186:189], v[202:205], 0
	v_mfma_f32_16x16x32_bf16 v[84:87], v[160:163], v[210:213], 0
	v_mfma_f32_16x16x32_bf16 v[80:83], v[186:189], v[210:213], 0
	v_mfma_f32_16x16x32_bf16 v[68:71], v[160:163], v[218:221], 0
	v_mfma_f32_16x16x32_bf16 v[64:67], v[186:189], v[218:221], 0
	v_mfma_f32_16x16x32_bf16 v[116:119], v[164:167], v[198:201], v[116:119]
	v_mfma_f32_16x16x32_bf16 v[112:115], v[190:193], v[198:201], v[112:115]
	v_mfma_f32_16x16x32_bf16 v[100:103], v[164:167], v[206:209], v[100:103]
	v_mfma_f32_16x16x32_bf16 v[96:99], v[190:193], v[206:209], v[96:99]
	v_mfma_f32_16x16x32_bf16 v[84:87], v[164:167], v[214:217], v[84:87]
	v_mfma_f32_16x16x32_bf16 v[80:83], v[190:193], v[214:217], v[80:83]
	v_mfma_f32_16x16x32_bf16 v[68:71], v[164:167], v[242:245], v[68:71]
	v_mfma_f32_16x16x32_bf16 v[64:67], v[190:193], v[242:245], v[64:67]
	s_setprio 0
	s_branch .Lzc15_0j
.Lzc15_1:
	s_setprio 1
	s_waitcnt lgkmcnt(0)
	v_mfma_f32_16x16x32_bf16 v[60:63], v[138:141], v[194:197], 0
	v_mfma_f32_16x16x32_bf16 v[56:59], v[152:155], v[194:197], 0
	v_mfma_f32_16x16x32_bf16 v[44:47], v[138:141], v[202:205], 0
	v_mfma_f32_16x16x32_bf16 v[40:43], v[152:155], v[202:205], 0
	v_mfma_f32_16x16x32_bf16 v[28:31], v[138:141], v[210:213], 0
	v_mfma_f32_16x16x32_bf16 v[24:27], v[152:155], v[210:213], 0
	v_mfma_f32_16x16x32_bf16 v[12:15], v[138:141], v[218:221], 0
	v_mfma_f32_16x16x32_bf16 v[8:11], v[152:155], v[218:221], 0
	v_mfma_f32_16x16x32_bf16 v[60:63], v[148:151], v[198:201], v[60:63]
	v_mfma_f32_16x16x32_bf16 v[56:59], v[156:159], v[198:201], v[56:59]
	v_mfma_f32_16x16x32_bf16 v[44:47], v[148:151], v[206:209], v[44:47]
	v_mfma_f32_16x16x32_bf16 v[40:43], v[156:159], v[206:209], v[40:43]
	v_mfma_f32_16x16x32_bf16 v[28:31], v[148:151], v[214:217], v[28:31]
	v_mfma_f32_16x16x32_bf16 v[24:27], v[156:159], v[214:217], v[24:27]
	v_mfma_f32_16x16x32_bf16 v[12:15], v[148:151], v[242:245], v[12:15]
	v_mfma_f32_16x16x32_bf16 v[8:11], v[156:159], v[242:245], v[8:11]
	s_setprio 0
	s_setprio 1
	v_mfma_f32_16x16x32_bf16 v[52:55], v[160:163], v[194:197], 0
	v_mfma_f32_16x16x32_bf16 v[48:51], v[186:189], v[194:197], 0
	v_mfma_f32_16x16x32_bf16 v[36:39], v[160:163], v[202:205], 0
	v_mfma_f32_16x16x32_bf16 v[32:35], v[186:189], v[202:205], 0
	v_mfma_f32_16x16x32_bf16 v[20:23], v[160:163], v[210:213], 0
	v_mfma_f32_16x16x32_bf16 v[16:19], v[186:189], v[210:213], 0
	v_mfma_f32_16x16x32_bf16 v[4:7], v[160:163], v[218:221], 0
	v_mfma_f32_16x16x32_bf16 v[0:3], v[186:189], v[218:221], 0
	v_mfma_f32_16x16x32_bf16 v[52:55], v[164:167], v[198:201], v[52:55]
	v_mfma_f32_16x16x32_bf16 v[48:51], v[190:193], v[198:201], v[48:51]
	v_mfma_f32_16x16x32_bf16 v[36:39], v[164:167], v[206:209], v[36:39]
	v_mfma_f32_16x16x32_bf16 v[32:35], v[190:193], v[206:209], v[32:35]
	v_mfma_f32_16x16x32_bf16 v[20:23], v[164:167], v[214:217], v[20:23]
	v_mfma_f32_16x16x32_bf16 v[16:19], v[190:193], v[214:217], v[16:19]
	v_mfma_f32_16x16x32_bf16 v[4:7], v[164:167], v[242:245], v[4:7]
	v_mfma_f32_16x16x32_bf16 v[0:3], v[190:193], v[242:245], v[0:3]
	s_setprio 0
	s_branch .Lzc15_1j

.LBB0_1030:
	s_ashr_i32 s41, s40, 31
	s_lshl_b64 s[2:3], s[40:41], 19
	v_readlane_b32 s44, v254, 43
	v_readlane_b32 s45, v254, 44
	s_add_u32 s2, s44, s2
	s_addc_u32 s3, s45, s3
	s_ashr_i32 s43, s42, 31
	s_lshl_b64 s[44:45], s[42:43], 19
	v_readlane_b32 s1, v254, 41
	s_add_u32 s44, s1, s44
	v_readlane_b32 s1, v254, 42
	s_addc_u32 s45, s1, s45
	s_andn2_b64 vcc, exec, s[22:23]
	s_cbranch_vccnz .Lzc15_skip
	s_and_b64 s[52:53], s[38:39], exec
	s_cselect_b32 s1, s3, s49
	s_cselect_b32 s41, s2, s48
	s_cselect_b32 s43, s45, s51
	s_cselect_b32 s47, s44, s50
	s_add_u32 s48, s48, 0x40080
	s_addc_u32 s49, s49, 0
	s_add_u32 s67, s50, 0x100
	s_addc_u32 s68, s51, 0
	s_mov_b32 s50, 0
	s_mov_b32 s32, 1
.LBB0_1032:
	s_add_i32 s69, s50, 2
	s_add_u32 s51, s48, 0xfffc0080
	s_addc_u32 s52, s49, -1
	s_add_i32 s70, 0, 0x10000
	s_cmp_eq_u32 s63, s50
	s_cselect_b32 s53, s1, s52
	s_cselect_b32 s52, s41, s51
	v_add_u32_e32 v142, s70, v146
	s_cselect_b32 s51, s43, s68
	s_cselect_b32 s50, s47, s67
	s_add_i32 s72, 0, 0x14000
	ds_read_b128 v[138:141], v142
	ds_read_b128 v[148:151], v142 offset:1024
	ds_read_b128 v[152:155], v142 offset:2048
	ds_read_b128 v[156:159], v142 offset:3072
	v_add_u32_e32 v142, s72, v146
	ds_read_b128 v[160:163], v142
	ds_read_b128 v[164:167], v142 offset:1024
	ds_read_b128 v[186:189], v142 offset:2048
	ds_read_b128 v[190:193], v142 offset:3072
	v_lshl_add_u64 v[142:143], s[48:49], 0, v[134:135]
	s_add_i32 m0, s54, 0xc000
	ds_read_b128 v[194:197], v147
	ds_read_b128 v[198:201], v147 offset:1024
	ds_read_b128 v[202:205], v147 offset:2048
	ds_read_b128 v[206:209], v147 offset:3072
	ds_read_b128 v[210:213], v147 offset:4096
	ds_read_b128 v[214:217], v147 offset:5120
	ds_read_b128 v[218:221], v147 offset:6144
	ds_read_b128 v[242:245], v147 offset:7168
	global_load_lds_dwordx4 v[142:143], off
	v_lshl_add_u64 v[142:143], s[48:49], 0, v[136:137]
	s_add_i32 m0, s54, 0xe000
	s_nop 0
	global_load_lds_dwordx4 v[142:143], off
	s_waitcnt vmcnt(8)
	s_waitcnt lgkmcnt(0)
	s_barrier
	s_cmp_lg_u32 s32, 0
	s_cbranch_scc1 .Lzc15_0
	s_setprio 1
	s_waitcnt lgkmcnt(0)
	v_mfma_f32_16x16x32_bf16 v[124:127], v[138:141], v[194:197], v[124:127]
	v_mfma_f32_16x16x32_bf16 v[120:123], v[152:155], v[194:197], v[120:123]
	v_mfma_f32_16x16x32_bf16 v[108:111], v[138:141], v[202:205], v[108:111]
	v_mfma_f32_16x16x32_bf16 v[104:107], v[152:155], v[202:205], v[104:107]
	v_mfma_f32_16x16x32_bf16 v[92:95], v[138:141], v[210:213], v[92:95]
	v_mfma_f32_16x16x32_bf16 v[88:91], v[152:155], v[210:213], v[88:91]
	v_mfma_f32_16x16x32_bf16 v[76:79], v[138:141], v[218:221], v[76:79]
	v_mfma_f32_16x16x32_bf16 v[72:75], v[152:155], v[218:221], v[72:75]
	v_mfma_f32_16x16x32_bf16 v[124:127], v[148:151], v[198:201], v[124:127]
	v_mfma_f32_16x16x32_bf16 v[120:123], v[156:159], v[198:201], v[120:123]
	v_mfma_f32_16x16x32_bf16 v[108:111], v[148:151], v[206:209], v[108:111]
	v_mfma_f32_16x16x32_bf16 v[104:107], v[156:159], v[206:209], v[104:107]
	v_mfma_f32_16x16x32_bf16 v[92:95], v[148:151], v[214:217], v[92:95]
	v_mfma_f32_16x16x32_bf16 v[88:91], v[156:159], v[214:217], v[88:91]
	v_mfma_f32_16x16x32_bf16 v[76:79], v[148:151], v[242:245], v[76:79]
	v_mfma_f32_16x16x32_bf16 v[72:75], v[156:159], v[242:245], v[72:75]
	s_setprio 0
	s_setprio 1
	v_mfma_f32_16x16x32_bf16 v[116:119], v[160:163], v[194:197], v[116:119]
	v_mfma_f32_16x16x32_bf16 v[112:115], v[186:189], v[194:197], v[112:115]
	v_mfma_f32_16x16x32_bf16 v[100:103], v[160:163], v[202:205], v[100:103]
	v_mfma_f32_16x16x32_bf16 v[96:99], v[186:189], v[202:205], v[96:99]
	v_mfma_f32_16x16x32_bf16 v[84:87], v[160:163], v[210:213], v[84:87]
	v_mfma_f32_16x16x32_bf16 v[80:83], v[186:189], v[210:213], v[80:83]
	v_mfma_f32_16x16x32_bf16 v[68:71], v[160:163], v[218:221], v[68:71]
	v_mfma_f32_16x16x32_bf16 v[64:67], v[186:189], v[218:221], v[64:67]
	v_mfma_f32_16x16x32_bf16 v[116:119], v[164:167], v[198:201], v[116:119]
	v_mfma_f32_16x16x32_bf16 v[112:115], v[190:193], v[198:201], v[112:115]
	v_mfma_f32_16x16x32_bf16 v[100:103], v[164:167], v[206:209], v[100:103]
	v_mfma_f32_16x16x32_bf16 v[96:99], v[190:193], v[206:209], v[96:99]
	v_mfma_f32_16x16x32_bf16 v[84:87], v[164:167], v[214:217], v[84:87]
	v_mfma_f32_16x16x32_bf16 v[80:83], v[190:193], v[214:217], v[80:83]
	v_mfma_f32_16x16x32_bf16 v[68:71], v[164:167], v[242:245], v[68:71]
	v_mfma_f32_16x16x32_bf16 v[64:67], v[190:193], v[242:245], v[64:67]
	s_setprio 0
.Lzc15_0j:
	s_barrier
	s_add_i32 s70, s70, s34
	v_lshl_add_u64 v[142:143], s[50:51], 0, v[168:169]
	s_mov_b32 m0, s70
	ds_read_b128 v[194:197], v147 offset:16384
	ds_read_b128 v[198:201], v147 offset:17408
	ds_read_b128 v[202:205], v147 offset:18432
	ds_read_b128 v[206:209], v147 offset:19456
	ds_read_b128 v[210:213], v147 offset:20480
	ds_read_b128 v[214:217], v147 offset:21504
	ds_read_b128 v[218:221], v147 offset:22528
	ds_read_b128 v[242:245], v147 offset:23552
	global_load_lds_dwordx4 v[142:143], off
	s_add_i32 m0, s70, 0x2000
	s_add_u32 s70, s50, 0x40000
	v_lshl_add_u64 v[222:223], s[50:51], 0, v[132:133]
	s_addc_u32 s71, s51, 0
	s_add_i32 s72, s72, s34
	global_load_lds_dwordx4 v[222:223], off
	v_lshl_add_u64 v[236:237], s[70:71], 0, v[168:169]
	s_mov_b32 m0, s72
	v_lshl_add_u64 v[246:247], s[52:53], 0, v[130:131]
	global_load_lds_dwordx4 v[236:237], off
	v_lshl_add_u64 v[236:237], s[70:71], 0, v[132:133]
	s_add_i32 m0, s72, 0x2000
	s_nop 0
	global_load_lds_dwordx4 v[236:237], off
	v_lshl_add_u64 v[236:237], s[52:53], 0, v[128:129]
	s_mov_b32 m0, s54
	s_nop 0
	global_load_lds_dwordx4 v[236:237], off
	s_mov_b32 m0, s55
	s_nop 0
	global_load_lds_dwordx4 v[246:247], off
	s_waitcnt vmcnt(8)
	s_waitcnt lgkmcnt(0)
	s_barrier
	s_cmp_lg_u32 s32, 0
	s_cbranch_scc1 .Lzc15_1
	s_setprio 1
	s_waitcnt lgkmcnt(0)
	v_mfma_f32_16x16x32_bf16 v[60:63], v[138:141], v[194:197], v[60:63]
	v_mfma_f32_16x16x32_bf16 v[56:59], v[152:155], v[194:197], v[56:59]
	v_mfma_f32_16x16x32_bf16 v[44:47], v[138:141], v[202:205], v[44:47]
	v_mfma_f32_16x16x32_bf16 v[40:43], v[152:155], v[202:205], v[40:43]
	v_mfma_f32_16x16x32_bf16 v[28:31], v[138:141], v[210:213], v[28:31]
	v_mfma_f32_16x16x32_bf16 v[24:27], v[152:155], v[210:213], v[24:27]
	v_mfma_f32_16x16x32_bf16 v[12:15], v[138:141], v[218:221], v[12:15]
	v_mfma_f32_16x16x32_bf16 v[8:11], v[152:155], v[218:221], v[8:11]
	v_mfma_f32_16x16x32_bf16 v[60:63], v[148:151], v[198:201], v[60:63]
	v_mfma_f32_16x16x32_bf16 v[56:59], v[156:159], v[198:201], v[56:59]
	v_mfma_f32_16x16x32_bf16 v[44:47], v[148:151], v[206:209], v[44:47]
	v_mfma_f32_16x16x32_bf16 v[40:43], v[156:159], v[206:209], v[40:43]
	v_mfma_f32_16x16x32_bf16 v[28:31], v[148:151], v[214:217], v[28:31]
	v_mfma_f32_16x16x32_bf16 v[24:27], v[156:159], v[214:217], v[24:27]
	v_mfma_f32_16x16x32_bf16 v[12:15], v[148:151], v[242:245], v[12:15]
	v_mfma_f32_16x16x32_bf16 v[8:11], v[156:159], v[242:245], v[8:11]
	s_setprio 0
	s_setprio 1
	v_mfma_f32_16x16x32_bf16 v[52:55], v[160:163], v[194:197], v[52:55]
	v_mfma_f32_16x16x32_bf16 v[48:51], v[186:189], v[194:197], v[48:51]
	v_mfma_f32_16x16x32_bf16 v[36:39], v[160:163], v[202:205], v[36:39]
	v_mfma_f32_16x16x32_bf16 v[32:35], v[186:189], v[202:205], v[32:35]
	v_mfma_f32_16x16x32_bf16 v[20:23], v[160:163], v[210:213], v[20:23]
	v_mfma_f32_16x16x32_bf16 v[16:19], v[186:189], v[210:213], v[16:19]
	v_mfma_f32_16x16x32_bf16 v[4:7], v[160:163], v[218:221], v[4:7]
	v_mfma_f32_16x16x32_bf16 v[0:3], v[186:189], v[218:221], v[0:3]
	v_mfma_f32_16x16x32_bf16 v[52:55], v[164:167], v[198:201], v[52:55]
	v_mfma_f32_16x16x32_bf16 v[48:51], v[190:193], v[198:201], v[48:51]
	v_mfma_f32_16x16x32_bf16 v[36:39], v[164:167], v[206:209], v[36:39]
	v_mfma_f32_16x16x32_bf16 v[32:35], v[190:193], v[206:209], v[32:35]
	v_mfma_f32_16x16x32_bf16 v[20:23], v[164:167], v[214:217], v[20:23]
	v_mfma_f32_16x16x32_bf16 v[16:19], v[190:193], v[214:217], v[16:19]
	v_mfma_f32_16x16x32_bf16 v[4:7], v[164:167], v[242:245], v[4:7]
	v_mfma_f32_16x16x32_bf16 v[0:3], v[190:193], v[242:245], v[0:3]
	s_setprio 0
.Lzc15_1j:
	s_barrier
	s_add_i32 s70, 0, 0x18000
	s_add_i32 s71, 0, 0x1c000
	v_add_u32_e32 v156, s70, v146
	v_add_u32_e32 v179, s71, v146
	ds_read_b128 v[138:141], v156
	ds_read_b128 v[148:151], v156 offset:1024
	ds_read_b128 v[152:155], v156 offset:2048
	ds_read_b128 v[156:159], v156 offset:3072
	ds_read_b128 v[160:163], v179
	ds_read_b128 v[164:167], v179 offset:1024
	ds_read_b128 v[186:189], v179 offset:2048
	ds_read_b128 v[190:193], v179 offset:3072
	s_add_u32 s52, s52, 0x40000
	s_addc_u32 s53, s53, 0
	s_mov_b32 m0, s56
	v_lshl_add_u64 v[248:249], s[52:53], 0, v[128:129]
	ds_read_b128 v[194:197], v147 offset:32768
	ds_read_b128 v[198:201], v147 offset:33792
	ds_read_b128 v[202:205], v147 offset:34816
	ds_read_b128 v[206:209], v147 offset:35840
	ds_read_b128 v[210:213], v147 offset:36864
	ds_read_b128 v[214:217], v147 offset:37888
	ds_read_b128 v[218:221], v147 offset:38912
	ds_read_b128 v[242:245], v147 offset:39936
	global_load_lds_dwordx4 v[248:249], off
	v_lshl_add_u64 v[248:249], s[52:53], 0, v[130:131]
	s_mov_b32 m0, s57
	s_nop 0
	global_load_lds_dwordx4 v[248:249], off
	s_waitcnt vmcnt(8)
	s_waitcnt lgkmcnt(0)
	s_barrier
	s_setprio 1
	s_waitcnt lgkmcnt(0)
	v_mfma_f32_16x16x32_bf16 v[124:127], v[138:141], v[194:197], v[124:127]
	v_mfma_f32_16x16x32_bf16 v[120:123], v[152:155], v[194:197], v[120:123]
	v_mfma_f32_16x16x32_bf16 v[108:111], v[138:141], v[202:205], v[108:111]
	v_mfma_f32_16x16x32_bf16 v[104:107], v[152:155], v[202:205], v[104:107]
	v_mfma_f32_16x16x32_bf16 v[92:95], v[138:141], v[210:213], v[92:95]
	v_mfma_f32_16x16x32_bf16 v[88:91], v[152:155], v[210:213], v[88:91]
	v_mfma_f32_16x16x32_bf16 v[76:79], v[138:141], v[218:221], v[76:79]
	v_mfma_f32_16x16x32_bf16 v[72:75], v[152:155], v[218:221], v[72:75]
	v_mfma_f32_16x16x32_bf16 v[124:127], v[148:151], v[198:201], v[124:127]
	v_mfma_f32_16x16x32_bf16 v[120:123], v[156:159], v[198:201], v[120:123]
	v_mfma_f32_16x16x32_bf16 v[108:111], v[148:151], v[206:209], v[108:111]
	v_mfma_f32_16x16x32_bf16 v[104:107], v[156:159], v[206:209], v[104:107]
	v_mfma_f32_16x16x32_bf16 v[92:95], v[148:151], v[214:217], v[92:95]
	v_mfma_f32_16x16x32_bf16 v[88:91], v[156:159], v[214:217], v[88:91]
	v_mfma_f32_16x16x32_bf16 v[76:79], v[148:151], v[242:245], v[76:79]
	v_mfma_f32_16x16x32_bf16 v[72:75], v[156:159], v[242:245], v[72:75]
	s_setprio 0
	s_setprio 1
	v_mfma_f32_16x16x32_bf16 v[116:119], v[160:163], v[194:197], v[116:119]
	v_mfma_f32_16x16x32_bf16 v[112:115], v[186:189], v[194:197], v[112:115]
	v_mfma_f32_16x16x32_bf16 v[100:103], v[160:163], v[202:205], v[100:103]
	v_mfma_f32_16x16x32_bf16 v[96:99], v[186:189], v[202:205], v[96:99]
	v_mfma_f32_16x16x32_bf16 v[84:87], v[160:163], v[210:213], v[84:87]
	v_mfma_f32_16x16x32_bf16 v[80:83], v[186:189], v[210:213], v[80:83]
	v_mfma_f32_16x16x32_bf16 v[68:71], v[160:163], v[218:221], v[68:71]
	v_mfma_f32_16x16x32_bf16 v[64:67], v[186:189], v[218:221], v[64:67]
	v_mfma_f32_16x16x32_bf16 v[116:119], v[164:167], v[198:201], v[116:119]
	v_mfma_f32_16x16x32_bf16 v[112:115], v[190:193], v[198:201], v[112:115]
	v_mfma_f32_16x16x32_bf16 v[100:103], v[164:167], v[206:209], v[100:103]
	v_mfma_f32_16x16x32_bf16 v[96:99], v[190:193], v[206:209], v[96:99]
	v_mfma_f32_16x16x32_bf16 v[84:87], v[164:167], v[214:217], v[84:87]
	v_mfma_f32_16x16x32_bf16 v[80:83], v[190:193], v[214:217], v[80:83]
	v_mfma_f32_16x16x32_bf16 v[68:71], v[164:167], v[242:245], v[68:71]
	v_mfma_f32_16x16x32_bf16 v[64:67], v[190:193], v[242:245], v[64:67]
	s_setprio 0
	s_barrier
	s_add_i32 s52, s70, s34
	v_lshl_add_u64 v[142:143], v[142:143], 0, s[28:29]
	s_mov_b32 m0, s52
	ds_read_b128 v[194:197], v147 offset:49152
	ds_read_b128 v[198:201], v147 offset:50176
	ds_read_b128 v[202:205], v147 offset:51200
	ds_read_b128 v[206:209], v147 offset:52224
	ds_read_b128 v[210:213], v147 offset:53248
	ds_read_b128 v[214:217], v147 offset:54272
	ds_read_b128 v[218:221], v147 offset:55296
	ds_read_b128 v[242:245], v147 offset:56320
	global_load_lds_dwordx4 v[142:143], off
	s_add_i32 m0, s52, 0x2000
	s_add_u32 s50, s50, 0x40080
	v_lshl_add_u64 v[142:143], v[222:223], 0, s[28:29]
	s_addc_u32 s51, s51, 0
	s_add_i32 s52, s71, s34
	global_load_lds_dwordx4 v[142:143], off
	v_lshl_add_u64 v[142:143], s[50:51], 0, v[168:169]
	s_mov_b32 m0, s52
	s_nop 0
	global_load_lds_dwordx4 v[142:143], off
	v_lshl_add_u64 v[142:143], s[50:51], 0, v[132:133]
	s_add_i32 m0, s52, 0x2000
	s_nop 0
	global_load_lds_dwordx4 v[142:143], off
	v_lshl_add_u64 v[142:143], v[236:237], 0, s[28:29]
	s_mov_b32 m0, s61
	s_nop 0
	global_load_lds_dwordx4 v[142:143], off
	v_lshl_add_u64 v[142:143], v[246:247], 0, s[28:29]
	s_mov_b32 m0, s62
	s_nop 0
	global_load_lds_dwordx4 v[142:143], off
	s_waitcnt vmcnt(8)
	s_waitcnt lgkmcnt(0)
	s_barrier
	s_setprio 1
	s_waitcnt lgkmcnt(0)
	v_mfma_f32_16x16x32_bf16 v[60:63], v[138:141], v[194:197], v[60:63]
	v_mfma_f32_16x16x32_bf16 v[56:59], v[152:155], v[194:197], v[56:59]
	v_mfma_f32_16x16x32_bf16 v[44:47], v[138:141], v[202:205], v[44:47]
	v_mfma_f32_16x16x32_bf16 v[40:43], v[152:155], v[202:205], v[40:43]
	v_mfma_f32_16x16x32_bf16 v[28:31], v[138:141], v[210:213], v[28:31]
	v_mfma_f32_16x16x32_bf16 v[24:27], v[152:155], v[210:213], v[24:27]
	v_mfma_f32_16x16x32_bf16 v[12:15], v[138:141], v[218:221], v[12:15]
	v_mfma_f32_16x16x32_bf16 v[8:11], v[152:155], v[218:221], v[8:11]
	v_mfma_f32_16x16x32_bf16 v[60:63], v[148:151], v[198:201], v[60:63]
	v_mfma_f32_16x16x32_bf16 v[56:59], v[156:159], v[198:201], v[56:59]
	v_mfma_f32_16x16x32_bf16 v[44:47], v[148:151], v[206:209], v[44:47]
	v_mfma_f32_16x16x32_bf16 v[40:43], v[156:159], v[206:209], v[40:43]
	v_mfma_f32_16x16x32_bf16 v[28:31], v[148:151], v[214:217], v[28:31]
	v_mfma_f32_16x16x32_bf16 v[24:27], v[156:159], v[214:217], v[24:27]
	v_mfma_f32_16x16x32_bf16 v[12:15], v[148:151], v[242:245], v[12:15]
	v_mfma_f32_16x16x32_bf16 v[8:11], v[156:159], v[242:245], v[8:11]
	s_setprio 0
	s_setprio 1
	v_mfma_f32_16x16x32_bf16 v[52:55], v[160:163], v[194:197], v[52:55]
	v_mfma_f32_16x16x32_bf16 v[48:51], v[186:189], v[194:197], v[48:51]
	v_mfma_f32_16x16x32_bf16 v[36:39], v[160:163], v[202:205], v[36:39]
	v_mfma_f32_16x16x32_bf16 v[32:35], v[186:189], v[202:205], v[32:35]
	v_mfma_f32_16x16x32_bf16 v[20:23], v[160:163], v[210:213], v[20:23]
	v_mfma_f32_16x16x32_bf16 v[16:19], v[186:189], v[210:213], v[16:19]
	v_mfma_f32_16x16x32_bf16 v[4:7], v[160:163], v[218:221], v[4:7]
	v_mfma_f32_16x16x32_bf16 v[0:3], v[186:189], v[218:221], v[0:3]
	v_mfma_f32_16x16x32_bf16 v[52:55], v[164:167], v[198:201], v[52:55]
	v_mfma_f32_16x16x32_bf16 v[48:51], v[190:193], v[198:201], v[48:51]
	v_mfma_f32_16x16x32_bf16 v[36:39], v[164:167], v[206:209], v[36:39]
	v_mfma_f32_16x16x32_bf16 v[32:35], v[190:193], v[206:209], v[32:35]
	v_mfma_f32_16x16x32_bf16 v[20:23], v[164:167], v[214:217], v[20:23]
	v_mfma_f32_16x16x32_bf16 v[16:19], v[190:193], v[214:217], v[16:19]
	v_mfma_f32_16x16x32_bf16 v[4:7], v[164:167], v[242:245], v[4:7]
	v_mfma_f32_16x16x32_bf16 v[0:3], v[190:193], v[242:245], v[0:3]
	s_setprio 0
	s_barrier
	s_add_u32 s48, s48, 0x100
	s_addc_u32 s49, s49, 0
	s_add_u32 s67, s67, 0x100
	s_addc_u32 s68, s68, 0
	s_cmp_ge_i32 s69, s58
	s_mov_b32 s50, s69
	s_mov_b32 s32, 0
	s_cbranch_scc0 .LBB0_1032
